# PEER top-k: the two single-element insertions use v_med3_u32 (new[i] = med3(a[i-1], a[i], x)): 32 fewer VALU instructions per lane
# speedup vs baseline: 1.0047x; 1.0029x over previous
; #define LAS __attribute__((address_space(3)))
; __device__ __forceinline__ unsigned f2key(float f) { const unsigned u = __float_as_uint(f); return (u & 0x80000000u) ? ~u : (u | 0x80000000u); }
; __device__ __forceinline__ void peer_tile(const Args& A, LAS unsigned char* lds, int tile) {
;     int tid_o = threadIdx.x; asm volatile("" : "+v"(tid_o)); const int tid = tid_o, lane = tid & 63, w = tid >> 6, g = lane >> 4, l15 = lane & 15;
;     const bf16_t* QRY = (const bf16_t*)(A.ws + WS_QRY);
;     const bf16_t* KEYS = (const bf16_t*)(A.ws + WS_KEYS);
;     const bf16_t* ACT = (const bf16_t*)(A.ws + WS_ACT);
;     const float* MOD = (const float*)(A.ws + WS_MOD);
;     LAS unsigned* idx = (LAS unsigned*)(lds + PE_IDX) + (w * 64 + lane) * 33;
;     LAS u32x2* SEL = (LAS u32x2*)(lds + PE_SEL);
;     {
;         const int tg = w & 3, hg = w >> 2, tl = 16 * tg + l15;
;         const size_t m = (size_t)tile * 64 + tl;
;         unsigned LA[4][2][16];
; #pragma unroll
;         for (int hh = 0; hh < 4; ++hh) {
;             const int h = 4 * hg + hh;
; #pragma unroll
;             for (int p = 0; p < 2; ++p) {
;                 const int hp = 2 * h + p;
;                 unsigned k0[16], k1[16];
;                 { const bf16_t* sp = QRY + m * 2048 + hp * 128 + 32 * g;
;                   const u32x4 s0 = *(const u32x4*)sp, s1 = *(const u32x4*)(sp + 8), s2 = *(const u32x4*)(sp + 16), s3 = *(const u32x4*)(sp + 24);
;                   const unsigned sw[16] = {s0.x, s0.y, s0.z, s0.w, s1.x, s1.y, s1.z, s1.w, s2.x, s2.y, s2.z, s2.w, s3.x, s3.y, s3.z, s3.w};
; #pragma unroll
;                   for (int i = 0; i < 16; ++i) {
;                       const float lo = (float)__builtin_bit_cast(_Float16, (unsigned short)(sw[i] & 0xffffu)), hi = (float)__builtin_bit_cast(_Float16, (unsigned short)(sw[i] >> 16));
;                       const unsigned klo = (f2key(lo) & ~127u) | (unsigned)(127 - (32 * g + 2 * i)), khi = (f2key(hi) & ~127u) | (unsigned)(127 - (32 * g + 2 * i + 1));
;                       if (i < 8) { k0[2 * i] = klo; k0[2 * i + 1] = khi; } else { k1[2 * (i - 8)] = klo; k1[2 * (i - 8) + 1] = khi; } } }
.LBB0_699:
	s_mov_b64 exec, -1
	s_mov_b32 s33, 0x80000000
	s_mov_b32 s40, 0x7fffff80
	s_mov_b32 s41, 0x7fffffff
	v_and_b32_e32 v68, 63, v214
	v_lshrrev_b32_e32 v66, 6, v214
	s_nop 0
	v_readfirstlane_b32 s36, v66
	s_lshl_b32 s0, s2, 18
	s_lshl_b32 s1, s36, 9
	s_add_u32 s34, s54, s0
	s_addc_u32 s35, s55, 0
	s_add_u32 s34, s34, s1
	s_addc_u32 s35, s35, 0
	v_lshrrev_b32_e32 v66, 3, v68
	v_and_b32_e32 v64, 7, v68
	v_lshlrev_b32_e32 v64, 4, v64
	v_mul_u32_u24_e32 v65, 0x90, v66
	v_lshl_add_u32 v66, v66, 12, v64
	s_mul_i32 s0, s36, 0x2400
	s_cmp_eq_u32 s36, 7
	s_cselect_b32 s0, 0x21000, s0
	v_add3_u32 v64, v64, v65, s0
	v_mul_u32_u24_e32 v65, 0x90, v68
	v_add_u32_e32 v65, s0, v65
	v_mul_u32_u24_e32 v67, 0x84, v68
	v_lshlrev_b32_e32 v68, 10, v68
	s_lshl_b32 s1, s36, 7
	s_add_i32 s1, s1, 0x11000
	v_add_u32_e32 v67, s0, v67
	v_add_u32_e32 v68, s1, v68
	s_mov_b64 s[38:39], s[34:35]
	global_load_dwordx4 v[0:3], v66, s[38:39] offset:0
	s_add_u32 s38, s38, 0x8000
	s_addc_u32 s39, s39, 0
	global_load_dwordx4 v[4:7], v66, s[38:39] offset:0
	s_add_u32 s38, s38, 0x8000
	s_addc_u32 s39, s39, 0
	global_load_dwordx4 v[8:11], v66, s[38:39] offset:0
	s_add_u32 s38, s38, 0x8000
	s_addc_u32 s39, s39, 0
	global_load_dwordx4 v[12:15], v66, s[38:39] offset:0
	s_add_u32 s38, s38, 0x8000
	s_addc_u32 s39, s39, 0
	global_load_dwordx4 v[16:19], v66, s[38:39] offset:0
	s_add_u32 s38, s38, 0x8000
	s_addc_u32 s39, s39, 0
	global_load_dwordx4 v[20:23], v66, s[38:39] offset:0
	s_add_u32 s38, s38, 0x8000
	s_addc_u32 s39, s39, 0
	global_load_dwordx4 v[24:27], v66, s[38:39] offset:0
	s_add_u32 s38, s38, 0x8000
	s_addc_u32 s39, s39, 0
	global_load_dwordx4 v[28:31], v66, s[38:39] offset:0
	s_mov_b64 s[38:39], s[34:35]
	global_load_dwordx4 v[32:35], v66, s[38:39] offset:128
	s_add_u32 s38, s38, 0x8000
	s_addc_u32 s39, s39, 0
	global_load_dwordx4 v[36:39], v66, s[38:39] offset:128
	s_add_u32 s38, s38, 0x8000
	s_addc_u32 s39, s39, 0
	global_load_dwordx4 v[40:43], v66, s[38:39] offset:128
	s_add_u32 s38, s38, 0x8000
	s_addc_u32 s39, s39, 0
	global_load_dwordx4 v[44:47], v66, s[38:39] offset:128
	s_add_u32 s38, s38, 0x8000
	s_addc_u32 s39, s39, 0
	global_load_dwordx4 v[48:51], v66, s[38:39] offset:128
	s_add_u32 s38, s38, 0x8000
	s_addc_u32 s39, s39, 0
	global_load_dwordx4 v[52:55], v66, s[38:39] offset:128
	s_add_u32 s38, s38, 0x8000
	s_addc_u32 s39, s39, 0
	global_load_dwordx4 v[56:59], v66, s[38:39] offset:128
	s_add_u32 s38, s38, 0x8000
	s_addc_u32 s39, s39, 0
	global_load_dwordx4 v[60:63], v66, s[38:39] offset:128
	s_waitcnt vmcnt(8)
	ds_write_b128 v64, v[0:3] offset:0
	ds_write_b128 v64, v[4:7] offset:1152
	ds_write_b128 v64, v[8:11] offset:2304
	ds_write_b128 v64, v[12:15] offset:3456
	ds_write_b128 v64, v[16:19] offset:4608
	ds_write_b128 v64, v[20:23] offset:5760
	ds_write_b128 v64, v[24:27] offset:6912
	ds_write_b128 v64, v[28:31] offset:8064
	s_waitcnt lgkmcnt(0)
	ds_read_b128 v[0:3], v65 offset:0
	ds_read_b128 v[4:7], v65 offset:16
	ds_read_b128 v[8:11], v65 offset:32
	ds_read_b128 v[12:15], v65 offset:48
	ds_read_b128 v[16:19], v65 offset:64
	ds_read_b128 v[20:23], v65 offset:80
	ds_read_b128 v[24:27], v65 offset:96
	ds_read_b128 v[28:31], v65 offset:112
	s_waitcnt lgkmcnt(0)
	v_cvt_f32_f16_e32 v70, v0
	v_cvt_f32_f16_sdwa v71, v0 dst_sel:DWORD dst_unused:UNUSED_PAD src0_sel:WORD_1
	v_ashrrev_i32_e32 v72, 31, v70
	v_bitop3_b32 v70, v70, v72, s40 bitop3:0x78
	v_xor_b32_e32 v70, 0x8000007f, v70
	v_ashrrev_i32_e32 v72, 31, v71
	v_bitop3_b32 v71, v71, v72, s40 bitop3:0x78
	v_xor_b32_e32 v71, 0x8000007e, v71
	v_cvt_f32_f16_e32 v72, v1
	v_cvt_f32_f16_sdwa v73, v1 dst_sel:DWORD dst_unused:UNUSED_PAD src0_sel:WORD_1
	v_ashrrev_i32_e32 v74, 31, v72
	v_bitop3_b32 v72, v72, v74, s40 bitop3:0x78
	v_xor_b32_e32 v72, 0x8000007d, v72
	v_ashrrev_i32_e32 v74, 31, v73
	v_bitop3_b32 v73, v73, v74, s40 bitop3:0x78
	v_xor_b32_e32 v73, 0x8000007c, v73
	v_cvt_f32_f16_e32 v74, v2
	v_cvt_f32_f16_sdwa v75, v2 dst_sel:DWORD dst_unused:UNUSED_PAD src0_sel:WORD_1
	v_ashrrev_i32_e32 v76, 31, v74
	v_bitop3_b32 v74, v74, v76, s40 bitop3:0x78
	v_xor_b32_e32 v74, 0x8000007b, v74
	v_ashrrev_i32_e32 v76, 31, v75
	v_bitop3_b32 v75, v75, v76, s40 bitop3:0x78
	v_xor_b32_e32 v75, 0x8000007a, v75
	v_cvt_f32_f16_e32 v76, v3
	v_cvt_f32_f16_sdwa v77, v3 dst_sel:DWORD dst_unused:UNUSED_PAD src0_sel:WORD_1
	v_ashrrev_i32_e32 v78, 31, v76
	v_bitop3_b32 v76, v76, v78, s40 bitop3:0x78
	v_xor_b32_e32 v76, 0x80000079, v76
	v_ashrrev_i32_e32 v78, 31, v77
	v_bitop3_b32 v77, v77, v78, s40 bitop3:0x78
	v_xor_b32_e32 v77, 0x80000078, v77
	v_cvt_f32_f16_e32 v78, v4
	v_cvt_f32_f16_sdwa v79, v4 dst_sel:DWORD dst_unused:UNUSED_PAD src0_sel:WORD_1
	v_ashrrev_i32_e32 v80, 31, v78
	v_bitop3_b32 v78, v78, v80, s40 bitop3:0x78
	v_xor_b32_e32 v78, 0x80000077, v78
	v_ashrrev_i32_e32 v80, 31, v79
	v_bitop3_b32 v79, v79, v80, s40 bitop3:0x78
	v_xor_b32_e32 v79, 0x80000076, v79
	v_cvt_f32_f16_e32 v80, v5
	v_cvt_f32_f16_sdwa v81, v5 dst_sel:DWORD dst_unused:UNUSED_PAD src0_sel:WORD_1
	v_ashrrev_i32_e32 v82, 31, v80
	v_bitop3_b32 v80, v80, v82, s40 bitop3:0x78
	v_xor_b32_e32 v80, 0x80000075, v80
	v_ashrrev_i32_e32 v82, 31, v81
	v_bitop3_b32 v81, v81, v82, s40 bitop3:0x78
	v_xor_b32_e32 v81, 0x80000074, v81
	v_cvt_f32_f16_e32 v82, v6
	v_cvt_f32_f16_sdwa v83, v6 dst_sel:DWORD dst_unused:UNUSED_PAD src0_sel:WORD_1
	v_ashrrev_i32_e32 v84, 31, v82
	v_bitop3_b32 v82, v82, v84, s40 bitop3:0x78
	v_xor_b32_e32 v82, 0x80000073, v82
	v_ashrrev_i32_e32 v84, 31, v83
	v_bitop3_b32 v83, v83, v84, s40 bitop3:0x78
	v_xor_b32_e32 v83, 0x80000072, v83
	v_cvt_f32_f16_e32 v84, v7
	v_cvt_f32_f16_sdwa v85, v7 dst_sel:DWORD dst_unused:UNUSED_PAD src0_sel:WORD_1
; __device__ __forceinline__ unsigned f2key(float f) { const unsigned u = __float_as_uint(f); return (u & 0x80000000u) ? ~u : (u | 0x80000000u); }
; #define CE_DESC(a, b) do { const unsigned _mx = (a) > (b) ? (a) : (b), _mn = (a) > (b) ? (b) : (a); (a) = _mx; (b) = _mn; } while (0)
; __device__ __forceinline__ void sort16_desc(unsigned (&k)[16]) {
; #pragma unroll
;     for (int size = 2; size <= 16; size <<= 1)
; #pragma unroll
;         for (int stride = size >> 1; stride > 0; stride >>= 1)
; #pragma unroll
;             for (int i = 0; i < 16; ++i) { const int j = i ^ stride;
;                 if (j > i) { if ((i & size) == 0) CE_DESC(k[i], k[j]); else CE_DESC(k[j], k[i]); } }
; }
; __device__ __forceinline__ void peer_tile(const Args& A, LAS unsigned char* lds, int tile) {
;     ...
;                   for (int i = 0; i < 16; ++i) {
;                       const float lo = (float)__builtin_bit_cast(_Float16, (unsigned short)(sw[i] & 0xffffu)), hi = (float)__builtin_bit_cast(_Float16, (unsigned short)(sw[i] >> 16));
;                       const unsigned klo = (f2key(lo) & ~127u) | (unsigned)(127 - (32 * g + 2 * i)), khi = (f2key(hi) & ~127u) | (unsigned)(127 - (32 * g + 2 * i + 1));
;                       if (i < 8) { k0[2 * i] = klo; k0[2 * i + 1] = khi; } else { k1[2 * (i - 8)] = klo; k1[2 * (i - 8) + 1] = khi; } } }
;                 sort16_desc(k0); sort16_desc(k1); merge16(k0, k1);
	v_ashrrev_i32_e32 v86, 31, v84
	v_bitop3_b32 v84, v84, v86, s40 bitop3:0x78
	v_xor_b32_e32 v84, 0x80000071, v84
	v_ashrrev_i32_e32 v86, 31, v85
	v_bitop3_b32 v85, v85, v86, s40 bitop3:0x78
	v_xor_b32_e32 v85, 0x80000070, v85
	v_max_u32_e32 v86, v70, v83
	v_min_u32_e32 v83, v70, v83
	v_max_u32_e32 v70, v71, v82
	v_min_u32_e32 v82, v71, v82
	v_max_u32_e32 v71, v72, v85
	v_min_u32_e32 v85, v72, v85
	v_max_u32_e32 v72, v73, v84
	v_min_u32_e32 v84, v73, v84
	v_max_u32_e32 v73, v74, v78
	v_min_u32_e32 v78, v74, v78
	v_max_u32_e32 v74, v75, v76
	v_min_u32_e32 v76, v75, v76
	v_max_u32_e32 v75, v77, v81
	v_min_u32_e32 v81, v77, v81
	v_max_u32_e32 v77, v79, v80
	v_min_u32_e32 v80, v79, v80
	v_max_u32_e32 v79, v86, v74
	v_min_u32_e32 v74, v86, v74
	v_max_u32_e32 v86, v70, v75
	v_min_u32_e32 v75, v70, v75
	v_max_u32_e32 v70, v71, v77
	v_min_u32_e32 v77, v71, v77
	v_max_u32_e32 v71, v72, v73
	v_min_u32_e32 v73, v72, v73
	v_max_u32_e32 v72, v76, v83
	v_min_u32_e32 v83, v76, v83
	v_max_u32_e32 v76, v78, v84
	v_min_u32_e32 v84, v78, v84
	v_max_u32_e32 v78, v80, v85
	v_min_u32_e32 v85, v80, v85
	v_max_u32_e32 v80, v81, v82
	v_min_u32_e32 v82, v81, v82
	v_max_u32_e32 v81, v79, v86
	v_min_u32_e32 v86, v79, v86
	v_max_u32_e32 v79, v70, v71
	v_min_u32_e32 v71, v70, v71
	v_max_u32_e32 v70, v73, v74
	v_min_u32_e32 v74, v73, v74
	v_max_u32_e32 v73, v72, v76
	v_min_u32_e32 v76, v72, v76
	v_max_u32_e32 v72, v75, v77
	v_min_u32_e32 v77, v75, v77
	v_max_u32_e32 v75, v78, v80
	v_min_u32_e32 v80, v78, v80
	v_max_u32_e32 v78, v82, v83
	v_min_u32_e32 v83, v82, v83
	v_max_u32_e32 v82, v84, v85
	v_min_u32_e32 v85, v84, v85
	v_max_u32_e32 v84, v81, v79
	v_min_u32_e32 v79, v81, v79
	v_max_u32_e32 v81, v86, v71
	v_min_u32_e32 v71, v86, v71
	v_max_u32_e32 v86, v70, v75
	v_min_u32_e32 v75, v70, v75
	v_max_u32_e32 v70, v74, v80
	v_min_u32_e32 v80, v74, v80
	v_max_u32_e32 v74, v73, v72
	v_min_u32_e32 v72, v73, v72
	v_max_u32_e32 v73, v76, v77
	v_min_u32_e32 v77, v76, v77
	v_max_u32_e32 v76, v78, v82
	v_min_u32_e32 v82, v78, v82
	v_max_u32_e32 v78, v83, v85
	v_min_u32_e32 v85, v83, v85
	v_max_u32_e32 v83, v81, v79
	v_min_u32_e32 v79, v81, v79
	v_max_u32_e32 v81, v71, v76
	v_min_u32_e32 v76, v71, v76
	v_max_u32_e32 v71, v86, v74
	v_min_u32_e32 v74, v86, v74
	v_max_u32_e32 v86, v70, v72
	v_min_u32_e32 v72, v70, v72
	v_max_u32_e32 v70, v73, v75
	v_min_u32_e32 v75, v73, v75
	v_max_u32_e32 v73, v77, v80
	v_min_u32_e32 v80, v77, v80
	v_max_u32_e32 v77, v78, v82
	v_min_u32_e32 v82, v78, v82
	v_max_u32_e32 v78, v83, v71
	v_min_u32_e32 v71, v83, v71
	v_max_u32_e32 v83, v79, v74
	v_min_u32_e32 v74, v79, v74
	v_max_u32_e32 v79, v86, v70
	v_min_u32_e32 v70, v86, v70
	v_max_u32_e32 v86, v72, v75
	v_min_u32_e32 v75, v72, v75
	v_max_u32_e32 v72, v73, v77
	v_min_u32_e32 v77, v73, v77
	v_max_u32_e32 v73, v80, v82
	v_min_u32_e32 v82, v80, v82
	v_max_u32_e32 v80, v83, v71
	v_min_u32_e32 v71, v83, v71
	v_max_u32_e32 v83, v81, v74
	v_min_u32_e32 v74, v81, v74
	v_max_u32_e32 v81, v72, v76
	v_min_u32_e32 v76, v72, v76
	v_max_u32_e32 v72, v73, v77
	v_min_u32_e32 v77, v73, v77
	v_max_u32_e32 v73, v83, v79
	v_min_u32_e32 v79, v83, v79
	v_max_u32_e32 v83, v74, v70
	v_min_u32_e32 v70, v74, v70
	v_max_u32_e32 v74, v86, v81
	v_min_u32_e32 v81, v86, v81
	v_max_u32_e32 v86, v75, v76
	v_min_u32_e32 v76, v75, v76
	v_max_u32_e32 v75, v73, v71
	v_min_u32_e32 v71, v73, v71
	v_max_u32_e32 v73, v79, v83
	v_min_u32_e32 v83, v79, v83
	v_max_u32_e32 v79, v74, v70
	v_min_u32_e32 v70, v74, v70
	v_max_u32_e32 v74, v81, v86
	v_min_u32_e32 v86, v81, v86
	v_max_u32_e32 v81, v72, v76
	v_min_u32_e32 v76, v72, v76
	v_max_u32_e32 v72, v83, v79
	v_min_u32_e32 v79, v83, v79
	v_max_u32_e32 v83, v70, v74
	v_min_u32_e32 v74, v70, v74
	v_cvt_f32_f16_e32 v70, v8
	v_cvt_f32_f16_sdwa v87, v8 dst_sel:DWORD dst_unused:UNUSED_PAD src0_sel:WORD_1
	v_ashrrev_i32_e32 v88, 31, v70
	v_bitop3_b32 v70, v70, v88, s40 bitop3:0x78
	v_xor_b32_e32 v70, 0x8000006f, v70
	v_ashrrev_i32_e32 v88, 31, v87
	v_bitop3_b32 v87, v87, v88, s40 bitop3:0x78
	v_xor_b32_e32 v87, 0x8000006e, v87
	v_cvt_f32_f16_e32 v88, v9
	v_cvt_f32_f16_sdwa v89, v9 dst_sel:DWORD dst_unused:UNUSED_PAD src0_sel:WORD_1
	v_ashrrev_i32_e32 v90, 31, v88
	v_bitop3_b32 v88, v88, v90, s40 bitop3:0x78
	v_xor_b32_e32 v88, 0x8000006d, v88
	v_ashrrev_i32_e32 v90, 31, v89
	v_bitop3_b32 v89, v89, v90, s40 bitop3:0x78
	v_xor_b32_e32 v89, 0x8000006c, v89
	v_cvt_f32_f16_e32 v90, v10
	v_cvt_f32_f16_sdwa v91, v10 dst_sel:DWORD dst_unused:UNUSED_PAD src0_sel:WORD_1
	v_ashrrev_i32_e32 v92, 31, v90
	v_bitop3_b32 v90, v90, v92, s40 bitop3:0x78
	v_xor_b32_e32 v90, 0x8000006b, v90
	v_ashrrev_i32_e32 v92, 31, v91
	v_bitop3_b32 v91, v91, v92, s40 bitop3:0x78
	v_xor_b32_e32 v91, 0x8000006a, v91
	v_cvt_f32_f16_e32 v92, v11
	v_cvt_f32_f16_sdwa v93, v11 dst_sel:DWORD dst_unused:UNUSED_PAD src0_sel:WORD_1
	v_ashrrev_i32_e32 v94, 31, v92
	v_bitop3_b32 v92, v92, v94, s40 bitop3:0x78
	v_xor_b32_e32 v92, 0x80000069, v92
	v_ashrrev_i32_e32 v94, 31, v93
	v_bitop3_b32 v93, v93, v94, s40 bitop3:0x78
	v_xor_b32_e32 v93, 0x80000068, v93
	v_cvt_f32_f16_e32 v94, v12
	v_cvt_f32_f16_sdwa v95, v12 dst_sel:DWORD dst_unused:UNUSED_PAD src0_sel:WORD_1
	v_ashrrev_i32_e32 v96, 31, v94
	v_bitop3_b32 v94, v94, v96, s40 bitop3:0x78
	v_xor_b32_e32 v94, 0x80000067, v94
	v_ashrrev_i32_e32 v96, 31, v95
	v_bitop3_b32 v95, v95, v96, s40 bitop3:0x78
	v_xor_b32_e32 v95, 0x80000066, v95
	v_cvt_f32_f16_e32 v96, v13
	v_cvt_f32_f16_sdwa v97, v13 dst_sel:DWORD dst_unused:UNUSED_PAD src0_sel:WORD_1
	v_ashrrev_i32_e32 v98, 31, v96
	v_bitop3_b32 v96, v96, v98, s40 bitop3:0x78
	v_xor_b32_e32 v96, 0x80000065, v96
	v_ashrrev_i32_e32 v98, 31, v97
; __device__ __forceinline__ unsigned f2key(float f) { const unsigned u = __float_as_uint(f); return (u & 0x80000000u) ? ~u : (u | 0x80000000u); }
; #define CE_DESC(a, b) do { const unsigned _mx = (a) > (b) ? (a) : (b), _mn = (a) > (b) ? (b) : (a); (a) = _mx; (b) = _mn; } while (0)
; __device__ __forceinline__ void sort16_desc(unsigned (&k)[16]) {
; #pragma unroll
;     for (int size = 2; size <= 16; size <<= 1)
; #pragma unroll
;         for (int stride = size >> 1; stride > 0; stride >>= 1)
; #pragma unroll
;             for (int i = 0; i < 16; ++i) { const int j = i ^ stride;
;                 if (j > i) { if ((i & size) == 0) CE_DESC(k[i], k[j]); else CE_DESC(k[j], k[i]); } }
; }
; __device__ __forceinline__ void merge16(unsigned (&a)[16], const unsigned (&b)[16]) {
; #pragma unroll
;     for (int i = 0; i < 16; ++i) a[i] = a[i] > b[15 - i] ? a[i] : b[15 - i];
; #pragma unroll
;     for (int stride = 8; stride > 0; stride >>= 1)
; #pragma unroll
;         for (int i = 0; i < 16; ++i) { const int j = i ^ stride; if (j > i) CE_DESC(a[i], a[j]); }
; }
; __device__ __forceinline__ void peer_tile(const Args& A, LAS unsigned char* lds, int tile) {
;     ...
;                   for (int i = 0; i < 16; ++i) {
;                       const float lo = (float)__builtin_bit_cast(_Float16, (unsigned short)(sw[i] & 0xffffu)), hi = (float)__builtin_bit_cast(_Float16, (unsigned short)(sw[i] >> 16));
;                       const unsigned klo = (f2key(lo) & ~127u) | (unsigned)(127 - (32 * g + 2 * i)), khi = (f2key(hi) & ~127u) | (unsigned)(127 - (32 * g + 2 * i + 1));
;                       if (i < 8) { k0[2 * i] = klo; k0[2 * i + 1] = khi; } else { k1[2 * (i - 8)] = klo; k1[2 * (i - 8) + 1] = khi; } } }
	v_bitop3_b32 v97, v97, v98, s40 bitop3:0x78
	v_xor_b32_e32 v97, 0x80000064, v97
	v_cvt_f32_f16_e32 v98, v14
	v_cvt_f32_f16_sdwa v99, v14 dst_sel:DWORD dst_unused:UNUSED_PAD src0_sel:WORD_1
	v_ashrrev_i32_e32 v100, 31, v98
	v_bitop3_b32 v98, v98, v100, s40 bitop3:0x78
	v_xor_b32_e32 v98, 0x80000063, v98
	v_ashrrev_i32_e32 v100, 31, v99
	v_bitop3_b32 v99, v99, v100, s40 bitop3:0x78
	v_xor_b32_e32 v99, 0x80000062, v99
	v_cvt_f32_f16_e32 v100, v15
	v_cvt_f32_f16_sdwa v101, v15 dst_sel:DWORD dst_unused:UNUSED_PAD src0_sel:WORD_1
	v_ashrrev_i32_e32 v102, 31, v100
	v_bitop3_b32 v100, v100, v102, s40 bitop3:0x78
	v_xor_b32_e32 v100, 0x80000061, v100
	v_ashrrev_i32_e32 v102, 31, v101
	v_bitop3_b32 v101, v101, v102, s40 bitop3:0x78
	v_xor_b32_e32 v101, 0x80000060, v101
	v_max_u32_e32 v102, v70, v99
	v_min_u32_e32 v99, v70, v99
	v_max_u32_e32 v70, v87, v98
	v_min_u32_e32 v98, v87, v98
	v_max_u32_e32 v87, v88, v101
	v_min_u32_e32 v101, v88, v101
	v_max_u32_e32 v88, v89, v100
	v_min_u32_e32 v100, v89, v100
	v_max_u32_e32 v89, v90, v94
	v_min_u32_e32 v94, v90, v94
	v_max_u32_e32 v90, v91, v92
	v_min_u32_e32 v92, v91, v92
	v_max_u32_e32 v91, v93, v97
	v_min_u32_e32 v97, v93, v97
	v_max_u32_e32 v93, v95, v96
	v_min_u32_e32 v96, v95, v96
	v_max_u32_e32 v95, v102, v90
	v_min_u32_e32 v90, v102, v90
	v_max_u32_e32 v102, v70, v91
	v_min_u32_e32 v91, v70, v91
	v_max_u32_e32 v70, v87, v93
	v_min_u32_e32 v93, v87, v93
	v_max_u32_e32 v87, v88, v89
	v_min_u32_e32 v89, v88, v89
	v_max_u32_e32 v88, v92, v99
	v_min_u32_e32 v99, v92, v99
	v_max_u32_e32 v92, v94, v100
	v_min_u32_e32 v100, v94, v100
	v_max_u32_e32 v94, v96, v101
	v_min_u32_e32 v101, v96, v101
	v_max_u32_e32 v96, v97, v98
	v_min_u32_e32 v98, v97, v98
	v_max_u32_e32 v97, v95, v102
	v_min_u32_e32 v102, v95, v102
	v_max_u32_e32 v95, v70, v87
	v_min_u32_e32 v87, v70, v87
	v_max_u32_e32 v70, v89, v90
	v_min_u32_e32 v90, v89, v90
	v_max_u32_e32 v89, v88, v92
	v_min_u32_e32 v92, v88, v92
	v_max_u32_e32 v88, v91, v93
	v_min_u32_e32 v93, v91, v93
	v_max_u32_e32 v91, v94, v96
	v_min_u32_e32 v96, v94, v96
	v_max_u32_e32 v94, v98, v99
	v_min_u32_e32 v99, v98, v99
	v_max_u32_e32 v98, v100, v101
	v_min_u32_e32 v101, v100, v101
	v_max_u32_e32 v100, v97, v95
	v_min_u32_e32 v95, v97, v95
	v_max_u32_e32 v97, v102, v87
	v_min_u32_e32 v87, v102, v87
	v_max_u32_e32 v102, v70, v91
	v_min_u32_e32 v91, v70, v91
	v_max_u32_e32 v70, v90, v96
	v_min_u32_e32 v96, v90, v96
	v_max_u32_e32 v90, v89, v88
	v_min_u32_e32 v88, v89, v88
	v_max_u32_e32 v89, v92, v93
	v_min_u32_e32 v93, v92, v93
	v_max_u32_e32 v92, v94, v98
	v_min_u32_e32 v98, v94, v98
	v_max_u32_e32 v94, v99, v101
	v_min_u32_e32 v101, v99, v101
	v_max_u32_e32 v99, v97, v95
	v_min_u32_e32 v95, v97, v95
	v_max_u32_e32 v97, v87, v92
	v_min_u32_e32 v92, v87, v92
	v_max_u32_e32 v87, v102, v90
	v_min_u32_e32 v90, v102, v90
	v_max_u32_e32 v102, v70, v88
	v_min_u32_e32 v88, v70, v88
	v_max_u32_e32 v70, v89, v91
	v_min_u32_e32 v91, v89, v91
	v_max_u32_e32 v89, v93, v96
	v_min_u32_e32 v96, v93, v96
	v_max_u32_e32 v93, v94, v98
	v_min_u32_e32 v98, v94, v98
	v_max_u32_e32 v94, v99, v87
	v_min_u32_e32 v87, v99, v87
	v_max_u32_e32 v99, v95, v90
	v_min_u32_e32 v90, v95, v90
	v_max_u32_e32 v95, v102, v70
	v_min_u32_e32 v70, v102, v70
	v_max_u32_e32 v102, v88, v91
	v_min_u32_e32 v91, v88, v91
	v_max_u32_e32 v88, v89, v93
	v_min_u32_e32 v93, v89, v93
	v_max_u32_e32 v89, v96, v98
	v_min_u32_e32 v98, v96, v98
	v_max_u32_e32 v96, v99, v87
	v_min_u32_e32 v87, v99, v87
	v_max_u32_e32 v99, v97, v90
	v_min_u32_e32 v90, v97, v90
	v_max_u32_e32 v97, v88, v92
	v_min_u32_e32 v92, v88, v92
	v_max_u32_e32 v88, v89, v93
	v_min_u32_e32 v93, v89, v93
	v_max_u32_e32 v89, v99, v95
	v_min_u32_e32 v95, v99, v95
	v_max_u32_e32 v99, v90, v70
	v_min_u32_e32 v70, v90, v70
	v_max_u32_e32 v90, v102, v97
	v_min_u32_e32 v97, v102, v97
	v_max_u32_e32 v102, v91, v92
	v_min_u32_e32 v92, v91, v92
	v_max_u32_e32 v91, v89, v87
	v_min_u32_e32 v87, v89, v87
	v_max_u32_e32 v89, v95, v99
	v_min_u32_e32 v99, v95, v99
	v_max_u32_e32 v95, v90, v70
	v_min_u32_e32 v70, v90, v70
	v_max_u32_e32 v90, v97, v102
	v_min_u32_e32 v102, v97, v102
	v_max_u32_e32 v97, v88, v92
	v_min_u32_e32 v92, v88, v92
	v_max_u32_e32 v88, v99, v95
	v_min_u32_e32 v95, v99, v95
	v_max_u32_e32 v99, v70, v90
	v_min_u32_e32 v90, v70, v90
	v_max_u32_e32 v84, v84, v101
	v_max_u32_e32 v78, v78, v98
	v_max_u32_e32 v80, v80, v93
	v_max_u32_e32 v75, v75, v92
	v_max_u32_e32 v71, v71, v97
	v_max_u32_e32 v73, v73, v102
	v_max_u32_e32 v72, v72, v90
	v_max_u32_e32 v79, v79, v99
	v_max_u32_e32 v83, v83, v95
	v_max_u32_e32 v74, v74, v88
	v_max_u32_e32 v86, v86, v89
	v_max_u32_e32 v81, v81, v87
	v_max_u32_e32 v76, v76, v91
	v_max_u32_e32 v77, v77, v96
	v_max_u32_e32 v82, v82, v94
	v_max_u32_e32 v85, v85, v100
	v_max_u32_e32 v101, v84, v83
	v_min_u32_e32 v83, v84, v83
	v_max_u32_e32 v84, v78, v74
	v_min_u32_e32 v74, v78, v74
	v_max_u32_e32 v78, v80, v86
	v_min_u32_e32 v86, v80, v86
	v_max_u32_e32 v80, v75, v81
	v_min_u32_e32 v81, v75, v81
	v_max_u32_e32 v75, v71, v76
	v_min_u32_e32 v76, v71, v76
	v_max_u32_e32 v71, v73, v77
	v_min_u32_e32 v77, v73, v77
	v_max_u32_e32 v73, v72, v82
	v_min_u32_e32 v82, v72, v82
	v_max_u32_e32 v72, v79, v85
	v_min_u32_e32 v85, v79, v85
	v_max_u32_e32 v79, v101, v75
	v_min_u32_e32 v75, v101, v75
	v_max_u32_e32 v101, v84, v71
	v_min_u32_e32 v71, v84, v71
	v_max_u32_e32 v84, v78, v73
	v_min_u32_e32 v73, v78, v73
	v_max_u32_e32 v78, v80, v72
	v_min_u32_e32 v72, v80, v72
	v_max_u32_e32 v80, v83, v76
	v_min_u32_e32 v76, v83, v76
	v_max_u32_e32 v83, v74, v77
	v_min_u32_e32 v77, v74, v77
	v_max_u32_e32 v74, v86, v82
	v_min_u32_e32 v82, v86, v82
; __device__ __forceinline__ unsigned f2key(float f) { const unsigned u = __float_as_uint(f); return (u & 0x80000000u) ? ~u : (u | 0x80000000u); }
; #define CE_DESC(a, b) do { const unsigned _mx = (a) > (b) ? (a) : (b), _mn = (a) > (b) ? (b) : (a); (a) = _mx; (b) = _mn; } while (0)
; __device__ __forceinline__ void merge16(unsigned (&a)[16], const unsigned (&b)[16]) {
; #pragma unroll
;     for (int i = 0; i < 16; ++i) a[i] = a[i] > b[15 - i] ? a[i] : b[15 - i];
; #pragma unroll
;     for (int stride = 8; stride > 0; stride >>= 1)
; #pragma unroll
;         for (int i = 0; i < 16; ++i) { const int j = i ^ stride; if (j > i) CE_DESC(a[i], a[j]); }
; }
; __device__ __forceinline__ void peer_tile(const Args& A, LAS unsigned char* lds, int tile) {
;     ...
;                   for (int i = 0; i < 16; ++i) {
;                       const float lo = (float)__builtin_bit_cast(_Float16, (unsigned short)(sw[i] & 0xffffu)), hi = (float)__builtin_bit_cast(_Float16, (unsigned short)(sw[i] >> 16));
;                       const unsigned klo = (f2key(lo) & ~127u) | (unsigned)(127 - (32 * g + 2 * i)), khi = (f2key(hi) & ~127u) | (unsigned)(127 - (32 * g + 2 * i + 1));
;                       if (i < 8) { k0[2 * i] = klo; k0[2 * i + 1] = khi; } else { k1[2 * (i - 8)] = klo; k1[2 * (i - 8) + 1] = khi; } } }
;                 sort16_desc(k0); sort16_desc(k1); merge16(k0, k1);
	v_max_u32_e32 v86, v81, v85
	v_min_u32_e32 v85, v81, v85
	v_max_u32_e32 v81, v79, v84
	v_min_u32_e32 v84, v79, v84
	v_max_u32_e32 v79, v101, v78
	v_min_u32_e32 v78, v101, v78
	v_max_u32_e32 v101, v75, v73
	v_min_u32_e32 v73, v75, v73
	v_max_u32_e32 v75, v71, v72
	v_min_u32_e32 v72, v71, v72
	v_max_u32_e32 v71, v80, v74
	v_min_u32_e32 v74, v80, v74
	v_max_u32_e32 v80, v83, v86
	v_min_u32_e32 v86, v83, v86
	v_max_u32_e32 v83, v76, v82
	v_min_u32_e32 v82, v76, v82
	v_max_u32_e32 v76, v77, v85
	v_min_u32_e32 v85, v77, v85
	v_max_u32_e32 v77, v81, v79
	v_min_u32_e32 v79, v81, v79
	v_max_u32_e32 v81, v84, v78
	v_min_u32_e32 v78, v84, v78
	v_max_u32_e32 v84, v101, v75
	v_min_u32_e32 v75, v101, v75
	v_max_u32_e32 v101, v73, v72
	v_min_u32_e32 v72, v73, v72
	v_max_u32_e32 v73, v71, v80
	v_min_u32_e32 v80, v71, v80
	v_max_u32_e32 v71, v74, v86
	v_min_u32_e32 v86, v74, v86
	v_max_u32_e32 v74, v83, v76
	v_min_u32_e32 v76, v83, v76
	v_max_u32_e32 v83, v82, v85
	v_min_u32_e32 v85, v82, v85
	v_cvt_f32_f16_e32 v82, v16
	v_cvt_f32_f16_sdwa v98, v16 dst_sel:DWORD dst_unused:UNUSED_PAD src0_sel:WORD_1
	v_ashrrev_i32_e32 v93, 31, v82
	v_bitop3_b32 v82, v82, v93, s40 bitop3:0x78
	v_xor_b32_e32 v82, 0x8000005f, v82
	v_ashrrev_i32_e32 v93, 31, v98
	v_bitop3_b32 v98, v98, v93, s40 bitop3:0x78
	v_xor_b32_e32 v98, 0x8000005e, v98
	v_cvt_f32_f16_e32 v93, v17
	v_cvt_f32_f16_sdwa v92, v17 dst_sel:DWORD dst_unused:UNUSED_PAD src0_sel:WORD_1
	v_ashrrev_i32_e32 v97, 31, v93
	v_bitop3_b32 v93, v93, v97, s40 bitop3:0x78
	v_xor_b32_e32 v93, 0x8000005d, v93
	v_ashrrev_i32_e32 v97, 31, v92
	v_bitop3_b32 v92, v92, v97, s40 bitop3:0x78
	v_xor_b32_e32 v92, 0x8000005c, v92
	v_cvt_f32_f16_e32 v97, v18
	v_cvt_f32_f16_sdwa v102, v18 dst_sel:DWORD dst_unused:UNUSED_PAD src0_sel:WORD_1
	v_ashrrev_i32_e32 v90, 31, v97
	v_bitop3_b32 v97, v97, v90, s40 bitop3:0x78
	v_xor_b32_e32 v97, 0x8000005b, v97
	v_ashrrev_i32_e32 v90, 31, v102
	v_bitop3_b32 v102, v102, v90, s40 bitop3:0x78
	v_xor_b32_e32 v102, 0x8000005a, v102
	v_cvt_f32_f16_e32 v90, v19
	v_cvt_f32_f16_sdwa v99, v19 dst_sel:DWORD dst_unused:UNUSED_PAD src0_sel:WORD_1
	v_ashrrev_i32_e32 v95, 31, v90
	v_bitop3_b32 v90, v90, v95, s40 bitop3:0x78
	v_xor_b32_e32 v90, 0x80000059, v90
	v_ashrrev_i32_e32 v95, 31, v99
	v_bitop3_b32 v99, v99, v95, s40 bitop3:0x78
	v_xor_b32_e32 v99, 0x80000058, v99
	v_cvt_f32_f16_e32 v95, v20
	v_cvt_f32_f16_sdwa v88, v20 dst_sel:DWORD dst_unused:UNUSED_PAD src0_sel:WORD_1
	v_ashrrev_i32_e32 v89, 31, v95
	v_bitop3_b32 v95, v95, v89, s40 bitop3:0x78
	v_xor_b32_e32 v95, 0x80000057, v95
	v_ashrrev_i32_e32 v89, 31, v88
	v_bitop3_b32 v88, v88, v89, s40 bitop3:0x78
	v_xor_b32_e32 v88, 0x80000056, v88
	v_cvt_f32_f16_e32 v89, v21
	v_cvt_f32_f16_sdwa v87, v21 dst_sel:DWORD dst_unused:UNUSED_PAD src0_sel:WORD_1
	v_ashrrev_i32_e32 v91, 31, v89
	v_bitop3_b32 v89, v89, v91, s40 bitop3:0x78
	v_xor_b32_e32 v89, 0x80000055, v89
	v_ashrrev_i32_e32 v91, 31, v87
	v_bitop3_b32 v87, v87, v91, s40 bitop3:0x78
	v_xor_b32_e32 v87, 0x80000054, v87
	v_cvt_f32_f16_e32 v91, v22
	v_cvt_f32_f16_sdwa v96, v22 dst_sel:DWORD dst_unused:UNUSED_PAD src0_sel:WORD_1
	v_ashrrev_i32_e32 v94, 31, v91
	v_bitop3_b32 v91, v91, v94, s40 bitop3:0x78
	v_xor_b32_e32 v91, 0x80000053, v91
	v_ashrrev_i32_e32 v94, 31, v96
	v_bitop3_b32 v96, v96, v94, s40 bitop3:0x78
	v_xor_b32_e32 v96, 0x80000052, v96
	v_cvt_f32_f16_e32 v94, v23
	v_cvt_f32_f16_sdwa v100, v23 dst_sel:DWORD dst_unused:UNUSED_PAD src0_sel:WORD_1
	v_ashrrev_i32_e32 v70, 31, v94
	v_bitop3_b32 v94, v94, v70, s40 bitop3:0x78
	v_xor_b32_e32 v94, 0x80000051, v94
	v_ashrrev_i32_e32 v70, 31, v100
	v_bitop3_b32 v100, v100, v70, s40 bitop3:0x78
	v_xor_b32_e32 v100, 0x80000050, v100
	v_max_u32_e32 v70, v82, v96
	v_min_u32_e32 v96, v82, v96
	v_max_u32_e32 v82, v98, v91
	v_min_u32_e32 v91, v98, v91
	v_max_u32_e32 v98, v93, v100
	v_min_u32_e32 v100, v93, v100
	v_max_u32_e32 v93, v92, v94
	v_min_u32_e32 v94, v92, v94
	v_max_u32_e32 v92, v97, v95
	v_min_u32_e32 v95, v97, v95
	v_max_u32_e32 v97, v102, v90
	v_min_u32_e32 v90, v102, v90
	v_max_u32_e32 v102, v99, v87
	v_min_u32_e32 v87, v99, v87
	v_max_u32_e32 v99, v88, v89
	v_min_u32_e32 v89, v88, v89
	v_max_u32_e32 v88, v70, v97
	v_min_u32_e32 v97, v70, v97
	v_max_u32_e32 v70, v82, v102
	v_min_u32_e32 v102, v82, v102
	v_max_u32_e32 v82, v98, v99
	v_min_u32_e32 v99, v98, v99
	v_max_u32_e32 v98, v93, v92
	v_min_u32_e32 v92, v93, v92
	v_max_u32_e32 v93, v90, v96
	v_min_u32_e32 v96, v90, v96
	v_max_u32_e32 v90, v95, v94
	v_min_u32_e32 v94, v95, v94
	v_max_u32_e32 v95, v89, v100
	v_min_u32_e32 v100, v89, v100
	v_max_u32_e32 v89, v87, v91
	v_min_u32_e32 v91, v87, v91
	v_max_u32_e32 v87, v88, v70
	v_min_u32_e32 v70, v88, v70
	v_max_u32_e32 v88, v82, v98
	v_min_u32_e32 v98, v82, v98
	v_max_u32_e32 v82, v92, v97
	v_min_u32_e32 v97, v92, v97
	v_max_u32_e32 v92, v93, v90
	v_min_u32_e32 v90, v93, v90
	v_max_u32_e32 v93, v102, v99
	v_min_u32_e32 v99, v102, v99
	v_max_u32_e32 v102, v95, v89
	v_min_u32_e32 v89, v95, v89
	v_max_u32_e32 v95, v91, v96
	v_min_u32_e32 v96, v91, v96
	v_max_u32_e32 v91, v94, v100
	v_min_u32_e32 v100, v94, v100
	v_max_u32_e32 v94, v87, v88
	v_min_u32_e32 v88, v87, v88
	v_max_u32_e32 v87, v70, v98
	v_min_u32_e32 v98, v70, v98
	v_max_u32_e32 v70, v82, v102
	v_min_u32_e32 v102, v82, v102
	v_max_u32_e32 v82, v97, v89
	v_min_u32_e32 v89, v97, v89
	v_max_u32_e32 v97, v92, v93
	v_min_u32_e32 v93, v92, v93
	v_max_u32_e32 v92, v90, v99
	v_min_u32_e32 v99, v90, v99
	v_max_u32_e32 v90, v95, v91
	v_min_u32_e32 v91, v95, v91
	v_max_u32_e32 v95, v96, v100
	v_min_u32_e32 v100, v96, v100
	v_max_u32_e32 v96, v87, v88
	v_min_u32_e32 v88, v87, v88
	v_max_u32_e32 v87, v98, v90
; __device__ __forceinline__ unsigned f2key(float f) { const unsigned u = __float_as_uint(f); return (u & 0x80000000u) ? ~u : (u | 0x80000000u); }
; #define CE_DESC(a, b) do { const unsigned _mx = (a) > (b) ? (a) : (b), _mn = (a) > (b) ? (b) : (a); (a) = _mx; (b) = _mn; } while (0)
; __device__ __forceinline__ void sort16_desc(unsigned (&k)[16]) {
; #pragma unroll
;     for (int size = 2; size <= 16; size <<= 1)
; #pragma unroll
;         for (int stride = size >> 1; stride > 0; stride >>= 1)
; #pragma unroll
;             for (int i = 0; i < 16; ++i) { const int j = i ^ stride;
;                 if (j > i) { if ((i & size) == 0) CE_DESC(k[i], k[j]); else CE_DESC(k[j], k[i]); } }
; }
; __device__ __forceinline__ void merge16(unsigned (&a)[16], const unsigned (&b)[16]) {
; #pragma unroll
;     for (int i = 0; i < 16; ++i) a[i] = a[i] > b[15 - i] ? a[i] : b[15 - i];
; #pragma unroll
;     for (int stride = 8; stride > 0; stride >>= 1)
; #pragma unroll
;         for (int i = 0; i < 16; ++i) { const int j = i ^ stride; if (j > i) CE_DESC(a[i], a[j]); }
; }
; __device__ __forceinline__ void peer_tile(const Args& A, LAS unsigned char* lds, int tile) {
;     ...
;                   for (int i = 0; i < 16; ++i) {
;                       const float lo = (float)__builtin_bit_cast(_Float16, (unsigned short)(sw[i] & 0xffffu)), hi = (float)__builtin_bit_cast(_Float16, (unsigned short)(sw[i] >> 16));
;                       const unsigned klo = (f2key(lo) & ~127u) | (unsigned)(127 - (32 * g + 2 * i)), khi = (f2key(hi) & ~127u) | (unsigned)(127 - (32 * g + 2 * i + 1));
;                       if (i < 8) { k0[2 * i] = klo; k0[2 * i + 1] = khi; } else { k1[2 * (i - 8)] = klo; k1[2 * (i - 8) + 1] = khi; } } }
	v_min_u32_e32 v90, v98, v90
	v_max_u32_e32 v98, v70, v97
	v_min_u32_e32 v97, v70, v97
	v_max_u32_e32 v70, v82, v93
	v_min_u32_e32 v93, v82, v93
	v_max_u32_e32 v82, v92, v102
	v_min_u32_e32 v102, v92, v102
	v_max_u32_e32 v92, v99, v89
	v_min_u32_e32 v89, v99, v89
	v_max_u32_e32 v99, v95, v91
	v_min_u32_e32 v91, v95, v91
	v_max_u32_e32 v95, v96, v98
	v_min_u32_e32 v98, v96, v98
	v_max_u32_e32 v96, v88, v97
	v_min_u32_e32 v97, v88, v97
	v_max_u32_e32 v88, v70, v82
	v_min_u32_e32 v82, v70, v82
	v_max_u32_e32 v70, v93, v102
	v_min_u32_e32 v102, v93, v102
	v_max_u32_e32 v93, v92, v99
	v_min_u32_e32 v99, v92, v99
	v_max_u32_e32 v92, v89, v91
	v_min_u32_e32 v91, v89, v91
	v_max_u32_e32 v89, v96, v98
	v_min_u32_e32 v98, v96, v98
	v_max_u32_e32 v96, v87, v97
	v_min_u32_e32 v97, v87, v97
	v_max_u32_e32 v87, v93, v90
	v_min_u32_e32 v90, v93, v90
	v_max_u32_e32 v93, v92, v99
	v_min_u32_e32 v99, v92, v99
	v_max_u32_e32 v92, v96, v88
	v_min_u32_e32 v88, v96, v88
	v_max_u32_e32 v96, v97, v82
	v_min_u32_e32 v82, v97, v82
	v_max_u32_e32 v97, v70, v87
	v_min_u32_e32 v87, v70, v87
	v_max_u32_e32 v70, v102, v90
	v_min_u32_e32 v90, v102, v90
	v_max_u32_e32 v102, v92, v98
	v_min_u32_e32 v98, v92, v98
	v_max_u32_e32 v92, v88, v96
	v_min_u32_e32 v96, v88, v96
	v_max_u32_e32 v88, v97, v82
	v_min_u32_e32 v82, v97, v82
	v_max_u32_e32 v97, v87, v70
	v_min_u32_e32 v70, v87, v70
	v_max_u32_e32 v87, v93, v90
	v_min_u32_e32 v90, v93, v90
	v_max_u32_e32 v93, v96, v88
	v_min_u32_e32 v88, v96, v88
	v_max_u32_e32 v96, v82, v97
	v_min_u32_e32 v97, v82, v97
	v_max_u32_e32 v77, v77, v100
	v_max_u32_e32 v79, v79, v91
	v_max_u32_e32 v81, v81, v99
	v_max_u32_e32 v78, v78, v90
	v_max_u32_e32 v84, v84, v87
	v_max_u32_e32 v75, v75, v70
	v_max_u32_e32 v101, v101, v97
	v_max_u32_e32 v72, v72, v96
	v_max_u32_e32 v73, v73, v88
	v_max_u32_e32 v80, v80, v93
	v_max_u32_e32 v71, v71, v92
	v_max_u32_e32 v86, v86, v98
	v_max_u32_e32 v74, v74, v102
	v_max_u32_e32 v76, v76, v89
	v_max_u32_e32 v83, v83, v95
	v_max_u32_e32 v85, v85, v94
	v_max_u32_e32 v100, v77, v73
	v_min_u32_e32 v73, v77, v73
	v_max_u32_e32 v77, v79, v80
	v_min_u32_e32 v80, v79, v80
	v_max_u32_e32 v79, v81, v71
	v_min_u32_e32 v71, v81, v71
	v_max_u32_e32 v81, v78, v86
	v_min_u32_e32 v86, v78, v86
	v_max_u32_e32 v78, v84, v74
	v_min_u32_e32 v74, v84, v74
	v_max_u32_e32 v84, v75, v76
	v_min_u32_e32 v76, v75, v76
	v_max_u32_e32 v75, v101, v83
	v_min_u32_e32 v83, v101, v83
	v_max_u32_e32 v101, v72, v85
	v_min_u32_e32 v85, v72, v85
	v_max_u32_e32 v72, v100, v78
	v_min_u32_e32 v78, v100, v78
	v_max_u32_e32 v100, v77, v84
	v_min_u32_e32 v84, v77, v84
	v_max_u32_e32 v77, v79, v75
	v_min_u32_e32 v75, v79, v75
	v_max_u32_e32 v79, v81, v101
	v_min_u32_e32 v101, v81, v101
	v_max_u32_e32 v81, v73, v74
	v_min_u32_e32 v74, v73, v74
	v_max_u32_e32 v73, v80, v76
	v_min_u32_e32 v76, v80, v76
	v_max_u32_e32 v80, v71, v83
	v_min_u32_e32 v83, v71, v83
	v_max_u32_e32 v71, v86, v85
	v_min_u32_e32 v85, v86, v85
	v_max_u32_e32 v86, v72, v77
	v_min_u32_e32 v77, v72, v77
	v_max_u32_e32 v72, v100, v79
	v_min_u32_e32 v79, v100, v79
	v_max_u32_e32 v100, v78, v75
	v_min_u32_e32 v75, v78, v75
	v_max_u32_e32 v78, v84, v101
	v_min_u32_e32 v101, v84, v101
	v_max_u32_e32 v84, v81, v80
	v_min_u32_e32 v80, v81, v80
	v_max_u32_e32 v81, v73, v71
	v_min_u32_e32 v71, v73, v71
	v_max_u32_e32 v73, v74, v83
	v_min_u32_e32 v83, v74, v83
	v_max_u32_e32 v74, v76, v85
	v_min_u32_e32 v85, v76, v85
	v_max_u32_e32 v76, v86, v72
	v_min_u32_e32 v72, v86, v72
	v_max_u32_e32 v86, v77, v79
	v_min_u32_e32 v79, v77, v79
	v_max_u32_e32 v77, v100, v78
	v_min_u32_e32 v78, v100, v78
	v_max_u32_e32 v100, v75, v101
	v_min_u32_e32 v101, v75, v101
	v_max_u32_e32 v75, v84, v81
	v_min_u32_e32 v81, v84, v81
	v_max_u32_e32 v84, v80, v71
	v_min_u32_e32 v71, v80, v71
	v_max_u32_e32 v80, v73, v74
	v_min_u32_e32 v74, v73, v74
	v_max_u32_e32 v73, v83, v85
	v_min_u32_e32 v85, v83, v85
	v_cvt_f32_f16_e32 v83, v24
	v_cvt_f32_f16_sdwa v91, v24 dst_sel:DWORD dst_unused:UNUSED_PAD src0_sel:WORD_1
	v_ashrrev_i32_e32 v99, 31, v83
	v_bitop3_b32 v83, v83, v99, s40 bitop3:0x78
	v_xor_b32_e32 v83, 0x8000004f, v83
	v_ashrrev_i32_e32 v99, 31, v91
	v_bitop3_b32 v91, v91, v99, s40 bitop3:0x78
	v_xor_b32_e32 v91, 0x8000004e, v91
	v_cvt_f32_f16_e32 v99, v25
	v_cvt_f32_f16_sdwa v90, v25 dst_sel:DWORD dst_unused:UNUSED_PAD src0_sel:WORD_1
	v_ashrrev_i32_e32 v87, 31, v99
	v_bitop3_b32 v99, v99, v87, s40 bitop3:0x78
	v_xor_b32_e32 v99, 0x8000004d, v99
	v_ashrrev_i32_e32 v87, 31, v90
	v_bitop3_b32 v90, v90, v87, s40 bitop3:0x78
	v_xor_b32_e32 v90, 0x8000004c, v90
	v_cvt_f32_f16_e32 v87, v26
	v_cvt_f32_f16_sdwa v70, v26 dst_sel:DWORD dst_unused:UNUSED_PAD src0_sel:WORD_1
	v_ashrrev_i32_e32 v97, 31, v87
	v_bitop3_b32 v87, v87, v97, s40 bitop3:0x78
	v_xor_b32_e32 v87, 0x8000004b, v87
	v_ashrrev_i32_e32 v97, 31, v70
	v_bitop3_b32 v70, v70, v97, s40 bitop3:0x78
	v_xor_b32_e32 v70, 0x8000004a, v70
	v_cvt_f32_f16_e32 v97, v27
	v_cvt_f32_f16_sdwa v96, v27 dst_sel:DWORD dst_unused:UNUSED_PAD src0_sel:WORD_1
	v_ashrrev_i32_e32 v88, 31, v97
	v_bitop3_b32 v97, v97, v88, s40 bitop3:0x78
	v_xor_b32_e32 v97, 0x80000049, v97
	v_ashrrev_i32_e32 v88, 31, v96
	v_bitop3_b32 v96, v96, v88, s40 bitop3:0x78
	v_xor_b32_e32 v96, 0x80000048, v96
	v_cvt_f32_f16_e32 v88, v28
	v_cvt_f32_f16_sdwa v93, v28 dst_sel:DWORD dst_unused:UNUSED_PAD src0_sel:WORD_1
	v_ashrrev_i32_e32 v92, 31, v88
	v_bitop3_b32 v88, v88, v92, s40 bitop3:0x78
	v_xor_b32_e32 v88, 0x80000047, v88
	v_ashrrev_i32_e32 v92, 31, v93
	v_bitop3_b32 v93, v93, v92, s40 bitop3:0x78
	v_xor_b32_e32 v93, 0x80000046, v93
	v_cvt_f32_f16_e32 v92, v29
	v_cvt_f32_f16_sdwa v98, v29 dst_sel:DWORD dst_unused:UNUSED_PAD src0_sel:WORD_1
; __device__ __forceinline__ unsigned f2key(float f) { const unsigned u = __float_as_uint(f); return (u & 0x80000000u) ? ~u : (u | 0x80000000u); }
; #define CE_DESC(a, b) do { const unsigned _mx = (a) > (b) ? (a) : (b), _mn = (a) > (b) ? (b) : (a); (a) = _mx; (b) = _mn; } while (0)
; __device__ __forceinline__ void sort16_desc(unsigned (&k)[16]) {
; #pragma unroll
;     for (int size = 2; size <= 16; size <<= 1)
; #pragma unroll
;         for (int stride = size >> 1; stride > 0; stride >>= 1)
; #pragma unroll
;             for (int i = 0; i < 16; ++i) { const int j = i ^ stride;
;                 if (j > i) { if ((i & size) == 0) CE_DESC(k[i], k[j]); else CE_DESC(k[j], k[i]); } }
; }
; __device__ __forceinline__ void merge16(unsigned (&a)[16], const unsigned (&b)[16]) {
; #pragma unroll
;     for (int i = 0; i < 16; ++i) a[i] = a[i] > b[15 - i] ? a[i] : b[15 - i];
; #pragma unroll
;     for (int stride = 8; stride > 0; stride >>= 1)
; #pragma unroll
;         for (int i = 0; i < 16; ++i) { const int j = i ^ stride; if (j > i) CE_DESC(a[i], a[j]); }
; }
; __device__ __forceinline__ void peer_tile(const Args& A, LAS unsigned char* lds, int tile) {
;     ...
;                   for (int i = 0; i < 16; ++i) {
;                       const float lo = (float)__builtin_bit_cast(_Float16, (unsigned short)(sw[i] & 0xffffu)), hi = (float)__builtin_bit_cast(_Float16, (unsigned short)(sw[i] >> 16));
;                       const unsigned klo = (f2key(lo) & ~127u) | (unsigned)(127 - (32 * g + 2 * i)), khi = (f2key(hi) & ~127u) | (unsigned)(127 - (32 * g + 2 * i + 1));
;                       if (i < 8) { k0[2 * i] = klo; k0[2 * i + 1] = khi; } else { k1[2 * (i - 8)] = klo; k1[2 * (i - 8) + 1] = khi; } } }
	v_ashrrev_i32_e32 v102, 31, v92
	v_bitop3_b32 v92, v92, v102, s40 bitop3:0x78
	v_xor_b32_e32 v92, 0x80000045, v92
	v_ashrrev_i32_e32 v102, 31, v98
	v_bitop3_b32 v98, v98, v102, s40 bitop3:0x78
	v_xor_b32_e32 v98, 0x80000044, v98
	v_cvt_f32_f16_e32 v102, v30
	v_cvt_f32_f16_sdwa v89, v30 dst_sel:DWORD dst_unused:UNUSED_PAD src0_sel:WORD_1
	v_ashrrev_i32_e32 v95, 31, v102
	v_bitop3_b32 v102, v102, v95, s40 bitop3:0x78
	v_xor_b32_e32 v102, 0x80000043, v102
	v_ashrrev_i32_e32 v95, 31, v89
	v_bitop3_b32 v89, v89, v95, s40 bitop3:0x78
	v_xor_b32_e32 v89, 0x80000042, v89
	v_cvt_f32_f16_e32 v95, v31
	v_cvt_f32_f16_sdwa v94, v31 dst_sel:DWORD dst_unused:UNUSED_PAD src0_sel:WORD_1
	v_ashrrev_i32_e32 v82, 31, v95
	v_bitop3_b32 v95, v95, v82, s40 bitop3:0x78
	v_xor_b32_e32 v95, 0x80000041, v95
	v_ashrrev_i32_e32 v82, 31, v94
	v_bitop3_b32 v94, v94, v82, s40 bitop3:0x78
	v_xor_b32_e32 v94, 0x80000040, v94
	v_max_u32_e32 v82, v83, v89
	v_min_u32_e32 v89, v83, v89
	v_max_u32_e32 v83, v91, v102
	v_min_u32_e32 v102, v91, v102
	v_max_u32_e32 v91, v99, v94
	v_min_u32_e32 v94, v99, v94
	v_max_u32_e32 v99, v90, v95
	v_min_u32_e32 v95, v90, v95
	v_max_u32_e32 v90, v87, v88
	v_min_u32_e32 v88, v87, v88
	v_max_u32_e32 v87, v70, v97
	v_min_u32_e32 v97, v70, v97
	v_max_u32_e32 v70, v96, v98
	v_min_u32_e32 v98, v96, v98
	v_max_u32_e32 v96, v93, v92
	v_min_u32_e32 v92, v93, v92
	v_max_u32_e32 v93, v82, v87
	v_min_u32_e32 v87, v82, v87
	v_max_u32_e32 v82, v83, v70
	v_min_u32_e32 v70, v83, v70
	v_max_u32_e32 v83, v91, v96
	v_min_u32_e32 v96, v91, v96
	v_max_u32_e32 v91, v99, v90
	v_min_u32_e32 v90, v99, v90
	v_max_u32_e32 v99, v97, v89
	v_min_u32_e32 v89, v97, v89
	v_max_u32_e32 v97, v88, v95
	v_min_u32_e32 v95, v88, v95
	v_max_u32_e32 v88, v92, v94
	v_min_u32_e32 v94, v92, v94
	v_max_u32_e32 v92, v98, v102
	v_min_u32_e32 v102, v98, v102
	v_max_u32_e32 v98, v93, v82
	v_min_u32_e32 v82, v93, v82
	v_max_u32_e32 v93, v83, v91
	v_min_u32_e32 v91, v83, v91
	v_max_u32_e32 v83, v90, v87
	v_min_u32_e32 v87, v90, v87
	v_max_u32_e32 v90, v99, v97
	v_min_u32_e32 v97, v99, v97
	v_max_u32_e32 v99, v70, v96
	v_min_u32_e32 v96, v70, v96
	v_max_u32_e32 v70, v88, v92
	v_min_u32_e32 v92, v88, v92
	v_max_u32_e32 v88, v102, v89
	v_min_u32_e32 v89, v102, v89
	v_max_u32_e32 v102, v95, v94
	v_min_u32_e32 v94, v95, v94
	v_max_u32_e32 v95, v98, v93
	v_min_u32_e32 v93, v98, v93
	v_max_u32_e32 v98, v82, v91
	v_min_u32_e32 v91, v82, v91
	v_max_u32_e32 v82, v83, v70
	v_min_u32_e32 v70, v83, v70
	v_max_u32_e32 v83, v87, v92
	v_min_u32_e32 v92, v87, v92
	v_max_u32_e32 v87, v90, v99
	v_min_u32_e32 v99, v90, v99
	v_max_u32_e32 v90, v97, v96
	v_min_u32_e32 v96, v97, v96
	v_max_u32_e32 v97, v88, v102
	v_min_u32_e32 v102, v88, v102
	v_max_u32_e32 v88, v89, v94
	v_min_u32_e32 v94, v89, v94
	v_max_u32_e32 v89, v98, v93
	v_min_u32_e32 v93, v98, v93
	v_max_u32_e32 v98, v91, v97
	v_min_u32_e32 v97, v91, v97
	v_max_u32_e32 v91, v82, v87
	v_min_u32_e32 v87, v82, v87
	v_max_u32_e32 v82, v83, v99
	v_min_u32_e32 v99, v83, v99
	v_max_u32_e32 v83, v90, v70
	v_min_u32_e32 v70, v90, v70
	v_max_u32_e32 v90, v96, v92
	v_min_u32_e32 v92, v96, v92
	v_max_u32_e32 v96, v88, v102
	v_min_u32_e32 v102, v88, v102
	v_max_u32_e32 v88, v89, v91
	v_min_u32_e32 v91, v89, v91
	v_max_u32_e32 v89, v93, v87
	v_min_u32_e32 v87, v93, v87
	v_max_u32_e32 v93, v82, v83
	v_min_u32_e32 v83, v82, v83
	v_max_u32_e32 v82, v99, v70
	v_min_u32_e32 v70, v99, v70
	v_max_u32_e32 v99, v90, v96
	v_min_u32_e32 v96, v90, v96
	v_max_u32_e32 v90, v92, v102
	v_min_u32_e32 v102, v92, v102
	v_max_u32_e32 v92, v89, v91
	v_min_u32_e32 v91, v89, v91
	v_max_u32_e32 v89, v98, v87
	v_min_u32_e32 v87, v98, v87
	v_max_u32_e32 v98, v99, v97
	v_min_u32_e32 v97, v99, v97
	v_max_u32_e32 v99, v90, v96
	v_min_u32_e32 v96, v90, v96
	v_max_u32_e32 v90, v89, v93
	v_min_u32_e32 v93, v89, v93
	v_max_u32_e32 v89, v87, v83
	v_min_u32_e32 v83, v87, v83
	v_max_u32_e32 v87, v82, v98
	v_min_u32_e32 v98, v82, v98
	v_max_u32_e32 v82, v70, v97
	v_min_u32_e32 v97, v70, v97
	v_max_u32_e32 v70, v90, v91
	v_min_u32_e32 v91, v90, v91
	v_max_u32_e32 v90, v93, v89
	v_min_u32_e32 v89, v93, v89
	v_max_u32_e32 v93, v87, v83
	v_min_u32_e32 v83, v87, v83
	v_max_u32_e32 v87, v98, v82
	v_min_u32_e32 v82, v98, v82
	v_max_u32_e32 v98, v99, v97
	v_min_u32_e32 v97, v99, v97
	v_max_u32_e32 v99, v89, v93
	v_min_u32_e32 v93, v89, v93
	v_max_u32_e32 v89, v83, v87
	v_min_u32_e32 v87, v83, v87
	v_max_u32_e32 v76, v76, v94
	v_max_u32_e32 v72, v72, v102
	v_max_u32_e32 v86, v86, v96
	v_max_u32_e32 v79, v79, v97
	v_max_u32_e32 v77, v77, v98
	v_max_u32_e32 v78, v78, v82
	v_max_u32_e32 v100, v100, v87
	v_max_u32_e32 v101, v101, v89
	v_max_u32_e32 v75, v75, v93
	v_max_u32_e32 v81, v81, v99
	v_max_u32_e32 v84, v84, v90
	v_max_u32_e32 v71, v71, v91
	v_max_u32_e32 v80, v80, v70
	v_max_u32_e32 v74, v74, v92
	v_max_u32_e32 v73, v73, v88
	v_max_u32_e32 v85, v85, v95
	v_max_u32_e32 v94, v76, v75
	v_min_u32_e32 v75, v76, v75
	v_max_u32_e32 v76, v72, v81
	v_min_u32_e32 v81, v72, v81
	v_max_u32_e32 v72, v86, v84
	v_min_u32_e32 v84, v86, v84
	v_max_u32_e32 v86, v79, v71
	v_min_u32_e32 v71, v79, v71
	v_max_u32_e32 v79, v77, v80
	v_min_u32_e32 v80, v77, v80
	v_max_u32_e32 v77, v78, v74
	v_min_u32_e32 v74, v78, v74
	v_max_u32_e32 v78, v100, v73
	v_min_u32_e32 v73, v100, v73
	v_max_u32_e32 v100, v101, v85
	v_min_u32_e32 v85, v101, v85
	v_max_u32_e32 v101, v94, v79
	v_min_u32_e32 v79, v94, v79
	v_max_u32_e32 v94, v76, v77
	v_min_u32_e32 v77, v76, v77
	v_max_u32_e32 v76, v72, v78
	v_min_u32_e32 v78, v72, v78
	v_max_u32_e32 v72, v86, v100
	v_min_u32_e32 v100, v86, v100
	v_max_u32_e32 v86, v75, v80
	v_min_u32_e32 v80, v75, v80
; __device__ __forceinline__ unsigned f2key(float f) { const unsigned u = __float_as_uint(f); return (u & 0x80000000u) ? ~u : (u | 0x80000000u); }
; #define CE_DESC(a, b) do { const unsigned _mx = (a) > (b) ? (a) : (b), _mn = (a) > (b) ? (b) : (a); (a) = _mx; (b) = _mn; } while (0)
; __device__ __forceinline__ void sort16_desc(unsigned (&k)[16]) {
; #pragma unroll
;     for (int size = 2; size <= 16; size <<= 1)
; #pragma unroll
;         for (int stride = size >> 1; stride > 0; stride >>= 1)
; #pragma unroll
;             for (int i = 0; i < 16; ++i) { const int j = i ^ stride;
;                 if (j > i) { if ((i & size) == 0) CE_DESC(k[i], k[j]); else CE_DESC(k[j], k[i]); } }
; }
; __device__ __forceinline__ void merge16(unsigned (&a)[16], const unsigned (&b)[16]) {
; #pragma unroll
;     for (int i = 0; i < 16; ++i) a[i] = a[i] > b[15 - i] ? a[i] : b[15 - i];
; #pragma unroll
;     for (int stride = 8; stride > 0; stride >>= 1)
; #pragma unroll
;         for (int i = 0; i < 16; ++i) { const int j = i ^ stride; if (j > i) CE_DESC(a[i], a[j]); }
; }
; __device__ __forceinline__ void peer_tile(const Args& A, LAS unsigned char* lds, int tile) {
;     ...
;                 { const bf16_t* sp = QRY + m * 2048 + hp * 128 + 32 * g;
;                   const u32x4 s0 = *(const u32x4*)sp, s1 = *(const u32x4*)(sp + 8), s2 = *(const u32x4*)(sp + 16), s3 = *(const u32x4*)(sp + 24);
;                   const unsigned sw[16] = {s0.x, s0.y, s0.z, s0.w, s1.x, s1.y, s1.z, s1.w, s2.x, s2.y, s2.z, s2.w, s3.x, s3.y, s3.z, s3.w};
; #pragma unroll
;                   for (int i = 0; i < 16; ++i) {
;                       const float lo = (float)__builtin_bit_cast(_Float16, (unsigned short)(sw[i] & 0xffffu)), hi = (float)__builtin_bit_cast(_Float16, (unsigned short)(sw[i] >> 16));
;                       const unsigned klo = (f2key(lo) & ~127u) | (unsigned)(127 - (32 * g + 2 * i)), khi = (f2key(hi) & ~127u) | (unsigned)(127 - (32 * g + 2 * i + 1));
;                       if (i < 8) { k0[2 * i] = klo; k0[2 * i + 1] = khi; } else { k1[2 * (i - 8)] = klo; k1[2 * (i - 8) + 1] = khi; } } }
;                 sort16_desc(k0); sort16_desc(k1); merge16(k0, k1);
	v_max_u32_e32 v75, v81, v74
	v_min_u32_e32 v74, v81, v74
	v_max_u32_e32 v81, v84, v73
	v_min_u32_e32 v73, v84, v73
	v_max_u32_e32 v84, v71, v85
	v_min_u32_e32 v85, v71, v85
	v_max_u32_e32 v71, v101, v76
	v_min_u32_e32 v76, v101, v76
	v_max_u32_e32 v101, v94, v72
	v_min_u32_e32 v72, v94, v72
	v_max_u32_e32 v94, v79, v78
	v_min_u32_e32 v78, v79, v78
	v_max_u32_e32 v79, v77, v100
	v_min_u32_e32 v100, v77, v100
	v_max_u32_e32 v77, v86, v81
	v_min_u32_e32 v81, v86, v81
	v_max_u32_e32 v86, v75, v84
	v_min_u32_e32 v84, v75, v84
	v_max_u32_e32 v75, v80, v73
	v_min_u32_e32 v73, v80, v73
	v_max_u32_e32 v80, v74, v85
	v_min_u32_e32 v85, v74, v85
	v_max_u32_e32 v74, v71, v101
	v_min_u32_e32 v101, v71, v101
	v_max_u32_e32 v71, v76, v72
	v_min_u32_e32 v72, v76, v72
	v_max_u32_e32 v76, v94, v79
	v_min_u32_e32 v79, v94, v79
	v_max_u32_e32 v94, v78, v100
	v_min_u32_e32 v100, v78, v100
	v_max_u32_e32 v78, v77, v86
	v_min_u32_e32 v86, v77, v86
	v_max_u32_e32 v77, v81, v84
	v_min_u32_e32 v84, v81, v84
	v_max_u32_e32 v81, v75, v80
	v_min_u32_e32 v80, v75, v80
	v_max_u32_e32 v75, v73, v85
	v_min_u32_e32 v85, v73, v85
	s_mov_b64 s[38:39], s[34:35]
	global_load_dwordx4 v[0:3], v66, s[38:39] offset:256
	s_add_u32 s38, s38, 0x8000
	s_addc_u32 s39, s39, 0
	global_load_dwordx4 v[4:7], v66, s[38:39] offset:256
	s_add_u32 s38, s38, 0x8000
	s_addc_u32 s39, s39, 0
	global_load_dwordx4 v[8:11], v66, s[38:39] offset:256
	s_add_u32 s38, s38, 0x8000
	s_addc_u32 s39, s39, 0
	global_load_dwordx4 v[12:15], v66, s[38:39] offset:256
	s_add_u32 s38, s38, 0x8000
	s_addc_u32 s39, s39, 0
	global_load_dwordx4 v[16:19], v66, s[38:39] offset:256
	s_add_u32 s38, s38, 0x8000
	s_addc_u32 s39, s39, 0
	global_load_dwordx4 v[20:23], v66, s[38:39] offset:256
	s_add_u32 s38, s38, 0x8000
	s_addc_u32 s39, s39, 0
	global_load_dwordx4 v[24:27], v66, s[38:39] offset:256
	s_add_u32 s38, s38, 0x8000
	s_addc_u32 s39, s39, 0
	global_load_dwordx4 v[28:31], v66, s[38:39] offset:256
	s_waitcnt vmcnt(8)
	ds_write_b128 v64, v[32:35] offset:0
	ds_write_b128 v64, v[36:39] offset:1152
	ds_write_b128 v64, v[40:43] offset:2304
	ds_write_b128 v64, v[44:47] offset:3456
	ds_write_b128 v64, v[48:51] offset:4608
	ds_write_b128 v64, v[52:55] offset:5760
	ds_write_b128 v64, v[56:59] offset:6912
	ds_write_b128 v64, v[60:63] offset:8064
	s_waitcnt lgkmcnt(0)
	ds_read_b128 v[32:35], v65 offset:0
	ds_read_b128 v[36:39], v65 offset:16
	ds_read_b128 v[40:43], v65 offset:32
	ds_read_b128 v[44:47], v65 offset:48
	ds_read_b128 v[48:51], v65 offset:64
	ds_read_b128 v[52:55], v65 offset:80
	ds_read_b128 v[56:59], v65 offset:96
	ds_read_b128 v[60:63], v65 offset:112
	s_waitcnt lgkmcnt(0)
	v_cvt_f32_f16_e32 v73, v32
	v_cvt_f32_f16_sdwa v102, v32 dst_sel:DWORD dst_unused:UNUSED_PAD src0_sel:WORD_1
	v_ashrrev_i32_e32 v96, 31, v73
	v_bitop3_b32 v73, v73, v96, s40 bitop3:0x78
	v_xor_b32_e32 v73, 0x8000003f, v73
	v_ashrrev_i32_e32 v96, 31, v102
	v_bitop3_b32 v102, v102, v96, s40 bitop3:0x78
	v_xor_b32_e32 v102, 0x8000003e, v102
	v_cvt_f32_f16_e32 v96, v33
	v_cvt_f32_f16_sdwa v97, v33 dst_sel:DWORD dst_unused:UNUSED_PAD src0_sel:WORD_1
	v_ashrrev_i32_e32 v98, 31, v96
	v_bitop3_b32 v96, v96, v98, s40 bitop3:0x78
	v_xor_b32_e32 v96, 0x8000003d, v96
	v_ashrrev_i32_e32 v98, 31, v97
	v_bitop3_b32 v97, v97, v98, s40 bitop3:0x78
	v_xor_b32_e32 v97, 0x8000003c, v97
	v_cvt_f32_f16_e32 v98, v34
	v_cvt_f32_f16_sdwa v82, v34 dst_sel:DWORD dst_unused:UNUSED_PAD src0_sel:WORD_1
	v_ashrrev_i32_e32 v87, 31, v98
	v_bitop3_b32 v98, v98, v87, s40 bitop3:0x78
	v_xor_b32_e32 v98, 0x8000003b, v98
	v_ashrrev_i32_e32 v87, 31, v82
	v_bitop3_b32 v82, v82, v87, s40 bitop3:0x78
	v_xor_b32_e32 v82, 0x8000003a, v82
	v_cvt_f32_f16_e32 v87, v35
	v_cvt_f32_f16_sdwa v89, v35 dst_sel:DWORD dst_unused:UNUSED_PAD src0_sel:WORD_1
	v_ashrrev_i32_e32 v93, 31, v87
	v_bitop3_b32 v87, v87, v93, s40 bitop3:0x78
	v_xor_b32_e32 v87, 0x80000039, v87
	v_ashrrev_i32_e32 v93, 31, v89
	v_bitop3_b32 v89, v89, v93, s40 bitop3:0x78
	v_xor_b32_e32 v89, 0x80000038, v89
	v_cvt_f32_f16_e32 v93, v36
	v_cvt_f32_f16_sdwa v99, v36 dst_sel:DWORD dst_unused:UNUSED_PAD src0_sel:WORD_1
	v_ashrrev_i32_e32 v90, 31, v93
	v_bitop3_b32 v93, v93, v90, s40 bitop3:0x78
	v_xor_b32_e32 v93, 0x80000037, v93
	v_ashrrev_i32_e32 v90, 31, v99
	v_bitop3_b32 v99, v99, v90, s40 bitop3:0x78
	v_xor_b32_e32 v99, 0x80000036, v99
	v_cvt_f32_f16_e32 v90, v37
	v_cvt_f32_f16_sdwa v91, v37 dst_sel:DWORD dst_unused:UNUSED_PAD src0_sel:WORD_1
	v_ashrrev_i32_e32 v70, 31, v90
	v_bitop3_b32 v90, v90, v70, s40 bitop3:0x78
	v_xor_b32_e32 v90, 0x80000035, v90
	v_ashrrev_i32_e32 v70, 31, v91
	v_bitop3_b32 v91, v91, v70, s40 bitop3:0x78
	v_xor_b32_e32 v91, 0x80000034, v91
	v_cvt_f32_f16_e32 v70, v38
	v_cvt_f32_f16_sdwa v92, v38 dst_sel:DWORD dst_unused:UNUSED_PAD src0_sel:WORD_1
	v_ashrrev_i32_e32 v88, 31, v70
	v_bitop3_b32 v70, v70, v88, s40 bitop3:0x78
	v_xor_b32_e32 v70, 0x80000033, v70
	v_ashrrev_i32_e32 v88, 31, v92
	v_bitop3_b32 v92, v92, v88, s40 bitop3:0x78
	v_xor_b32_e32 v92, 0x80000032, v92
	v_cvt_f32_f16_e32 v88, v39
	v_cvt_f32_f16_sdwa v95, v39 dst_sel:DWORD dst_unused:UNUSED_PAD src0_sel:WORD_1
	v_ashrrev_i32_e32 v83, 31, v88
	v_bitop3_b32 v88, v88, v83, s40 bitop3:0x78
	v_xor_b32_e32 v88, 0x80000031, v88
	v_ashrrev_i32_e32 v83, 31, v95
	v_bitop3_b32 v95, v95, v83, s40 bitop3:0x78
	v_xor_b32_e32 v95, 0x80000030, v95
	v_max_u32_e32 v83, v73, v92
	v_min_u32_e32 v92, v73, v92
	v_max_u32_e32 v73, v102, v70
	v_min_u32_e32 v70, v102, v70
	v_max_u32_e32 v102, v96, v95
	v_min_u32_e32 v95, v96, v95
	v_max_u32_e32 v96, v97, v88
	v_min_u32_e32 v88, v97, v88
	v_max_u32_e32 v97, v98, v93
	v_min_u32_e32 v93, v98, v93
	v_max_u32_e32 v98, v82, v87
; __device__ __forceinline__ unsigned f2key(float f) { const unsigned u = __float_as_uint(f); return (u & 0x80000000u) ? ~u : (u | 0x80000000u); }
; #define CE_DESC(a, b) do { const unsigned _mx = (a) > (b) ? (a) : (b), _mn = (a) > (b) ? (b) : (a); (a) = _mx; (b) = _mn; } while (0)
; __device__ __forceinline__ void sort16_desc(unsigned (&k)[16]) {
; #pragma unroll
;     for (int size = 2; size <= 16; size <<= 1)
; #pragma unroll
;         for (int stride = size >> 1; stride > 0; stride >>= 1)
; #pragma unroll
;             for (int i = 0; i < 16; ++i) { const int j = i ^ stride;
;                 if (j > i) { if ((i & size) == 0) CE_DESC(k[i], k[j]); else CE_DESC(k[j], k[i]); } }
; }
; __device__ __forceinline__ void merge16(unsigned (&a)[16], const unsigned (&b)[16]) {
; #pragma unroll
;     for (int i = 0; i < 16; ++i) a[i] = a[i] > b[15 - i] ? a[i] : b[15 - i];
; #pragma unroll
;     for (int stride = 8; stride > 0; stride >>= 1)
; #pragma unroll
;         for (int i = 0; i < 16; ++i) { const int j = i ^ stride; if (j > i) CE_DESC(a[i], a[j]); }
; }
; __device__ __forceinline__ void peer_tile(const Args& A, LAS unsigned char* lds, int tile) {
;     ...
;                   for (int i = 0; i < 16; ++i) {
;                       const float lo = (float)__builtin_bit_cast(_Float16, (unsigned short)(sw[i] & 0xffffu)), hi = (float)__builtin_bit_cast(_Float16, (unsigned short)(sw[i] >> 16));
;                       const unsigned klo = (f2key(lo) & ~127u) | (unsigned)(127 - (32 * g + 2 * i)), khi = (f2key(hi) & ~127u) | (unsigned)(127 - (32 * g + 2 * i + 1));
;                       if (i < 8) { k0[2 * i] = klo; k0[2 * i + 1] = khi; } else { k1[2 * (i - 8)] = klo; k1[2 * (i - 8) + 1] = khi; } } }
	v_min_u32_e32 v87, v82, v87
	v_max_u32_e32 v82, v89, v91
	v_min_u32_e32 v91, v89, v91
	v_max_u32_e32 v89, v99, v90
	v_min_u32_e32 v90, v99, v90
	v_max_u32_e32 v99, v83, v98
	v_min_u32_e32 v98, v83, v98
	v_max_u32_e32 v83, v73, v82
	v_min_u32_e32 v82, v73, v82
	v_max_u32_e32 v73, v102, v89
	v_min_u32_e32 v89, v102, v89
	v_max_u32_e32 v102, v96, v97
	v_min_u32_e32 v97, v96, v97
	v_max_u32_e32 v96, v87, v92
	v_min_u32_e32 v92, v87, v92
	v_max_u32_e32 v87, v93, v88
	v_min_u32_e32 v88, v93, v88
	v_max_u32_e32 v93, v90, v95
	v_min_u32_e32 v95, v90, v95
	v_max_u32_e32 v90, v91, v70
	v_min_u32_e32 v70, v91, v70
	v_max_u32_e32 v91, v99, v83
	v_min_u32_e32 v83, v99, v83
	v_max_u32_e32 v99, v73, v102
	v_min_u32_e32 v102, v73, v102
	v_max_u32_e32 v73, v97, v98
	v_min_u32_e32 v98, v97, v98
	v_max_u32_e32 v97, v96, v87
	v_min_u32_e32 v87, v96, v87
	v_max_u32_e32 v96, v82, v89
	v_min_u32_e32 v89, v82, v89
	v_max_u32_e32 v82, v93, v90
	v_min_u32_e32 v90, v93, v90
	v_max_u32_e32 v93, v70, v92
	v_min_u32_e32 v92, v70, v92
	v_max_u32_e32 v70, v88, v95
	v_min_u32_e32 v95, v88, v95
	v_max_u32_e32 v88, v91, v99
	v_min_u32_e32 v99, v91, v99
	v_max_u32_e32 v91, v83, v102
	v_min_u32_e32 v102, v83, v102
	v_max_u32_e32 v83, v73, v82
	v_min_u32_e32 v82, v73, v82
	v_max_u32_e32 v73, v98, v90
	v_min_u32_e32 v90, v98, v90
	v_max_u32_e32 v98, v97, v96
	v_min_u32_e32 v96, v97, v96
	v_max_u32_e32 v97, v87, v89
	v_min_u32_e32 v89, v87, v89
	v_max_u32_e32 v87, v93, v70
	v_min_u32_e32 v70, v93, v70
	v_max_u32_e32 v93, v92, v95
	v_min_u32_e32 v95, v92, v95
	v_max_u32_e32 v92, v91, v99
	v_min_u32_e32 v99, v91, v99
	v_max_u32_e32 v91, v102, v87
	v_min_u32_e32 v87, v102, v87
	v_max_u32_e32 v102, v83, v98
	v_min_u32_e32 v98, v83, v98
	v_max_u32_e32 v83, v73, v96
	v_min_u32_e32 v96, v73, v96
	v_max_u32_e32 v73, v97, v82
	v_min_u32_e32 v82, v97, v82
	v_max_u32_e32 v97, v89, v90
	v_min_u32_e32 v90, v89, v90
	v_max_u32_e32 v89, v93, v70
	v_min_u32_e32 v70, v93, v70
	v_max_u32_e32 v93, v92, v102
	v_min_u32_e32 v102, v92, v102
	v_max_u32_e32 v92, v99, v98
	v_min_u32_e32 v98, v99, v98
	v_max_u32_e32 v99, v83, v73
	v_min_u32_e32 v73, v83, v73
	v_max_u32_e32 v83, v96, v82
	v_min_u32_e32 v82, v96, v82
	v_max_u32_e32 v96, v97, v89
	v_min_u32_e32 v89, v97, v89
	v_max_u32_e32 v97, v90, v70
	v_min_u32_e32 v70, v90, v70
	v_max_u32_e32 v90, v92, v102
	v_min_u32_e32 v102, v92, v102
	v_max_u32_e32 v92, v91, v98
	v_min_u32_e32 v98, v91, v98
	v_max_u32_e32 v91, v96, v87
	v_min_u32_e32 v87, v96, v87
	v_max_u32_e32 v96, v97, v89
	v_min_u32_e32 v89, v97, v89
	v_max_u32_e32 v97, v92, v99
	v_min_u32_e32 v99, v92, v99
	v_max_u32_e32 v92, v98, v73
	v_min_u32_e32 v73, v98, v73
	v_max_u32_e32 v98, v83, v91
	v_min_u32_e32 v91, v83, v91
	v_max_u32_e32 v83, v82, v87
	v_min_u32_e32 v87, v82, v87
	v_max_u32_e32 v82, v97, v102
	v_min_u32_e32 v102, v97, v102
	v_max_u32_e32 v97, v99, v92
	v_min_u32_e32 v92, v99, v92
	v_max_u32_e32 v99, v98, v73
	v_min_u32_e32 v73, v98, v73
	v_max_u32_e32 v98, v91, v83
	v_min_u32_e32 v83, v91, v83
	v_max_u32_e32 v91, v96, v87
	v_min_u32_e32 v87, v96, v87
	v_max_u32_e32 v96, v92, v99
	v_min_u32_e32 v99, v92, v99
	v_max_u32_e32 v92, v73, v98
	v_min_u32_e32 v98, v73, v98
	v_max_u32_e32 v74, v74, v95
	v_max_u32_e32 v101, v101, v70
	v_max_u32_e32 v71, v71, v89
	v_max_u32_e32 v72, v72, v87
	v_max_u32_e32 v76, v76, v91
	v_max_u32_e32 v79, v79, v83
	v_max_u32_e32 v94, v94, v98
	v_max_u32_e32 v100, v100, v92
	v_max_u32_e32 v78, v78, v99
	v_max_u32_e32 v86, v86, v96
	v_max_u32_e32 v77, v77, v97
	v_max_u32_e32 v84, v84, v102
	v_max_u32_e32 v81, v81, v82
	v_max_u32_e32 v80, v80, v90
	v_max_u32_e32 v75, v75, v93
	v_max_u32_e32 v85, v85, v88
	v_max_u32_e32 v95, v74, v78
	v_min_u32_e32 v78, v74, v78
	v_max_u32_e32 v74, v101, v86
	v_min_u32_e32 v86, v101, v86
	v_max_u32_e32 v101, v71, v77
	v_min_u32_e32 v77, v71, v77
	v_max_u32_e32 v71, v72, v84
	v_min_u32_e32 v84, v72, v84
	v_max_u32_e32 v72, v76, v81
	v_min_u32_e32 v81, v76, v81
	v_max_u32_e32 v76, v79, v80
	v_min_u32_e32 v80, v79, v80
	v_max_u32_e32 v79, v94, v75
	v_min_u32_e32 v75, v94, v75
	v_max_u32_e32 v94, v100, v85
	v_min_u32_e32 v85, v100, v85
	v_max_u32_e32 v100, v95, v72
	v_min_u32_e32 v72, v95, v72
	v_max_u32_e32 v95, v74, v76
	v_min_u32_e32 v76, v74, v76
	v_max_u32_e32 v74, v101, v79
	v_min_u32_e32 v79, v101, v79
	v_max_u32_e32 v101, v71, v94
	v_min_u32_e32 v94, v71, v94
	v_max_u32_e32 v71, v78, v81
	v_min_u32_e32 v81, v78, v81
	v_max_u32_e32 v78, v86, v80
	v_min_u32_e32 v80, v86, v80
	v_max_u32_e32 v86, v77, v75
	v_min_u32_e32 v75, v77, v75
	v_max_u32_e32 v77, v84, v85
	v_min_u32_e32 v85, v84, v85
	v_max_u32_e32 v84, v100, v74
	v_min_u32_e32 v74, v100, v74
	v_max_u32_e32 v100, v95, v101
	v_min_u32_e32 v101, v95, v101
	v_max_u32_e32 v95, v72, v79
	v_min_u32_e32 v79, v72, v79
	v_max_u32_e32 v72, v76, v94
	v_min_u32_e32 v94, v76, v94
	v_max_u32_e32 v76, v71, v86
	v_min_u32_e32 v86, v71, v86
	v_max_u32_e32 v71, v78, v77
	v_min_u32_e32 v77, v78, v77
	v_max_u32_e32 v78, v81, v75
	v_min_u32_e32 v75, v81, v75
	v_max_u32_e32 v81, v80, v85
	v_min_u32_e32 v85, v80, v85
	v_max_u32_e32 v80, v84, v100
	v_min_u32_e32 v100, v84, v100
	v_max_u32_e32 v84, v74, v101
	v_min_u32_e32 v101, v74, v101
	v_max_u32_e32 v74, v95, v72
	v_min_u32_e32 v72, v95, v72
	v_max_u32_e32 v95, v79, v94
	v_min_u32_e32 v94, v79, v94
	v_max_u32_e32 v79, v76, v71
	v_min_u32_e32 v71, v76, v71
	v_max_u32_e32 v76, v86, v77
	v_min_u32_e32 v77, v86, v77
	v_max_u32_e32 v86, v78, v81
	v_min_u32_e32 v81, v78, v81
	v_max_u32_e32 v78, v75, v85
	v_min_u32_e32 v85, v75, v85
	v_cvt_f32_f16_e32 v75, v40
	v_cvt_f32_f16_sdwa v70, v40 dst_sel:DWORD dst_unused:UNUSED_PAD src0_sel:WORD_1
; __device__ __forceinline__ unsigned f2key(float f) { const unsigned u = __float_as_uint(f); return (u & 0x80000000u) ? ~u : (u | 0x80000000u); }
; #define CE_DESC(a, b) do { const unsigned _mx = (a) > (b) ? (a) : (b), _mn = (a) > (b) ? (b) : (a); (a) = _mx; (b) = _mn; } while (0)
; __device__ __forceinline__ void sort16_desc(unsigned (&k)[16]) {
; #pragma unroll
;     for (int size = 2; size <= 16; size <<= 1)
; #pragma unroll
;         for (int stride = size >> 1; stride > 0; stride >>= 1)
; #pragma unroll
;             for (int i = 0; i < 16; ++i) { const int j = i ^ stride;
;                 if (j > i) { if ((i & size) == 0) CE_DESC(k[i], k[j]); else CE_DESC(k[j], k[i]); } }
; }
; __device__ __forceinline__ void peer_tile(const Args& A, LAS unsigned char* lds, int tile) {
;     ...
;                   for (int i = 0; i < 16; ++i) {
;                       const float lo = (float)__builtin_bit_cast(_Float16, (unsigned short)(sw[i] & 0xffffu)), hi = (float)__builtin_bit_cast(_Float16, (unsigned short)(sw[i] >> 16));
;                       const unsigned klo = (f2key(lo) & ~127u) | (unsigned)(127 - (32 * g + 2 * i)), khi = (f2key(hi) & ~127u) | (unsigned)(127 - (32 * g + 2 * i + 1));
;                       if (i < 8) { k0[2 * i] = klo; k0[2 * i + 1] = khi; } else { k1[2 * (i - 8)] = klo; k1[2 * (i - 8) + 1] = khi; } } }
;                 sort16_desc(k0); sort16_desc(k1); merge16(k0, k1);
	v_ashrrev_i32_e32 v89, 31, v75
	v_bitop3_b32 v75, v75, v89, s40 bitop3:0x78
	v_xor_b32_e32 v75, 0x8000002f, v75
	v_ashrrev_i32_e32 v89, 31, v70
	v_bitop3_b32 v70, v70, v89, s40 bitop3:0x78
	v_xor_b32_e32 v70, 0x8000002e, v70
	v_cvt_f32_f16_e32 v89, v41
	v_cvt_f32_f16_sdwa v87, v41 dst_sel:DWORD dst_unused:UNUSED_PAD src0_sel:WORD_1
	v_ashrrev_i32_e32 v91, 31, v89
	v_bitop3_b32 v89, v89, v91, s40 bitop3:0x78
	v_xor_b32_e32 v89, 0x8000002d, v89
	v_ashrrev_i32_e32 v91, 31, v87
	v_bitop3_b32 v87, v87, v91, s40 bitop3:0x78
	v_xor_b32_e32 v87, 0x8000002c, v87
	v_cvt_f32_f16_e32 v91, v42
	v_cvt_f32_f16_sdwa v83, v42 dst_sel:DWORD dst_unused:UNUSED_PAD src0_sel:WORD_1
	v_ashrrev_i32_e32 v98, 31, v91
	v_bitop3_b32 v91, v91, v98, s40 bitop3:0x78
	v_xor_b32_e32 v91, 0x8000002b, v91
	v_ashrrev_i32_e32 v98, 31, v83
	v_bitop3_b32 v83, v83, v98, s40 bitop3:0x78
	v_xor_b32_e32 v83, 0x8000002a, v83
	v_cvt_f32_f16_e32 v98, v43
	v_cvt_f32_f16_sdwa v92, v43 dst_sel:DWORD dst_unused:UNUSED_PAD src0_sel:WORD_1
	v_ashrrev_i32_e32 v99, 31, v98
	v_bitop3_b32 v98, v98, v99, s40 bitop3:0x78
	v_xor_b32_e32 v98, 0x80000029, v98
	v_ashrrev_i32_e32 v99, 31, v92
	v_bitop3_b32 v92, v92, v99, s40 bitop3:0x78
	v_xor_b32_e32 v92, 0x80000028, v92
	v_cvt_f32_f16_e32 v99, v44
	v_cvt_f32_f16_sdwa v96, v44 dst_sel:DWORD dst_unused:UNUSED_PAD src0_sel:WORD_1
	v_ashrrev_i32_e32 v97, 31, v99
	v_bitop3_b32 v99, v99, v97, s40 bitop3:0x78
	v_xor_b32_e32 v99, 0x80000027, v99
	v_ashrrev_i32_e32 v97, 31, v96
	v_bitop3_b32 v96, v96, v97, s40 bitop3:0x78
	v_xor_b32_e32 v96, 0x80000026, v96
	v_cvt_f32_f16_e32 v97, v45
	v_cvt_f32_f16_sdwa v102, v45 dst_sel:DWORD dst_unused:UNUSED_PAD src0_sel:WORD_1
	v_ashrrev_i32_e32 v82, 31, v97
	v_bitop3_b32 v97, v97, v82, s40 bitop3:0x78
	v_xor_b32_e32 v97, 0x80000025, v97
	v_ashrrev_i32_e32 v82, 31, v102
	v_bitop3_b32 v102, v102, v82, s40 bitop3:0x78
	v_xor_b32_e32 v102, 0x80000024, v102
	v_cvt_f32_f16_e32 v82, v46
	v_cvt_f32_f16_sdwa v90, v46 dst_sel:DWORD dst_unused:UNUSED_PAD src0_sel:WORD_1
	v_ashrrev_i32_e32 v93, 31, v82
	v_bitop3_b32 v82, v82, v93, s40 bitop3:0x78
	v_xor_b32_e32 v82, 0x80000023, v82
	v_ashrrev_i32_e32 v93, 31, v90
	v_bitop3_b32 v90, v90, v93, s40 bitop3:0x78
	v_xor_b32_e32 v90, 0x80000022, v90
	v_cvt_f32_f16_e32 v93, v47
	v_cvt_f32_f16_sdwa v88, v47 dst_sel:DWORD dst_unused:UNUSED_PAD src0_sel:WORD_1
	v_ashrrev_i32_e32 v73, 31, v93
	v_bitop3_b32 v93, v93, v73, s40 bitop3:0x78
	v_xor_b32_e32 v93, 0x80000021, v93
	v_ashrrev_i32_e32 v73, 31, v88
	v_bitop3_b32 v88, v88, v73, s40 bitop3:0x78
	v_xor_b32_e32 v88, 0x80000020, v88
	v_max_u32_e32 v73, v75, v90
	v_min_u32_e32 v90, v75, v90
	v_max_u32_e32 v75, v70, v82
	v_min_u32_e32 v82, v70, v82
	v_max_u32_e32 v70, v89, v88
	v_min_u32_e32 v88, v89, v88
	v_max_u32_e32 v89, v87, v93
	v_min_u32_e32 v93, v87, v93
	v_max_u32_e32 v87, v91, v99
	v_min_u32_e32 v99, v91, v99
	v_max_u32_e32 v91, v83, v98
	v_min_u32_e32 v98, v83, v98
	v_max_u32_e32 v83, v92, v102
	v_min_u32_e32 v102, v92, v102
	v_max_u32_e32 v92, v96, v97
	v_min_u32_e32 v97, v96, v97
	v_max_u32_e32 v96, v73, v91
	v_min_u32_e32 v91, v73, v91
	v_max_u32_e32 v73, v75, v83
	v_min_u32_e32 v83, v75, v83
	v_max_u32_e32 v75, v70, v92
	v_min_u32_e32 v92, v70, v92
	v_max_u32_e32 v70, v89, v87
	v_min_u32_e32 v87, v89, v87
	v_max_u32_e32 v89, v98, v90
	v_min_u32_e32 v90, v98, v90
	v_max_u32_e32 v98, v99, v93
	v_min_u32_e32 v93, v99, v93
	v_max_u32_e32 v99, v97, v88
	v_min_u32_e32 v88, v97, v88
	v_max_u32_e32 v97, v102, v82
	v_min_u32_e32 v82, v102, v82
	v_max_u32_e32 v102, v96, v73
	v_min_u32_e32 v73, v96, v73
	v_max_u32_e32 v96, v75, v70
	v_min_u32_e32 v70, v75, v70
	v_max_u32_e32 v75, v87, v91
	v_min_u32_e32 v91, v87, v91
	v_max_u32_e32 v87, v89, v98
	v_min_u32_e32 v98, v89, v98
	v_max_u32_e32 v89, v83, v92
	v_min_u32_e32 v92, v83, v92
	v_max_u32_e32 v83, v99, v97
	v_min_u32_e32 v97, v99, v97
	v_max_u32_e32 v99, v82, v90
	v_min_u32_e32 v90, v82, v90
	v_max_u32_e32 v82, v93, v88
	v_min_u32_e32 v88, v93, v88
	v_max_u32_e32 v93, v102, v96
	v_min_u32_e32 v96, v102, v96
	v_max_u32_e32 v102, v73, v70
	v_min_u32_e32 v70, v73, v70
	v_max_u32_e32 v73, v75, v83
	v_min_u32_e32 v83, v75, v83
	v_max_u32_e32 v75, v91, v97
	v_min_u32_e32 v97, v91, v97
	v_max_u32_e32 v91, v87, v89
	v_min_u32_e32 v89, v87, v89
	v_max_u32_e32 v87, v98, v92
	v_min_u32_e32 v92, v98, v92
	v_max_u32_e32 v98, v99, v82
	v_min_u32_e32 v82, v99, v82
	v_max_u32_e32 v99, v90, v88
	v_min_u32_e32 v88, v90, v88
	v_max_u32_e32 v90, v102, v96
	v_min_u32_e32 v96, v102, v96
	v_max_u32_e32 v102, v70, v98
	v_min_u32_e32 v98, v70, v98
	v_max_u32_e32 v70, v73, v91
	v_min_u32_e32 v91, v73, v91
	v_max_u32_e32 v73, v75, v89
	v_min_u32_e32 v89, v75, v89
	v_max_u32_e32 v75, v87, v83
	v_min_u32_e32 v83, v87, v83
	v_max_u32_e32 v87, v92, v97
	v_min_u32_e32 v97, v92, v97
	v_max_u32_e32 v92, v99, v82
	v_min_u32_e32 v82, v99, v82
	v_max_u32_e32 v99, v90, v70
	v_min_u32_e32 v70, v90, v70
	v_max_u32_e32 v90, v96, v91
	v_min_u32_e32 v91, v96, v91
	v_max_u32_e32 v96, v73, v75
	v_min_u32_e32 v75, v73, v75
	v_max_u32_e32 v73, v89, v83
	v_min_u32_e32 v83, v89, v83
	v_max_u32_e32 v89, v87, v92
	v_min_u32_e32 v92, v87, v92
	v_max_u32_e32 v87, v97, v82
	v_min_u32_e32 v82, v97, v82
	v_max_u32_e32 v97, v90, v70
	v_min_u32_e32 v70, v90, v70
	v_max_u32_e32 v90, v102, v91
	v_min_u32_e32 v91, v102, v91
	v_max_u32_e32 v102, v89, v98
	v_min_u32_e32 v98, v89, v98
	v_max_u32_e32 v89, v87, v92
	v_min_u32_e32 v92, v87, v92
	v_max_u32_e32 v87, v90, v96
	v_min_u32_e32 v96, v90, v96
	v_max_u32_e32 v90, v91, v75
	v_min_u32_e32 v75, v91, v75
	v_max_u32_e32 v91, v73, v102
	v_min_u32_e32 v102, v73, v102
	v_max_u32_e32 v73, v83, v98
; __device__ __forceinline__ unsigned f2key(float f) { const unsigned u = __float_as_uint(f); return (u & 0x80000000u) ? ~u : (u | 0x80000000u); }
; #define CE_DESC(a, b) do { const unsigned _mx = (a) > (b) ? (a) : (b), _mn = (a) > (b) ? (b) : (a); (a) = _mx; (b) = _mn; } while (0)
; __device__ __forceinline__ void sort16_desc(unsigned (&k)[16]) {
; #pragma unroll
;     for (int size = 2; size <= 16; size <<= 1)
; #pragma unroll
;         for (int stride = size >> 1; stride > 0; stride >>= 1)
; #pragma unroll
;             for (int i = 0; i < 16; ++i) { const int j = i ^ stride;
;                 if (j > i) { if ((i & size) == 0) CE_DESC(k[i], k[j]); else CE_DESC(k[j], k[i]); } }
; }
; __device__ __forceinline__ void merge16(unsigned (&a)[16], const unsigned (&b)[16]) {
; #pragma unroll
;     for (int i = 0; i < 16; ++i) a[i] = a[i] > b[15 - i] ? a[i] : b[15 - i];
; #pragma unroll
;     for (int stride = 8; stride > 0; stride >>= 1)
; #pragma unroll
;         for (int i = 0; i < 16; ++i) { const int j = i ^ stride; if (j > i) CE_DESC(a[i], a[j]); }
; }
; __device__ __forceinline__ void peer_tile(const Args& A, LAS unsigned char* lds, int tile) {
;     ...
;                   for (int i = 0; i < 16; ++i) {
;                       const float lo = (float)__builtin_bit_cast(_Float16, (unsigned short)(sw[i] & 0xffffu)), hi = (float)__builtin_bit_cast(_Float16, (unsigned short)(sw[i] >> 16));
;                       const unsigned klo = (f2key(lo) & ~127u) | (unsigned)(127 - (32 * g + 2 * i)), khi = (f2key(hi) & ~127u) | (unsigned)(127 - (32 * g + 2 * i + 1));
;                       if (i < 8) { k0[2 * i] = klo; k0[2 * i + 1] = khi; } else { k1[2 * (i - 8)] = klo; k1[2 * (i - 8) + 1] = khi; } } }
	v_min_u32_e32 v98, v83, v98
	v_max_u32_e32 v83, v87, v70
	v_min_u32_e32 v70, v87, v70
	v_max_u32_e32 v87, v96, v90
	v_min_u32_e32 v90, v96, v90
	v_max_u32_e32 v96, v91, v75
	v_min_u32_e32 v75, v91, v75
	v_max_u32_e32 v91, v102, v73
	v_min_u32_e32 v73, v102, v73
	v_max_u32_e32 v102, v89, v98
	v_min_u32_e32 v98, v89, v98
	v_max_u32_e32 v89, v90, v96
	v_min_u32_e32 v96, v90, v96
	v_max_u32_e32 v90, v75, v91
	v_min_u32_e32 v91, v75, v91
	v_max_u32_e32 v80, v80, v88
	v_max_u32_e32 v100, v100, v82
	v_max_u32_e32 v84, v84, v92
	v_max_u32_e32 v101, v101, v98
	v_max_u32_e32 v74, v74, v102
	v_max_u32_e32 v72, v72, v73
	v_max_u32_e32 v95, v95, v91
	v_max_u32_e32 v94, v94, v90
	v_max_u32_e32 v79, v79, v96
	v_max_u32_e32 v71, v71, v89
	v_max_u32_e32 v76, v76, v87
	v_max_u32_e32 v77, v77, v70
	v_max_u32_e32 v86, v86, v83
	v_max_u32_e32 v81, v81, v97
	v_max_u32_e32 v78, v78, v99
	v_max_u32_e32 v85, v85, v93
	v_max_u32_e32 v88, v80, v79
	v_min_u32_e32 v79, v80, v79
	v_max_u32_e32 v80, v100, v71
	v_min_u32_e32 v71, v100, v71
	v_max_u32_e32 v100, v84, v76
	v_min_u32_e32 v76, v84, v76
	v_max_u32_e32 v84, v101, v77
	v_min_u32_e32 v77, v101, v77
	v_max_u32_e32 v101, v74, v86
	v_min_u32_e32 v86, v74, v86
	v_max_u32_e32 v74, v72, v81
	v_min_u32_e32 v81, v72, v81
	v_max_u32_e32 v72, v95, v78
	v_min_u32_e32 v78, v95, v78
	v_max_u32_e32 v95, v94, v85
	v_min_u32_e32 v85, v94, v85
	v_max_u32_e32 v94, v88, v101
	v_min_u32_e32 v101, v88, v101
	v_max_u32_e32 v88, v80, v74
	v_min_u32_e32 v74, v80, v74
	v_max_u32_e32 v80, v100, v72
	v_min_u32_e32 v72, v100, v72
	v_max_u32_e32 v100, v84, v95
	v_min_u32_e32 v95, v84, v95
	v_max_u32_e32 v84, v79, v86
	v_min_u32_e32 v86, v79, v86
	v_max_u32_e32 v79, v71, v81
	v_min_u32_e32 v81, v71, v81
	v_max_u32_e32 v71, v76, v78
	v_min_u32_e32 v78, v76, v78
	v_max_u32_e32 v76, v77, v85
	v_min_u32_e32 v85, v77, v85
	v_max_u32_e32 v77, v94, v80
	v_min_u32_e32 v80, v94, v80
	v_max_u32_e32 v94, v88, v100
	v_min_u32_e32 v100, v88, v100
	v_max_u32_e32 v88, v101, v72
	v_min_u32_e32 v72, v101, v72
	v_max_u32_e32 v101, v74, v95
	v_min_u32_e32 v95, v74, v95
	v_max_u32_e32 v74, v84, v71
	v_min_u32_e32 v71, v84, v71
	v_max_u32_e32 v84, v79, v76
	v_min_u32_e32 v76, v79, v76
	v_max_u32_e32 v79, v86, v78
	v_min_u32_e32 v78, v86, v78
	v_max_u32_e32 v86, v81, v85
	v_min_u32_e32 v85, v81, v85
	v_max_u32_e32 v81, v77, v94
	v_min_u32_e32 v94, v77, v94
	v_max_u32_e32 v77, v80, v100
	v_min_u32_e32 v100, v80, v100
	v_max_u32_e32 v80, v88, v101
	v_min_u32_e32 v101, v88, v101
	v_max_u32_e32 v88, v72, v95
	v_min_u32_e32 v95, v72, v95
	v_max_u32_e32 v72, v74, v84
	v_min_u32_e32 v84, v74, v84
	v_max_u32_e32 v74, v71, v76
	v_min_u32_e32 v76, v71, v76
	v_max_u32_e32 v71, v79, v86
	v_min_u32_e32 v86, v79, v86
	v_max_u32_e32 v79, v78, v85
	v_min_u32_e32 v85, v78, v85
	v_cvt_f32_f16_e32 v78, v48
	v_cvt_f32_f16_sdwa v82, v48 dst_sel:DWORD dst_unused:UNUSED_PAD src0_sel:WORD_1
	v_ashrrev_i32_e32 v92, 31, v78
	v_bitop3_b32 v78, v78, v92, s40 bitop3:0x78
	v_xor_b32_e32 v78, 0x8000001f, v78
	v_ashrrev_i32_e32 v92, 31, v82
	v_bitop3_b32 v82, v82, v92, s40 bitop3:0x78
	v_xor_b32_e32 v82, 0x8000001e, v82
	v_cvt_f32_f16_e32 v92, v49
	v_cvt_f32_f16_sdwa v98, v49 dst_sel:DWORD dst_unused:UNUSED_PAD src0_sel:WORD_1
	v_ashrrev_i32_e32 v102, 31, v92
	v_bitop3_b32 v92, v92, v102, s40 bitop3:0x78
	v_xor_b32_e32 v92, 0x8000001d, v92
	v_ashrrev_i32_e32 v102, 31, v98
	v_bitop3_b32 v98, v98, v102, s40 bitop3:0x78
	v_xor_b32_e32 v98, 0x8000001c, v98
	v_cvt_f32_f16_e32 v102, v50
	v_cvt_f32_f16_sdwa v73, v50 dst_sel:DWORD dst_unused:UNUSED_PAD src0_sel:WORD_1
	v_ashrrev_i32_e32 v91, 31, v102
	v_bitop3_b32 v102, v102, v91, s40 bitop3:0x78
	v_xor_b32_e32 v102, 0x8000001b, v102
	v_ashrrev_i32_e32 v91, 31, v73
	v_bitop3_b32 v73, v73, v91, s40 bitop3:0x78
	v_xor_b32_e32 v73, 0x8000001a, v73
	v_cvt_f32_f16_e32 v91, v51
	v_cvt_f32_f16_sdwa v90, v51 dst_sel:DWORD dst_unused:UNUSED_PAD src0_sel:WORD_1
	v_ashrrev_i32_e32 v96, 31, v91
	v_bitop3_b32 v91, v91, v96, s40 bitop3:0x78
	v_xor_b32_e32 v91, 0x80000019, v91
	v_ashrrev_i32_e32 v96, 31, v90
	v_bitop3_b32 v90, v90, v96, s40 bitop3:0x78
	v_xor_b32_e32 v90, 0x80000018, v90
	v_cvt_f32_f16_e32 v96, v52
	v_cvt_f32_f16_sdwa v89, v52 dst_sel:DWORD dst_unused:UNUSED_PAD src0_sel:WORD_1
	v_ashrrev_i32_e32 v87, 31, v96
	v_bitop3_b32 v96, v96, v87, s40 bitop3:0x78
	v_xor_b32_e32 v96, 0x80000017, v96
	v_ashrrev_i32_e32 v87, 31, v89
	v_bitop3_b32 v89, v89, v87, s40 bitop3:0x78
	v_xor_b32_e32 v89, 0x80000016, v89
	v_cvt_f32_f16_e32 v87, v53
	v_cvt_f32_f16_sdwa v70, v53 dst_sel:DWORD dst_unused:UNUSED_PAD src0_sel:WORD_1
	v_ashrrev_i32_e32 v83, 31, v87
	v_bitop3_b32 v87, v87, v83, s40 bitop3:0x78
	v_xor_b32_e32 v87, 0x80000015, v87
	v_ashrrev_i32_e32 v83, 31, v70
	v_bitop3_b32 v70, v70, v83, s40 bitop3:0x78
	v_xor_b32_e32 v70, 0x80000014, v70
	v_cvt_f32_f16_e32 v83, v54
	v_cvt_f32_f16_sdwa v97, v54 dst_sel:DWORD dst_unused:UNUSED_PAD src0_sel:WORD_1
	v_ashrrev_i32_e32 v99, 31, v83
	v_bitop3_b32 v83, v83, v99, s40 bitop3:0x78
	v_xor_b32_e32 v83, 0x80000013, v83
	v_ashrrev_i32_e32 v99, 31, v97
	v_bitop3_b32 v97, v97, v99, s40 bitop3:0x78
	v_xor_b32_e32 v97, 0x80000012, v97
	v_cvt_f32_f16_e32 v99, v55
	v_cvt_f32_f16_sdwa v93, v55 dst_sel:DWORD dst_unused:UNUSED_PAD src0_sel:WORD_1
	v_ashrrev_i32_e32 v75, 31, v99
	v_bitop3_b32 v99, v99, v75, s40 bitop3:0x78
	v_xor_b32_e32 v99, 0x80000011, v99
	v_ashrrev_i32_e32 v75, 31, v93
	v_bitop3_b32 v93, v93, v75, s40 bitop3:0x78
	v_xor_b32_e32 v93, 0x80000010, v93
	v_max_u32_e32 v75, v78, v97
	v_min_u32_e32 v97, v78, v97
	v_max_u32_e32 v78, v82, v83
	v_min_u32_e32 v83, v82, v83
	v_max_u32_e32 v82, v92, v93
	v_min_u32_e32 v93, v92, v93
; #define CE_DESC(a, b) do { const unsigned _mx = (a) > (b) ? (a) : (b), _mn = (a) > (b) ? (b) : (a); (a) = _mx; (b) = _mn; } while (0)
; __device__ __forceinline__ void sort16_desc(unsigned (&k)[16]) {
; #pragma unroll
;     for (int size = 2; size <= 16; size <<= 1)
; #pragma unroll
;         for (int stride = size >> 1; stride > 0; stride >>= 1)
; #pragma unroll
;             for (int i = 0; i < 16; ++i) { const int j = i ^ stride;
;                 if (j > i) { if ((i & size) == 0) CE_DESC(k[i], k[j]); else CE_DESC(k[j], k[i]); } }
; }
; __device__ __forceinline__ void merge16(unsigned (&a)[16], const unsigned (&b)[16]) {
; #pragma unroll
;     for (int i = 0; i < 16; ++i) a[i] = a[i] > b[15 - i] ? a[i] : b[15 - i];
; #pragma unroll
;     for (int stride = 8; stride > 0; stride >>= 1)
; #pragma unroll
;         for (int i = 0; i < 16; ++i) { const int j = i ^ stride; if (j > i) CE_DESC(a[i], a[j]); }
; }
	v_max_u32_e32 v92, v98, v99
	v_min_u32_e32 v99, v98, v99
	v_max_u32_e32 v98, v102, v96
	v_min_u32_e32 v96, v102, v96
	v_max_u32_e32 v102, v73, v91
	v_min_u32_e32 v91, v73, v91
	v_max_u32_e32 v73, v90, v70
	v_min_u32_e32 v70, v90, v70
	v_max_u32_e32 v90, v89, v87
	v_min_u32_e32 v87, v89, v87
	v_max_u32_e32 v89, v75, v102
	v_min_u32_e32 v102, v75, v102
	v_max_u32_e32 v75, v78, v73
	v_min_u32_e32 v73, v78, v73
	v_max_u32_e32 v78, v82, v90
	v_min_u32_e32 v90, v82, v90
	v_max_u32_e32 v82, v92, v98
	v_min_u32_e32 v98, v92, v98
	v_max_u32_e32 v92, v91, v97
	v_min_u32_e32 v97, v91, v97
	v_max_u32_e32 v91, v96, v99
	v_min_u32_e32 v99, v96, v99
	v_max_u32_e32 v96, v87, v93
	v_min_u32_e32 v93, v87, v93
	v_max_u32_e32 v87, v70, v83
	v_min_u32_e32 v83, v70, v83
	v_max_u32_e32 v70, v89, v75
	v_min_u32_e32 v75, v89, v75
	v_max_u32_e32 v89, v78, v82
	v_min_u32_e32 v82, v78, v82
	v_max_u32_e32 v78, v98, v102
	v_min_u32_e32 v102, v98, v102
	v_max_u32_e32 v98, v92, v91
	v_min_u32_e32 v91, v92, v91
	v_max_u32_e32 v92, v73, v90
	v_min_u32_e32 v90, v73, v90
	v_max_u32_e32 v73, v96, v87
	v_min_u32_e32 v87, v96, v87
	v_max_u32_e32 v96, v83, v97
	v_min_u32_e32 v97, v83, v97
	v_max_u32_e32 v83, v99, v93
	v_min_u32_e32 v93, v99, v93
	v_max_u32_e32 v99, v70, v89
	v_min_u32_e32 v89, v70, v89
	v_max_u32_e32 v70, v75, v82
	v_min_u32_e32 v82, v75, v82
	v_max_u32_e32 v75, v78, v73
	v_min_u32_e32 v73, v78, v73
	v_max_u32_e32 v78, v102, v87
	v_min_u32_e32 v87, v102, v87
	v_max_u32_e32 v102, v98, v92
	v_min_u32_e32 v92, v98, v92
	v_max_u32_e32 v98, v91, v90
	v_min_u32_e32 v90, v91, v90
	v_max_u32_e32 v91, v96, v83
	v_min_u32_e32 v83, v96, v83
	v_max_u32_e32 v96, v97, v93
	v_min_u32_e32 v93, v97, v93
	v_max_u32_e32 v97, v70, v89
	v_min_u32_e32 v89, v70, v89
	v_max_u32_e32 v70, v82, v91
	v_min_u32_e32 v91, v82, v91
	v_max_u32_e32 v82, v75, v102
	v_min_u32_e32 v102, v75, v102
	v_max_u32_e32 v75, v78, v92
	v_min_u32_e32 v92, v78, v92
	v_max_u32_e32 v78, v98, v73
	v_min_u32_e32 v73, v98, v73
	v_max_u32_e32 v98, v90, v87
	v_min_u32_e32 v87, v90, v87
	v_max_u32_e32 v90, v96, v83
	v_min_u32_e32 v83, v96, v83
	v_max_u32_e32 v96, v97, v82
	v_min_u32_e32 v82, v97, v82
	v_max_u32_e32 v97, v89, v102
	v_min_u32_e32 v102, v89, v102
	v_max_u32_e32 v89, v75, v78
	v_min_u32_e32 v78, v75, v78
	v_max_u32_e32 v75, v92, v73
	v_min_u32_e32 v73, v92, v73
	v_max_u32_e32 v92, v98, v90
	v_min_u32_e32 v90, v98, v90
	v_max_u32_e32 v98, v87, v83
	v_min_u32_e32 v83, v87, v83
	v_max_u32_e32 v87, v97, v82
	v_min_u32_e32 v82, v97, v82
	v_max_u32_e32 v97, v70, v102
	v_min_u32_e32 v102, v70, v102
	v_max_u32_e32 v70, v92, v91
	v_min_u32_e32 v91, v92, v91
	v_max_u32_e32 v92, v98, v90
	v_min_u32_e32 v90, v98, v90
	v_max_u32_e32 v98, v97, v89
	v_min_u32_e32 v89, v97, v89
	v_max_u32_e32 v97, v102, v78
	v_min_u32_e32 v78, v102, v78
	v_max_u32_e32 v102, v75, v70
	v_min_u32_e32 v70, v75, v70
	v_max_u32_e32 v75, v73, v91
	v_min_u32_e32 v91, v73, v91
	v_max_u32_e32 v73, v98, v82
	v_min_u32_e32 v82, v98, v82
	v_max_u32_e32 v98, v89, v97
	v_min_u32_e32 v97, v89, v97
	v_max_u32_e32 v89, v102, v78
	v_min_u32_e32 v78, v102, v78
	v_max_u32_e32 v102, v70, v75
	v_min_u32_e32 v75, v70, v75
	v_max_u32_e32 v70, v92, v91
	v_min_u32_e32 v91, v92, v91
	v_max_u32_e32 v92, v97, v89
	v_min_u32_e32 v89, v97, v89
	v_max_u32_e32 v97, v78, v102
	v_min_u32_e32 v102, v78, v102
	v_max_u32_e32 v81, v81, v93
	v_max_u32_e32 v94, v94, v83
	v_max_u32_e32 v77, v77, v90
	v_max_u32_e32 v100, v100, v91
	v_max_u32_e32 v80, v80, v70
	v_max_u32_e32 v101, v101, v75
	v_max_u32_e32 v88, v88, v102
	v_max_u32_e32 v95, v95, v97
	v_max_u32_e32 v72, v72, v89
	v_max_u32_e32 v84, v84, v92
	v_max_u32_e32 v74, v74, v98
	v_max_u32_e32 v76, v76, v82
	v_max_u32_e32 v71, v71, v73
	v_max_u32_e32 v86, v86, v87
	v_max_u32_e32 v79, v79, v96
	v_max_u32_e32 v85, v85, v99
	v_max_u32_e32 v93, v81, v72
	v_min_u32_e32 v72, v81, v72
	v_max_u32_e32 v81, v94, v84
	v_min_u32_e32 v84, v94, v84
	v_max_u32_e32 v94, v77, v74
	v_min_u32_e32 v74, v77, v74
	v_max_u32_e32 v77, v100, v76
	v_min_u32_e32 v76, v100, v76
	v_max_u32_e32 v100, v80, v71
	v_min_u32_e32 v71, v80, v71
	v_max_u32_e32 v80, v101, v86
	v_min_u32_e32 v86, v101, v86
	v_max_u32_e32 v101, v88, v79
	v_min_u32_e32 v79, v88, v79
	v_max_u32_e32 v88, v95, v85
	v_min_u32_e32 v85, v95, v85
	v_max_u32_e32 v95, v93, v100
	v_min_u32_e32 v100, v93, v100
	v_max_u32_e32 v93, v81, v80
	v_min_u32_e32 v80, v81, v80
	v_max_u32_e32 v81, v94, v101
	v_min_u32_e32 v101, v94, v101
	v_max_u32_e32 v94, v77, v88
	v_min_u32_e32 v88, v77, v88
	v_max_u32_e32 v77, v72, v71
	v_min_u32_e32 v71, v72, v71
	v_max_u32_e32 v72, v84, v86
	v_min_u32_e32 v86, v84, v86
	v_max_u32_e32 v84, v74, v79
	v_min_u32_e32 v79, v74, v79
	v_max_u32_e32 v74, v76, v85
	v_min_u32_e32 v85, v76, v85
	v_max_u32_e32 v76, v95, v81
	v_min_u32_e32 v81, v95, v81
	v_max_u32_e32 v95, v93, v94
	v_min_u32_e32 v94, v93, v94
	v_max_u32_e32 v93, v100, v101
	v_min_u32_e32 v101, v100, v101
	v_max_u32_e32 v100, v80, v88
	v_min_u32_e32 v88, v80, v88
	v_max_u32_e32 v80, v77, v84
	v_min_u32_e32 v84, v77, v84
	v_max_u32_e32 v77, v72, v74
	v_min_u32_e32 v74, v72, v74
	v_max_u32_e32 v72, v71, v79
	v_min_u32_e32 v79, v71, v79
	v_max_u32_e32 v71, v86, v85
	v_min_u32_e32 v85, v86, v85
	v_max_u32_e32 v86, v76, v95
	v_min_u32_e32 v95, v76, v95
	v_max_u32_e32 v76, v81, v94
	v_min_u32_e32 v94, v81, v94
	v_max_u32_e32 v81, v93, v100
	v_min_u32_e32 v100, v93, v100
	v_max_u32_e32 v93, v101, v88
	v_min_u32_e32 v88, v101, v88
	v_max_u32_e32 v101, v80, v77
	v_min_u32_e32 v77, v80, v77
	v_max_u32_e32 v80, v84, v74
	v_min_u32_e32 v74, v84, v74
	v_max_u32_e32 v84, v72, v71
	v_min_u32_e32 v71, v72, v71
; __device__ __forceinline__ unsigned f2key(float f) { const unsigned u = __float_as_uint(f); return (u & 0x80000000u) ? ~u : (u | 0x80000000u); }
; #define CE_DESC(a, b) do { const unsigned _mx = (a) > (b) ? (a) : (b), _mn = (a) > (b) ? (b) : (a); (a) = _mx; (b) = _mn; } while (0)
; __device__ __forceinline__ void sort16_desc(unsigned (&k)[16]) {
; #pragma unroll
;     for (int size = 2; size <= 16; size <<= 1)
; #pragma unroll
;         for (int stride = size >> 1; stride > 0; stride >>= 1)
; #pragma unroll
;             for (int i = 0; i < 16; ++i) { const int j = i ^ stride;
;                 if (j > i) { if ((i & size) == 0) CE_DESC(k[i], k[j]); else CE_DESC(k[j], k[i]); } }
; }
; __device__ __forceinline__ void peer_tile(const Args& A, LAS unsigned char* lds, int tile) {
;     ...
;                   for (int i = 0; i < 16; ++i) {
;                       const float lo = (float)__builtin_bit_cast(_Float16, (unsigned short)(sw[i] & 0xffffu)), hi = (float)__builtin_bit_cast(_Float16, (unsigned short)(sw[i] >> 16));
;                       const unsigned klo = (f2key(lo) & ~127u) | (unsigned)(127 - (32 * g + 2 * i)), khi = (f2key(hi) & ~127u) | (unsigned)(127 - (32 * g + 2 * i + 1));
;                       if (i < 8) { k0[2 * i] = klo; k0[2 * i + 1] = khi; } else { k1[2 * (i - 8)] = klo; k1[2 * (i - 8) + 1] = khi; } } }
;                 sort16_desc(k0); sort16_desc(k1); merge16(k0, k1);
	v_max_u32_e32 v72, v79, v85
	v_min_u32_e32 v85, v79, v85
	v_cvt_f32_f16_e32 v79, v56
	v_cvt_f32_f16_sdwa v83, v56 dst_sel:DWORD dst_unused:UNUSED_PAD src0_sel:WORD_1
	v_ashrrev_i32_e32 v90, 31, v79
	v_bitop3_b32 v79, v79, v90, s40 bitop3:0x78
	v_xor_b32_e32 v79, 0x8000000f, v79
	v_ashrrev_i32_e32 v90, 31, v83
	v_bitop3_b32 v83, v83, v90, s40 bitop3:0x78
	v_xor_b32_e32 v83, 0x8000000e, v83
	v_cvt_f32_f16_e32 v90, v57
	v_cvt_f32_f16_sdwa v91, v57 dst_sel:DWORD dst_unused:UNUSED_PAD src0_sel:WORD_1
	v_ashrrev_i32_e32 v70, 31, v90
	v_bitop3_b32 v90, v90, v70, s40 bitop3:0x78
	v_xor_b32_e32 v90, 0x8000000d, v90
	v_ashrrev_i32_e32 v70, 31, v91
	v_bitop3_b32 v91, v91, v70, s40 bitop3:0x78
	v_xor_b32_e32 v91, 0x8000000c, v91
	v_cvt_f32_f16_e32 v70, v58
	v_cvt_f32_f16_sdwa v75, v58 dst_sel:DWORD dst_unused:UNUSED_PAD src0_sel:WORD_1
	v_ashrrev_i32_e32 v102, 31, v70
	v_bitop3_b32 v70, v70, v102, s40 bitop3:0x78
	v_xor_b32_e32 v70, 0x8000000b, v70
	v_ashrrev_i32_e32 v102, 31, v75
	v_bitop3_b32 v75, v75, v102, s40 bitop3:0x78
	v_xor_b32_e32 v75, 0x8000000a, v75
	v_cvt_f32_f16_e32 v102, v59
	v_cvt_f32_f16_sdwa v97, v59 dst_sel:DWORD dst_unused:UNUSED_PAD src0_sel:WORD_1
	v_ashrrev_i32_e32 v89, 31, v102
	v_bitop3_b32 v102, v102, v89, s40 bitop3:0x78
	v_xor_b32_e32 v102, 0x80000009, v102
	v_ashrrev_i32_e32 v89, 31, v97
	v_bitop3_b32 v97, v97, v89, s40 bitop3:0x78
	v_xor_b32_e32 v97, 0x80000008, v97
	v_cvt_f32_f16_e32 v89, v60
	v_cvt_f32_f16_sdwa v92, v60 dst_sel:DWORD dst_unused:UNUSED_PAD src0_sel:WORD_1
	v_ashrrev_i32_e32 v98, 31, v89
	v_bitop3_b32 v89, v89, v98, s40 bitop3:0x78
	v_xor_b32_e32 v89, 0x80000007, v89
	v_ashrrev_i32_e32 v98, 31, v92
	v_bitop3_b32 v92, v92, v98, s40 bitop3:0x78
	v_xor_b32_e32 v92, 0x80000006, v92
	v_cvt_f32_f16_e32 v98, v61
	v_cvt_f32_f16_sdwa v82, v61 dst_sel:DWORD dst_unused:UNUSED_PAD src0_sel:WORD_1
	v_ashrrev_i32_e32 v73, 31, v98
	v_bitop3_b32 v98, v98, v73, s40 bitop3:0x78
	v_xor_b32_e32 v98, 0x80000005, v98
	v_ashrrev_i32_e32 v73, 31, v82
	v_bitop3_b32 v82, v82, v73, s40 bitop3:0x78
	v_xor_b32_e32 v82, 0x80000004, v82
	v_cvt_f32_f16_e32 v73, v62
	v_cvt_f32_f16_sdwa v87, v62 dst_sel:DWORD dst_unused:UNUSED_PAD src0_sel:WORD_1
	v_ashrrev_i32_e32 v96, 31, v73
	v_bitop3_b32 v73, v73, v96, s40 bitop3:0x78
	v_xor_b32_e32 v73, 0x80000003, v73
	v_ashrrev_i32_e32 v96, 31, v87
	v_bitop3_b32 v87, v87, v96, s40 bitop3:0x78
	v_xor_b32_e32 v87, 0x80000002, v87
	v_cvt_f32_f16_e32 v96, v63
	v_cvt_f32_f16_sdwa v99, v63 dst_sel:DWORD dst_unused:UNUSED_PAD src0_sel:WORD_1
	v_ashrrev_i32_e32 v78, 31, v96
	v_bitop3_b32 v96, v96, v78, s40 bitop3:0x78
	v_xor_b32_e32 v96, 0x80000001, v96
	v_ashrrev_i32_e32 v78, 31, v99
	v_bitop3_b32 v99, v99, v78, s40 bitop3:0x78
	v_xor_b32_e32 v99, 0x80000000, v99
	v_max_u32_e32 v78, v79, v87
	v_min_u32_e32 v87, v79, v87
	v_max_u32_e32 v79, v83, v73
	v_min_u32_e32 v73, v83, v73
	v_max_u32_e32 v83, v90, v99
	v_min_u32_e32 v99, v90, v99
	v_max_u32_e32 v90, v91, v96
	v_min_u32_e32 v96, v91, v96
	v_max_u32_e32 v91, v70, v89
	v_min_u32_e32 v89, v70, v89
	v_max_u32_e32 v70, v75, v102
	v_min_u32_e32 v102, v75, v102
	v_max_u32_e32 v75, v97, v82
	v_min_u32_e32 v82, v97, v82
	v_max_u32_e32 v97, v92, v98
	v_min_u32_e32 v98, v92, v98
	v_max_u32_e32 v92, v78, v70
	v_min_u32_e32 v70, v78, v70
	v_max_u32_e32 v78, v79, v75
	v_min_u32_e32 v75, v79, v75
	v_max_u32_e32 v79, v83, v97
	v_min_u32_e32 v97, v83, v97
	v_max_u32_e32 v83, v90, v91
	v_min_u32_e32 v91, v90, v91
	v_max_u32_e32 v90, v102, v87
	v_min_u32_e32 v87, v102, v87
	v_max_u32_e32 v102, v89, v96
	v_min_u32_e32 v96, v89, v96
	v_max_u32_e32 v89, v98, v99
	v_min_u32_e32 v99, v98, v99
	v_max_u32_e32 v98, v82, v73
	v_min_u32_e32 v73, v82, v73
	v_max_u32_e32 v82, v92, v78
	v_min_u32_e32 v78, v92, v78
	v_max_u32_e32 v92, v79, v83
	v_min_u32_e32 v83, v79, v83
	v_max_u32_e32 v79, v91, v70
	v_min_u32_e32 v70, v91, v70
	v_max_u32_e32 v91, v90, v102
	v_min_u32_e32 v102, v90, v102
	v_max_u32_e32 v90, v75, v97
	v_min_u32_e32 v97, v75, v97
	v_max_u32_e32 v75, v89, v98
	v_min_u32_e32 v98, v89, v98
	v_max_u32_e32 v89, v73, v87
	v_min_u32_e32 v87, v73, v87
	v_max_u32_e32 v73, v96, v99
	v_min_u32_e32 v99, v96, v99
	v_max_u32_e32 v96, v82, v92
	v_min_u32_e32 v92, v82, v92
	v_max_u32_e32 v82, v78, v83
	v_min_u32_e32 v83, v78, v83
	v_max_u32_e32 v78, v79, v75
	v_min_u32_e32 v75, v79, v75
	v_max_u32_e32 v79, v70, v98
	v_min_u32_e32 v98, v70, v98
	v_max_u32_e32 v70, v91, v90
	v_min_u32_e32 v90, v91, v90
	v_max_u32_e32 v91, v102, v97
	v_min_u32_e32 v97, v102, v97
	v_max_u32_e32 v102, v89, v73
	v_min_u32_e32 v73, v89, v73
	v_max_u32_e32 v89, v87, v99
	v_min_u32_e32 v99, v87, v99
	v_max_u32_e32 v87, v82, v92
	v_min_u32_e32 v92, v82, v92
	v_max_u32_e32 v82, v83, v102
	v_min_u32_e32 v102, v83, v102
	v_max_u32_e32 v83, v78, v70
	v_min_u32_e32 v70, v78, v70
	v_max_u32_e32 v78, v79, v90
	v_min_u32_e32 v90, v79, v90
	v_max_u32_e32 v79, v91, v75
	v_min_u32_e32 v75, v91, v75
	v_max_u32_e32 v91, v97, v98
	v_min_u32_e32 v98, v97, v98
	v_max_u32_e32 v97, v89, v73
	v_min_u32_e32 v73, v89, v73
	v_max_u32_e32 v89, v87, v83
	v_min_u32_e32 v83, v87, v83
	v_max_u32_e32 v87, v92, v70
	v_min_u32_e32 v70, v92, v70
	v_max_u32_e32 v92, v78, v79
	v_min_u32_e32 v79, v78, v79
	v_max_u32_e32 v78, v90, v75
	v_min_u32_e32 v75, v90, v75
	v_max_u32_e32 v90, v91, v97
	v_min_u32_e32 v97, v91, v97
	v_max_u32_e32 v91, v98, v73
	v_min_u32_e32 v73, v98, v73
	v_max_u32_e32 v98, v87, v83
	v_min_u32_e32 v83, v87, v83
	v_max_u32_e32 v87, v82, v70
	v_min_u32_e32 v70, v82, v70
	v_max_u32_e32 v82, v90, v102
	v_min_u32_e32 v102, v90, v102
	v_max_u32_e32 v90, v91, v97
	v_min_u32_e32 v97, v91, v97
	v_max_u32_e32 v91, v87, v92
; #define CE_DESC(a, b) do { const unsigned _mx = (a) > (b) ? (a) : (b), _mn = (a) > (b) ? (b) : (a); (a) = _mx; (b) = _mn; } while (0)
; __device__ __forceinline__ void sort16_desc(unsigned (&k)[16]) {
; #pragma unroll
;     for (int size = 2; size <= 16; size <<= 1)
; #pragma unroll
;         for (int stride = size >> 1; stride > 0; stride >>= 1)
; #pragma unroll
;             for (int i = 0; i < 16; ++i) { const int j = i ^ stride;
;                 if (j > i) { if ((i & size) == 0) CE_DESC(k[i], k[j]); else CE_DESC(k[j], k[i]); } }
; }
; __device__ __forceinline__ void merge16(unsigned (&a)[16], const unsigned (&b)[16]) {
; #pragma unroll
;     for (int i = 0; i < 16; ++i) a[i] = a[i] > b[15 - i] ? a[i] : b[15 - i];
; #pragma unroll
;     for (int stride = 8; stride > 0; stride >>= 1)
; #pragma unroll
;         for (int i = 0; i < 16; ++i) { const int j = i ^ stride; if (j > i) CE_DESC(a[i], a[j]); }
; }
; __device__ __forceinline__ void peer_tile(const Args& A, LAS unsigned char* lds, int tile) {
;     ...
;                 { const bf16_t* sp = QRY + m * 2048 + hp * 128 + 32 * g;
;                   const u32x4 s0 = *(const u32x4*)sp, s1 = *(const u32x4*)(sp + 8), s2 = *(const u32x4*)(sp + 16), s3 = *(const u32x4*)(sp + 24);
	v_min_u32_e32 v92, v87, v92
	v_max_u32_e32 v87, v70, v79
	v_min_u32_e32 v79, v70, v79
	v_max_u32_e32 v70, v78, v82
	v_min_u32_e32 v82, v78, v82
	v_max_u32_e32 v78, v75, v102
	v_min_u32_e32 v102, v75, v102
	v_max_u32_e32 v75, v91, v83
	v_min_u32_e32 v83, v91, v83
	v_max_u32_e32 v91, v92, v87
	v_min_u32_e32 v87, v92, v87
	v_max_u32_e32 v92, v70, v79
	v_min_u32_e32 v79, v70, v79
	v_max_u32_e32 v70, v82, v78
	v_min_u32_e32 v78, v82, v78
	v_max_u32_e32 v82, v90, v102
	v_min_u32_e32 v102, v90, v102
	v_max_u32_e32 v90, v87, v92
	v_min_u32_e32 v92, v87, v92
	v_max_u32_e32 v87, v79, v70
	v_min_u32_e32 v70, v79, v70
	v_max_u32_e32 v86, v86, v99
	v_max_u32_e32 v95, v95, v73
	v_max_u32_e32 v76, v76, v97
	v_max_u32_e32 v94, v94, v102
	v_max_u32_e32 v81, v81, v82
	v_max_u32_e32 v100, v100, v78
	v_max_u32_e32 v93, v93, v70
	v_max_u32_e32 v88, v88, v87
	v_max_u32_e32 v101, v101, v92
	v_max_u32_e32 v77, v77, v90
	v_max_u32_e32 v80, v80, v91
	v_max_u32_e32 v74, v74, v83
	v_max_u32_e32 v84, v84, v75
	v_max_u32_e32 v71, v71, v98
	v_max_u32_e32 v72, v72, v89
	v_max_u32_e32 v85, v85, v96
	v_max_u32_e32 v99, v86, v101
	v_min_u32_e32 v101, v86, v101
	v_max_u32_e32 v86, v95, v77
	v_min_u32_e32 v77, v95, v77
	v_max_u32_e32 v95, v76, v80
	v_min_u32_e32 v80, v76, v80
	v_max_u32_e32 v76, v94, v74
	v_min_u32_e32 v74, v94, v74
	v_max_u32_e32 v94, v81, v84
	v_min_u32_e32 v84, v81, v84
	v_max_u32_e32 v81, v100, v71
	v_min_u32_e32 v71, v100, v71
	v_max_u32_e32 v100, v93, v72
	v_min_u32_e32 v72, v93, v72
	v_max_u32_e32 v93, v88, v85
	v_min_u32_e32 v85, v88, v85
	v_max_u32_e32 v88, v99, v94
	v_min_u32_e32 v94, v99, v94
	v_max_u32_e32 v99, v86, v81
	v_min_u32_e32 v81, v86, v81
	v_max_u32_e32 v86, v95, v100
	v_min_u32_e32 v100, v95, v100
	v_max_u32_e32 v95, v76, v93
	v_min_u32_e32 v93, v76, v93
	v_max_u32_e32 v76, v101, v84
	v_min_u32_e32 v84, v101, v84
	v_max_u32_e32 v101, v77, v71
	v_min_u32_e32 v71, v77, v71
	v_max_u32_e32 v77, v80, v72
	v_min_u32_e32 v72, v80, v72
	v_max_u32_e32 v80, v74, v85
	v_min_u32_e32 v85, v74, v85
	v_max_u32_e32 v74, v88, v86
	v_min_u32_e32 v86, v88, v86
	v_max_u32_e32 v88, v99, v95
	v_min_u32_e32 v95, v99, v95
	v_max_u32_e32 v99, v94, v100
	v_min_u32_e32 v100, v94, v100
	v_max_u32_e32 v94, v81, v93
	v_min_u32_e32 v93, v81, v93
	v_max_u32_e32 v81, v76, v77
	v_min_u32_e32 v77, v76, v77
	v_max_u32_e32 v76, v101, v80
	v_min_u32_e32 v80, v101, v80
	v_max_u32_e32 v101, v84, v72
	v_min_u32_e32 v72, v84, v72
	v_max_u32_e32 v84, v71, v85
	v_min_u32_e32 v85, v71, v85
	v_max_u32_e32 v71, v74, v88
	v_min_u32_e32 v88, v74, v88
	v_max_u32_e32 v74, v86, v95
	v_min_u32_e32 v95, v86, v95
	v_max_u32_e32 v86, v99, v94
	v_min_u32_e32 v94, v99, v94
	v_max_u32_e32 v99, v100, v93
	v_min_u32_e32 v93, v100, v93
	v_max_u32_e32 v100, v81, v76
	v_min_u32_e32 v76, v81, v76
	v_max_u32_e32 v81, v77, v80
	v_min_u32_e32 v80, v77, v80
	v_max_u32_e32 v77, v101, v84
	v_min_u32_e32 v84, v101, v84
	v_max_u32_e32 v101, v72, v85
	v_min_u32_e32 v85, v72, v85
	s_mov_b64 s[38:39], s[34:35]
	global_load_dwordx4 v[32:35], v66, s[38:39] offset:384
	s_add_u32 s38, s38, 0x8000
	s_addc_u32 s39, s39, 0
	global_load_dwordx4 v[36:39], v66, s[38:39] offset:384
	s_add_u32 s38, s38, 0x8000
	s_addc_u32 s39, s39, 0
	global_load_dwordx4 v[40:43], v66, s[38:39] offset:384
	s_add_u32 s38, s38, 0x8000
	s_addc_u32 s39, s39, 0
	global_load_dwordx4 v[44:47], v66, s[38:39] offset:384
	s_add_u32 s38, s38, 0x8000
	s_addc_u32 s39, s39, 0
	global_load_dwordx4 v[48:51], v66, s[38:39] offset:384
	s_add_u32 s38, s38, 0x8000
	s_addc_u32 s39, s39, 0
	global_load_dwordx4 v[52:55], v66, s[38:39] offset:384
	s_add_u32 s38, s38, 0x8000
	s_addc_u32 s39, s39, 0
	global_load_dwordx4 v[56:59], v66, s[38:39] offset:384
	s_add_u32 s38, s38, 0x8000
	s_addc_u32 s39, s39, 0
	global_load_dwordx4 v[60:63], v66, s[38:39] offset:384
	s_waitcnt vmcnt(8)
	ds_write_b128 v64, v[0:3] offset:0
	ds_write_b128 v64, v[4:7] offset:1152
	ds_write_b128 v64, v[8:11] offset:2304
	ds_write_b128 v64, v[12:15] offset:3456
	ds_write_b128 v64, v[16:19] offset:4608
	ds_write_b128 v64, v[20:23] offset:5760
	ds_write_b128 v64, v[24:27] offset:6912
	ds_write_b128 v64, v[28:31] offset:8064
	s_waitcnt lgkmcnt(0)
	ds_read_b128 v[0:3], v65 offset:0
	ds_read_b128 v[4:7], v65 offset:16
	ds_read_b128 v[8:11], v65 offset:32
	ds_read_b128 v[12:15], v65 offset:48
	ds_read_b128 v[16:19], v65 offset:64
	ds_read_b128 v[20:23], v65 offset:80
	ds_read_b128 v[24:27], v65 offset:96
	ds_read_b128 v[28:31], v65 offset:112
	s_waitcnt lgkmcnt(0)
; __device__ __forceinline__ unsigned f2key(float f) { const unsigned u = __float_as_uint(f); return (u & 0x80000000u) ? ~u : (u | 0x80000000u); }
; #define CE_DESC(a, b) do { const unsigned _mx = (a) > (b) ? (a) : (b), _mn = (a) > (b) ? (b) : (a); (a) = _mx; (b) = _mn; } while (0)
; __device__ __forceinline__ void sort16_desc(unsigned (&k)[16]) {
; #pragma unroll
;     for (int size = 2; size <= 16; size <<= 1)
; #pragma unroll
;         for (int stride = size >> 1; stride > 0; stride >>= 1)
; #pragma unroll
;             for (int i = 0; i < 16; ++i) { const int j = i ^ stride;
;                 if (j > i) { if ((i & size) == 0) CE_DESC(k[i], k[j]); else CE_DESC(k[j], k[i]); } }
; }
; __device__ __forceinline__ void peer_tile(const Args& A, LAS unsigned char* lds, int tile) {
;     ...
;                   for (int i = 0; i < 16; ++i) {
;                       const float lo = (float)__builtin_bit_cast(_Float16, (unsigned short)(sw[i] & 0xffffu)), hi = (float)__builtin_bit_cast(_Float16, (unsigned short)(sw[i] >> 16));
;                       const unsigned klo = (f2key(lo) & ~127u) | (unsigned)(127 - (32 * g + 2 * i)), khi = (f2key(hi) & ~127u) | (unsigned)(127 - (32 * g + 2 * i + 1));
;                       if (i < 8) { k0[2 * i] = klo; k0[2 * i + 1] = khi; } else { k1[2 * (i - 8)] = klo; k1[2 * (i - 8) + 1] = khi; } } }
;                 sort16_desc(k0); sort16_desc(k1); merge16(k0, k1);
	v_cvt_f32_f16_e32 v72, v0
	v_cvt_f32_f16_sdwa v73, v0 dst_sel:DWORD dst_unused:UNUSED_PAD src0_sel:WORD_1
	v_ashrrev_i32_e32 v97, 31, v72
	v_bitop3_b32 v72, v72, v97, s40 bitop3:0x78
	v_xor_b32_e32 v72, 0x8000007f, v72
	v_ashrrev_i32_e32 v97, 31, v73
	v_bitop3_b32 v73, v73, v97, s40 bitop3:0x78
	v_xor_b32_e32 v73, 0x8000007e, v73
	v_cvt_f32_f16_e32 v97, v1
	v_cvt_f32_f16_sdwa v102, v1 dst_sel:DWORD dst_unused:UNUSED_PAD src0_sel:WORD_1
	v_ashrrev_i32_e32 v82, 31, v97
	v_bitop3_b32 v97, v97, v82, s40 bitop3:0x78
	v_xor_b32_e32 v97, 0x8000007d, v97
	v_ashrrev_i32_e32 v82, 31, v102
	v_bitop3_b32 v102, v102, v82, s40 bitop3:0x78
	v_xor_b32_e32 v102, 0x8000007c, v102
	v_cvt_f32_f16_e32 v82, v2
	v_cvt_f32_f16_sdwa v78, v2 dst_sel:DWORD dst_unused:UNUSED_PAD src0_sel:WORD_1
	v_ashrrev_i32_e32 v70, 31, v82
	v_bitop3_b32 v82, v82, v70, s40 bitop3:0x78
	v_xor_b32_e32 v82, 0x8000007b, v82
	v_ashrrev_i32_e32 v70, 31, v78
	v_bitop3_b32 v78, v78, v70, s40 bitop3:0x78
	v_xor_b32_e32 v78, 0x8000007a, v78
	v_cvt_f32_f16_e32 v70, v3
	v_cvt_f32_f16_sdwa v87, v3 dst_sel:DWORD dst_unused:UNUSED_PAD src0_sel:WORD_1
	v_ashrrev_i32_e32 v92, 31, v70
	v_bitop3_b32 v70, v70, v92, s40 bitop3:0x78
	v_xor_b32_e32 v70, 0x80000079, v70
	v_ashrrev_i32_e32 v92, 31, v87
	v_bitop3_b32 v87, v87, v92, s40 bitop3:0x78
	v_xor_b32_e32 v87, 0x80000078, v87
	v_cvt_f32_f16_e32 v92, v4
	v_cvt_f32_f16_sdwa v90, v4 dst_sel:DWORD dst_unused:UNUSED_PAD src0_sel:WORD_1
	v_ashrrev_i32_e32 v91, 31, v92
	v_bitop3_b32 v92, v92, v91, s40 bitop3:0x78
	v_xor_b32_e32 v92, 0x80000077, v92
	v_ashrrev_i32_e32 v91, 31, v90
	v_bitop3_b32 v90, v90, v91, s40 bitop3:0x78
	v_xor_b32_e32 v90, 0x80000076, v90
	v_cvt_f32_f16_e32 v91, v5
	v_cvt_f32_f16_sdwa v83, v5 dst_sel:DWORD dst_unused:UNUSED_PAD src0_sel:WORD_1
	v_ashrrev_i32_e32 v75, 31, v91
	v_bitop3_b32 v91, v91, v75, s40 bitop3:0x78
	v_xor_b32_e32 v91, 0x80000075, v91
	v_ashrrev_i32_e32 v75, 31, v83
	v_bitop3_b32 v83, v83, v75, s40 bitop3:0x78
	v_xor_b32_e32 v83, 0x80000074, v83
	v_cvt_f32_f16_e32 v75, v6
	v_cvt_f32_f16_sdwa v98, v6 dst_sel:DWORD dst_unused:UNUSED_PAD src0_sel:WORD_1
	v_ashrrev_i32_e32 v89, 31, v75
	v_bitop3_b32 v75, v75, v89, s40 bitop3:0x78
	v_xor_b32_e32 v75, 0x80000073, v75
	v_ashrrev_i32_e32 v89, 31, v98
	v_bitop3_b32 v98, v98, v89, s40 bitop3:0x78
	v_xor_b32_e32 v98, 0x80000072, v98
	v_cvt_f32_f16_e32 v89, v7
	v_cvt_f32_f16_sdwa v96, v7 dst_sel:DWORD dst_unused:UNUSED_PAD src0_sel:WORD_1
	v_ashrrev_i32_e32 v79, 31, v89
	v_bitop3_b32 v89, v89, v79, s40 bitop3:0x78
	v_xor_b32_e32 v89, 0x80000071, v89
	v_ashrrev_i32_e32 v79, 31, v96
	v_bitop3_b32 v96, v96, v79, s40 bitop3:0x78
	v_xor_b32_e32 v96, 0x80000070, v96
	v_max_u32_e32 v79, v72, v98
	v_min_u32_e32 v98, v72, v98
	v_max_u32_e32 v72, v73, v75
	v_min_u32_e32 v75, v73, v75
	v_max_u32_e32 v73, v97, v96
	v_min_u32_e32 v96, v97, v96
	v_max_u32_e32 v97, v102, v89
	v_min_u32_e32 v89, v102, v89
	v_max_u32_e32 v102, v82, v92
	v_min_u32_e32 v92, v82, v92
	v_max_u32_e32 v82, v78, v70
	v_min_u32_e32 v70, v78, v70
	v_max_u32_e32 v78, v87, v83
	v_min_u32_e32 v83, v87, v83
	v_max_u32_e32 v87, v90, v91
	v_min_u32_e32 v91, v90, v91
	v_max_u32_e32 v90, v79, v82
	v_min_u32_e32 v82, v79, v82
	v_max_u32_e32 v79, v72, v78
	v_min_u32_e32 v78, v72, v78
	v_max_u32_e32 v72, v73, v87
	v_min_u32_e32 v87, v73, v87
	v_max_u32_e32 v73, v97, v102
	v_min_u32_e32 v102, v97, v102
	v_max_u32_e32 v97, v70, v98
	v_min_u32_e32 v98, v70, v98
	v_max_u32_e32 v70, v92, v89
	v_min_u32_e32 v89, v92, v89
	v_max_u32_e32 v92, v91, v96
	v_min_u32_e32 v96, v91, v96
	v_max_u32_e32 v91, v83, v75
	v_min_u32_e32 v75, v83, v75
	v_max_u32_e32 v83, v90, v79
	v_min_u32_e32 v79, v90, v79
	v_max_u32_e32 v90, v72, v73
	v_min_u32_e32 v73, v72, v73
	v_max_u32_e32 v72, v102, v82
	v_min_u32_e32 v82, v102, v82
	v_max_u32_e32 v102, v97, v70
	v_min_u32_e32 v70, v97, v70
	v_max_u32_e32 v97, v78, v87
	v_min_u32_e32 v87, v78, v87
	v_max_u32_e32 v78, v92, v91
	v_min_u32_e32 v91, v92, v91
	v_max_u32_e32 v92, v75, v98
	v_min_u32_e32 v98, v75, v98
	v_max_u32_e32 v75, v89, v96
	v_min_u32_e32 v96, v89, v96
	v_max_u32_e32 v89, v83, v90
	v_min_u32_e32 v90, v83, v90
	v_max_u32_e32 v83, v79, v73
	v_min_u32_e32 v73, v79, v73
	v_max_u32_e32 v79, v72, v78
	v_min_u32_e32 v78, v72, v78
	v_max_u32_e32 v72, v82, v91
	v_min_u32_e32 v91, v82, v91
	v_max_u32_e32 v82, v102, v97
	v_min_u32_e32 v97, v102, v97
	v_max_u32_e32 v102, v70, v87
	v_min_u32_e32 v87, v70, v87
	v_max_u32_e32 v70, v92, v75
	v_min_u32_e32 v75, v92, v75
	v_max_u32_e32 v92, v98, v96
	v_min_u32_e32 v96, v98, v96
	v_max_u32_e32 v98, v83, v90
	v_min_u32_e32 v90, v83, v90
	v_max_u32_e32 v83, v73, v70
	v_min_u32_e32 v70, v73, v70
	v_max_u32_e32 v73, v79, v82
	v_min_u32_e32 v82, v79, v82
	v_max_u32_e32 v79, v72, v97
	v_min_u32_e32 v97, v72, v97
	v_max_u32_e32 v72, v102, v78
	v_min_u32_e32 v78, v102, v78
	v_max_u32_e32 v102, v87, v91
	v_min_u32_e32 v91, v87, v91
	v_max_u32_e32 v87, v92, v75
	v_min_u32_e32 v75, v92, v75
	v_max_u32_e32 v92, v98, v73
	v_min_u32_e32 v73, v98, v73
	v_max_u32_e32 v98, v90, v82
	v_min_u32_e32 v82, v90, v82
	v_max_u32_e32 v90, v79, v72
	v_min_u32_e32 v72, v79, v72
	v_max_u32_e32 v79, v97, v78
	v_min_u32_e32 v78, v97, v78
	v_max_u32_e32 v97, v102, v87
	v_min_u32_e32 v87, v102, v87
	v_max_u32_e32 v102, v91, v75
	v_min_u32_e32 v75, v91, v75
	v_max_u32_e32 v91, v98, v73
	v_min_u32_e32 v73, v98, v73
	v_max_u32_e32 v98, v83, v82
	v_min_u32_e32 v82, v83, v82
	v_max_u32_e32 v83, v97, v70
	v_min_u32_e32 v70, v97, v70
	v_max_u32_e32 v97, v102, v87
	v_min_u32_e32 v87, v102, v87
	v_max_u32_e32 v102, v98, v90
	v_min_u32_e32 v90, v98, v90
	v_max_u32_e32 v98, v82, v72
	v_min_u32_e32 v72, v82, v72
; __device__ __forceinline__ unsigned f2key(float f) { const unsigned u = __float_as_uint(f); return (u & 0x80000000u) ? ~u : (u | 0x80000000u); }
; #define CE_DESC(a, b) do { const unsigned _mx = (a) > (b) ? (a) : (b), _mn = (a) > (b) ? (b) : (a); (a) = _mx; (b) = _mn; } while (0)
; __device__ __forceinline__ void sort16_desc(unsigned (&k)[16]) {
; #pragma unroll
;     for (int size = 2; size <= 16; size <<= 1)
; #pragma unroll
;         for (int stride = size >> 1; stride > 0; stride >>= 1)
; #pragma unroll
;             for (int i = 0; i < 16; ++i) { const int j = i ^ stride;
;                 if (j > i) { if ((i & size) == 0) CE_DESC(k[i], k[j]); else CE_DESC(k[j], k[i]); } }
; }
; __device__ __forceinline__ void peer_tile(const Args& A, LAS unsigned char* lds, int tile) {
;     ...
;                   for (int i = 0; i < 16; ++i) {
;                       const float lo = (float)__builtin_bit_cast(_Float16, (unsigned short)(sw[i] & 0xffffu)), hi = (float)__builtin_bit_cast(_Float16, (unsigned short)(sw[i] >> 16));
;                       const unsigned klo = (f2key(lo) & ~127u) | (unsigned)(127 - (32 * g + 2 * i)), khi = (f2key(hi) & ~127u) | (unsigned)(127 - (32 * g + 2 * i + 1));
;                       if (i < 8) { k0[2 * i] = klo; k0[2 * i + 1] = khi; } else { k1[2 * (i - 8)] = klo; k1[2 * (i - 8) + 1] = khi; } } }
	v_max_u32_e32 v82, v79, v83
	v_min_u32_e32 v83, v79, v83
	v_max_u32_e32 v79, v78, v70
	v_min_u32_e32 v70, v78, v70
	v_max_u32_e32 v78, v102, v73
	v_min_u32_e32 v73, v102, v73
	v_max_u32_e32 v102, v90, v98
	v_min_u32_e32 v98, v90, v98
	v_max_u32_e32 v90, v82, v72
	v_min_u32_e32 v72, v82, v72
	v_max_u32_e32 v82, v83, v79
	v_min_u32_e32 v79, v83, v79
	v_max_u32_e32 v83, v97, v70
	v_min_u32_e32 v70, v97, v70
	v_max_u32_e32 v97, v98, v90
	v_min_u32_e32 v90, v98, v90
	v_max_u32_e32 v98, v72, v82
	v_min_u32_e32 v82, v72, v82
	v_cvt_f32_f16_e32 v72, v8
	v_cvt_f32_f16_sdwa v103, v8 dst_sel:DWORD dst_unused:UNUSED_PAD src0_sel:WORD_1
	v_ashrrev_i32_e32 v104, 31, v72
	v_bitop3_b32 v72, v72, v104, s40 bitop3:0x78
	v_xor_b32_e32 v72, 0x8000006f, v72
	v_ashrrev_i32_e32 v104, 31, v103
	v_bitop3_b32 v103, v103, v104, s40 bitop3:0x78
	v_xor_b32_e32 v103, 0x8000006e, v103
	v_cvt_f32_f16_e32 v104, v9
	v_cvt_f32_f16_sdwa v105, v9 dst_sel:DWORD dst_unused:UNUSED_PAD src0_sel:WORD_1
	v_ashrrev_i32_e32 v106, 31, v104
	v_bitop3_b32 v104, v104, v106, s40 bitop3:0x78
	v_xor_b32_e32 v104, 0x8000006d, v104
	v_ashrrev_i32_e32 v106, 31, v105
	v_bitop3_b32 v105, v105, v106, s40 bitop3:0x78
	v_xor_b32_e32 v105, 0x8000006c, v105
	v_cvt_f32_f16_e32 v106, v10
	v_cvt_f32_f16_sdwa v107, v10 dst_sel:DWORD dst_unused:UNUSED_PAD src0_sel:WORD_1
	v_ashrrev_i32_e32 v108, 31, v106
	v_bitop3_b32 v106, v106, v108, s40 bitop3:0x78
	v_xor_b32_e32 v106, 0x8000006b, v106
	v_ashrrev_i32_e32 v108, 31, v107
	v_bitop3_b32 v107, v107, v108, s40 bitop3:0x78
	v_xor_b32_e32 v107, 0x8000006a, v107
	v_cvt_f32_f16_e32 v108, v11
	v_cvt_f32_f16_sdwa v109, v11 dst_sel:DWORD dst_unused:UNUSED_PAD src0_sel:WORD_1
	v_ashrrev_i32_e32 v110, 31, v108
	v_bitop3_b32 v108, v108, v110, s40 bitop3:0x78
	v_xor_b32_e32 v108, 0x80000069, v108
	v_ashrrev_i32_e32 v110, 31, v109
	v_bitop3_b32 v109, v109, v110, s40 bitop3:0x78
	v_xor_b32_e32 v109, 0x80000068, v109
	v_cvt_f32_f16_e32 v110, v12
	v_cvt_f32_f16_sdwa v111, v12 dst_sel:DWORD dst_unused:UNUSED_PAD src0_sel:WORD_1
	v_ashrrev_i32_e32 v112, 31, v110
	v_bitop3_b32 v110, v110, v112, s40 bitop3:0x78
	v_xor_b32_e32 v110, 0x80000067, v110
	v_ashrrev_i32_e32 v112, 31, v111
	v_bitop3_b32 v111, v111, v112, s40 bitop3:0x78
	v_xor_b32_e32 v111, 0x80000066, v111
	v_cvt_f32_f16_e32 v112, v13
	v_cvt_f32_f16_sdwa v114, v13 dst_sel:DWORD dst_unused:UNUSED_PAD src0_sel:WORD_1
	v_ashrrev_i32_e32 v115, 31, v112
	v_bitop3_b32 v112, v112, v115, s40 bitop3:0x78
	v_xor_b32_e32 v112, 0x80000065, v112
	v_ashrrev_i32_e32 v115, 31, v114
	v_bitop3_b32 v114, v114, v115, s40 bitop3:0x78
	v_xor_b32_e32 v114, 0x80000064, v114
	v_cvt_f32_f16_e32 v115, v14
	v_cvt_f32_f16_sdwa v116, v14 dst_sel:DWORD dst_unused:UNUSED_PAD src0_sel:WORD_1
	v_ashrrev_i32_e32 v117, 31, v115
	v_bitop3_b32 v115, v115, v117, s40 bitop3:0x78
	v_xor_b32_e32 v115, 0x80000063, v115
	v_ashrrev_i32_e32 v117, 31, v116
	v_bitop3_b32 v116, v116, v117, s40 bitop3:0x78
	v_xor_b32_e32 v116, 0x80000062, v116
	v_cvt_f32_f16_e32 v117, v15
	v_cvt_f32_f16_sdwa v118, v15 dst_sel:DWORD dst_unused:UNUSED_PAD src0_sel:WORD_1
	v_ashrrev_i32_e32 v119, 31, v117
	v_bitop3_b32 v117, v117, v119, s40 bitop3:0x78
	v_xor_b32_e32 v117, 0x80000061, v117
	v_ashrrev_i32_e32 v119, 31, v118
	v_bitop3_b32 v118, v118, v119, s40 bitop3:0x78
	v_xor_b32_e32 v118, 0x80000060, v118
	v_max_u32_e32 v119, v72, v116
	v_min_u32_e32 v116, v72, v116
	v_max_u32_e32 v72, v103, v115
	v_min_u32_e32 v115, v103, v115
	v_max_u32_e32 v103, v104, v118
	v_min_u32_e32 v118, v104, v118
	v_max_u32_e32 v104, v105, v117
	v_min_u32_e32 v117, v105, v117
	v_max_u32_e32 v105, v106, v110
	v_min_u32_e32 v110, v106, v110
	v_max_u32_e32 v106, v107, v108
	v_min_u32_e32 v108, v107, v108
	v_max_u32_e32 v107, v109, v114
	v_min_u32_e32 v114, v109, v114
	v_max_u32_e32 v109, v111, v112
	v_min_u32_e32 v112, v111, v112
	v_max_u32_e32 v111, v119, v106
	v_min_u32_e32 v106, v119, v106
	v_max_u32_e32 v119, v72, v107
	v_min_u32_e32 v107, v72, v107
	v_max_u32_e32 v72, v103, v109
	v_min_u32_e32 v109, v103, v109
	v_max_u32_e32 v103, v104, v105
	v_min_u32_e32 v105, v104, v105
	v_max_u32_e32 v104, v108, v116
	v_min_u32_e32 v116, v108, v116
	v_max_u32_e32 v108, v110, v117
	v_min_u32_e32 v117, v110, v117
	v_max_u32_e32 v110, v112, v118
	v_min_u32_e32 v118, v112, v118
	v_max_u32_e32 v112, v114, v115
	v_min_u32_e32 v115, v114, v115
	v_max_u32_e32 v114, v111, v119
	v_min_u32_e32 v119, v111, v119
	v_max_u32_e32 v111, v72, v103
	v_min_u32_e32 v103, v72, v103
	v_max_u32_e32 v72, v105, v106
	v_min_u32_e32 v106, v105, v106
	v_max_u32_e32 v105, v104, v108
	v_min_u32_e32 v108, v104, v108
	v_max_u32_e32 v104, v107, v109
	v_min_u32_e32 v109, v107, v109
	v_max_u32_e32 v107, v110, v112
	v_min_u32_e32 v112, v110, v112
	v_max_u32_e32 v110, v115, v116
	v_min_u32_e32 v116, v115, v116
	v_max_u32_e32 v115, v117, v118
	v_min_u32_e32 v118, v117, v118
	v_max_u32_e32 v117, v114, v111
	v_min_u32_e32 v111, v114, v111
	v_max_u32_e32 v114, v119, v103
	v_min_u32_e32 v103, v119, v103
	v_max_u32_e32 v119, v72, v107
	v_min_u32_e32 v107, v72, v107
	v_max_u32_e32 v72, v106, v112
	v_min_u32_e32 v112, v106, v112
	v_max_u32_e32 v106, v105, v104
	v_min_u32_e32 v104, v105, v104
	v_max_u32_e32 v105, v108, v109
	v_min_u32_e32 v109, v108, v109
	v_max_u32_e32 v108, v110, v115
	v_min_u32_e32 v115, v110, v115
	v_max_u32_e32 v110, v116, v118
	v_min_u32_e32 v118, v116, v118
	v_max_u32_e32 v116, v114, v111
	v_min_u32_e32 v111, v114, v111
	v_max_u32_e32 v114, v103, v108
	v_min_u32_e32 v108, v103, v108
	v_max_u32_e32 v103, v119, v106
	v_min_u32_e32 v106, v119, v106
	v_max_u32_e32 v119, v72, v104
	v_min_u32_e32 v104, v72, v104
	v_max_u32_e32 v72, v105, v107
; __device__ __forceinline__ unsigned f2key(float f) { const unsigned u = __float_as_uint(f); return (u & 0x80000000u) ? ~u : (u | 0x80000000u); }
; #define CE_DESC(a, b) do { const unsigned _mx = (a) > (b) ? (a) : (b), _mn = (a) > (b) ? (b) : (a); (a) = _mx; (b) = _mn; } while (0)
; __device__ __forceinline__ void sort16_desc(unsigned (&k)[16]) {
; #pragma unroll
;     for (int size = 2; size <= 16; size <<= 1)
; #pragma unroll
;         for (int stride = size >> 1; stride > 0; stride >>= 1)
; #pragma unroll
;             for (int i = 0; i < 16; ++i) { const int j = i ^ stride;
;                 if (j > i) { if ((i & size) == 0) CE_DESC(k[i], k[j]); else CE_DESC(k[j], k[i]); } }
; }
; __device__ __forceinline__ void merge16(unsigned (&a)[16], const unsigned (&b)[16]) {
; #pragma unroll
;     for (int i = 0; i < 16; ++i) a[i] = a[i] > b[15 - i] ? a[i] : b[15 - i];
; #pragma unroll
;     for (int stride = 8; stride > 0; stride >>= 1)
; #pragma unroll
;         for (int i = 0; i < 16; ++i) { const int j = i ^ stride; if (j > i) CE_DESC(a[i], a[j]); }
; }
; __device__ __forceinline__ void peer_tile(const Args& A, LAS unsigned char* lds, int tile) {
;     ...
;                   for (int i = 0; i < 16; ++i) {
;                       const float lo = (float)__builtin_bit_cast(_Float16, (unsigned short)(sw[i] & 0xffffu)), hi = (float)__builtin_bit_cast(_Float16, (unsigned short)(sw[i] >> 16));
;                       const unsigned klo = (f2key(lo) & ~127u) | (unsigned)(127 - (32 * g + 2 * i)), khi = (f2key(hi) & ~127u) | (unsigned)(127 - (32 * g + 2 * i + 1));
;                       if (i < 8) { k0[2 * i] = klo; k0[2 * i + 1] = khi; } else { k1[2 * (i - 8)] = klo; k1[2 * (i - 8) + 1] = khi; } } }
	v_min_u32_e32 v107, v105, v107
	v_max_u32_e32 v105, v109, v112
	v_min_u32_e32 v112, v109, v112
	v_max_u32_e32 v109, v110, v115
	v_min_u32_e32 v115, v110, v115
	v_max_u32_e32 v110, v116, v103
	v_min_u32_e32 v103, v116, v103
	v_max_u32_e32 v116, v111, v106
	v_min_u32_e32 v106, v111, v106
	v_max_u32_e32 v111, v119, v72
	v_min_u32_e32 v72, v119, v72
	v_max_u32_e32 v119, v104, v107
	v_min_u32_e32 v107, v104, v107
	v_max_u32_e32 v104, v105, v109
	v_min_u32_e32 v109, v105, v109
	v_max_u32_e32 v105, v112, v115
	v_min_u32_e32 v115, v112, v115
	v_max_u32_e32 v112, v116, v103
	v_min_u32_e32 v103, v116, v103
	v_max_u32_e32 v116, v114, v106
	v_min_u32_e32 v106, v114, v106
	v_max_u32_e32 v114, v104, v108
	v_min_u32_e32 v108, v104, v108
	v_max_u32_e32 v104, v105, v109
	v_min_u32_e32 v109, v105, v109
	v_max_u32_e32 v105, v116, v111
	v_min_u32_e32 v111, v116, v111
	v_max_u32_e32 v116, v106, v72
	v_min_u32_e32 v72, v106, v72
	v_max_u32_e32 v106, v119, v114
	v_min_u32_e32 v114, v119, v114
	v_max_u32_e32 v119, v107, v108
	v_min_u32_e32 v108, v107, v108
	v_max_u32_e32 v107, v105, v103
	v_min_u32_e32 v103, v105, v103
	v_max_u32_e32 v105, v111, v116
	v_min_u32_e32 v116, v111, v116
	v_max_u32_e32 v111, v106, v72
	v_min_u32_e32 v72, v106, v72
	v_max_u32_e32 v106, v114, v119
	v_min_u32_e32 v119, v114, v119
	v_max_u32_e32 v114, v104, v108
	v_min_u32_e32 v108, v104, v108
	v_max_u32_e32 v104, v116, v111
	v_min_u32_e32 v111, v116, v111
	v_max_u32_e32 v116, v72, v106
	v_min_u32_e32 v106, v72, v106
	v_max_u32_e32 v89, v89, v118
	v_max_u32_e32 v92, v92, v115
	v_max_u32_e32 v91, v91, v109
	v_max_u32_e32 v78, v78, v108
	v_max_u32_e32 v73, v73, v114
	v_max_u32_e32 v102, v102, v119
	v_max_u32_e32 v97, v97, v106
	v_max_u32_e32 v90, v90, v116
	v_max_u32_e32 v98, v98, v111
	v_max_u32_e32 v82, v82, v104
	v_max_u32_e32 v79, v79, v105
	v_max_u32_e32 v83, v83, v103
	v_max_u32_e32 v70, v70, v107
	v_max_u32_e32 v87, v87, v112
	v_max_u32_e32 v75, v75, v110
	v_max_u32_e32 v96, v96, v117
	v_max_u32_e32 v118, v89, v98
	v_min_u32_e32 v98, v89, v98
	v_max_u32_e32 v89, v92, v82
	v_min_u32_e32 v82, v92, v82
	v_max_u32_e32 v92, v91, v79
	v_min_u32_e32 v79, v91, v79
	v_max_u32_e32 v91, v78, v83
	v_min_u32_e32 v83, v78, v83
	v_max_u32_e32 v78, v73, v70
	v_min_u32_e32 v70, v73, v70
	v_max_u32_e32 v73, v102, v87
	v_min_u32_e32 v87, v102, v87
	v_max_u32_e32 v102, v97, v75
	v_min_u32_e32 v75, v97, v75
	v_max_u32_e32 v97, v90, v96
	v_min_u32_e32 v96, v90, v96
	v_max_u32_e32 v90, v118, v78
	v_min_u32_e32 v78, v118, v78
	v_max_u32_e32 v118, v89, v73
	v_min_u32_e32 v73, v89, v73
	v_max_u32_e32 v89, v92, v102
	v_min_u32_e32 v102, v92, v102
	v_max_u32_e32 v92, v91, v97
	v_min_u32_e32 v97, v91, v97
	v_max_u32_e32 v91, v98, v70
	v_min_u32_e32 v70, v98, v70
	v_max_u32_e32 v98, v82, v87
	v_min_u32_e32 v87, v82, v87
	v_max_u32_e32 v82, v79, v75
	v_min_u32_e32 v75, v79, v75
	v_max_u32_e32 v79, v83, v96
	v_min_u32_e32 v96, v83, v96
	v_max_u32_e32 v83, v90, v89
	v_min_u32_e32 v89, v90, v89
	v_max_u32_e32 v90, v118, v92
	v_min_u32_e32 v92, v118, v92
	v_max_u32_e32 v118, v78, v102
	v_min_u32_e32 v102, v78, v102
	v_max_u32_e32 v78, v73, v97
	v_min_u32_e32 v97, v73, v97
	v_max_u32_e32 v73, v91, v82
	v_min_u32_e32 v82, v91, v82
	v_max_u32_e32 v91, v98, v79
	v_min_u32_e32 v79, v98, v79
	v_max_u32_e32 v98, v70, v75
	v_min_u32_e32 v75, v70, v75
	v_max_u32_e32 v70, v87, v96
	v_min_u32_e32 v96, v87, v96
	v_max_u32_e32 v87, v83, v90
	v_min_u32_e32 v90, v83, v90
	v_max_u32_e32 v83, v89, v92
	v_min_u32_e32 v92, v89, v92
	v_max_u32_e32 v89, v118, v78
	v_min_u32_e32 v78, v118, v78
	v_max_u32_e32 v118, v102, v97
	v_min_u32_e32 v97, v102, v97
	v_max_u32_e32 v102, v73, v91
	v_min_u32_e32 v91, v73, v91
	v_max_u32_e32 v73, v82, v79
	v_min_u32_e32 v79, v82, v79
	v_max_u32_e32 v82, v98, v70
	v_min_u32_e32 v70, v98, v70
	v_max_u32_e32 v98, v75, v96
	v_min_u32_e32 v96, v75, v96
	v_cvt_f32_f16_e32 v75, v16
	v_cvt_f32_f16_sdwa v115, v16 dst_sel:DWORD dst_unused:UNUSED_PAD src0_sel:WORD_1
	v_ashrrev_i32_e32 v109, 31, v75
	v_bitop3_b32 v75, v75, v109, s40 bitop3:0x78
	v_xor_b32_e32 v75, 0x8000005f, v75
	v_ashrrev_i32_e32 v109, 31, v115
	v_bitop3_b32 v115, v115, v109, s40 bitop3:0x78
	v_xor_b32_e32 v115, 0x8000005e, v115
	v_cvt_f32_f16_e32 v109, v17
	v_cvt_f32_f16_sdwa v108, v17 dst_sel:DWORD dst_unused:UNUSED_PAD src0_sel:WORD_1
	v_ashrrev_i32_e32 v114, 31, v109
	v_bitop3_b32 v109, v109, v114, s40 bitop3:0x78
	v_xor_b32_e32 v109, 0x8000005d, v109
	v_ashrrev_i32_e32 v114, 31, v108
	v_bitop3_b32 v108, v108, v114, s40 bitop3:0x78
	v_xor_b32_e32 v108, 0x8000005c, v108
	v_cvt_f32_f16_e32 v114, v18
	v_cvt_f32_f16_sdwa v119, v18 dst_sel:DWORD dst_unused:UNUSED_PAD src0_sel:WORD_1
	v_ashrrev_i32_e32 v106, 31, v114
	v_bitop3_b32 v114, v114, v106, s40 bitop3:0x78
	v_xor_b32_e32 v114, 0x8000005b, v114
	v_ashrrev_i32_e32 v106, 31, v119
	v_bitop3_b32 v119, v119, v106, s40 bitop3:0x78
	v_xor_b32_e32 v119, 0x8000005a, v119
	v_cvt_f32_f16_e32 v106, v19
	v_cvt_f32_f16_sdwa v116, v19 dst_sel:DWORD dst_unused:UNUSED_PAD src0_sel:WORD_1
	v_ashrrev_i32_e32 v111, 31, v106
	v_bitop3_b32 v106, v106, v111, s40 bitop3:0x78
	v_xor_b32_e32 v106, 0x80000059, v106
	v_ashrrev_i32_e32 v111, 31, v116
	v_bitop3_b32 v116, v116, v111, s40 bitop3:0x78
	v_xor_b32_e32 v116, 0x80000058, v116
	v_cvt_f32_f16_e32 v111, v20
	v_cvt_f32_f16_sdwa v104, v20 dst_sel:DWORD dst_unused:UNUSED_PAD src0_sel:WORD_1
	v_ashrrev_i32_e32 v105, 31, v111
	v_bitop3_b32 v111, v111, v105, s40 bitop3:0x78
	v_xor_b32_e32 v111, 0x80000057, v111
	v_ashrrev_i32_e32 v105, 31, v104
	v_bitop3_b32 v104, v104, v105, s40 bitop3:0x78
	v_xor_b32_e32 v104, 0x80000056, v104
	v_cvt_f32_f16_e32 v105, v21
; __device__ __forceinline__ unsigned f2key(float f) { const unsigned u = __float_as_uint(f); return (u & 0x80000000u) ? ~u : (u | 0x80000000u); }
; #define CE_DESC(a, b) do { const unsigned _mx = (a) > (b) ? (a) : (b), _mn = (a) > (b) ? (b) : (a); (a) = _mx; (b) = _mn; } while (0)
; __device__ __forceinline__ void sort16_desc(unsigned (&k)[16]) {
; #pragma unroll
;     for (int size = 2; size <= 16; size <<= 1)
; #pragma unroll
;         for (int stride = size >> 1; stride > 0; stride >>= 1)
; #pragma unroll
;             for (int i = 0; i < 16; ++i) { const int j = i ^ stride;
;                 if (j > i) { if ((i & size) == 0) CE_DESC(k[i], k[j]); else CE_DESC(k[j], k[i]); } }
; }
; __device__ __forceinline__ void merge16(unsigned (&a)[16], const unsigned (&b)[16]) {
; #pragma unroll
;     for (int i = 0; i < 16; ++i) a[i] = a[i] > b[15 - i] ? a[i] : b[15 - i];
; #pragma unroll
;     for (int stride = 8; stride > 0; stride >>= 1)
; #pragma unroll
;         for (int i = 0; i < 16; ++i) { const int j = i ^ stride; if (j > i) CE_DESC(a[i], a[j]); }
; }
; __device__ __forceinline__ void peer_tile(const Args& A, LAS unsigned char* lds, int tile) {
;     ...
;                   for (int i = 0; i < 16; ++i) {
;                       const float lo = (float)__builtin_bit_cast(_Float16, (unsigned short)(sw[i] & 0xffffu)), hi = (float)__builtin_bit_cast(_Float16, (unsigned short)(sw[i] >> 16));
;                       const unsigned klo = (f2key(lo) & ~127u) | (unsigned)(127 - (32 * g + 2 * i)), khi = (f2key(hi) & ~127u) | (unsigned)(127 - (32 * g + 2 * i + 1));
;                       if (i < 8) { k0[2 * i] = klo; k0[2 * i + 1] = khi; } else { k1[2 * (i - 8)] = klo; k1[2 * (i - 8) + 1] = khi; } } }
	v_cvt_f32_f16_sdwa v103, v21 dst_sel:DWORD dst_unused:UNUSED_PAD src0_sel:WORD_1
	v_ashrrev_i32_e32 v107, 31, v105
	v_bitop3_b32 v105, v105, v107, s40 bitop3:0x78
	v_xor_b32_e32 v105, 0x80000055, v105
	v_ashrrev_i32_e32 v107, 31, v103
	v_bitop3_b32 v103, v103, v107, s40 bitop3:0x78
	v_xor_b32_e32 v103, 0x80000054, v103
	v_cvt_f32_f16_e32 v107, v22
	v_cvt_f32_f16_sdwa v112, v22 dst_sel:DWORD dst_unused:UNUSED_PAD src0_sel:WORD_1
	v_ashrrev_i32_e32 v110, 31, v107
	v_bitop3_b32 v107, v107, v110, s40 bitop3:0x78
	v_xor_b32_e32 v107, 0x80000053, v107
	v_ashrrev_i32_e32 v110, 31, v112
	v_bitop3_b32 v112, v112, v110, s40 bitop3:0x78
	v_xor_b32_e32 v112, 0x80000052, v112
	v_cvt_f32_f16_e32 v110, v23
	v_cvt_f32_f16_sdwa v117, v23 dst_sel:DWORD dst_unused:UNUSED_PAD src0_sel:WORD_1
	v_ashrrev_i32_e32 v72, 31, v110
	v_bitop3_b32 v110, v110, v72, s40 bitop3:0x78
	v_xor_b32_e32 v110, 0x80000051, v110
	v_ashrrev_i32_e32 v72, 31, v117
	v_bitop3_b32 v117, v117, v72, s40 bitop3:0x78
	v_xor_b32_e32 v117, 0x80000050, v117
	v_max_u32_e32 v72, v75, v112
	v_min_u32_e32 v112, v75, v112
	v_max_u32_e32 v75, v115, v107
	v_min_u32_e32 v107, v115, v107
	v_max_u32_e32 v115, v109, v117
	v_min_u32_e32 v117, v109, v117
	v_max_u32_e32 v109, v108, v110
	v_min_u32_e32 v110, v108, v110
	v_max_u32_e32 v108, v114, v111
	v_min_u32_e32 v111, v114, v111
	v_max_u32_e32 v114, v119, v106
	v_min_u32_e32 v106, v119, v106
	v_max_u32_e32 v119, v116, v103
	v_min_u32_e32 v103, v116, v103
	v_max_u32_e32 v116, v104, v105
	v_min_u32_e32 v105, v104, v105
	v_max_u32_e32 v104, v72, v114
	v_min_u32_e32 v114, v72, v114
	v_max_u32_e32 v72, v75, v119
	v_min_u32_e32 v119, v75, v119
	v_max_u32_e32 v75, v115, v116
	v_min_u32_e32 v116, v115, v116
	v_max_u32_e32 v115, v109, v108
	v_min_u32_e32 v108, v109, v108
	v_max_u32_e32 v109, v106, v112
	v_min_u32_e32 v112, v106, v112
	v_max_u32_e32 v106, v111, v110
	v_min_u32_e32 v110, v111, v110
	v_max_u32_e32 v111, v105, v117
	v_min_u32_e32 v117, v105, v117
	v_max_u32_e32 v105, v103, v107
	v_min_u32_e32 v107, v103, v107
	v_max_u32_e32 v103, v104, v72
	v_min_u32_e32 v72, v104, v72
	v_max_u32_e32 v104, v75, v115
	v_min_u32_e32 v115, v75, v115
	v_max_u32_e32 v75, v108, v114
	v_min_u32_e32 v114, v108, v114
	v_max_u32_e32 v108, v109, v106
	v_min_u32_e32 v106, v109, v106
	v_max_u32_e32 v109, v119, v116
	v_min_u32_e32 v116, v119, v116
	v_max_u32_e32 v119, v111, v105
	v_min_u32_e32 v105, v111, v105
	v_max_u32_e32 v111, v107, v112
	v_min_u32_e32 v112, v107, v112
	v_max_u32_e32 v107, v110, v117
	v_min_u32_e32 v117, v110, v117
	v_max_u32_e32 v110, v103, v104
	v_min_u32_e32 v104, v103, v104
	v_max_u32_e32 v103, v72, v115
	v_min_u32_e32 v115, v72, v115
	v_max_u32_e32 v72, v75, v119
	v_min_u32_e32 v119, v75, v119
	v_max_u32_e32 v75, v114, v105
	v_min_u32_e32 v105, v114, v105
	v_max_u32_e32 v114, v108, v109
	v_min_u32_e32 v109, v108, v109
	v_max_u32_e32 v108, v106, v116
	v_min_u32_e32 v116, v106, v116
	v_max_u32_e32 v106, v111, v107
	v_min_u32_e32 v107, v111, v107
	v_max_u32_e32 v111, v112, v117
	v_min_u32_e32 v117, v112, v117
	v_max_u32_e32 v112, v103, v104
	v_min_u32_e32 v104, v103, v104
	v_max_u32_e32 v103, v115, v106
	v_min_u32_e32 v106, v115, v106
	v_max_u32_e32 v115, v72, v114
	v_min_u32_e32 v114, v72, v114
	v_max_u32_e32 v72, v75, v109
	v_min_u32_e32 v109, v75, v109
	v_max_u32_e32 v75, v108, v119
	v_min_u32_e32 v119, v108, v119
	v_max_u32_e32 v108, v116, v105
	v_min_u32_e32 v105, v116, v105
	v_max_u32_e32 v116, v111, v107
	v_min_u32_e32 v107, v111, v107
	v_max_u32_e32 v111, v112, v115
	v_min_u32_e32 v115, v112, v115
	v_max_u32_e32 v112, v104, v114
	v_min_u32_e32 v114, v104, v114
	v_max_u32_e32 v104, v72, v75
	v_min_u32_e32 v75, v72, v75
	v_max_u32_e32 v72, v109, v119
	v_min_u32_e32 v119, v109, v119
	v_max_u32_e32 v109, v108, v116
	v_min_u32_e32 v116, v108, v116
	v_max_u32_e32 v108, v105, v107
	v_min_u32_e32 v107, v105, v107
	v_max_u32_e32 v105, v112, v115
	v_min_u32_e32 v115, v112, v115
	v_max_u32_e32 v112, v103, v114
	v_min_u32_e32 v114, v103, v114
	v_max_u32_e32 v103, v109, v106
	v_min_u32_e32 v106, v109, v106
	v_max_u32_e32 v109, v108, v116
	v_min_u32_e32 v116, v108, v116
	v_max_u32_e32 v108, v112, v104
	v_min_u32_e32 v104, v112, v104
	v_max_u32_e32 v112, v114, v75
	v_min_u32_e32 v75, v114, v75
	v_max_u32_e32 v114, v72, v103
	v_min_u32_e32 v103, v72, v103
	v_max_u32_e32 v72, v119, v106
	v_min_u32_e32 v106, v119, v106
	v_max_u32_e32 v119, v108, v115
	v_min_u32_e32 v115, v108, v115
	v_max_u32_e32 v108, v104, v112
	v_min_u32_e32 v112, v104, v112
	v_max_u32_e32 v104, v114, v75
	v_min_u32_e32 v75, v114, v75
	v_max_u32_e32 v114, v103, v72
	v_min_u32_e32 v72, v103, v72
	v_max_u32_e32 v103, v109, v106
	v_min_u32_e32 v106, v109, v106
	v_max_u32_e32 v109, v112, v104
	v_min_u32_e32 v104, v112, v104
	v_max_u32_e32 v112, v75, v114
	v_min_u32_e32 v114, v75, v114
	v_max_u32_e32 v87, v87, v117
	v_max_u32_e32 v90, v90, v107
	v_max_u32_e32 v83, v83, v116
	v_max_u32_e32 v92, v92, v106
	v_max_u32_e32 v89, v89, v103
	v_max_u32_e32 v78, v78, v72
	v_max_u32_e32 v118, v118, v114
	v_max_u32_e32 v97, v97, v112
	v_max_u32_e32 v102, v102, v104
	v_max_u32_e32 v91, v91, v109
	v_max_u32_e32 v73, v73, v108
	v_max_u32_e32 v79, v79, v115
	v_max_u32_e32 v82, v82, v119
	v_max_u32_e32 v70, v70, v105
	v_max_u32_e32 v98, v98, v111
	v_max_u32_e32 v96, v96, v110
	v_max_u32_e32 v117, v87, v102
	v_min_u32_e32 v102, v87, v102
	v_max_u32_e32 v87, v90, v91
	v_min_u32_e32 v91, v90, v91
	v_max_u32_e32 v90, v83, v73
	v_min_u32_e32 v73, v83, v73
	v_max_u32_e32 v83, v92, v79
	v_min_u32_e32 v79, v92, v79
	v_max_u32_e32 v92, v89, v82
	v_min_u32_e32 v82, v89, v82
	v_max_u32_e32 v89, v78, v70
	v_min_u32_e32 v70, v78, v70
; __device__ __forceinline__ unsigned f2key(float f) { const unsigned u = __float_as_uint(f); return (u & 0x80000000u) ? ~u : (u | 0x80000000u); }
; #define CE_DESC(a, b) do { const unsigned _mx = (a) > (b) ? (a) : (b), _mn = (a) > (b) ? (b) : (a); (a) = _mx; (b) = _mn; } while (0)
; __device__ __forceinline__ void sort16_desc(unsigned (&k)[16]) {
; #pragma unroll
;     for (int size = 2; size <= 16; size <<= 1)
; #pragma unroll
;         for (int stride = size >> 1; stride > 0; stride >>= 1)
; #pragma unroll
;             for (int i = 0; i < 16; ++i) { const int j = i ^ stride;
;                 if (j > i) { if ((i & size) == 0) CE_DESC(k[i], k[j]); else CE_DESC(k[j], k[i]); } }
; }
; __device__ __forceinline__ void merge16(unsigned (&a)[16], const unsigned (&b)[16]) {
; #pragma unroll
;     for (int i = 0; i < 16; ++i) a[i] = a[i] > b[15 - i] ? a[i] : b[15 - i];
; #pragma unroll
;     for (int stride = 8; stride > 0; stride >>= 1)
; #pragma unroll
;         for (int i = 0; i < 16; ++i) { const int j = i ^ stride; if (j > i) CE_DESC(a[i], a[j]); }
; }
; __device__ __forceinline__ void peer_tile(const Args& A, LAS unsigned char* lds, int tile) {
;     ...
;                   for (int i = 0; i < 16; ++i) {
;                       const float lo = (float)__builtin_bit_cast(_Float16, (unsigned short)(sw[i] & 0xffffu)), hi = (float)__builtin_bit_cast(_Float16, (unsigned short)(sw[i] >> 16));
;                       const unsigned klo = (f2key(lo) & ~127u) | (unsigned)(127 - (32 * g + 2 * i)), khi = (f2key(hi) & ~127u) | (unsigned)(127 - (32 * g + 2 * i + 1));
;                       if (i < 8) { k0[2 * i] = klo; k0[2 * i + 1] = khi; } else { k1[2 * (i - 8)] = klo; k1[2 * (i - 8) + 1] = khi; } } }
	v_max_u32_e32 v78, v118, v98
	v_min_u32_e32 v98, v118, v98
	v_max_u32_e32 v118, v97, v96
	v_min_u32_e32 v96, v97, v96
	v_max_u32_e32 v97, v117, v92
	v_min_u32_e32 v92, v117, v92
	v_max_u32_e32 v117, v87, v89
	v_min_u32_e32 v89, v87, v89
	v_max_u32_e32 v87, v90, v78
	v_min_u32_e32 v78, v90, v78
	v_max_u32_e32 v90, v83, v118
	v_min_u32_e32 v118, v83, v118
	v_max_u32_e32 v83, v102, v82
	v_min_u32_e32 v82, v102, v82
	v_max_u32_e32 v102, v91, v70
	v_min_u32_e32 v70, v91, v70
	v_max_u32_e32 v91, v73, v98
	v_min_u32_e32 v98, v73, v98
	v_max_u32_e32 v73, v79, v96
	v_min_u32_e32 v96, v79, v96
	v_max_u32_e32 v79, v97, v87
	v_min_u32_e32 v87, v97, v87
	v_max_u32_e32 v97, v117, v90
	v_min_u32_e32 v90, v117, v90
	v_max_u32_e32 v117, v92, v78
	v_min_u32_e32 v78, v92, v78
	v_max_u32_e32 v92, v89, v118
	v_min_u32_e32 v118, v89, v118
	v_max_u32_e32 v89, v83, v91
	v_min_u32_e32 v91, v83, v91
	v_max_u32_e32 v83, v102, v73
	v_min_u32_e32 v73, v102, v73
	v_max_u32_e32 v102, v82, v98
	v_min_u32_e32 v98, v82, v98
	v_max_u32_e32 v82, v70, v96
	v_min_u32_e32 v96, v70, v96
	v_max_u32_e32 v70, v79, v97
	v_min_u32_e32 v97, v79, v97
	v_max_u32_e32 v79, v87, v90
	v_min_u32_e32 v90, v87, v90
	v_max_u32_e32 v87, v117, v92
	v_min_u32_e32 v92, v117, v92
	v_max_u32_e32 v117, v78, v118
	v_min_u32_e32 v118, v78, v118
	v_max_u32_e32 v78, v89, v83
	v_min_u32_e32 v83, v89, v83
	v_max_u32_e32 v89, v91, v73
	v_min_u32_e32 v73, v91, v73
	v_max_u32_e32 v91, v102, v82
	v_min_u32_e32 v82, v102, v82
	v_max_u32_e32 v102, v98, v96
	v_min_u32_e32 v96, v98, v96
	v_cvt_f32_f16_e32 v98, v24
	v_cvt_f32_f16_sdwa v107, v24 dst_sel:DWORD dst_unused:UNUSED_PAD src0_sel:WORD_1
	v_ashrrev_i32_e32 v116, 31, v98
	v_bitop3_b32 v98, v98, v116, s40 bitop3:0x78
	v_xor_b32_e32 v98, 0x8000004f, v98
	v_ashrrev_i32_e32 v116, 31, v107
	v_bitop3_b32 v107, v107, v116, s40 bitop3:0x78
	v_xor_b32_e32 v107, 0x8000004e, v107
	v_cvt_f32_f16_e32 v116, v25
	v_cvt_f32_f16_sdwa v106, v25 dst_sel:DWORD dst_unused:UNUSED_PAD src0_sel:WORD_1
	v_ashrrev_i32_e32 v103, 31, v116
	v_bitop3_b32 v116, v116, v103, s40 bitop3:0x78
	v_xor_b32_e32 v116, 0x8000004d, v116
	v_ashrrev_i32_e32 v103, 31, v106
	v_bitop3_b32 v106, v106, v103, s40 bitop3:0x78
	v_xor_b32_e32 v106, 0x8000004c, v106
	v_cvt_f32_f16_e32 v103, v26
	v_cvt_f32_f16_sdwa v72, v26 dst_sel:DWORD dst_unused:UNUSED_PAD src0_sel:WORD_1
	v_ashrrev_i32_e32 v114, 31, v103
	v_bitop3_b32 v103, v103, v114, s40 bitop3:0x78
	v_xor_b32_e32 v103, 0x8000004b, v103
	v_ashrrev_i32_e32 v114, 31, v72
	v_bitop3_b32 v72, v72, v114, s40 bitop3:0x78
	v_xor_b32_e32 v72, 0x8000004a, v72
	v_cvt_f32_f16_e32 v114, v27
	v_cvt_f32_f16_sdwa v112, v27 dst_sel:DWORD dst_unused:UNUSED_PAD src0_sel:WORD_1
	v_ashrrev_i32_e32 v104, 31, v114
	v_bitop3_b32 v114, v114, v104, s40 bitop3:0x78
	v_xor_b32_e32 v114, 0x80000049, v114
	v_ashrrev_i32_e32 v104, 31, v112
	v_bitop3_b32 v112, v112, v104, s40 bitop3:0x78
	v_xor_b32_e32 v112, 0x80000048, v112
	v_cvt_f32_f16_e32 v104, v28
	v_cvt_f32_f16_sdwa v109, v28 dst_sel:DWORD dst_unused:UNUSED_PAD src0_sel:WORD_1
	v_ashrrev_i32_e32 v108, 31, v104
	v_bitop3_b32 v104, v104, v108, s40 bitop3:0x78
	v_xor_b32_e32 v104, 0x80000047, v104
	v_ashrrev_i32_e32 v108, 31, v109
	v_bitop3_b32 v109, v109, v108, s40 bitop3:0x78
	v_xor_b32_e32 v109, 0x80000046, v109
	v_cvt_f32_f16_e32 v108, v29
	v_cvt_f32_f16_sdwa v115, v29 dst_sel:DWORD dst_unused:UNUSED_PAD src0_sel:WORD_1
	v_ashrrev_i32_e32 v119, 31, v108
	v_bitop3_b32 v108, v108, v119, s40 bitop3:0x78
	v_xor_b32_e32 v108, 0x80000045, v108
	v_ashrrev_i32_e32 v119, 31, v115
	v_bitop3_b32 v115, v115, v119, s40 bitop3:0x78
	v_xor_b32_e32 v115, 0x80000044, v115
	v_cvt_f32_f16_e32 v119, v30
	v_cvt_f32_f16_sdwa v105, v30 dst_sel:DWORD dst_unused:UNUSED_PAD src0_sel:WORD_1
	v_ashrrev_i32_e32 v111, 31, v119
	v_bitop3_b32 v119, v119, v111, s40 bitop3:0x78
	v_xor_b32_e32 v119, 0x80000043, v119
	v_ashrrev_i32_e32 v111, 31, v105
	v_bitop3_b32 v105, v105, v111, s40 bitop3:0x78
	v_xor_b32_e32 v105, 0x80000042, v105
	v_cvt_f32_f16_e32 v111, v31
	v_cvt_f32_f16_sdwa v110, v31 dst_sel:DWORD dst_unused:UNUSED_PAD src0_sel:WORD_1
	v_ashrrev_i32_e32 v75, 31, v111
	v_bitop3_b32 v111, v111, v75, s40 bitop3:0x78
	v_xor_b32_e32 v111, 0x80000041, v111
	v_ashrrev_i32_e32 v75, 31, v110
	v_bitop3_b32 v110, v110, v75, s40 bitop3:0x78
	v_xor_b32_e32 v110, 0x80000040, v110
	v_max_u32_e32 v75, v98, v105
	v_min_u32_e32 v105, v98, v105
	v_max_u32_e32 v98, v107, v119
	v_min_u32_e32 v119, v107, v119
	v_max_u32_e32 v107, v116, v110
	v_min_u32_e32 v110, v116, v110
	v_max_u32_e32 v116, v106, v111
	v_min_u32_e32 v111, v106, v111
	v_max_u32_e32 v106, v103, v104
	v_min_u32_e32 v104, v103, v104
	v_max_u32_e32 v103, v72, v114
	v_min_u32_e32 v114, v72, v114
	v_max_u32_e32 v72, v112, v115
	v_min_u32_e32 v115, v112, v115
	v_max_u32_e32 v112, v109, v108
	v_min_u32_e32 v108, v109, v108
	v_max_u32_e32 v109, v75, v103
	v_min_u32_e32 v103, v75, v103
	v_max_u32_e32 v75, v98, v72
	v_min_u32_e32 v72, v98, v72
	v_max_u32_e32 v98, v107, v112
	v_min_u32_e32 v112, v107, v112
	v_max_u32_e32 v107, v116, v106
	v_min_u32_e32 v106, v116, v106
	v_max_u32_e32 v116, v114, v105
	v_min_u32_e32 v105, v114, v105
	v_max_u32_e32 v114, v104, v111
	v_min_u32_e32 v111, v104, v111
	v_max_u32_e32 v104, v108, v110
	v_min_u32_e32 v110, v108, v110
	v_max_u32_e32 v108, v115, v119
	v_min_u32_e32 v119, v115, v119
	v_max_u32_e32 v115, v109, v75
	v_min_u32_e32 v75, v109, v75
	v_max_u32_e32 v109, v98, v107
	v_min_u32_e32 v107, v98, v107
	v_max_u32_e32 v98, v106, v103
	v_min_u32_e32 v103, v106, v103
	v_max_u32_e32 v106, v116, v114
	v_min_u32_e32 v114, v116, v114
	v_max_u32_e32 v116, v72, v112
	v_min_u32_e32 v112, v72, v112
; #define CE_DESC(a, b) do { const unsigned _mx = (a) > (b) ? (a) : (b), _mn = (a) > (b) ? (b) : (a); (a) = _mx; (b) = _mn; } while (0)
; __device__ __forceinline__ void sort16_desc(unsigned (&k)[16]) {
; #pragma unroll
;     for (int size = 2; size <= 16; size <<= 1)
; #pragma unroll
;         for (int stride = size >> 1; stride > 0; stride >>= 1)
; #pragma unroll
;             for (int i = 0; i < 16; ++i) { const int j = i ^ stride;
;                 if (j > i) { if ((i & size) == 0) CE_DESC(k[i], k[j]); else CE_DESC(k[j], k[i]); } }
; }
; __device__ __forceinline__ void merge16(unsigned (&a)[16], const unsigned (&b)[16]) {
; #pragma unroll
;     for (int i = 0; i < 16; ++i) a[i] = a[i] > b[15 - i] ? a[i] : b[15 - i];
; #pragma unroll
;     for (int stride = 8; stride > 0; stride >>= 1)
; #pragma unroll
;         for (int i = 0; i < 16; ++i) { const int j = i ^ stride; if (j > i) CE_DESC(a[i], a[j]); }
; }
; __device__ __forceinline__ void peer_tile(const Args& A, LAS unsigned char* lds, int tile) {
;     ...
;                 { const bf16_t* sp = QRY + m * 2048 + hp * 128 + 32 * g;
;                   const u32x4 s0 = *(const u32x4*)sp, s1 = *(const u32x4*)(sp + 8), s2 = *(const u32x4*)(sp + 16), s3 = *(const u32x4*)(sp + 24);
	v_max_u32_e32 v72, v104, v108
	v_min_u32_e32 v108, v104, v108
	v_max_u32_e32 v104, v119, v105
	v_min_u32_e32 v105, v119, v105
	v_max_u32_e32 v119, v111, v110
	v_min_u32_e32 v110, v111, v110
	v_max_u32_e32 v111, v115, v109
	v_min_u32_e32 v109, v115, v109
	v_max_u32_e32 v115, v75, v107
	v_min_u32_e32 v107, v75, v107
	v_max_u32_e32 v75, v98, v72
	v_min_u32_e32 v72, v98, v72
	v_max_u32_e32 v98, v103, v108
	v_min_u32_e32 v108, v103, v108
	v_max_u32_e32 v103, v106, v116
	v_min_u32_e32 v116, v106, v116
	v_max_u32_e32 v106, v114, v112
	v_min_u32_e32 v112, v114, v112
	v_max_u32_e32 v114, v104, v119
	v_min_u32_e32 v119, v104, v119
	v_max_u32_e32 v104, v105, v110
	v_min_u32_e32 v110, v105, v110
	v_max_u32_e32 v105, v115, v109
	v_min_u32_e32 v109, v115, v109
	v_max_u32_e32 v115, v107, v114
	v_min_u32_e32 v114, v107, v114
	v_max_u32_e32 v107, v75, v103
	v_min_u32_e32 v103, v75, v103
	v_max_u32_e32 v75, v98, v116
	v_min_u32_e32 v116, v98, v116
	v_max_u32_e32 v98, v106, v72
	v_min_u32_e32 v72, v106, v72
	v_max_u32_e32 v106, v112, v108
	v_min_u32_e32 v108, v112, v108
	v_max_u32_e32 v112, v104, v119
	v_min_u32_e32 v119, v104, v119
	v_max_u32_e32 v104, v105, v107
	v_min_u32_e32 v107, v105, v107
	v_max_u32_e32 v105, v109, v103
	v_min_u32_e32 v103, v109, v103
	v_max_u32_e32 v109, v75, v98
	v_min_u32_e32 v98, v75, v98
	v_max_u32_e32 v75, v116, v72
	v_min_u32_e32 v72, v116, v72
	v_max_u32_e32 v116, v106, v112
	v_min_u32_e32 v112, v106, v112
	v_max_u32_e32 v106, v108, v119
	v_min_u32_e32 v119, v108, v119
	v_max_u32_e32 v108, v105, v107
	v_min_u32_e32 v107, v105, v107
	v_max_u32_e32 v105, v115, v103
	v_min_u32_e32 v103, v115, v103
	v_max_u32_e32 v115, v116, v114
	v_min_u32_e32 v114, v116, v114
	v_max_u32_e32 v116, v106, v112
	v_min_u32_e32 v112, v106, v112
	v_max_u32_e32 v106, v105, v109
	v_min_u32_e32 v109, v105, v109
	v_max_u32_e32 v105, v103, v98
	v_min_u32_e32 v98, v103, v98
	v_max_u32_e32 v103, v75, v115
	v_min_u32_e32 v115, v75, v115
	v_max_u32_e32 v75, v72, v114
	v_min_u32_e32 v114, v72, v114
	v_max_u32_e32 v72, v106, v107
	v_min_u32_e32 v107, v106, v107
	v_max_u32_e32 v106, v109, v105
	v_min_u32_e32 v105, v109, v105
	v_max_u32_e32 v109, v103, v98
	v_min_u32_e32 v98, v103, v98
	v_max_u32_e32 v103, v115, v75
	v_min_u32_e32 v75, v115, v75
	v_max_u32_e32 v115, v116, v114
	v_min_u32_e32 v114, v116, v114
	v_max_u32_e32 v116, v105, v109
	v_min_u32_e32 v109, v105, v109
	v_max_u32_e32 v105, v98, v103
	v_min_u32_e32 v103, v98, v103
	v_max_u32_e32 v70, v70, v110
	v_max_u32_e32 v97, v97, v119
	v_max_u32_e32 v79, v79, v112
	v_max_u32_e32 v90, v90, v114
	v_max_u32_e32 v87, v87, v115
	v_max_u32_e32 v92, v92, v75
	v_max_u32_e32 v117, v117, v103
	v_max_u32_e32 v118, v118, v105
	v_max_u32_e32 v78, v78, v109
	v_max_u32_e32 v83, v83, v116
	v_max_u32_e32 v89, v89, v106
	v_max_u32_e32 v73, v73, v107
	v_max_u32_e32 v91, v91, v72
	v_max_u32_e32 v82, v82, v108
	v_max_u32_e32 v102, v102, v104
	v_max_u32_e32 v96, v96, v111
	v_max_u32_e32 v110, v70, v78
	v_min_u32_e32 v78, v70, v78
	v_max_u32_e32 v70, v97, v83
	v_min_u32_e32 v83, v97, v83
	v_max_u32_e32 v97, v79, v89
	v_min_u32_e32 v89, v79, v89
	v_max_u32_e32 v79, v90, v73
	v_min_u32_e32 v73, v90, v73
	v_max_u32_e32 v90, v87, v91
	v_min_u32_e32 v91, v87, v91
	v_max_u32_e32 v87, v92, v82
	v_min_u32_e32 v82, v92, v82
	v_max_u32_e32 v92, v117, v102
	v_min_u32_e32 v102, v117, v102
	v_max_u32_e32 v117, v118, v96
	v_min_u32_e32 v96, v118, v96
	v_max_u32_e32 v118, v110, v90
	v_min_u32_e32 v90, v110, v90
	v_max_u32_e32 v110, v70, v87
	v_min_u32_e32 v87, v70, v87
	v_max_u32_e32 v70, v97, v92
	v_min_u32_e32 v92, v97, v92
	v_max_u32_e32 v97, v79, v117
	v_min_u32_e32 v117, v79, v117
	v_max_u32_e32 v79, v78, v91
	v_min_u32_e32 v91, v78, v91
	v_max_u32_e32 v78, v83, v82
	v_min_u32_e32 v82, v83, v82
	v_max_u32_e32 v83, v89, v102
	v_min_u32_e32 v102, v89, v102
	v_max_u32_e32 v89, v73, v96
	v_min_u32_e32 v96, v73, v96
	v_max_u32_e32 v73, v118, v70
	v_min_u32_e32 v70, v118, v70
	v_max_u32_e32 v118, v110, v97
	v_min_u32_e32 v97, v110, v97
	v_max_u32_e32 v110, v90, v92
	v_min_u32_e32 v92, v90, v92
	v_max_u32_e32 v90, v87, v117
	v_min_u32_e32 v117, v87, v117
	v_max_u32_e32 v87, v79, v83
	v_min_u32_e32 v83, v79, v83
	v_max_u32_e32 v79, v78, v89
	v_min_u32_e32 v89, v78, v89
	v_max_u32_e32 v78, v91, v102
	v_min_u32_e32 v102, v91, v102
	v_max_u32_e32 v91, v82, v96
	v_min_u32_e32 v96, v82, v96
	v_max_u32_e32 v82, v73, v118
	v_min_u32_e32 v118, v73, v118
	v_max_u32_e32 v73, v70, v97
	v_min_u32_e32 v97, v70, v97
	v_max_u32_e32 v70, v110, v90
	v_min_u32_e32 v90, v110, v90
	v_max_u32_e32 v110, v92, v117
	v_min_u32_e32 v117, v92, v117
	v_max_u32_e32 v92, v87, v79
	v_min_u32_e32 v79, v87, v79
	v_max_u32_e32 v87, v83, v89
	v_min_u32_e32 v89, v83, v89
	v_max_u32_e32 v83, v78, v91
	v_min_u32_e32 v91, v78, v91
	v_max_u32_e32 v78, v102, v96
	v_min_u32_e32 v96, v102, v96
	s_waitcnt vmcnt(0)
	ds_write_b128 v64, v[32:35] offset:0
	ds_write_b128 v64, v[36:39] offset:1152
	ds_write_b128 v64, v[40:43] offset:2304
	ds_write_b128 v64, v[44:47] offset:3456
	ds_write_b128 v64, v[48:51] offset:4608
	ds_write_b128 v64, v[52:55] offset:5760
	ds_write_b128 v64, v[56:59] offset:6912
	ds_write_b128 v64, v[60:63] offset:8064
	s_waitcnt lgkmcnt(0)
	ds_read_b128 v[32:35], v65 offset:0
	ds_read_b128 v[36:39], v65 offset:16
	ds_read_b128 v[40:43], v65 offset:32
	ds_read_b128 v[44:47], v65 offset:48
	ds_read_b128 v[48:51], v65 offset:64
	ds_read_b128 v[52:55], v65 offset:80
	ds_read_b128 v[56:59], v65 offset:96
	ds_read_b128 v[60:63], v65 offset:112
	s_waitcnt lgkmcnt(0)
; __device__ __forceinline__ unsigned f2key(float f) { const unsigned u = __float_as_uint(f); return (u & 0x80000000u) ? ~u : (u | 0x80000000u); }
; #define CE_DESC(a, b) do { const unsigned _mx = (a) > (b) ? (a) : (b), _mn = (a) > (b) ? (b) : (a); (a) = _mx; (b) = _mn; } while (0)
; __device__ __forceinline__ void sort16_desc(unsigned (&k)[16]) {
; #pragma unroll
;     for (int size = 2; size <= 16; size <<= 1)
; #pragma unroll
;         for (int stride = size >> 1; stride > 0; stride >>= 1)
; #pragma unroll
;             for (int i = 0; i < 16; ++i) { const int j = i ^ stride;
;                 if (j > i) { if ((i & size) == 0) CE_DESC(k[i], k[j]); else CE_DESC(k[j], k[i]); } }
; }
; __device__ __forceinline__ void peer_tile(const Args& A, LAS unsigned char* lds, int tile) {
;     ...
;                   for (int i = 0; i < 16; ++i) {
;                       const float lo = (float)__builtin_bit_cast(_Float16, (unsigned short)(sw[i] & 0xffffu)), hi = (float)__builtin_bit_cast(_Float16, (unsigned short)(sw[i] >> 16));
;                       const unsigned klo = (f2key(lo) & ~127u) | (unsigned)(127 - (32 * g + 2 * i)), khi = (f2key(hi) & ~127u) | (unsigned)(127 - (32 * g + 2 * i + 1));
;                       if (i < 8) { k0[2 * i] = klo; k0[2 * i + 1] = khi; } else { k1[2 * (i - 8)] = klo; k1[2 * (i - 8) + 1] = khi; } } }
;                 sort16_desc(k0); sort16_desc(k1); merge16(k0, k1);
	v_cvt_f32_f16_e32 v102, v32
	v_cvt_f32_f16_sdwa v119, v32 dst_sel:DWORD dst_unused:UNUSED_PAD src0_sel:WORD_1
	v_ashrrev_i32_e32 v112, 31, v102
	v_bitop3_b32 v102, v102, v112, s40 bitop3:0x78
	v_xor_b32_e32 v102, 0x8000003f, v102
	v_ashrrev_i32_e32 v112, 31, v119
	v_bitop3_b32 v119, v119, v112, s40 bitop3:0x78
	v_xor_b32_e32 v119, 0x8000003e, v119
	v_cvt_f32_f16_e32 v112, v33
	v_cvt_f32_f16_sdwa v114, v33 dst_sel:DWORD dst_unused:UNUSED_PAD src0_sel:WORD_1
	v_ashrrev_i32_e32 v115, 31, v112
	v_bitop3_b32 v112, v112, v115, s40 bitop3:0x78
	v_xor_b32_e32 v112, 0x8000003d, v112
	v_ashrrev_i32_e32 v115, 31, v114
	v_bitop3_b32 v114, v114, v115, s40 bitop3:0x78
	v_xor_b32_e32 v114, 0x8000003c, v114
	v_cvt_f32_f16_e32 v115, v34
	v_cvt_f32_f16_sdwa v75, v34 dst_sel:DWORD dst_unused:UNUSED_PAD src0_sel:WORD_1
	v_ashrrev_i32_e32 v103, 31, v115
	v_bitop3_b32 v115, v115, v103, s40 bitop3:0x78
	v_xor_b32_e32 v115, 0x8000003b, v115
	v_ashrrev_i32_e32 v103, 31, v75
	v_bitop3_b32 v75, v75, v103, s40 bitop3:0x78
	v_xor_b32_e32 v75, 0x8000003a, v75
	v_cvt_f32_f16_e32 v103, v35
	v_cvt_f32_f16_sdwa v105, v35 dst_sel:DWORD dst_unused:UNUSED_PAD src0_sel:WORD_1
	v_ashrrev_i32_e32 v109, 31, v103
	v_bitop3_b32 v103, v103, v109, s40 bitop3:0x78
	v_xor_b32_e32 v103, 0x80000039, v103
	v_ashrrev_i32_e32 v109, 31, v105
	v_bitop3_b32 v105, v105, v109, s40 bitop3:0x78
	v_xor_b32_e32 v105, 0x80000038, v105
	v_cvt_f32_f16_e32 v109, v36
	v_cvt_f32_f16_sdwa v116, v36 dst_sel:DWORD dst_unused:UNUSED_PAD src0_sel:WORD_1
	v_ashrrev_i32_e32 v106, 31, v109
	v_bitop3_b32 v109, v109, v106, s40 bitop3:0x78
	v_xor_b32_e32 v109, 0x80000037, v109
	v_ashrrev_i32_e32 v106, 31, v116
	v_bitop3_b32 v116, v116, v106, s40 bitop3:0x78
	v_xor_b32_e32 v116, 0x80000036, v116
	v_cvt_f32_f16_e32 v106, v37
	v_cvt_f32_f16_sdwa v107, v37 dst_sel:DWORD dst_unused:UNUSED_PAD src0_sel:WORD_1
	v_ashrrev_i32_e32 v72, 31, v106
	v_bitop3_b32 v106, v106, v72, s40 bitop3:0x78
	v_xor_b32_e32 v106, 0x80000035, v106
	v_ashrrev_i32_e32 v72, 31, v107
	v_bitop3_b32 v107, v107, v72, s40 bitop3:0x78
	v_xor_b32_e32 v107, 0x80000034, v107
	v_cvt_f32_f16_e32 v72, v38
	v_cvt_f32_f16_sdwa v108, v38 dst_sel:DWORD dst_unused:UNUSED_PAD src0_sel:WORD_1
	v_ashrrev_i32_e32 v104, 31, v72
	v_bitop3_b32 v72, v72, v104, s40 bitop3:0x78
	v_xor_b32_e32 v72, 0x80000033, v72
	v_ashrrev_i32_e32 v104, 31, v108
	v_bitop3_b32 v108, v108, v104, s40 bitop3:0x78
	v_xor_b32_e32 v108, 0x80000032, v108
	v_cvt_f32_f16_e32 v104, v39
	v_cvt_f32_f16_sdwa v111, v39 dst_sel:DWORD dst_unused:UNUSED_PAD src0_sel:WORD_1
	v_ashrrev_i32_e32 v98, 31, v104
	v_bitop3_b32 v104, v104, v98, s40 bitop3:0x78
	v_xor_b32_e32 v104, 0x80000031, v104
	v_ashrrev_i32_e32 v98, 31, v111
	v_bitop3_b32 v111, v111, v98, s40 bitop3:0x78
	v_xor_b32_e32 v111, 0x80000030, v111
	v_max_u32_e32 v98, v102, v108
	v_min_u32_e32 v108, v102, v108
	v_max_u32_e32 v102, v119, v72
	v_min_u32_e32 v72, v119, v72
	v_max_u32_e32 v119, v112, v111
	v_min_u32_e32 v111, v112, v111
	v_max_u32_e32 v112, v114, v104
	v_min_u32_e32 v104, v114, v104
	v_max_u32_e32 v114, v115, v109
	v_min_u32_e32 v109, v115, v109
	v_max_u32_e32 v115, v75, v103
	v_min_u32_e32 v103, v75, v103
	v_max_u32_e32 v75, v105, v107
	v_min_u32_e32 v107, v105, v107
	v_max_u32_e32 v105, v116, v106
	v_min_u32_e32 v106, v116, v106
	v_max_u32_e32 v116, v98, v115
	v_min_u32_e32 v115, v98, v115
	v_max_u32_e32 v98, v102, v75
	v_min_u32_e32 v75, v102, v75
	v_max_u32_e32 v102, v119, v105
	v_min_u32_e32 v105, v119, v105
	v_max_u32_e32 v119, v112, v114
	v_min_u32_e32 v114, v112, v114
	v_max_u32_e32 v112, v103, v108
	v_min_u32_e32 v108, v103, v108
	v_max_u32_e32 v103, v109, v104
	v_min_u32_e32 v104, v109, v104
	v_max_u32_e32 v109, v106, v111
	v_min_u32_e32 v111, v106, v111
	v_max_u32_e32 v106, v107, v72
	v_min_u32_e32 v72, v107, v72
	v_max_u32_e32 v107, v116, v98
	v_min_u32_e32 v98, v116, v98
	v_max_u32_e32 v116, v102, v119
	v_min_u32_e32 v119, v102, v119
	v_max_u32_e32 v102, v114, v115
	v_min_u32_e32 v115, v114, v115
	v_max_u32_e32 v114, v112, v103
	v_min_u32_e32 v103, v112, v103
	v_max_u32_e32 v112, v75, v105
	v_min_u32_e32 v105, v75, v105
	v_max_u32_e32 v75, v109, v106
	v_min_u32_e32 v106, v109, v106
	v_max_u32_e32 v109, v72, v108
	v_min_u32_e32 v108, v72, v108
	v_max_u32_e32 v72, v104, v111
	v_min_u32_e32 v111, v104, v111
	v_max_u32_e32 v104, v107, v116
	v_min_u32_e32 v116, v107, v116
	v_max_u32_e32 v107, v98, v119
	v_min_u32_e32 v119, v98, v119
	v_max_u32_e32 v98, v102, v75
	v_min_u32_e32 v75, v102, v75
	v_max_u32_e32 v102, v115, v106
	v_min_u32_e32 v106, v115, v106
	v_max_u32_e32 v115, v114, v112
	v_min_u32_e32 v112, v114, v112
	v_max_u32_e32 v114, v103, v105
	v_min_u32_e32 v105, v103, v105
	v_max_u32_e32 v103, v109, v72
	v_min_u32_e32 v72, v109, v72
	v_max_u32_e32 v109, v108, v111
	v_min_u32_e32 v111, v108, v111
	v_max_u32_e32 v108, v107, v116
	v_min_u32_e32 v116, v107, v116
	v_max_u32_e32 v107, v119, v103
	v_min_u32_e32 v103, v119, v103
	v_max_u32_e32 v119, v98, v115
	v_min_u32_e32 v115, v98, v115
	v_max_u32_e32 v98, v102, v112
	v_min_u32_e32 v112, v102, v112
	v_max_u32_e32 v102, v114, v75
	v_min_u32_e32 v75, v114, v75
	v_max_u32_e32 v114, v105, v106
	v_min_u32_e32 v106, v105, v106
	v_max_u32_e32 v105, v109, v72
	v_min_u32_e32 v72, v109, v72
	v_max_u32_e32 v109, v108, v119
	v_min_u32_e32 v119, v108, v119
	v_max_u32_e32 v108, v116, v115
	v_min_u32_e32 v115, v116, v115
	v_max_u32_e32 v116, v98, v102
	v_min_u32_e32 v102, v98, v102
	v_max_u32_e32 v98, v112, v75
	v_min_u32_e32 v75, v112, v75
	v_max_u32_e32 v112, v114, v105
	v_min_u32_e32 v105, v114, v105
	v_max_u32_e32 v114, v106, v72
	v_min_u32_e32 v72, v106, v72
	v_max_u32_e32 v106, v108, v119
; __device__ __forceinline__ unsigned f2key(float f) { const unsigned u = __float_as_uint(f); return (u & 0x80000000u) ? ~u : (u | 0x80000000u); }
; #define CE_DESC(a, b) do { const unsigned _mx = (a) > (b) ? (a) : (b), _mn = (a) > (b) ? (b) : (a); (a) = _mx; (b) = _mn; } while (0)
; __device__ __forceinline__ void sort16_desc(unsigned (&k)[16]) {
; #pragma unroll
;     for (int size = 2; size <= 16; size <<= 1)
; #pragma unroll
;         for (int stride = size >> 1; stride > 0; stride >>= 1)
; #pragma unroll
;             for (int i = 0; i < 16; ++i) { const int j = i ^ stride;
;                 if (j > i) { if ((i & size) == 0) CE_DESC(k[i], k[j]); else CE_DESC(k[j], k[i]); } }
; }
; __device__ __forceinline__ void merge16(unsigned (&a)[16], const unsigned (&b)[16]) {
; #pragma unroll
;     for (int i = 0; i < 16; ++i) a[i] = a[i] > b[15 - i] ? a[i] : b[15 - i];
; #pragma unroll
;     for (int stride = 8; stride > 0; stride >>= 1)
; #pragma unroll
;         for (int i = 0; i < 16; ++i) { const int j = i ^ stride; if (j > i) CE_DESC(a[i], a[j]); }
; }
; __device__ __forceinline__ void peer_tile(const Args& A, LAS unsigned char* lds, int tile) {
;     ...
;                 { const bf16_t* sp = QRY + m * 2048 + hp * 128 + 32 * g;
;                   const u32x4 s0 = *(const u32x4*)sp, s1 = *(const u32x4*)(sp + 8), s2 = *(const u32x4*)(sp + 16), s3 = *(const u32x4*)(sp + 24);
;                   const unsigned sw[16] = {s0.x, s0.y, s0.z, s0.w, s1.x, s1.y, s1.z, s1.w, s2.x, s2.y, s2.z, s2.w, s3.x, s3.y, s3.z, s3.w};
; #pragma unroll
;                   for (int i = 0; i < 16; ++i) {
;                       const float lo = (float)__builtin_bit_cast(_Float16, (unsigned short)(sw[i] & 0xffffu)), hi = (float)__builtin_bit_cast(_Float16, (unsigned short)(sw[i] >> 16));
;                       const unsigned klo = (f2key(lo) & ~127u) | (unsigned)(127 - (32 * g + 2 * i)), khi = (f2key(hi) & ~127u) | (unsigned)(127 - (32 * g + 2 * i + 1));
;                       if (i < 8) { k0[2 * i] = klo; k0[2 * i + 1] = khi; } else { k1[2 * (i - 8)] = klo; k1[2 * (i - 8) + 1] = khi; } } }
;                 sort16_desc(k0); sort16_desc(k1); merge16(k0, k1);
; #pragma unroll
;                 for (int msk = 16; msk <= 32; msk <<= 1) {
; #pragma unroll
;                     for (int i = 0; i < 16; ++i) k1[i] = (unsigned)__shfl_xor((int)k0[i], msk);
;                     merge16(k0, k1); }
	v_min_u32_e32 v119, v108, v119
	v_max_u32_e32 v108, v107, v115
	v_min_u32_e32 v115, v107, v115
	v_max_u32_e32 v107, v112, v103
	v_min_u32_e32 v103, v112, v103
	v_max_u32_e32 v112, v114, v105
	v_min_u32_e32 v105, v114, v105
	v_max_u32_e32 v114, v108, v116
	v_min_u32_e32 v116, v108, v116
	v_max_u32_e32 v108, v115, v102
	v_min_u32_e32 v102, v115, v102
	v_max_u32_e32 v115, v98, v107
	v_min_u32_e32 v107, v98, v107
	v_max_u32_e32 v98, v75, v103
	v_min_u32_e32 v103, v75, v103
	v_max_u32_e32 v75, v114, v119
	v_min_u32_e32 v119, v114, v119
	v_max_u32_e32 v114, v116, v108
	v_min_u32_e32 v108, v116, v108
	v_max_u32_e32 v116, v115, v102
	v_min_u32_e32 v102, v115, v102
	v_max_u32_e32 v115, v107, v98
	v_min_u32_e32 v98, v107, v98
	v_max_u32_e32 v107, v112, v103
	v_min_u32_e32 v103, v112, v103
	v_max_u32_e32 v112, v108, v116
	v_min_u32_e32 v116, v108, v116
	v_max_u32_e32 v108, v102, v115
	v_min_u32_e32 v115, v102, v115
	v_max_u32_e32 v82, v82, v111
	v_max_u32_e32 v118, v118, v72
	v_max_u32_e32 v73, v73, v105
	v_max_u32_e32 v97, v97, v103
	v_max_u32_e32 v70, v70, v107
	v_max_u32_e32 v90, v90, v98
	v_max_u32_e32 v110, v110, v115
	v_max_u32_e32 v117, v117, v108
	v_max_u32_e32 v92, v92, v116
	v_max_u32_e32 v79, v79, v112
	v_max_u32_e32 v87, v87, v114
	v_max_u32_e32 v89, v89, v119
	v_max_u32_e32 v83, v83, v75
	v_max_u32_e32 v91, v91, v106
	v_max_u32_e32 v78, v78, v109
	v_max_u32_e32 v96, v96, v104
	v_max_u32_e32 v111, v82, v92
	v_min_u32_e32 v92, v82, v92
	v_max_u32_e32 v82, v118, v79
	v_min_u32_e32 v79, v118, v79
	v_max_u32_e32 v118, v73, v87
	v_min_u32_e32 v87, v73, v87
	v_max_u32_e32 v73, v97, v89
	v_min_u32_e32 v89, v97, v89
	v_max_u32_e32 v97, v70, v83
	v_min_u32_e32 v83, v70, v83
	v_max_u32_e32 v70, v90, v91
	v_min_u32_e32 v91, v90, v91
	v_max_u32_e32 v90, v110, v78
	v_min_u32_e32 v78, v110, v78
	v_max_u32_e32 v110, v117, v96
	v_min_u32_e32 v96, v117, v96
	v_max_u32_e32 v117, v111, v97
	v_min_u32_e32 v97, v111, v97
	v_max_u32_e32 v111, v82, v70
	v_min_u32_e32 v70, v82, v70
	v_max_u32_e32 v82, v118, v90
	v_min_u32_e32 v90, v118, v90
	v_max_u32_e32 v118, v73, v110
	v_min_u32_e32 v110, v73, v110
	v_max_u32_e32 v73, v92, v83
	v_min_u32_e32 v83, v92, v83
	v_max_u32_e32 v92, v79, v91
	v_min_u32_e32 v91, v79, v91
	v_max_u32_e32 v79, v87, v78
	v_min_u32_e32 v78, v87, v78
	v_max_u32_e32 v87, v89, v96
	v_min_u32_e32 v96, v89, v96
	v_max_u32_e32 v89, v117, v82
	v_min_u32_e32 v82, v117, v82
	v_max_u32_e32 v117, v111, v118
	v_min_u32_e32 v118, v111, v118
	v_max_u32_e32 v111, v97, v90
	v_min_u32_e32 v90, v97, v90
	v_max_u32_e32 v97, v70, v110
	v_min_u32_e32 v110, v70, v110
	v_max_u32_e32 v70, v73, v79
	v_min_u32_e32 v79, v73, v79
	v_max_u32_e32 v73, v92, v87
	v_min_u32_e32 v87, v92, v87
	v_max_u32_e32 v92, v83, v78
	v_min_u32_e32 v78, v83, v78
	v_max_u32_e32 v83, v91, v96
	v_min_u32_e32 v96, v91, v96
	v_max_u32_e32 v91, v89, v117
	v_min_u32_e32 v117, v89, v117
	v_max_u32_e32 v89, v82, v118
	v_min_u32_e32 v118, v82, v118
	v_max_u32_e32 v82, v111, v97
	v_min_u32_e32 v97, v111, v97
	v_max_u32_e32 v111, v90, v110
	v_min_u32_e32 v110, v90, v110
	v_max_u32_e32 v90, v70, v73
	v_min_u32_e32 v73, v70, v73
	v_max_u32_e32 v70, v79, v87
	v_min_u32_e32 v87, v79, v87
	v_max_u32_e32 v79, v92, v83
	v_min_u32_e32 v83, v92, v83
	v_max_u32_e32 v92, v78, v96
	v_min_u32_e32 v96, v78, v96
	v_cvt_f32_f16_e32 v78, v40
	v_cvt_f32_f16_sdwa v72, v40 dst_sel:DWORD dst_unused:UNUSED_PAD src0_sel:WORD_1
	v_ashrrev_i32_e32 v105, 31, v78
	v_bitop3_b32 v78, v78, v105, s40 bitop3:0x78
	v_xor_b32_e32 v78, 0x8000002f, v78
	v_ashrrev_i32_e32 v105, 31, v72
	v_bitop3_b32 v72, v72, v105, s40 bitop3:0x78
	v_xor_b32_e32 v72, 0x8000002e, v72
	v_cvt_f32_f16_e32 v105, v41
	v_cvt_f32_f16_sdwa v103, v41 dst_sel:DWORD dst_unused:UNUSED_PAD src0_sel:WORD_1
	v_ashrrev_i32_e32 v107, 31, v105
	v_bitop3_b32 v105, v105, v107, s40 bitop3:0x78
	v_xor_b32_e32 v105, 0x8000002d, v105
	v_ashrrev_i32_e32 v107, 31, v103
	v_bitop3_b32 v103, v103, v107, s40 bitop3:0x78
	v_xor_b32_e32 v103, 0x8000002c, v103
	v_cvt_f32_f16_e32 v107, v42
	v_cvt_f32_f16_sdwa v98, v42 dst_sel:DWORD dst_unused:UNUSED_PAD src0_sel:WORD_1
	v_ashrrev_i32_e32 v115, 31, v107
	v_bitop3_b32 v107, v107, v115, s40 bitop3:0x78
	v_xor_b32_e32 v107, 0x8000002b, v107
	v_ashrrev_i32_e32 v115, 31, v98
	v_bitop3_b32 v98, v98, v115, s40 bitop3:0x78
	v_xor_b32_e32 v98, 0x8000002a, v98
	v_cvt_f32_f16_e32 v115, v43
	v_cvt_f32_f16_sdwa v108, v43 dst_sel:DWORD dst_unused:UNUSED_PAD src0_sel:WORD_1
	v_ashrrev_i32_e32 v116, 31, v115
	v_bitop3_b32 v115, v115, v116, s40 bitop3:0x78
	v_xor_b32_e32 v115, 0x80000029, v115
	v_ashrrev_i32_e32 v116, 31, v108
	v_bitop3_b32 v108, v108, v116, s40 bitop3:0x78
	v_xor_b32_e32 v108, 0x80000028, v108
	v_cvt_f32_f16_e32 v116, v44
	v_cvt_f32_f16_sdwa v112, v44 dst_sel:DWORD dst_unused:UNUSED_PAD src0_sel:WORD_1
	v_ashrrev_i32_e32 v114, 31, v116
	v_bitop3_b32 v116, v116, v114, s40 bitop3:0x78
	v_xor_b32_e32 v116, 0x80000027, v116
	v_ashrrev_i32_e32 v114, 31, v112
	v_bitop3_b32 v112, v112, v114, s40 bitop3:0x78
	v_xor_b32_e32 v112, 0x80000026, v112
	v_cvt_f32_f16_e32 v114, v45
	v_cvt_f32_f16_sdwa v119, v45 dst_sel:DWORD dst_unused:UNUSED_PAD src0_sel:WORD_1
	v_ashrrev_i32_e32 v75, 31, v114
	v_bitop3_b32 v114, v114, v75, s40 bitop3:0x78
	v_xor_b32_e32 v114, 0x80000025, v114
	v_ashrrev_i32_e32 v75, 31, v119
	v_bitop3_b32 v119, v119, v75, s40 bitop3:0x78
	v_xor_b32_e32 v119, 0x80000024, v119
	v_cvt_f32_f16_e32 v75, v46
	v_cvt_f32_f16_sdwa v106, v46 dst_sel:DWORD dst_unused:UNUSED_PAD src0_sel:WORD_1
	v_ashrrev_i32_e32 v109, 31, v75
	v_bitop3_b32 v75, v75, v109, s40 bitop3:0x78
	v_xor_b32_e32 v75, 0x80000023, v75
	v_ashrrev_i32_e32 v109, 31, v106
; __device__ __forceinline__ unsigned f2key(float f) { const unsigned u = __float_as_uint(f); return (u & 0x80000000u) ? ~u : (u | 0x80000000u); }
; #define CE_DESC(a, b) do { const unsigned _mx = (a) > (b) ? (a) : (b), _mn = (a) > (b) ? (b) : (a); (a) = _mx; (b) = _mn; } while (0)
; __device__ __forceinline__ void sort16_desc(unsigned (&k)[16]) {
; #pragma unroll
;     for (int size = 2; size <= 16; size <<= 1)
; #pragma unroll
;         for (int stride = size >> 1; stride > 0; stride >>= 1)
; #pragma unroll
;             for (int i = 0; i < 16; ++i) { const int j = i ^ stride;
;                 if (j > i) { if ((i & size) == 0) CE_DESC(k[i], k[j]); else CE_DESC(k[j], k[i]); } }
; }
; __device__ __forceinline__ void merge16(unsigned (&a)[16], const unsigned (&b)[16]) {
; #pragma unroll
;     for (int i = 0; i < 16; ++i) a[i] = a[i] > b[15 - i] ? a[i] : b[15 - i];
; #pragma unroll
;     for (int stride = 8; stride > 0; stride >>= 1)
; #pragma unroll
;         for (int i = 0; i < 16; ++i) { const int j = i ^ stride; if (j > i) CE_DESC(a[i], a[j]); }
; }
; __device__ __forceinline__ void peer_tile(const Args& A, LAS unsigned char* lds, int tile) {
;     ...
;                 { const bf16_t* sp = QRY + m * 2048 + hp * 128 + 32 * g;
;                   const u32x4 s0 = *(const u32x4*)sp, s1 = *(const u32x4*)(sp + 8), s2 = *(const u32x4*)(sp + 16), s3 = *(const u32x4*)(sp + 24);
;                   const unsigned sw[16] = {s0.x, s0.y, s0.z, s0.w, s1.x, s1.y, s1.z, s1.w, s2.x, s2.y, s2.z, s2.w, s3.x, s3.y, s3.z, s3.w};
; #pragma unroll
;                   for (int i = 0; i < 16; ++i) {
;                       const float lo = (float)__builtin_bit_cast(_Float16, (unsigned short)(sw[i] & 0xffffu)), hi = (float)__builtin_bit_cast(_Float16, (unsigned short)(sw[i] >> 16));
;                       const unsigned klo = (f2key(lo) & ~127u) | (unsigned)(127 - (32 * g + 2 * i)), khi = (f2key(hi) & ~127u) | (unsigned)(127 - (32 * g + 2 * i + 1));
;                       if (i < 8) { k0[2 * i] = klo; k0[2 * i + 1] = khi; } else { k1[2 * (i - 8)] = klo; k1[2 * (i - 8) + 1] = khi; } } }
;                 sort16_desc(k0); sort16_desc(k1); merge16(k0, k1);
; #pragma unroll
;                 for (int msk = 16; msk <= 32; msk <<= 1) {
; #pragma unroll
;                     for (int i = 0; i < 16; ++i) k1[i] = (unsigned)__shfl_xor((int)k0[i], msk);
;                     merge16(k0, k1); }
	v_bitop3_b32 v106, v106, v109, s40 bitop3:0x78
	v_xor_b32_e32 v106, 0x80000022, v106
	v_cvt_f32_f16_e32 v109, v47
	v_cvt_f32_f16_sdwa v104, v47 dst_sel:DWORD dst_unused:UNUSED_PAD src0_sel:WORD_1
	v_ashrrev_i32_e32 v102, 31, v109
	v_bitop3_b32 v109, v109, v102, s40 bitop3:0x78
	v_xor_b32_e32 v109, 0x80000021, v109
	v_ashrrev_i32_e32 v102, 31, v104
	v_bitop3_b32 v104, v104, v102, s40 bitop3:0x78
	v_xor_b32_e32 v104, 0x80000020, v104
	v_max_u32_e32 v102, v78, v106
	v_min_u32_e32 v106, v78, v106
	v_max_u32_e32 v78, v72, v75
	v_min_u32_e32 v75, v72, v75
	v_max_u32_e32 v72, v105, v104
	v_min_u32_e32 v104, v105, v104
	v_max_u32_e32 v105, v103, v109
	v_min_u32_e32 v109, v103, v109
	v_max_u32_e32 v103, v107, v116
	v_min_u32_e32 v116, v107, v116
	v_max_u32_e32 v107, v98, v115
	v_min_u32_e32 v115, v98, v115
	v_max_u32_e32 v98, v108, v119
	v_min_u32_e32 v119, v108, v119
	v_max_u32_e32 v108, v112, v114
	v_min_u32_e32 v114, v112, v114
	v_max_u32_e32 v112, v102, v107
	v_min_u32_e32 v107, v102, v107
	v_max_u32_e32 v102, v78, v98
	v_min_u32_e32 v98, v78, v98
	v_max_u32_e32 v78, v72, v108
	v_min_u32_e32 v108, v72, v108
	v_max_u32_e32 v72, v105, v103
	v_min_u32_e32 v103, v105, v103
	v_max_u32_e32 v105, v115, v106
	v_min_u32_e32 v106, v115, v106
	v_max_u32_e32 v115, v116, v109
	v_min_u32_e32 v109, v116, v109
	v_max_u32_e32 v116, v114, v104
	v_min_u32_e32 v104, v114, v104
	v_max_u32_e32 v114, v119, v75
	v_min_u32_e32 v75, v119, v75
	v_max_u32_e32 v119, v112, v102
	v_min_u32_e32 v102, v112, v102
	v_max_u32_e32 v112, v78, v72
	v_min_u32_e32 v72, v78, v72
	v_max_u32_e32 v78, v103, v107
	v_min_u32_e32 v107, v103, v107
	v_max_u32_e32 v103, v105, v115
	v_min_u32_e32 v115, v105, v115
	v_max_u32_e32 v105, v98, v108
	v_min_u32_e32 v108, v98, v108
	v_max_u32_e32 v98, v116, v114
	v_min_u32_e32 v114, v116, v114
	v_max_u32_e32 v116, v75, v106
	v_min_u32_e32 v106, v75, v106
	v_max_u32_e32 v75, v109, v104
	v_min_u32_e32 v104, v109, v104
	v_max_u32_e32 v109, v119, v112
	v_min_u32_e32 v112, v119, v112
	v_max_u32_e32 v119, v102, v72
	v_min_u32_e32 v72, v102, v72
	v_max_u32_e32 v102, v78, v98
	v_min_u32_e32 v98, v78, v98
	v_max_u32_e32 v78, v107, v114
	v_min_u32_e32 v114, v107, v114
	v_max_u32_e32 v107, v103, v105
	v_min_u32_e32 v105, v103, v105
	v_max_u32_e32 v103, v115, v108
	v_min_u32_e32 v108, v115, v108
	v_max_u32_e32 v115, v116, v75
	v_min_u32_e32 v75, v116, v75
	v_max_u32_e32 v116, v106, v104
	v_min_u32_e32 v104, v106, v104
	v_max_u32_e32 v106, v119, v112
	v_min_u32_e32 v112, v119, v112
	v_max_u32_e32 v119, v72, v115
	v_min_u32_e32 v115, v72, v115
	v_max_u32_e32 v72, v102, v107
	v_min_u32_e32 v107, v102, v107
	v_max_u32_e32 v102, v78, v105
	v_min_u32_e32 v105, v78, v105
	v_max_u32_e32 v78, v103, v98
	v_min_u32_e32 v98, v103, v98
	v_max_u32_e32 v103, v108, v114
	v_min_u32_e32 v114, v108, v114
	v_max_u32_e32 v108, v116, v75
	v_min_u32_e32 v75, v116, v75
	v_max_u32_e32 v116, v106, v72
	v_min_u32_e32 v72, v106, v72
	v_max_u32_e32 v106, v112, v107
	v_min_u32_e32 v107, v112, v107
	v_max_u32_e32 v112, v102, v78
	v_min_u32_e32 v78, v102, v78
	v_max_u32_e32 v102, v105, v98
	v_min_u32_e32 v98, v105, v98
	v_max_u32_e32 v105, v103, v108
	v_min_u32_e32 v108, v103, v108
	v_max_u32_e32 v103, v114, v75
	v_min_u32_e32 v75, v114, v75
	v_max_u32_e32 v114, v106, v72
	v_min_u32_e32 v72, v106, v72
	v_max_u32_e32 v106, v119, v107
	v_min_u32_e32 v107, v119, v107
	v_max_u32_e32 v119, v105, v115
	v_min_u32_e32 v115, v105, v115
	v_max_u32_e32 v105, v103, v108
	v_min_u32_e32 v108, v103, v108
	v_max_u32_e32 v103, v106, v112
	v_min_u32_e32 v112, v106, v112
	v_max_u32_e32 v106, v107, v78
	v_min_u32_e32 v78, v107, v78
	v_max_u32_e32 v107, v102, v119
	v_min_u32_e32 v119, v102, v119
	v_max_u32_e32 v102, v98, v115
	v_min_u32_e32 v115, v98, v115
	v_max_u32_e32 v98, v103, v72
	v_min_u32_e32 v72, v103, v72
	v_max_u32_e32 v103, v112, v106
	v_min_u32_e32 v106, v112, v106
	v_max_u32_e32 v112, v107, v78
	v_min_u32_e32 v78, v107, v78
	v_max_u32_e32 v107, v119, v102
	v_min_u32_e32 v102, v119, v102
	v_max_u32_e32 v119, v105, v115
	v_min_u32_e32 v115, v105, v115
	v_max_u32_e32 v105, v106, v112
	v_min_u32_e32 v112, v106, v112
	v_max_u32_e32 v106, v78, v107
	v_min_u32_e32 v107, v78, v107
	v_max_u32_e32 v91, v91, v104
	v_max_u32_e32 v117, v117, v75
	v_max_u32_e32 v89, v89, v108
	v_max_u32_e32 v118, v118, v115
	v_max_u32_e32 v82, v82, v119
	v_max_u32_e32 v97, v97, v102
	v_max_u32_e32 v111, v111, v107
	v_max_u32_e32 v110, v110, v106
	v_max_u32_e32 v90, v90, v112
	v_max_u32_e32 v73, v73, v105
	v_max_u32_e32 v70, v70, v103
	v_max_u32_e32 v87, v87, v72
	v_max_u32_e32 v79, v79, v98
	v_max_u32_e32 v83, v83, v114
	v_max_u32_e32 v92, v92, v116
	v_max_u32_e32 v96, v96, v109
	v_max_u32_e32 v104, v91, v90
	v_min_u32_e32 v90, v91, v90
	v_max_u32_e32 v91, v117, v73
	v_min_u32_e32 v73, v117, v73
	v_max_u32_e32 v117, v89, v70
	v_min_u32_e32 v70, v89, v70
	v_max_u32_e32 v89, v118, v87
	v_min_u32_e32 v87, v118, v87
	v_max_u32_e32 v118, v82, v79
	v_min_u32_e32 v79, v82, v79
	v_max_u32_e32 v82, v97, v83
	v_min_u32_e32 v83, v97, v83
	v_max_u32_e32 v97, v111, v92
	v_min_u32_e32 v92, v111, v92
	v_max_u32_e32 v111, v110, v96
	v_min_u32_e32 v96, v110, v96
	v_max_u32_e32 v110, v104, v118
	v_min_u32_e32 v118, v104, v118
	v_max_u32_e32 v104, v91, v82
	v_min_u32_e32 v82, v91, v82
	v_max_u32_e32 v91, v117, v97
	v_min_u32_e32 v97, v117, v97
	v_max_u32_e32 v117, v89, v111
	v_min_u32_e32 v111, v89, v111
	v_max_u32_e32 v89, v90, v79
	v_min_u32_e32 v79, v90, v79
	v_max_u32_e32 v90, v73, v83
	v_min_u32_e32 v83, v73, v83
	v_max_u32_e32 v73, v70, v92
	v_min_u32_e32 v92, v70, v92
	v_max_u32_e32 v70, v87, v96
	v_min_u32_e32 v96, v87, v96
; __device__ __forceinline__ unsigned f2key(float f) { const unsigned u = __float_as_uint(f); return (u & 0x80000000u) ? ~u : (u | 0x80000000u); }
; #define CE_DESC(a, b) do { const unsigned _mx = (a) > (b) ? (a) : (b), _mn = (a) > (b) ? (b) : (a); (a) = _mx; (b) = _mn; } while (0)
; __device__ __forceinline__ void sort16_desc(unsigned (&k)[16]) {
; #pragma unroll
;     for (int size = 2; size <= 16; size <<= 1)
; #pragma unroll
;         for (int stride = size >> 1; stride > 0; stride >>= 1)
; #pragma unroll
;             for (int i = 0; i < 16; ++i) { const int j = i ^ stride;
;                 if (j > i) { if ((i & size) == 0) CE_DESC(k[i], k[j]); else CE_DESC(k[j], k[i]); } }
; }
; __device__ __forceinline__ void merge16(unsigned (&a)[16], const unsigned (&b)[16]) {
; #pragma unroll
;     for (int i = 0; i < 16; ++i) a[i] = a[i] > b[15 - i] ? a[i] : b[15 - i];
; #pragma unroll
;     for (int stride = 8; stride > 0; stride >>= 1)
; #pragma unroll
;         for (int i = 0; i < 16; ++i) { const int j = i ^ stride; if (j > i) CE_DESC(a[i], a[j]); }
; }
; __device__ __forceinline__ void peer_tile(const Args& A, LAS unsigned char* lds, int tile) {
;     ...
;                 { const bf16_t* sp = QRY + m * 2048 + hp * 128 + 32 * g;
;                   const u32x4 s0 = *(const u32x4*)sp, s1 = *(const u32x4*)(sp + 8), s2 = *(const u32x4*)(sp + 16), s3 = *(const u32x4*)(sp + 24);
;                   const unsigned sw[16] = {s0.x, s0.y, s0.z, s0.w, s1.x, s1.y, s1.z, s1.w, s2.x, s2.y, s2.z, s2.w, s3.x, s3.y, s3.z, s3.w};
; #pragma unroll
;                   for (int i = 0; i < 16; ++i) {
;                       const float lo = (float)__builtin_bit_cast(_Float16, (unsigned short)(sw[i] & 0xffffu)), hi = (float)__builtin_bit_cast(_Float16, (unsigned short)(sw[i] >> 16));
;                       const unsigned klo = (f2key(lo) & ~127u) | (unsigned)(127 - (32 * g + 2 * i)), khi = (f2key(hi) & ~127u) | (unsigned)(127 - (32 * g + 2 * i + 1));
;                       if (i < 8) { k0[2 * i] = klo; k0[2 * i + 1] = khi; } else { k1[2 * (i - 8)] = klo; k1[2 * (i - 8) + 1] = khi; } } }
;                 sort16_desc(k0); sort16_desc(k1); merge16(k0, k1);
; #pragma unroll
;                 for (int msk = 16; msk <= 32; msk <<= 1) {
; #pragma unroll
;                     for (int i = 0; i < 16; ++i) k1[i] = (unsigned)__shfl_xor((int)k0[i], msk);
;                     merge16(k0, k1); }
	v_max_u32_e32 v87, v110, v91
	v_min_u32_e32 v91, v110, v91
	v_max_u32_e32 v110, v104, v117
	v_min_u32_e32 v117, v104, v117
	v_max_u32_e32 v104, v118, v97
	v_min_u32_e32 v97, v118, v97
	v_max_u32_e32 v118, v82, v111
	v_min_u32_e32 v111, v82, v111
	v_max_u32_e32 v82, v89, v73
	v_min_u32_e32 v73, v89, v73
	v_max_u32_e32 v89, v90, v70
	v_min_u32_e32 v70, v90, v70
	v_max_u32_e32 v90, v79, v92
	v_min_u32_e32 v92, v79, v92
	v_max_u32_e32 v79, v83, v96
	v_min_u32_e32 v96, v83, v96
	v_max_u32_e32 v83, v87, v110
	v_min_u32_e32 v110, v87, v110
	v_max_u32_e32 v87, v91, v117
	v_min_u32_e32 v117, v91, v117
	v_max_u32_e32 v91, v104, v118
	v_min_u32_e32 v118, v104, v118
	v_max_u32_e32 v104, v97, v111
	v_min_u32_e32 v111, v97, v111
	v_max_u32_e32 v97, v82, v89
	v_min_u32_e32 v89, v82, v89
	v_max_u32_e32 v82, v73, v70
	v_min_u32_e32 v70, v73, v70
	v_max_u32_e32 v73, v90, v79
	v_min_u32_e32 v79, v90, v79
	v_max_u32_e32 v90, v92, v96
	v_min_u32_e32 v96, v92, v96
	v_cvt_f32_f16_e32 v92, v48
	v_cvt_f32_f16_sdwa v75, v48 dst_sel:DWORD dst_unused:UNUSED_PAD src0_sel:WORD_1
	v_ashrrev_i32_e32 v108, 31, v92
	v_bitop3_b32 v92, v92, v108, s40 bitop3:0x78
	v_xor_b32_e32 v92, 0x8000001f, v92
	v_ashrrev_i32_e32 v108, 31, v75
	v_bitop3_b32 v75, v75, v108, s40 bitop3:0x78
	v_xor_b32_e32 v75, 0x8000001e, v75
	v_cvt_f32_f16_e32 v108, v49
	v_cvt_f32_f16_sdwa v115, v49 dst_sel:DWORD dst_unused:UNUSED_PAD src0_sel:WORD_1
	v_ashrrev_i32_e32 v119, 31, v108
	v_bitop3_b32 v108, v108, v119, s40 bitop3:0x78
	v_xor_b32_e32 v108, 0x8000001d, v108
	v_ashrrev_i32_e32 v119, 31, v115
	v_bitop3_b32 v115, v115, v119, s40 bitop3:0x78
	v_xor_b32_e32 v115, 0x8000001c, v115
	v_cvt_f32_f16_e32 v119, v50
	v_cvt_f32_f16_sdwa v102, v50 dst_sel:DWORD dst_unused:UNUSED_PAD src0_sel:WORD_1
	v_ashrrev_i32_e32 v107, 31, v119
	v_bitop3_b32 v119, v119, v107, s40 bitop3:0x78
	v_xor_b32_e32 v119, 0x8000001b, v119
	v_ashrrev_i32_e32 v107, 31, v102
	v_bitop3_b32 v102, v102, v107, s40 bitop3:0x78
	v_xor_b32_e32 v102, 0x8000001a, v102
	v_cvt_f32_f16_e32 v107, v51
	v_cvt_f32_f16_sdwa v106, v51 dst_sel:DWORD dst_unused:UNUSED_PAD src0_sel:WORD_1
	v_ashrrev_i32_e32 v112, 31, v107
	v_bitop3_b32 v107, v107, v112, s40 bitop3:0x78
	v_xor_b32_e32 v107, 0x80000019, v107
	v_ashrrev_i32_e32 v112, 31, v106
	v_bitop3_b32 v106, v106, v112, s40 bitop3:0x78
	v_xor_b32_e32 v106, 0x80000018, v106
	v_cvt_f32_f16_e32 v112, v52
	v_cvt_f32_f16_sdwa v105, v52 dst_sel:DWORD dst_unused:UNUSED_PAD src0_sel:WORD_1
	v_ashrrev_i32_e32 v103, 31, v112
	v_bitop3_b32 v112, v112, v103, s40 bitop3:0x78
	v_xor_b32_e32 v112, 0x80000017, v112
	v_ashrrev_i32_e32 v103, 31, v105
	v_bitop3_b32 v105, v105, v103, s40 bitop3:0x78
	v_xor_b32_e32 v105, 0x80000016, v105
	v_cvt_f32_f16_e32 v103, v53
	v_cvt_f32_f16_sdwa v72, v53 dst_sel:DWORD dst_unused:UNUSED_PAD src0_sel:WORD_1
	v_ashrrev_i32_e32 v98, 31, v103
	v_bitop3_b32 v103, v103, v98, s40 bitop3:0x78
	v_xor_b32_e32 v103, 0x80000015, v103
	v_ashrrev_i32_e32 v98, 31, v72
	v_bitop3_b32 v72, v72, v98, s40 bitop3:0x78
	v_xor_b32_e32 v72, 0x80000014, v72
	v_cvt_f32_f16_e32 v98, v54
	v_cvt_f32_f16_sdwa v114, v54 dst_sel:DWORD dst_unused:UNUSED_PAD src0_sel:WORD_1
	v_ashrrev_i32_e32 v116, 31, v98
	v_bitop3_b32 v98, v98, v116, s40 bitop3:0x78
	v_xor_b32_e32 v98, 0x80000013, v98
	v_ashrrev_i32_e32 v116, 31, v114
	v_bitop3_b32 v114, v114, v116, s40 bitop3:0x78
	v_xor_b32_e32 v114, 0x80000012, v114
	v_cvt_f32_f16_e32 v116, v55
	v_cvt_f32_f16_sdwa v109, v55 dst_sel:DWORD dst_unused:UNUSED_PAD src0_sel:WORD_1
	v_ashrrev_i32_e32 v78, 31, v116
	v_bitop3_b32 v116, v116, v78, s40 bitop3:0x78
	v_xor_b32_e32 v116, 0x80000011, v116
	v_ashrrev_i32_e32 v78, 31, v109
	v_bitop3_b32 v109, v109, v78, s40 bitop3:0x78
	v_xor_b32_e32 v109, 0x80000010, v109
	v_max_u32_e32 v78, v92, v114
	v_min_u32_e32 v114, v92, v114
	v_max_u32_e32 v92, v75, v98
	v_min_u32_e32 v98, v75, v98
	v_max_u32_e32 v75, v108, v109
	v_min_u32_e32 v109, v108, v109
	v_max_u32_e32 v108, v115, v116
	v_min_u32_e32 v116, v115, v116
	v_max_u32_e32 v115, v119, v112
	v_min_u32_e32 v112, v119, v112
	v_max_u32_e32 v119, v102, v107
	v_min_u32_e32 v107, v102, v107
	v_max_u32_e32 v102, v106, v72
	v_min_u32_e32 v72, v106, v72
	v_max_u32_e32 v106, v105, v103
	v_min_u32_e32 v103, v105, v103
	v_max_u32_e32 v105, v78, v119
	v_min_u32_e32 v119, v78, v119
	v_max_u32_e32 v78, v92, v102
	v_min_u32_e32 v102, v92, v102
	v_max_u32_e32 v92, v75, v106
	v_min_u32_e32 v106, v75, v106
	v_max_u32_e32 v75, v108, v115
	v_min_u32_e32 v115, v108, v115
	v_max_u32_e32 v108, v107, v114
	v_min_u32_e32 v114, v107, v114
	v_max_u32_e32 v107, v112, v116
	v_min_u32_e32 v116, v112, v116
	v_max_u32_e32 v112, v103, v109
	v_min_u32_e32 v109, v103, v109
	v_max_u32_e32 v103, v72, v98
	v_min_u32_e32 v98, v72, v98
	v_max_u32_e32 v72, v105, v78
	v_min_u32_e32 v78, v105, v78
	v_max_u32_e32 v105, v92, v75
	v_min_u32_e32 v75, v92, v75
	v_max_u32_e32 v92, v115, v119
	v_min_u32_e32 v119, v115, v119
	v_max_u32_e32 v115, v108, v107
	v_min_u32_e32 v107, v108, v107
	v_max_u32_e32 v108, v102, v106
	v_min_u32_e32 v106, v102, v106
	v_max_u32_e32 v102, v112, v103
	v_min_u32_e32 v103, v112, v103
	v_max_u32_e32 v112, v98, v114
	v_min_u32_e32 v114, v98, v114
	v_max_u32_e32 v98, v116, v109
	v_min_u32_e32 v109, v116, v109
	v_max_u32_e32 v116, v72, v105
	v_min_u32_e32 v105, v72, v105
	v_max_u32_e32 v72, v78, v75
	v_min_u32_e32 v75, v78, v75
	v_max_u32_e32 v78, v92, v102
	v_min_u32_e32 v102, v92, v102
	v_max_u32_e32 v92, v119, v103
	v_min_u32_e32 v103, v119, v103
	v_max_u32_e32 v119, v115, v108
	v_min_u32_e32 v108, v115, v108
	v_max_u32_e32 v115, v107, v106
	v_min_u32_e32 v106, v107, v106
	v_max_u32_e32 v107, v112, v98
; __device__ __forceinline__ unsigned f2key(float f) { const unsigned u = __float_as_uint(f); return (u & 0x80000000u) ? ~u : (u | 0x80000000u); }
; #define CE_DESC(a, b) do { const unsigned _mx = (a) > (b) ? (a) : (b), _mn = (a) > (b) ? (b) : (a); (a) = _mx; (b) = _mn; } while (0)
; __device__ __forceinline__ void sort16_desc(unsigned (&k)[16]) {
; #pragma unroll
;     for (int size = 2; size <= 16; size <<= 1)
; #pragma unroll
;         for (int stride = size >> 1; stride > 0; stride >>= 1)
; #pragma unroll
;             for (int i = 0; i < 16; ++i) { const int j = i ^ stride;
;                 if (j > i) { if ((i & size) == 0) CE_DESC(k[i], k[j]); else CE_DESC(k[j], k[i]); } }
; }
; __device__ __forceinline__ void merge16(unsigned (&a)[16], const unsigned (&b)[16]) {
; #pragma unroll
;     for (int i = 0; i < 16; ++i) a[i] = a[i] > b[15 - i] ? a[i] : b[15 - i];
; #pragma unroll
;     for (int stride = 8; stride > 0; stride >>= 1)
; #pragma unroll
;         for (int i = 0; i < 16; ++i) { const int j = i ^ stride; if (j > i) CE_DESC(a[i], a[j]); }
; }
; __device__ __forceinline__ void peer_tile(const Args& A, LAS unsigned char* lds, int tile) {
;     ...
;                 { const bf16_t* sp = QRY + m * 2048 + hp * 128 + 32 * g;
;                   const u32x4 s0 = *(const u32x4*)sp, s1 = *(const u32x4*)(sp + 8), s2 = *(const u32x4*)(sp + 16), s3 = *(const u32x4*)(sp + 24);
;                   const unsigned sw[16] = {s0.x, s0.y, s0.z, s0.w, s1.x, s1.y, s1.z, s1.w, s2.x, s2.y, s2.z, s2.w, s3.x, s3.y, s3.z, s3.w};
; #pragma unroll
;                   for (int i = 0; i < 16; ++i) {
;                       const float lo = (float)__builtin_bit_cast(_Float16, (unsigned short)(sw[i] & 0xffffu)), hi = (float)__builtin_bit_cast(_Float16, (unsigned short)(sw[i] >> 16));
;                       const unsigned klo = (f2key(lo) & ~127u) | (unsigned)(127 - (32 * g + 2 * i)), khi = (f2key(hi) & ~127u) | (unsigned)(127 - (32 * g + 2 * i + 1));
;                       if (i < 8) { k0[2 * i] = klo; k0[2 * i + 1] = khi; } else { k1[2 * (i - 8)] = klo; k1[2 * (i - 8) + 1] = khi; } } }
;                 sort16_desc(k0); sort16_desc(k1); merge16(k0, k1);
; #pragma unroll
;                 for (int msk = 16; msk <= 32; msk <<= 1) {
; #pragma unroll
;                     for (int i = 0; i < 16; ++i) k1[i] = (unsigned)__shfl_xor((int)k0[i], msk);
;                     merge16(k0, k1); }
	v_min_u32_e32 v98, v112, v98
	v_max_u32_e32 v112, v114, v109
	v_min_u32_e32 v109, v114, v109
	v_max_u32_e32 v114, v72, v105
	v_min_u32_e32 v105, v72, v105
	v_max_u32_e32 v72, v75, v107
	v_min_u32_e32 v107, v75, v107
	v_max_u32_e32 v75, v78, v119
	v_min_u32_e32 v119, v78, v119
	v_max_u32_e32 v78, v92, v108
	v_min_u32_e32 v108, v92, v108
	v_max_u32_e32 v92, v115, v102
	v_min_u32_e32 v102, v115, v102
	v_max_u32_e32 v115, v106, v103
	v_min_u32_e32 v103, v106, v103
	v_max_u32_e32 v106, v112, v98
	v_min_u32_e32 v98, v112, v98
	v_max_u32_e32 v112, v114, v75
	v_min_u32_e32 v75, v114, v75
	v_max_u32_e32 v114, v105, v119
	v_min_u32_e32 v119, v105, v119
	v_max_u32_e32 v105, v78, v92
	v_min_u32_e32 v92, v78, v92
	v_max_u32_e32 v78, v108, v102
	v_min_u32_e32 v102, v108, v102
	v_max_u32_e32 v108, v115, v106
	v_min_u32_e32 v106, v115, v106
	v_max_u32_e32 v115, v103, v98
	v_min_u32_e32 v98, v103, v98
	v_max_u32_e32 v103, v114, v75
	v_min_u32_e32 v75, v114, v75
	v_max_u32_e32 v114, v72, v119
	v_min_u32_e32 v119, v72, v119
	v_max_u32_e32 v72, v108, v107
	v_min_u32_e32 v107, v108, v107
	v_max_u32_e32 v108, v115, v106
	v_min_u32_e32 v106, v115, v106
	v_max_u32_e32 v115, v114, v105
	v_min_u32_e32 v105, v114, v105
	v_max_u32_e32 v114, v119, v92
	v_min_u32_e32 v92, v119, v92
	v_max_u32_e32 v119, v78, v72
	v_min_u32_e32 v72, v78, v72
	v_max_u32_e32 v78, v102, v107
	v_min_u32_e32 v107, v102, v107
	v_max_u32_e32 v102, v115, v75
	v_min_u32_e32 v75, v115, v75
	v_max_u32_e32 v115, v105, v114
	v_min_u32_e32 v114, v105, v114
	v_max_u32_e32 v105, v119, v92
	v_min_u32_e32 v92, v119, v92
	v_max_u32_e32 v119, v72, v78
	v_min_u32_e32 v78, v72, v78
	v_max_u32_e32 v72, v108, v107
	v_min_u32_e32 v107, v108, v107
	v_max_u32_e32 v108, v114, v105
	v_min_u32_e32 v105, v114, v105
	v_max_u32_e32 v114, v92, v119
	v_min_u32_e32 v119, v92, v119
	v_max_u32_e32 v83, v83, v109
	v_max_u32_e32 v110, v110, v98
	v_max_u32_e32 v87, v87, v106
	v_max_u32_e32 v117, v117, v107
	v_max_u32_e32 v91, v91, v72
	v_max_u32_e32 v118, v118, v78
	v_max_u32_e32 v104, v104, v119
	v_max_u32_e32 v111, v111, v114
	v_max_u32_e32 v97, v97, v105
	v_max_u32_e32 v89, v89, v108
	v_max_u32_e32 v82, v82, v115
	v_max_u32_e32 v70, v70, v75
	v_max_u32_e32 v73, v73, v102
	v_max_u32_e32 v79, v79, v103
	v_max_u32_e32 v90, v90, v112
	v_max_u32_e32 v96, v96, v116
	v_max_u32_e32 v109, v83, v97
	v_min_u32_e32 v97, v83, v97
	v_max_u32_e32 v83, v110, v89
	v_min_u32_e32 v89, v110, v89
	v_max_u32_e32 v110, v87, v82
	v_min_u32_e32 v82, v87, v82
	v_max_u32_e32 v87, v117, v70
	v_min_u32_e32 v70, v117, v70
	v_max_u32_e32 v117, v91, v73
	v_min_u32_e32 v73, v91, v73
	v_max_u32_e32 v91, v118, v79
	v_min_u32_e32 v79, v118, v79
	v_max_u32_e32 v118, v104, v90
	v_min_u32_e32 v90, v104, v90
	v_max_u32_e32 v104, v111, v96
	v_min_u32_e32 v96, v111, v96
	v_max_u32_e32 v111, v109, v117
	v_min_u32_e32 v117, v109, v117
	v_max_u32_e32 v109, v83, v91
	v_min_u32_e32 v91, v83, v91
	v_max_u32_e32 v83, v110, v118
	v_min_u32_e32 v118, v110, v118
	v_max_u32_e32 v110, v87, v104
	v_min_u32_e32 v104, v87, v104
	v_max_u32_e32 v87, v97, v73
	v_min_u32_e32 v73, v97, v73
	v_max_u32_e32 v97, v89, v79
	v_min_u32_e32 v79, v89, v79
	v_max_u32_e32 v89, v82, v90
	v_min_u32_e32 v90, v82, v90
	v_max_u32_e32 v82, v70, v96
	v_min_u32_e32 v96, v70, v96
	v_max_u32_e32 v70, v111, v83
	v_min_u32_e32 v83, v111, v83
	v_max_u32_e32 v111, v109, v110
	v_min_u32_e32 v110, v109, v110
	v_max_u32_e32 v109, v117, v118
	v_min_u32_e32 v118, v117, v118
	v_max_u32_e32 v117, v91, v104
	v_min_u32_e32 v104, v91, v104
	v_max_u32_e32 v91, v87, v89
	v_min_u32_e32 v89, v87, v89
	v_max_u32_e32 v87, v97, v82
	v_min_u32_e32 v82, v97, v82
	v_max_u32_e32 v97, v73, v90
	v_min_u32_e32 v90, v73, v90
	v_max_u32_e32 v73, v79, v96
	v_min_u32_e32 v96, v79, v96
	v_max_u32_e32 v79, v70, v111
	v_min_u32_e32 v111, v70, v111
	v_max_u32_e32 v70, v83, v110
	v_min_u32_e32 v110, v83, v110
	v_max_u32_e32 v83, v109, v117
	v_min_u32_e32 v117, v109, v117
	v_max_u32_e32 v109, v118, v104
	v_min_u32_e32 v104, v118, v104
	v_max_u32_e32 v118, v91, v87
	v_min_u32_e32 v87, v91, v87
	v_max_u32_e32 v91, v89, v82
	v_min_u32_e32 v82, v89, v82
	v_max_u32_e32 v89, v97, v73
	v_min_u32_e32 v73, v97, v73
	v_max_u32_e32 v97, v90, v96
	v_min_u32_e32 v96, v90, v96
	v_cvt_f32_f16_e32 v90, v56
	v_cvt_f32_f16_sdwa v98, v56 dst_sel:DWORD dst_unused:UNUSED_PAD src0_sel:WORD_1
	v_ashrrev_i32_e32 v106, 31, v90
	v_bitop3_b32 v90, v90, v106, s40 bitop3:0x78
	v_xor_b32_e32 v90, 0x8000000f, v90
	v_ashrrev_i32_e32 v106, 31, v98
	v_bitop3_b32 v98, v98, v106, s40 bitop3:0x78
	v_xor_b32_e32 v98, 0x8000000e, v98
	v_cvt_f32_f16_e32 v106, v57
	v_cvt_f32_f16_sdwa v107, v57 dst_sel:DWORD dst_unused:UNUSED_PAD src0_sel:WORD_1
	v_ashrrev_i32_e32 v72, 31, v106
	v_bitop3_b32 v106, v106, v72, s40 bitop3:0x78
	v_xor_b32_e32 v106, 0x8000000d, v106
	v_ashrrev_i32_e32 v72, 31, v107
	v_bitop3_b32 v107, v107, v72, s40 bitop3:0x78
	v_xor_b32_e32 v107, 0x8000000c, v107
	v_cvt_f32_f16_e32 v72, v58
	v_cvt_f32_f16_sdwa v78, v58 dst_sel:DWORD dst_unused:UNUSED_PAD src0_sel:WORD_1
	v_ashrrev_i32_e32 v119, 31, v72
	v_bitop3_b32 v72, v72, v119, s40 bitop3:0x78
	v_xor_b32_e32 v72, 0x8000000b, v72
	v_ashrrev_i32_e32 v119, 31, v78
	v_bitop3_b32 v78, v78, v119, s40 bitop3:0x78
	v_xor_b32_e32 v78, 0x8000000a, v78
	v_cvt_f32_f16_e32 v119, v59
	v_cvt_f32_f16_sdwa v114, v59 dst_sel:DWORD dst_unused:UNUSED_PAD src0_sel:WORD_1
	v_ashrrev_i32_e32 v105, 31, v119
	v_bitop3_b32 v119, v119, v105, s40 bitop3:0x78
	v_xor_b32_e32 v119, 0x80000009, v119
	v_ashrrev_i32_e32 v105, 31, v114
	v_bitop3_b32 v114, v114, v105, s40 bitop3:0x78
	v_xor_b32_e32 v114, 0x80000008, v114
	v_cvt_f32_f16_e32 v105, v60
; __device__ __forceinline__ unsigned f2key(float f) { const unsigned u = __float_as_uint(f); return (u & 0x80000000u) ? ~u : (u | 0x80000000u); }
; #define CE_DESC(a, b) do { const unsigned _mx = (a) > (b) ? (a) : (b), _mn = (a) > (b) ? (b) : (a); (a) = _mx; (b) = _mn; } while (0)
; __device__ __forceinline__ void sort16_desc(unsigned (&k)[16]) {
; #pragma unroll
;     for (int size = 2; size <= 16; size <<= 1)
; #pragma unroll
;         for (int stride = size >> 1; stride > 0; stride >>= 1)
; #pragma unroll
;             for (int i = 0; i < 16; ++i) { const int j = i ^ stride;
;                 if (j > i) { if ((i & size) == 0) CE_DESC(k[i], k[j]); else CE_DESC(k[j], k[i]); } }
; }
; __device__ __forceinline__ void merge16(unsigned (&a)[16], const unsigned (&b)[16]) {
; #pragma unroll
;     for (int i = 0; i < 16; ++i) a[i] = a[i] > b[15 - i] ? a[i] : b[15 - i];
; #pragma unroll
;     for (int stride = 8; stride > 0; stride >>= 1)
; #pragma unroll
;         for (int i = 0; i < 16; ++i) { const int j = i ^ stride; if (j > i) CE_DESC(a[i], a[j]); }
; }
; __device__ __forceinline__ void peer_tile(const Args& A, LAS unsigned char* lds, int tile) {
;     ...
;                 { const bf16_t* sp = QRY + m * 2048 + hp * 128 + 32 * g;
;                   const u32x4 s0 = *(const u32x4*)sp, s1 = *(const u32x4*)(sp + 8), s2 = *(const u32x4*)(sp + 16), s3 = *(const u32x4*)(sp + 24);
;                   const unsigned sw[16] = {s0.x, s0.y, s0.z, s0.w, s1.x, s1.y, s1.z, s1.w, s2.x, s2.y, s2.z, s2.w, s3.x, s3.y, s3.z, s3.w};
; #pragma unroll
;                   for (int i = 0; i < 16; ++i) {
;                       const float lo = (float)__builtin_bit_cast(_Float16, (unsigned short)(sw[i] & 0xffffu)), hi = (float)__builtin_bit_cast(_Float16, (unsigned short)(sw[i] >> 16));
;                       const unsigned klo = (f2key(lo) & ~127u) | (unsigned)(127 - (32 * g + 2 * i)), khi = (f2key(hi) & ~127u) | (unsigned)(127 - (32 * g + 2 * i + 1));
;                       if (i < 8) { k0[2 * i] = klo; k0[2 * i + 1] = khi; } else { k1[2 * (i - 8)] = klo; k1[2 * (i - 8) + 1] = khi; } } }
;                 sort16_desc(k0); sort16_desc(k1); merge16(k0, k1);
; #pragma unroll
;                 for (int msk = 16; msk <= 32; msk <<= 1) {
; #pragma unroll
;                     for (int i = 0; i < 16; ++i) k1[i] = (unsigned)__shfl_xor((int)k0[i], msk);
;                     merge16(k0, k1); }
	v_cvt_f32_f16_sdwa v108, v60 dst_sel:DWORD dst_unused:UNUSED_PAD src0_sel:WORD_1
	v_ashrrev_i32_e32 v115, 31, v105
	v_bitop3_b32 v105, v105, v115, s40 bitop3:0x78
	v_xor_b32_e32 v105, 0x80000007, v105
	v_ashrrev_i32_e32 v115, 31, v108
	v_bitop3_b32 v108, v108, v115, s40 bitop3:0x78
	v_xor_b32_e32 v108, 0x80000006, v108
	v_cvt_f32_f16_e32 v115, v61
	v_cvt_f32_f16_sdwa v75, v61 dst_sel:DWORD dst_unused:UNUSED_PAD src0_sel:WORD_1
	v_ashrrev_i32_e32 v102, 31, v115
	v_bitop3_b32 v115, v115, v102, s40 bitop3:0x78
	v_xor_b32_e32 v115, 0x80000005, v115
	v_ashrrev_i32_e32 v102, 31, v75
	v_bitop3_b32 v75, v75, v102, s40 bitop3:0x78
	v_xor_b32_e32 v75, 0x80000004, v75
	v_cvt_f32_f16_e32 v102, v62
	v_cvt_f32_f16_sdwa v103, v62 dst_sel:DWORD dst_unused:UNUSED_PAD src0_sel:WORD_1
	v_ashrrev_i32_e32 v112, 31, v102
	v_bitop3_b32 v102, v102, v112, s40 bitop3:0x78
	v_xor_b32_e32 v102, 0x80000003, v102
	v_ashrrev_i32_e32 v112, 31, v103
	v_bitop3_b32 v103, v103, v112, s40 bitop3:0x78
	v_xor_b32_e32 v103, 0x80000002, v103
	v_cvt_f32_f16_e32 v112, v63
	v_cvt_f32_f16_sdwa v116, v63 dst_sel:DWORD dst_unused:UNUSED_PAD src0_sel:WORD_1
	v_ashrrev_i32_e32 v92, 31, v112
	v_bitop3_b32 v112, v112, v92, s40 bitop3:0x78
	v_xor_b32_e32 v112, 0x80000001, v112
	v_ashrrev_i32_e32 v92, 31, v116
	v_bitop3_b32 v116, v116, v92, s40 bitop3:0x78
	v_xor_b32_e32 v116, 0x80000000, v116
	v_max_u32_e32 v92, v90, v103
	v_min_u32_e32 v103, v90, v103
	v_max_u32_e32 v90, v98, v102
	v_min_u32_e32 v102, v98, v102
	v_max_u32_e32 v98, v106, v116
	v_min_u32_e32 v116, v106, v116
	v_max_u32_e32 v106, v107, v112
	v_min_u32_e32 v112, v107, v112
	v_max_u32_e32 v107, v72, v105
	v_min_u32_e32 v105, v72, v105
	v_max_u32_e32 v72, v78, v119
	v_min_u32_e32 v119, v78, v119
	v_max_u32_e32 v78, v114, v75
	v_min_u32_e32 v75, v114, v75
	v_max_u32_e32 v114, v108, v115
	v_min_u32_e32 v115, v108, v115
	v_max_u32_e32 v108, v92, v72
	v_min_u32_e32 v72, v92, v72
	v_max_u32_e32 v92, v90, v78
	v_min_u32_e32 v78, v90, v78
	v_max_u32_e32 v90, v98, v114
	v_min_u32_e32 v114, v98, v114
	v_max_u32_e32 v98, v106, v107
	v_min_u32_e32 v107, v106, v107
	v_max_u32_e32 v106, v119, v103
	v_min_u32_e32 v103, v119, v103
	v_max_u32_e32 v119, v105, v112
	v_min_u32_e32 v112, v105, v112
	v_max_u32_e32 v105, v115, v116
	v_min_u32_e32 v116, v115, v116
	v_max_u32_e32 v115, v75, v102
	v_min_u32_e32 v102, v75, v102
	v_max_u32_e32 v75, v108, v92
	v_min_u32_e32 v92, v108, v92
	v_max_u32_e32 v108, v90, v98
	v_min_u32_e32 v98, v90, v98
	v_max_u32_e32 v90, v107, v72
	v_min_u32_e32 v72, v107, v72
	v_max_u32_e32 v107, v106, v119
	v_min_u32_e32 v119, v106, v119
	v_max_u32_e32 v106, v78, v114
	v_min_u32_e32 v114, v78, v114
	v_max_u32_e32 v78, v105, v115
	v_min_u32_e32 v115, v105, v115
	v_max_u32_e32 v105, v102, v103
	v_min_u32_e32 v103, v102, v103
	v_max_u32_e32 v102, v112, v116
	v_min_u32_e32 v116, v112, v116
	v_max_u32_e32 v112, v75, v108
	v_min_u32_e32 v108, v75, v108
	v_max_u32_e32 v75, v92, v98
	v_min_u32_e32 v98, v92, v98
	v_max_u32_e32 v92, v90, v78
	v_min_u32_e32 v78, v90, v78
	v_max_u32_e32 v90, v72, v115
	v_min_u32_e32 v115, v72, v115
	v_max_u32_e32 v72, v107, v106
	v_min_u32_e32 v106, v107, v106
	v_max_u32_e32 v107, v119, v114
	v_min_u32_e32 v114, v119, v114
	v_max_u32_e32 v119, v105, v102
	v_min_u32_e32 v102, v105, v102
	v_max_u32_e32 v105, v103, v116
	v_min_u32_e32 v116, v103, v116
	v_max_u32_e32 v103, v75, v108
	v_min_u32_e32 v108, v75, v108
	v_max_u32_e32 v75, v98, v119
	v_min_u32_e32 v119, v98, v119
	v_max_u32_e32 v98, v92, v72
	v_min_u32_e32 v72, v92, v72
	v_max_u32_e32 v92, v90, v106
	v_min_u32_e32 v106, v90, v106
	v_max_u32_e32 v90, v107, v78
	v_min_u32_e32 v78, v107, v78
	v_max_u32_e32 v107, v114, v115
	v_min_u32_e32 v115, v114, v115
	v_max_u32_e32 v114, v105, v102
	v_min_u32_e32 v102, v105, v102
	v_max_u32_e32 v105, v103, v98
	v_min_u32_e32 v98, v103, v98
	v_max_u32_e32 v103, v108, v72
	v_min_u32_e32 v72, v108, v72
	v_max_u32_e32 v108, v92, v90
	v_min_u32_e32 v90, v92, v90
	v_max_u32_e32 v92, v106, v78
	v_min_u32_e32 v78, v106, v78
	v_max_u32_e32 v106, v107, v114
	v_min_u32_e32 v114, v107, v114
	v_max_u32_e32 v107, v115, v102
	v_min_u32_e32 v102, v115, v102
	v_max_u32_e32 v115, v103, v98
	v_min_u32_e32 v98, v103, v98
	v_max_u32_e32 v103, v75, v72
	v_min_u32_e32 v72, v75, v72
	v_max_u32_e32 v75, v106, v119
	v_min_u32_e32 v119, v106, v119
	v_max_u32_e32 v106, v107, v114
	v_min_u32_e32 v114, v107, v114
	v_max_u32_e32 v107, v103, v108
	v_min_u32_e32 v108, v103, v108
	v_max_u32_e32 v103, v72, v90
	v_min_u32_e32 v90, v72, v90
	v_max_u32_e32 v72, v92, v75
	v_min_u32_e32 v75, v92, v75
	v_max_u32_e32 v92, v78, v119
	v_min_u32_e32 v119, v78, v119
	v_max_u32_e32 v78, v107, v98
	v_min_u32_e32 v98, v107, v98
	v_max_u32_e32 v107, v108, v103
	v_min_u32_e32 v103, v108, v103
	v_max_u32_e32 v108, v72, v90
	v_min_u32_e32 v90, v72, v90
	v_max_u32_e32 v72, v75, v92
	v_min_u32_e32 v92, v75, v92
	v_max_u32_e32 v75, v106, v119
	v_min_u32_e32 v119, v106, v119
	v_max_u32_e32 v106, v103, v108
	v_min_u32_e32 v108, v103, v108
	v_max_u32_e32 v103, v90, v72
	v_min_u32_e32 v72, v90, v72
	v_max_u32_e32 v79, v79, v116
	v_max_u32_e32 v111, v111, v102
	v_max_u32_e32 v70, v70, v114
	v_max_u32_e32 v110, v110, v119
	v_max_u32_e32 v83, v83, v75
	v_max_u32_e32 v117, v117, v92
	v_max_u32_e32 v109, v109, v72
	v_max_u32_e32 v104, v104, v103
	v_max_u32_e32 v118, v118, v108
	v_max_u32_e32 v87, v87, v106
	v_max_u32_e32 v91, v91, v107
	v_max_u32_e32 v82, v82, v98
	v_max_u32_e32 v89, v89, v78
	v_max_u32_e32 v73, v73, v115
	v_max_u32_e32 v97, v97, v105
	v_max_u32_e32 v96, v96, v112
	v_max_u32_e32 v116, v79, v118
	v_min_u32_e32 v118, v79, v118
	v_max_u32_e32 v79, v111, v87
; __device__ __forceinline__ float key2f(unsigned k) { const unsigned u = (k & 0x80000000u) ? (k & 0x7fffffffu) : ~k; return __uint_as_float(u); }
; #define CE_DESC(a, b) do { const unsigned _mx = (a) > (b) ? (a) : (b), _mn = (a) > (b) ? (b) : (a); (a) = _mx; (b) = _mn; } while (0)
; __device__ __forceinline__ void merge16(unsigned (&a)[16], const unsigned (&b)[16]) {
; #pragma unroll
;     for (int i = 0; i < 16; ++i) a[i] = a[i] > b[15 - i] ? a[i] : b[15 - i];
; #pragma unroll
;     for (int stride = 8; stride > 0; stride >>= 1)
; #pragma unroll
;         for (int i = 0; i < 16; ++i) { const int j = i ^ stride; if (j > i) CE_DESC(a[i], a[j]); }
; }
; __device__ __forceinline__ void peer_tile(const Args& A, LAS unsigned char* lds, int tile) {
;     ...
;                 for (int i = 0; i < 16; ++i) L2[p][i] = (g & 2) ? ((g & 1) ? LA[3][p][i] : LA[2][p][i]) : ((g & 1) ? LA[1][p][i] : LA[0][p][i]);
;             float va[16], vb[16];
; #pragma unroll
;             for (int i = 0; i < 16; ++i) { va[i] = key2f(L2[0][i] & ~127u); vb[i] = key2f(L2[1][i] & ~127u); idx[i] = 127u - (L2[0][i] & 127u); idx[16 + i] = 127u - (L2[1][i] & 127u); }
	v_min_u32_e32 v87, v111, v87
	v_max_u32_e32 v111, v70, v91
	v_min_u32_e32 v91, v70, v91
	v_max_u32_e32 v70, v110, v82
	v_min_u32_e32 v82, v110, v82
	v_max_u32_e32 v110, v83, v89
	v_min_u32_e32 v89, v83, v89
	v_max_u32_e32 v83, v117, v73
	v_min_u32_e32 v73, v117, v73
	v_max_u32_e32 v117, v109, v97
	v_min_u32_e32 v97, v109, v97
	v_max_u32_e32 v109, v104, v96
	v_min_u32_e32 v96, v104, v96
	v_max_u32_e32 v104, v116, v110
	v_min_u32_e32 v110, v116, v110
	v_max_u32_e32 v116, v79, v83
	v_min_u32_e32 v83, v79, v83
	v_max_u32_e32 v79, v111, v117
	v_min_u32_e32 v117, v111, v117
	v_max_u32_e32 v111, v70, v109
	v_min_u32_e32 v109, v70, v109
	v_max_u32_e32 v70, v118, v89
	v_min_u32_e32 v89, v118, v89
	v_max_u32_e32 v118, v87, v73
	v_min_u32_e32 v73, v87, v73
	v_max_u32_e32 v87, v91, v97
	v_min_u32_e32 v97, v91, v97
	v_max_u32_e32 v91, v82, v96
	v_min_u32_e32 v96, v82, v96
	v_max_u32_e32 v82, v104, v79
	v_min_u32_e32 v79, v104, v79
	v_max_u32_e32 v104, v116, v111
	v_min_u32_e32 v111, v116, v111
	v_max_u32_e32 v116, v110, v117
	v_min_u32_e32 v117, v110, v117
	v_max_u32_e32 v110, v83, v109
	v_min_u32_e32 v109, v83, v109
	v_max_u32_e32 v83, v70, v87
	v_min_u32_e32 v87, v70, v87
	v_max_u32_e32 v70, v118, v91
	v_min_u32_e32 v91, v118, v91
	v_max_u32_e32 v118, v89, v97
	v_min_u32_e32 v97, v89, v97
	v_max_u32_e32 v89, v73, v96
	v_min_u32_e32 v96, v73, v96
	v_max_u32_e32 v73, v82, v104
	v_min_u32_e32 v104, v82, v104
	v_max_u32_e32 v82, v79, v111
	v_min_u32_e32 v111, v79, v111
	v_max_u32_e32 v79, v116, v110
	v_min_u32_e32 v110, v116, v110
	v_max_u32_e32 v116, v117, v109
	v_min_u32_e32 v109, v117, v109
	v_max_u32_e32 v117, v83, v70
	v_min_u32_e32 v70, v83, v70
	v_max_u32_e32 v83, v87, v91
	v_min_u32_e32 v91, v87, v91
	v_max_u32_e32 v87, v118, v89
	v_min_u32_e32 v89, v118, v89
	v_max_u32_e32 v118, v97, v96
	v_min_u32_e32 v96, v97, v96
	v_xor_b32_e32 v97, 0x7f, v71
	v_xor_b32_e32 v102, 0x7f, v88
	v_and_b32_e32 v97, 0x7f, v97
	v_and_b32_e32 v102, 0x7f, v102
	ds_write2_b32 v67, v97, v102 offset0:0 offset1:1
	v_xor_b32_e32 v102, 0x7f, v74
	v_xor_b32_e32 v97, 0x7f, v95
	v_and_b32_e32 v102, 0x7f, v102
	v_and_b32_e32 v97, 0x7f, v97
	ds_write2_b32 v67, v102, v97 offset0:2 offset1:3
	v_xor_b32_e32 v97, 0x7f, v86
	v_xor_b32_e32 v102, 0x7f, v94
	v_and_b32_e32 v97, 0x7f, v97
	v_and_b32_e32 v102, 0x7f, v102
	ds_write2_b32 v67, v97, v102 offset0:4 offset1:5
	v_xor_b32_e32 v102, 0x7f, v99
	v_xor_b32_e32 v97, 0x7f, v93
	v_and_b32_e32 v102, 0x7f, v102
	v_and_b32_e32 v97, 0x7f, v97
	ds_write2_b32 v67, v102, v97 offset0:6 offset1:7
	v_xor_b32_e32 v97, 0x7f, v100
	v_xor_b32_e32 v102, 0x7f, v76
	v_and_b32_e32 v97, 0x7f, v97
	v_and_b32_e32 v102, 0x7f, v102
	ds_write2_b32 v67, v97, v102 offset0:8 offset1:9
	v_xor_b32_e32 v102, 0x7f, v81
	v_xor_b32_e32 v97, 0x7f, v80
	v_and_b32_e32 v102, 0x7f, v102
	v_and_b32_e32 v97, 0x7f, v97
	ds_write2_b32 v67, v102, v97 offset0:10 offset1:11
	v_xor_b32_e32 v97, 0x7f, v77
	v_xor_b32_e32 v102, 0x7f, v84
	v_and_b32_e32 v97, 0x7f, v97
	v_and_b32_e32 v102, 0x7f, v102
	ds_write2_b32 v67, v97, v102 offset0:12 offset1:13
	v_xor_b32_e32 v102, 0x7f, v101
	v_xor_b32_e32 v97, 0x7f, v85
	v_and_b32_e32 v102, 0x7f, v102
	v_and_b32_e32 v97, 0x7f, v97
	ds_write2_b32 v67, v102, v97 offset0:14 offset1:15
	v_xor_b32_e32 v97, 0x7f, v73
	v_xor_b32_e32 v102, 0x7f, v104
	v_and_b32_e32 v97, 0x7f, v97
	v_and_b32_e32 v102, 0x7f, v102
	ds_write2_b32 v67, v97, v102 offset0:16 offset1:17
	v_xor_b32_e32 v102, 0x7f, v82
	v_xor_b32_e32 v97, 0x7f, v111
	v_and_b32_e32 v102, 0x7f, v102
	v_and_b32_e32 v97, 0x7f, v97
	ds_write2_b32 v67, v102, v97 offset0:18 offset1:19
	v_xor_b32_e32 v97, 0x7f, v79
	v_xor_b32_e32 v102, 0x7f, v110
	v_and_b32_e32 v97, 0x7f, v97
	v_and_b32_e32 v102, 0x7f, v102
	ds_write2_b32 v67, v97, v102 offset0:20 offset1:21
	v_xor_b32_e32 v102, 0x7f, v116
	v_xor_b32_e32 v97, 0x7f, v109
	v_and_b32_e32 v102, 0x7f, v102
	v_and_b32_e32 v97, 0x7f, v97
	ds_write2_b32 v67, v102, v97 offset0:22 offset1:23
	v_xor_b32_e32 v97, 0x7f, v117
	v_xor_b32_e32 v102, 0x7f, v70
	v_and_b32_e32 v97, 0x7f, v97
	v_and_b32_e32 v102, 0x7f, v102
	ds_write2_b32 v67, v97, v102 offset0:24 offset1:25
	v_xor_b32_e32 v102, 0x7f, v83
	v_xor_b32_e32 v97, 0x7f, v91
	v_and_b32_e32 v102, 0x7f, v102
	v_and_b32_e32 v97, 0x7f, v97
	ds_write2_b32 v67, v102, v97 offset0:26 offset1:27
	v_xor_b32_e32 v97, 0x7f, v87
	v_xor_b32_e32 v102, 0x7f, v89
	v_and_b32_e32 v97, 0x7f, v97
	v_and_b32_e32 v102, 0x7f, v102
	ds_write2_b32 v67, v97, v102 offset0:28 offset1:29
	v_xor_b32_e32 v102, 0x7f, v118
	v_xor_b32_e32 v97, 0x7f, v96
	v_and_b32_e32 v102, 0x7f, v102
	v_and_b32_e32 v97, 0x7f, v97
	ds_write2_b32 v67, v102, v97 offset0:30 offset1:31
	v_ashrrev_i32_e32 v102, 31, v71
	v_and_b32_e32 v97, 0xffffff80, v71
	v_bitop3_b32 v97, v97, v102, s41 bitop3:0x87
	v_ashrrev_i32_e32 v114, 31, v88
	v_and_b32_e32 v102, 0xffffff80, v88
	v_bitop3_b32 v102, v102, v114, s41 bitop3:0x87
	v_ashrrev_i32_e32 v119, 31, v74
	v_and_b32_e32 v114, 0xffffff80, v74
	v_bitop3_b32 v114, v114, v119, s41 bitop3:0x87
	v_ashrrev_i32_e32 v75, 31, v95
	v_and_b32_e32 v119, 0xffffff80, v95
	v_bitop3_b32 v119, v119, v75, s41 bitop3:0x87
	v_ashrrev_i32_e32 v92, 31, v86
	v_and_b32_e32 v75, 0xffffff80, v86
	v_bitop3_b32 v75, v75, v92, s41 bitop3:0x87
	v_ashrrev_i32_e32 v72, 31, v94
	v_and_b32_e32 v92, 0xffffff80, v94
	v_bitop3_b32 v92, v92, v72, s41 bitop3:0x87
	v_ashrrev_i32_e32 v103, 31, v99
	v_and_b32_e32 v72, 0xffffff80, v99
	v_bitop3_b32 v72, v72, v103, s41 bitop3:0x87
	v_ashrrev_i32_e32 v108, 31, v93
	v_and_b32_e32 v103, 0xffffff80, v93
	v_bitop3_b32 v103, v103, v108, s41 bitop3:0x87
	v_ashrrev_i32_e32 v106, 31, v100
	v_and_b32_e32 v108, 0xffffff80, v100
; __device__ __forceinline__ float key2f(unsigned k) { const unsigned u = (k & 0x80000000u) ? (k & 0x7fffffffu) : ~k; return __uint_as_float(u); }
; #define CK(i, j) ((f2key(va[i] + vb[j]) & ~255u) | (unsigned)(255 - (16 * (i) + (j))))
; __device__ __forceinline__ void peer_tile(const Args& A, LAS unsigned char* lds, int tile) {
;     ...
;             for (int i = 0; i < 16; ++i) { va[i] = key2f(L2[0][i] & ~127u); vb[i] = key2f(L2[1][i] & ~127u); idx[i] = 127u - (L2[0][i] & 127u); idx[16 + i] = 127u - (L2[1][i] & 127u); }
;     ...
;             unsigned Lf[16], Bt[16];
; #pragma unroll
;             for (int j = 0; j < 16; ++j) Lf[j] = CK(0, j);
; #pragma unroll
;             for (int j = 0; j < 8; ++j) Bt[j] = CK(1, j);
	v_bitop3_b32 v108, v108, v106, s41 bitop3:0x87
	v_ashrrev_i32_e32 v107, 31, v76
	v_and_b32_e32 v106, 0xffffff80, v76
	v_bitop3_b32 v106, v106, v107, s41 bitop3:0x87
	v_ashrrev_i32_e32 v98, 31, v81
	v_and_b32_e32 v107, 0xffffff80, v81
	v_bitop3_b32 v107, v107, v98, s41 bitop3:0x87
	v_ashrrev_i32_e32 v78, 31, v80
	v_and_b32_e32 v98, 0xffffff80, v80
	v_bitop3_b32 v98, v98, v78, s41 bitop3:0x87
	v_ashrrev_i32_e32 v115, 31, v77
	v_and_b32_e32 v78, 0xffffff80, v77
	v_bitop3_b32 v78, v78, v115, s41 bitop3:0x87
	v_ashrrev_i32_e32 v105, 31, v84
	v_and_b32_e32 v115, 0xffffff80, v84
	v_bitop3_b32 v115, v115, v105, s41 bitop3:0x87
	v_ashrrev_i32_e32 v112, 31, v101
	v_and_b32_e32 v105, 0xffffff80, v101
	v_bitop3_b32 v105, v105, v112, s41 bitop3:0x87
	v_ashrrev_i32_e32 v90, 31, v85
	v_and_b32_e32 v112, 0xffffff80, v85
	v_bitop3_b32 v112, v112, v90, s41 bitop3:0x87
	v_ashrrev_i32_e32 v120, 31, v73
	v_and_b32_e32 v90, 0xffffff80, v73
	v_bitop3_b32 v90, v90, v120, s41 bitop3:0x87
	v_ashrrev_i32_e32 v121, 31, v104
	v_and_b32_e32 v120, 0xffffff80, v104
	v_bitop3_b32 v120, v120, v121, s41 bitop3:0x87
	v_ashrrev_i32_e32 v122, 31, v82
	v_and_b32_e32 v121, 0xffffff80, v82
	v_bitop3_b32 v121, v121, v122, s41 bitop3:0x87
	v_ashrrev_i32_e32 v123, 31, v111
	v_and_b32_e32 v122, 0xffffff80, v111
	v_bitop3_b32 v122, v122, v123, s41 bitop3:0x87
	v_ashrrev_i32_e32 v124, 31, v79
	v_and_b32_e32 v123, 0xffffff80, v79
	v_bitop3_b32 v123, v123, v124, s41 bitop3:0x87
	v_ashrrev_i32_e32 v125, 31, v110
	v_and_b32_e32 v124, 0xffffff80, v110
	v_bitop3_b32 v124, v124, v125, s41 bitop3:0x87
	v_ashrrev_i32_e32 v126, 31, v116
	v_and_b32_e32 v125, 0xffffff80, v116
	v_bitop3_b32 v125, v125, v126, s41 bitop3:0x87
	v_ashrrev_i32_e32 v127, 31, v109
	v_and_b32_e32 v126, 0xffffff80, v109
	v_bitop3_b32 v126, v126, v127, s41 bitop3:0x87
	v_ashrrev_i32_e32 v128, 31, v117
	v_and_b32_e32 v127, 0xffffff80, v117
	v_bitop3_b32 v127, v127, v128, s41 bitop3:0x87
	v_ashrrev_i32_e32 v129, 31, v70
	v_and_b32_e32 v128, 0xffffff80, v70
	v_bitop3_b32 v128, v128, v129, s41 bitop3:0x87
	v_ashrrev_i32_e32 v130, 31, v83
	v_and_b32_e32 v129, 0xffffff80, v83
	v_bitop3_b32 v129, v129, v130, s41 bitop3:0x87
	v_ashrrev_i32_e32 v131, 31, v91
	v_and_b32_e32 v130, 0xffffff80, v91
	v_bitop3_b32 v130, v130, v131, s41 bitop3:0x87
	v_ashrrev_i32_e32 v132, 31, v87
	v_and_b32_e32 v131, 0xffffff80, v87
	v_bitop3_b32 v131, v131, v132, s41 bitop3:0x87
	v_ashrrev_i32_e32 v133, 31, v89
	v_and_b32_e32 v132, 0xffffff80, v89
	v_bitop3_b32 v132, v132, v133, s41 bitop3:0x87
	v_ashrrev_i32_e32 v134, 31, v118
	v_and_b32_e32 v133, 0xffffff80, v118
	v_bitop3_b32 v133, v133, v134, s41 bitop3:0x87
	v_ashrrev_i32_e32 v135, 31, v96
	v_and_b32_e32 v134, 0xffffff80, v96
	v_bitop3_b32 v134, v134, v135, s41 bitop3:0x87
	v_add_f32_e32 v96, v97, v90
	v_ashrrev_i32_e32 v118, 31, v96
	v_and_b32_e32 v96, 0xffffff00, v96
	v_lshl_or_b32 v118, v118, 8, s33
	v_xor_b32_e32 v96, v96, v118
	v_xor_b32_e32 v96, 0xff, v96
	v_add_f32_e32 v118, v97, v120
	v_ashrrev_i32_e32 v89, 31, v118
	v_and_b32_e32 v118, 0xffffff00, v118
	v_lshl_or_b32 v89, v89, 8, s33
	v_xor_b32_e32 v118, v118, v89
	v_xor_b32_e32 v118, 0xfe, v118
	v_add_f32_e32 v89, v97, v121
	v_ashrrev_i32_e32 v87, 31, v89
	v_and_b32_e32 v89, 0xffffff00, v89
	v_lshl_or_b32 v87, v87, 8, s33
	v_xor_b32_e32 v89, v89, v87
	v_xor_b32_e32 v89, 0xfd, v89
	v_add_f32_e32 v87, v97, v122
	v_ashrrev_i32_e32 v91, 31, v87
	v_and_b32_e32 v87, 0xffffff00, v87
	v_lshl_or_b32 v91, v91, 8, s33
	v_xor_b32_e32 v87, v87, v91
	v_xor_b32_e32 v87, 0xfc, v87
	v_add_f32_e32 v91, v97, v123
	v_ashrrev_i32_e32 v83, 31, v91
	v_and_b32_e32 v91, 0xffffff00, v91
	v_lshl_or_b32 v83, v83, 8, s33
	v_xor_b32_e32 v91, v91, v83
	v_xor_b32_e32 v91, 0xfb, v91
	v_add_f32_e32 v83, v97, v124
	v_ashrrev_i32_e32 v70, 31, v83
	v_and_b32_e32 v83, 0xffffff00, v83
	v_lshl_or_b32 v70, v70, 8, s33
	v_xor_b32_e32 v83, v83, v70
	v_xor_b32_e32 v83, 0xfa, v83
	v_add_f32_e32 v70, v97, v125
	v_ashrrev_i32_e32 v117, 31, v70
	v_and_b32_e32 v70, 0xffffff00, v70
	v_lshl_or_b32 v117, v117, 8, s33
	v_xor_b32_e32 v70, v70, v117
	v_xor_b32_e32 v70, 0xf9, v70
	v_add_f32_e32 v117, v97, v126
	v_ashrrev_i32_e32 v109, 31, v117
	v_and_b32_e32 v117, 0xffffff00, v117
	v_lshl_or_b32 v109, v109, 8, s33
	v_xor_b32_e32 v117, v117, v109
	v_xor_b32_e32 v117, 0xf8, v117
	v_add_f32_e32 v109, v97, v127
	v_ashrrev_i32_e32 v116, 31, v109
	v_and_b32_e32 v109, 0xffffff00, v109
	v_lshl_or_b32 v116, v116, 8, s33
	v_xor_b32_e32 v109, v109, v116
	v_xor_b32_e32 v109, 0xf7, v109
	v_add_f32_e32 v116, v97, v128
	v_ashrrev_i32_e32 v110, 31, v116
	v_and_b32_e32 v116, 0xffffff00, v116
	v_lshl_or_b32 v110, v110, 8, s33
	v_xor_b32_e32 v116, v116, v110
	v_xor_b32_e32 v116, 0xf6, v116
	v_add_f32_e32 v110, v97, v129
	v_ashrrev_i32_e32 v79, 31, v110
	v_and_b32_e32 v110, 0xffffff00, v110
	v_lshl_or_b32 v79, v79, 8, s33
	v_xor_b32_e32 v110, v110, v79
	v_xor_b32_e32 v110, 0xf5, v110
	v_add_f32_e32 v79, v97, v130
	v_ashrrev_i32_e32 v111, 31, v79
	v_and_b32_e32 v79, 0xffffff00, v79
	v_lshl_or_b32 v111, v111, 8, s33
	v_xor_b32_e32 v79, v79, v111
	v_xor_b32_e32 v79, 0xf4, v79
	v_add_f32_e32 v111, v97, v131
	v_ashrrev_i32_e32 v82, 31, v111
	v_and_b32_e32 v111, 0xffffff00, v111
	v_lshl_or_b32 v82, v82, 8, s33
	v_xor_b32_e32 v111, v111, v82
	v_xor_b32_e32 v111, 0xf3, v111
	v_add_f32_e32 v82, v97, v132
	v_ashrrev_i32_e32 v104, 31, v82
	v_and_b32_e32 v82, 0xffffff00, v82
	v_lshl_or_b32 v104, v104, 8, s33
	v_xor_b32_e32 v82, v82, v104
	v_xor_b32_e32 v82, 0xf2, v82
	v_add_f32_e32 v104, v97, v133
	v_ashrrev_i32_e32 v73, 31, v104
	v_and_b32_e32 v104, 0xffffff00, v104
	v_lshl_or_b32 v73, v73, 8, s33
	v_xor_b32_e32 v104, v104, v73
; #define CE_DESC(a, b) do { const unsigned _mx = (a) > (b) ? (a) : (b), _mn = (a) > (b) ? (b) : (a); (a) = _mx; (b) = _mn; } while (0)
; #define CK(i, j) ((f2key(va[i] + vb[j]) & ~255u) | (unsigned)(255 - (16 * (i) + (j))))
; __device__ __forceinline__ void sort16_desc(unsigned (&k)[16]) {
; #pragma unroll
;     for (int size = 2; size <= 16; size <<= 1)
; #pragma unroll
;         for (int stride = size >> 1; stride > 0; stride >>= 1)
; #pragma unroll
;             for (int i = 0; i < 16; ++i) { const int j = i ^ stride;
;                 if (j > i) { if ((i & size) == 0) CE_DESC(k[i], k[j]); else CE_DESC(k[j], k[i]); } }
; }
; __device__ __forceinline__ void peer_tile(const Args& A, LAS unsigned char* lds, int tile) {
;     ...
;             unsigned Lf[16], Bt[16];
; #pragma unroll
;             for (int j = 0; j < 16; ++j) Lf[j] = CK(0, j);
; #pragma unroll
;             for (int j = 0; j < 8; ++j) Bt[j] = CK(1, j);
; #pragma unroll
;             for (int j = 0; j < 5; ++j) Bt[8 + j] = CK(2, j);
; #pragma unroll
;             for (int j = 0; j < 3; ++j) Bt[13 + j] = CK(4, j);
;             sort16_desc(Bt); merge16(Lf, Bt);
	v_xor_b32_e32 v104, 0xf1, v104
	v_add_f32_e32 v73, v97, v134
	v_ashrrev_i32_e32 v85, 31, v73
	v_and_b32_e32 v73, 0xffffff00, v73
	v_lshl_or_b32 v85, v85, 8, s33
	v_xor_b32_e32 v73, v73, v85
	v_xor_b32_e32 v73, 0xf0, v73
	v_add_f32_e32 v85, v102, v90
	v_ashrrev_i32_e32 v101, 31, v85
	v_and_b32_e32 v85, 0xffffff00, v85
	v_lshl_or_b32 v101, v101, 8, s33
	v_xor_b32_e32 v85, v85, v101
	v_xor_b32_e32 v85, 0xef, v85
	v_add_f32_e32 v101, v102, v120
	v_ashrrev_i32_e32 v84, 31, v101
	v_and_b32_e32 v101, 0xffffff00, v101
	v_lshl_or_b32 v84, v84, 8, s33
	v_xor_b32_e32 v101, v101, v84
	v_xor_b32_e32 v101, 0xee, v101
	v_add_f32_e32 v84, v102, v121
	v_ashrrev_i32_e32 v77, 31, v84
	v_and_b32_e32 v84, 0xffffff00, v84
	v_lshl_or_b32 v77, v77, 8, s33
	v_xor_b32_e32 v84, v84, v77
	v_xor_b32_e32 v84, 0xed, v84
	v_add_f32_e32 v77, v102, v122
	v_ashrrev_i32_e32 v80, 31, v77
	v_and_b32_e32 v77, 0xffffff00, v77
	v_lshl_or_b32 v80, v80, 8, s33
	v_xor_b32_e32 v77, v77, v80
	v_xor_b32_e32 v77, 0xec, v77
	v_add_f32_e32 v80, v102, v123
	v_ashrrev_i32_e32 v81, 31, v80
	v_and_b32_e32 v80, 0xffffff00, v80
	v_lshl_or_b32 v81, v81, 8, s33
	v_xor_b32_e32 v80, v80, v81
	v_xor_b32_e32 v80, 0xeb, v80
	v_add_f32_e32 v81, v102, v124
	v_ashrrev_i32_e32 v76, 31, v81
	v_and_b32_e32 v81, 0xffffff00, v81
	v_lshl_or_b32 v76, v76, 8, s33
	v_xor_b32_e32 v81, v81, v76
	v_xor_b32_e32 v81, 0xea, v81
	v_add_f32_e32 v76, v102, v125
	v_ashrrev_i32_e32 v100, 31, v76
	v_and_b32_e32 v76, 0xffffff00, v76
	v_lshl_or_b32 v100, v100, 8, s33
	v_xor_b32_e32 v76, v76, v100
	v_xor_b32_e32 v76, 0xe9, v76
	v_add_f32_e32 v100, v102, v126
	v_ashrrev_i32_e32 v93, 31, v100
	v_and_b32_e32 v100, 0xffffff00, v100
	v_lshl_or_b32 v93, v93, 8, s33
	v_xor_b32_e32 v100, v100, v93
	v_xor_b32_e32 v100, 0xe8, v100
	v_add_f32_e32 v93, v114, v90
	v_ashrrev_i32_e32 v99, 31, v93
	v_and_b32_e32 v93, 0xffffff00, v93
	v_lshl_or_b32 v99, v99, 8, s33
	v_xor_b32_e32 v93, v93, v99
	v_xor_b32_e32 v93, 0xdf, v93
	v_add_f32_e32 v99, v114, v120
	v_ashrrev_i32_e32 v94, 31, v99
	v_and_b32_e32 v99, 0xffffff00, v99
	v_lshl_or_b32 v94, v94, 8, s33
	v_xor_b32_e32 v99, v99, v94
	v_xor_b32_e32 v99, 0xde, v99
	v_add_f32_e32 v94, v114, v121
	v_ashrrev_i32_e32 v86, 31, v94
	v_and_b32_e32 v94, 0xffffff00, v94
	v_lshl_or_b32 v86, v86, 8, s33
	v_xor_b32_e32 v94, v94, v86
	v_xor_b32_e32 v94, 0xdd, v94
	v_add_f32_e32 v86, v114, v122
	v_ashrrev_i32_e32 v95, 31, v86
	v_and_b32_e32 v86, 0xffffff00, v86
	v_lshl_or_b32 v95, v95, 8, s33
	v_xor_b32_e32 v86, v86, v95
	v_xor_b32_e32 v86, 0xdc, v86
	v_add_f32_e32 v95, v114, v123
	v_ashrrev_i32_e32 v74, 31, v95
	v_and_b32_e32 v95, 0xffffff00, v95
	v_lshl_or_b32 v74, v74, 8, s33
	v_xor_b32_e32 v95, v95, v74
	v_xor_b32_e32 v95, 0xdb, v95
	v_add_f32_e32 v74, v75, v90
	v_ashrrev_i32_e32 v88, 31, v74
	v_and_b32_e32 v74, 0xffffff00, v74
	v_lshl_or_b32 v88, v88, 8, s33
	v_xor_b32_e32 v74, v74, v88
	v_xor_b32_e32 v74, 0xbf, v74
	v_add_f32_e32 v88, v75, v120
	v_ashrrev_i32_e32 v71, 31, v88
	v_and_b32_e32 v88, 0xffffff00, v88
	v_lshl_or_b32 v71, v71, 8, s33
	v_xor_b32_e32 v88, v88, v71
	v_xor_b32_e32 v88, 0xbe, v88
	v_add_f32_e32 v71, v75, v121
	v_ashrrev_i32_e32 v135, 31, v71
	v_and_b32_e32 v71, 0xffffff00, v71
	v_lshl_or_b32 v135, v135, 8, s33
	v_xor_b32_e32 v71, v71, v135
	v_xor_b32_e32 v71, 0xbd, v71
	v_max_u32_e32 v135, v85, v74
	v_min_u32_e32 v74, v85, v74
	v_max_u32_e32 v85, v101, v95
	v_min_u32_e32 v95, v101, v95
	v_max_u32_e32 v101, v84, v71
	v_min_u32_e32 v71, v84, v71
	v_max_u32_e32 v84, v77, v88
	v_min_u32_e32 v88, v77, v88
	v_max_u32_e32 v77, v80, v93
	v_min_u32_e32 v93, v80, v93
	v_max_u32_e32 v80, v81, v76
	v_min_u32_e32 v76, v81, v76
	v_max_u32_e32 v81, v100, v86
	v_min_u32_e32 v86, v100, v86
	v_max_u32_e32 v100, v99, v94
	v_min_u32_e32 v94, v99, v94
	v_max_u32_e32 v99, v135, v80
	v_min_u32_e32 v80, v135, v80
	v_max_u32_e32 v135, v85, v81
	v_min_u32_e32 v81, v85, v81
	v_max_u32_e32 v85, v101, v100
	v_min_u32_e32 v100, v101, v100
	v_max_u32_e32 v101, v84, v77
	v_min_u32_e32 v77, v84, v77
	v_max_u32_e32 v84, v76, v74
	v_min_u32_e32 v74, v76, v74
	v_max_u32_e32 v76, v93, v88
	v_min_u32_e32 v88, v93, v88
	v_max_u32_e32 v93, v94, v71
	v_min_u32_e32 v71, v94, v71
	v_max_u32_e32 v94, v86, v95
	v_min_u32_e32 v95, v86, v95
	v_max_u32_e32 v86, v99, v135
	v_min_u32_e32 v135, v99, v135
	v_max_u32_e32 v99, v85, v101
	v_min_u32_e32 v101, v85, v101
	v_max_u32_e32 v85, v77, v80
	v_min_u32_e32 v80, v77, v80
	v_max_u32_e32 v77, v84, v76
	v_min_u32_e32 v76, v84, v76
	v_max_u32_e32 v84, v81, v100
	v_min_u32_e32 v100, v81, v100
	v_max_u32_e32 v81, v93, v94
	v_min_u32_e32 v94, v93, v94
	v_max_u32_e32 v93, v95, v74
	v_min_u32_e32 v74, v95, v74
	v_max_u32_e32 v95, v88, v71
	v_min_u32_e32 v71, v88, v71
	v_max_u32_e32 v88, v86, v99
	v_min_u32_e32 v99, v86, v99
	v_max_u32_e32 v86, v135, v101
	v_min_u32_e32 v101, v135, v101
	v_max_u32_e32 v135, v85, v81
	v_min_u32_e32 v81, v85, v81
	v_max_u32_e32 v85, v80, v94
	v_min_u32_e32 v94, v80, v94
	v_max_u32_e32 v80, v77, v84
	v_min_u32_e32 v84, v77, v84
	v_max_u32_e32 v77, v76, v100
	v_min_u32_e32 v100, v76, v100
	v_max_u32_e32 v76, v93, v95
	v_min_u32_e32 v95, v93, v95
	v_max_u32_e32 v93, v74, v71
	v_min_u32_e32 v71, v74, v71
	v_max_u32_e32 v74, v86, v99
	v_min_u32_e32 v99, v86, v99
	v_max_u32_e32 v86, v101, v76
	v_min_u32_e32 v76, v101, v76
	v_max_u32_e32 v101, v135, v80
	v_min_u32_e32 v80, v135, v80
	v_max_u32_e32 v135, v85, v84
	v_min_u32_e32 v84, v85, v84
	v_max_u32_e32 v85, v77, v81
	v_min_u32_e32 v81, v77, v81
	v_max_u32_e32 v77, v100, v94
	v_min_u32_e32 v94, v100, v94
	v_max_u32_e32 v100, v93, v95
	v_min_u32_e32 v95, v93, v95
	v_max_u32_e32 v93, v74, v101
	v_min_u32_e32 v101, v74, v101
; #define CE_DESC(a, b) do { const unsigned _mx = (a) > (b) ? (a) : (b), _mn = (a) > (b) ? (b) : (a); (a) = _mx; (b) = _mn; } while (0)
; #define CK(i, j) ((f2key(va[i] + vb[j]) & ~255u) | (unsigned)(255 - (16 * (i) + (j))))
; __device__ __forceinline__ void merge16(unsigned (&a)[16], const unsigned (&b)[16]) {
; #pragma unroll
;     for (int i = 0; i < 16; ++i) a[i] = a[i] > b[15 - i] ? a[i] : b[15 - i];
; #pragma unroll
;     for (int stride = 8; stride > 0; stride >>= 1)
; #pragma unroll
;         for (int i = 0; i < 16; ++i) { const int j = i ^ stride; if (j > i) CE_DESC(a[i], a[j]); }
; }
; __device__ __forceinline__ void peer_tile(const Args& A, LAS unsigned char* lds, int tile) {
;     ...
;             sort16_desc(Bt); merge16(Lf, Bt);
; #pragma unroll
;             for (int j = 0; j < 4; ++j) Bt[j] = CK(3, j);
;             Bt[4] = CK(5, 0); Bt[5] = CK(5, 1); Bt[6] = CK(6, 0); Bt[7] = CK(6, 1); Bt[8] = CK(7, 0); Bt[9] = CK(7, 1);
;             Bt[10] = CK(8, 0); Bt[11] = CK(9, 0); Bt[12] = CK(10, 0); Bt[13] = CK(11, 0); Bt[14] = CK(12, 0); Bt[15] = CK(13, 0);
	v_max_u32_e32 v74, v99, v80
	v_min_u32_e32 v80, v99, v80
	v_max_u32_e32 v99, v135, v85
	v_min_u32_e32 v85, v135, v85
	v_max_u32_e32 v135, v84, v81
	v_min_u32_e32 v81, v84, v81
	v_max_u32_e32 v84, v77, v100
	v_min_u32_e32 v100, v77, v100
	v_max_u32_e32 v77, v94, v95
	v_min_u32_e32 v95, v94, v95
	v_max_u32_e32 v94, v74, v101
	v_min_u32_e32 v101, v74, v101
	v_max_u32_e32 v74, v86, v80
	v_min_u32_e32 v80, v86, v80
	v_max_u32_e32 v86, v84, v76
	v_min_u32_e32 v76, v84, v76
	v_max_u32_e32 v84, v77, v100
	v_min_u32_e32 v100, v77, v100
	v_max_u32_e32 v77, v74, v99
	v_min_u32_e32 v99, v74, v99
	v_max_u32_e32 v74, v80, v85
	v_min_u32_e32 v85, v80, v85
	v_max_u32_e32 v80, v135, v86
	v_min_u32_e32 v86, v135, v86
	v_max_u32_e32 v135, v81, v76
	v_min_u32_e32 v76, v81, v76
	v_max_u32_e32 v81, v77, v101
	v_min_u32_e32 v101, v77, v101
	v_max_u32_e32 v77, v99, v74
	v_min_u32_e32 v74, v99, v74
	v_max_u32_e32 v99, v80, v85
	v_min_u32_e32 v85, v80, v85
	v_max_u32_e32 v80, v86, v135
	v_min_u32_e32 v135, v86, v135
	v_max_u32_e32 v86, v84, v76
	v_min_u32_e32 v76, v84, v76
	v_max_u32_e32 v84, v74, v99
	v_min_u32_e32 v99, v74, v99
	v_max_u32_e32 v74, v85, v80
	v_min_u32_e32 v80, v85, v80
	v_max_u32_e32 v96, v96, v71
	v_max_u32_e32 v118, v118, v95
	v_max_u32_e32 v89, v89, v100
	v_max_u32_e32 v87, v87, v76
	v_max_u32_e32 v91, v91, v86
	v_max_u32_e32 v83, v83, v135
	v_max_u32_e32 v70, v70, v80
	v_max_u32_e32 v117, v117, v74
	v_max_u32_e32 v109, v109, v99
	v_max_u32_e32 v116, v116, v84
	v_max_u32_e32 v110, v110, v77
	v_max_u32_e32 v79, v79, v101
	v_max_u32_e32 v111, v111, v81
	v_max_u32_e32 v82, v82, v94
	v_max_u32_e32 v104, v104, v93
	v_max_u32_e32 v73, v73, v88
	v_max_u32_e32 v71, v96, v109
	v_min_u32_e32 v109, v96, v109
	v_max_u32_e32 v96, v118, v116
	v_min_u32_e32 v116, v118, v116
	v_max_u32_e32 v118, v89, v110
	v_min_u32_e32 v110, v89, v110
	v_max_u32_e32 v89, v87, v79
	v_min_u32_e32 v79, v87, v79
	v_max_u32_e32 v87, v91, v111
	v_min_u32_e32 v111, v91, v111
	v_max_u32_e32 v91, v83, v82
	v_min_u32_e32 v82, v83, v82
	v_max_u32_e32 v83, v70, v104
	v_min_u32_e32 v104, v70, v104
	v_max_u32_e32 v70, v117, v73
	v_min_u32_e32 v73, v117, v73
	v_max_u32_e32 v117, v71, v87
	v_min_u32_e32 v87, v71, v87
	v_max_u32_e32 v71, v96, v91
	v_min_u32_e32 v91, v96, v91
	v_max_u32_e32 v96, v118, v83
	v_min_u32_e32 v83, v118, v83
	v_max_u32_e32 v118, v89, v70
	v_min_u32_e32 v70, v89, v70
	v_max_u32_e32 v89, v109, v111
	v_min_u32_e32 v111, v109, v111
	v_max_u32_e32 v109, v116, v82
	v_min_u32_e32 v82, v116, v82
	v_max_u32_e32 v116, v110, v104
	v_min_u32_e32 v104, v110, v104
	v_max_u32_e32 v110, v79, v73
	v_min_u32_e32 v73, v79, v73
	v_max_u32_e32 v79, v117, v96
	v_min_u32_e32 v96, v117, v96
	v_max_u32_e32 v117, v71, v118
	v_min_u32_e32 v118, v71, v118
	v_max_u32_e32 v71, v87, v83
	v_min_u32_e32 v83, v87, v83
	v_max_u32_e32 v87, v91, v70
	v_min_u32_e32 v70, v91, v70
	v_max_u32_e32 v91, v89, v116
	v_min_u32_e32 v116, v89, v116
	v_max_u32_e32 v89, v109, v110
	v_min_u32_e32 v110, v109, v110
	v_max_u32_e32 v109, v111, v104
	v_min_u32_e32 v104, v111, v104
	v_max_u32_e32 v111, v82, v73
	v_min_u32_e32 v73, v82, v73
	v_max_u32_e32 v82, v79, v117
	v_min_u32_e32 v117, v79, v117
	v_max_u32_e32 v79, v96, v118
	v_min_u32_e32 v118, v96, v118
	v_max_u32_e32 v96, v71, v87
	v_min_u32_e32 v87, v71, v87
	v_max_u32_e32 v71, v83, v70
	v_min_u32_e32 v70, v83, v70
	v_max_u32_e32 v83, v91, v89
	v_min_u32_e32 v89, v91, v89
	v_max_u32_e32 v91, v116, v110
	v_min_u32_e32 v110, v116, v110
	v_max_u32_e32 v116, v109, v111
	v_min_u32_e32 v111, v109, v111
	v_max_u32_e32 v109, v104, v73
	v_min_u32_e32 v73, v104, v73
	v_add_f32_e32 v104, v119, v90
	v_ashrrev_i32_e32 v95, 31, v104
	v_and_b32_e32 v104, 0xffffff00, v104
	v_lshl_or_b32 v95, v95, 8, s33
	v_xor_b32_e32 v104, v104, v95
	v_xor_b32_e32 v104, 0xcf, v104
	v_add_f32_e32 v95, v119, v120
	v_ashrrev_i32_e32 v100, 31, v95
	v_and_b32_e32 v95, 0xffffff00, v95
	v_lshl_or_b32 v100, v100, 8, s33
	v_xor_b32_e32 v95, v95, v100
	v_xor_b32_e32 v95, 0xce, v95
	v_add_f32_e32 v100, v119, v121
	v_ashrrev_i32_e32 v76, 31, v100
	v_and_b32_e32 v100, 0xffffff00, v100
	v_lshl_or_b32 v76, v76, 8, s33
	v_xor_b32_e32 v100, v100, v76
	v_xor_b32_e32 v100, 0xcd, v100
	v_add_f32_e32 v76, v119, v122
	v_ashrrev_i32_e32 v86, 31, v76
	v_and_b32_e32 v76, 0xffffff00, v76
	v_lshl_or_b32 v86, v86, 8, s33
	v_xor_b32_e32 v76, v76, v86
	v_xor_b32_e32 v76, 0xcc, v76
	v_add_f32_e32 v86, v92, v90
	v_ashrrev_i32_e32 v135, 31, v86
	v_and_b32_e32 v86, 0xffffff00, v86
	v_lshl_or_b32 v135, v135, 8, s33
	v_xor_b32_e32 v86, v86, v135
	v_xor_b32_e32 v86, 0xaf, v86
	v_add_f32_e32 v135, v92, v120
	v_ashrrev_i32_e32 v80, 31, v135
	v_and_b32_e32 v135, 0xffffff00, v135
	v_lshl_or_b32 v80, v80, 8, s33
	v_xor_b32_e32 v135, v135, v80
	v_xor_b32_e32 v135, 0xae, v135
	v_add_f32_e32 v80, v72, v90
	v_ashrrev_i32_e32 v74, 31, v80
	v_and_b32_e32 v80, 0xffffff00, v80
	v_lshl_or_b32 v74, v74, 8, s33
	v_xor_b32_e32 v80, v80, v74
	v_xor_b32_e32 v80, 0x9f, v80
	v_add_f32_e32 v74, v72, v120
	v_ashrrev_i32_e32 v99, 31, v74
	v_and_b32_e32 v74, 0xffffff00, v74
	v_lshl_or_b32 v99, v99, 8, s33
	v_xor_b32_e32 v74, v74, v99
	v_xor_b32_e32 v74, 0x9e, v74
	v_add_f32_e32 v99, v103, v90
	v_ashrrev_i32_e32 v84, 31, v99
	v_and_b32_e32 v99, 0xffffff00, v99
	v_lshl_or_b32 v84, v84, 8, s33
	v_xor_b32_e32 v99, v99, v84
	v_xor_b32_e32 v99, 0x8f, v99
	v_add_f32_e32 v84, v103, v120
	v_ashrrev_i32_e32 v77, 31, v84
	v_and_b32_e32 v84, 0xffffff00, v84
	v_lshl_or_b32 v77, v77, 8, s33
	v_xor_b32_e32 v84, v84, v77
	v_xor_b32_e32 v84, 0x8e, v84
	v_add_f32_e32 v77, v108, v90
	v_ashrrev_i32_e32 v101, 31, v77
	v_and_b32_e32 v77, 0xffffff00, v77
	v_lshl_or_b32 v101, v101, 8, s33
; #define CE_DESC(a, b) do { const unsigned _mx = (a) > (b) ? (a) : (b), _mn = (a) > (b) ? (b) : (a); (a) = _mx; (b) = _mn; } while (0)
; #define CK(i, j) ((f2key(va[i] + vb[j]) & ~255u) | (unsigned)(255 - (16 * (i) + (j))))
; __device__ __forceinline__ void sort16_desc(unsigned (&k)[16]) {
; #pragma unroll
;     for (int size = 2; size <= 16; size <<= 1)
; #pragma unroll
;         for (int stride = size >> 1; stride > 0; stride >>= 1)
; #pragma unroll
;             for (int i = 0; i < 16; ++i) { const int j = i ^ stride;
;                 if (j > i) { if ((i & size) == 0) CE_DESC(k[i], k[j]); else CE_DESC(k[j], k[i]); } }
; }
; __device__ __forceinline__ void merge16(unsigned (&a)[16], const unsigned (&b)[16]) {
; #pragma unroll
;     for (int i = 0; i < 16; ++i) a[i] = a[i] > b[15 - i] ? a[i] : b[15 - i];
; #pragma unroll
;     for (int stride = 8; stride > 0; stride >>= 1)
; #pragma unroll
;         for (int i = 0; i < 16; ++i) { const int j = i ^ stride; if (j > i) CE_DESC(a[i], a[j]); }
; }
; __device__ __forceinline__ void peer_tile(const Args& A, LAS unsigned char* lds, int tile) {
;     ...
;             sort16_desc(Bt); merge16(Lf, Bt);
; #pragma unroll
;             for (int j = 0; j < 4; ++j) Bt[j] = CK(3, j);
;             Bt[4] = CK(5, 0); Bt[5] = CK(5, 1); Bt[6] = CK(6, 0); Bt[7] = CK(6, 1); Bt[8] = CK(7, 0); Bt[9] = CK(7, 1);
;             Bt[10] = CK(8, 0); Bt[11] = CK(9, 0); Bt[12] = CK(10, 0); Bt[13] = CK(11, 0); Bt[14] = CK(12, 0); Bt[15] = CK(13, 0);
;             sort16_desc(Bt); merge16(Lf, Bt);
	v_xor_b32_e32 v77, v77, v101
	v_xor_b32_e32 v77, 0x7f, v77
	v_add_f32_e32 v101, v106, v90
	v_ashrrev_i32_e32 v81, 31, v101
	v_and_b32_e32 v101, 0xffffff00, v101
	v_lshl_or_b32 v81, v81, 8, s33
	v_xor_b32_e32 v101, v101, v81
	v_xor_b32_e32 v101, 0x6f, v101
	v_add_f32_e32 v81, v107, v90
	v_ashrrev_i32_e32 v94, 31, v81
	v_and_b32_e32 v81, 0xffffff00, v81
	v_lshl_or_b32 v94, v94, 8, s33
	v_xor_b32_e32 v81, v81, v94
	v_xor_b32_e32 v81, 0x5f, v81
	v_add_f32_e32 v94, v98, v90
	v_ashrrev_i32_e32 v93, 31, v94
	v_and_b32_e32 v94, 0xffffff00, v94
	v_lshl_or_b32 v93, v93, 8, s33
	v_xor_b32_e32 v94, v94, v93
	v_xor_b32_e32 v94, 0x4f, v94
	v_add_f32_e32 v93, v78, v90
	v_ashrrev_i32_e32 v88, 31, v93
	v_and_b32_e32 v93, 0xffffff00, v93
	v_lshl_or_b32 v88, v88, 8, s33
	v_xor_b32_e32 v93, v93, v88
	v_xor_b32_e32 v93, 63, v93
	v_add_f32_e32 v88, v115, v90
	v_ashrrev_i32_e32 v85, 31, v88
	v_and_b32_e32 v88, 0xffffff00, v88
	v_lshl_or_b32 v85, v85, 8, s33
	v_xor_b32_e32 v88, v88, v85
	v_xor_b32_e32 v88, 47, v88
	v_max_u32_e32 v85, v104, v94
	v_min_u32_e32 v94, v104, v94
	v_max_u32_e32 v104, v95, v81
	v_min_u32_e32 v81, v95, v81
	v_max_u32_e32 v95, v100, v88
	v_min_u32_e32 v88, v100, v88
	v_max_u32_e32 v100, v76, v93
	v_min_u32_e32 v93, v76, v93
	v_max_u32_e32 v76, v86, v99
	v_min_u32_e32 v99, v86, v99
	v_max_u32_e32 v86, v135, v80
	v_min_u32_e32 v80, v135, v80
	v_max_u32_e32 v135, v74, v101
	v_min_u32_e32 v101, v74, v101
	v_max_u32_e32 v74, v84, v77
	v_min_u32_e32 v77, v84, v77
	v_max_u32_e32 v84, v85, v86
	v_min_u32_e32 v86, v85, v86
	v_max_u32_e32 v85, v104, v135
	v_min_u32_e32 v135, v104, v135
	v_max_u32_e32 v104, v95, v74
	v_min_u32_e32 v74, v95, v74
	v_max_u32_e32 v95, v100, v76
	v_min_u32_e32 v76, v100, v76
	v_max_u32_e32 v100, v80, v94
	v_min_u32_e32 v94, v80, v94
	v_max_u32_e32 v80, v99, v93
	v_min_u32_e32 v93, v99, v93
	v_max_u32_e32 v99, v77, v88
	v_min_u32_e32 v88, v77, v88
	v_max_u32_e32 v77, v101, v81
	v_min_u32_e32 v81, v101, v81
	v_max_u32_e32 v101, v84, v85
	v_min_u32_e32 v85, v84, v85
	v_max_u32_e32 v84, v104, v95
	v_min_u32_e32 v95, v104, v95
	v_max_u32_e32 v104, v76, v86
	v_min_u32_e32 v86, v76, v86
	v_max_u32_e32 v76, v100, v80
	v_min_u32_e32 v80, v100, v80
	v_max_u32_e32 v100, v135, v74
	v_min_u32_e32 v74, v135, v74
	v_max_u32_e32 v135, v99, v77
	v_min_u32_e32 v77, v99, v77
	v_max_u32_e32 v99, v81, v94
	v_min_u32_e32 v94, v81, v94
	v_max_u32_e32 v81, v93, v88
	v_min_u32_e32 v88, v93, v88
	v_max_u32_e32 v93, v101, v84
	v_min_u32_e32 v84, v101, v84
	v_max_u32_e32 v101, v85, v95
	v_min_u32_e32 v95, v85, v95
	v_max_u32_e32 v85, v104, v135
	v_min_u32_e32 v135, v104, v135
	v_max_u32_e32 v104, v86, v77
	v_min_u32_e32 v77, v86, v77
	v_max_u32_e32 v86, v76, v100
	v_min_u32_e32 v100, v76, v100
	v_max_u32_e32 v76, v80, v74
	v_min_u32_e32 v74, v80, v74
	v_max_u32_e32 v80, v99, v81
	v_min_u32_e32 v81, v99, v81
	v_max_u32_e32 v99, v94, v88
	v_min_u32_e32 v88, v94, v88
	v_max_u32_e32 v94, v101, v84
	v_min_u32_e32 v84, v101, v84
	v_max_u32_e32 v101, v95, v80
	v_min_u32_e32 v80, v95, v80
	v_max_u32_e32 v95, v85, v86
	v_min_u32_e32 v86, v85, v86
	v_max_u32_e32 v85, v104, v100
	v_min_u32_e32 v100, v104, v100
	v_max_u32_e32 v104, v76, v135
	v_min_u32_e32 v135, v76, v135
	v_max_u32_e32 v76, v74, v77
	v_min_u32_e32 v77, v74, v77
	v_max_u32_e32 v74, v99, v81
	v_min_u32_e32 v81, v99, v81
	v_max_u32_e32 v99, v94, v95
	v_min_u32_e32 v95, v94, v95
	v_max_u32_e32 v94, v84, v86
	v_min_u32_e32 v86, v84, v86
	v_max_u32_e32 v84, v85, v104
	v_min_u32_e32 v104, v85, v104
	v_max_u32_e32 v85, v100, v135
	v_min_u32_e32 v135, v100, v135
	v_max_u32_e32 v100, v76, v74
	v_min_u32_e32 v74, v76, v74
	v_max_u32_e32 v76, v77, v81
	v_min_u32_e32 v81, v77, v81
	v_max_u32_e32 v77, v94, v95
	v_min_u32_e32 v95, v94, v95
	v_max_u32_e32 v94, v101, v86
	v_min_u32_e32 v86, v101, v86
	v_max_u32_e32 v101, v100, v80
	v_min_u32_e32 v80, v100, v80
	v_max_u32_e32 v100, v76, v74
	v_min_u32_e32 v74, v76, v74
	v_max_u32_e32 v76, v94, v84
	v_min_u32_e32 v84, v94, v84
	v_max_u32_e32 v94, v86, v104
	v_min_u32_e32 v104, v86, v104
	v_max_u32_e32 v86, v85, v101
	v_min_u32_e32 v101, v85, v101
	v_max_u32_e32 v85, v135, v80
	v_min_u32_e32 v80, v135, v80
	v_max_u32_e32 v135, v76, v95
	v_min_u32_e32 v95, v76, v95
	v_max_u32_e32 v76, v84, v94
	v_min_u32_e32 v94, v84, v94
	v_max_u32_e32 v84, v86, v104
	v_min_u32_e32 v104, v86, v104
	v_max_u32_e32 v86, v101, v85
	v_min_u32_e32 v85, v101, v85
	v_max_u32_e32 v101, v100, v80
	v_min_u32_e32 v80, v100, v80
	v_max_u32_e32 v100, v94, v84
	v_min_u32_e32 v84, v94, v84
	v_max_u32_e32 v94, v104, v86
	v_min_u32_e32 v86, v104, v86
	v_max_u32_e32 v82, v82, v88
	v_max_u32_e32 v117, v117, v81
	v_max_u32_e32 v79, v79, v74
	v_max_u32_e32 v118, v118, v80
	v_max_u32_e32 v96, v96, v101
	v_max_u32_e32 v87, v87, v85
	v_max_u32_e32 v71, v71, v86
	v_max_u32_e32 v70, v70, v94
	v_max_u32_e32 v83, v83, v84
	v_max_u32_e32 v89, v89, v100
	v_max_u32_e32 v91, v91, v76
	v_max_u32_e32 v110, v110, v95
	v_max_u32_e32 v116, v116, v135
	v_max_u32_e32 v111, v111, v77
	v_max_u32_e32 v109, v109, v99
	v_max_u32_e32 v73, v73, v93
	v_max_u32_e32 v88, v82, v83
	v_min_u32_e32 v83, v82, v83
	v_max_u32_e32 v82, v117, v89
	v_min_u32_e32 v89, v117, v89
	v_max_u32_e32 v117, v79, v91
	v_min_u32_e32 v91, v79, v91
	v_max_u32_e32 v79, v118, v110
	v_min_u32_e32 v110, v118, v110
	v_max_u32_e32 v118, v96, v116
	v_min_u32_e32 v116, v96, v116
	v_max_u32_e32 v96, v87, v111
	v_min_u32_e32 v111, v87, v111
	v_max_u32_e32 v87, v71, v109
	v_min_u32_e32 v109, v71, v109
	v_max_u32_e32 v71, v70, v73
	v_min_u32_e32 v73, v70, v73
	v_max_u32_e32 v70, v88, v118
	v_min_u32_e32 v118, v88, v118
	v_max_u32_e32 v88, v82, v96
; __device__ __forceinline__ float key2f(unsigned k) { const unsigned u = (k & 0x80000000u) ? (k & 0x7fffffffu) : ~k; return __uint_as_float(u); }
; #define CE_DESC(a, b) do { const unsigned _mx = (a) > (b) ? (a) : (b), _mn = (a) > (b) ? (b) : (a); (a) = _mx; (b) = _mn; } while (0)
; #define CK(i, j) ((f2key(va[i] + vb[j]) & ~255u) | (unsigned)(255 - (16 * (i) + (j))))
; __device__ __forceinline__ void peer_tile(const Args& A, LAS unsigned char* lds, int tile) {
;     ...
;             { unsigned x0 = CK(14, 0), x1 = CK(15, 0);
; #pragma unroll
;               for (int i = 0; i < 16; ++i) CE_DESC(Lf[i], x0);
; #pragma unroll
;               for (int i = 0; i < 16; ++i) CE_DESC(Lf[i], x1); }
;     ...
;             float fv[16], den = 0.f; const float f0 = key2f(Lf[0] & ~255u);
; #pragma unroll
;             for (int k = 0; k < 16; ++k) { fv[k] = __expf(key2f(Lf[k] & ~255u) - f0); den += fv[k]; }
	v_min_u32_e32 v96, v82, v96
	v_max_u32_e32 v82, v117, v87
	v_min_u32_e32 v87, v117, v87
	v_max_u32_e32 v117, v79, v71
	v_min_u32_e32 v71, v79, v71
	v_max_u32_e32 v79, v83, v116
	v_min_u32_e32 v116, v83, v116
	v_max_u32_e32 v83, v89, v111
	v_min_u32_e32 v111, v89, v111
	v_max_u32_e32 v89, v91, v109
	v_min_u32_e32 v109, v91, v109
	v_max_u32_e32 v91, v110, v73
	v_min_u32_e32 v73, v110, v73
	v_max_u32_e32 v110, v70, v82
	v_min_u32_e32 v82, v70, v82
	v_max_u32_e32 v70, v88, v117
	v_min_u32_e32 v117, v88, v117
	v_max_u32_e32 v88, v118, v87
	v_min_u32_e32 v87, v118, v87
	v_max_u32_e32 v118, v96, v71
	v_min_u32_e32 v71, v96, v71
	v_max_u32_e32 v96, v79, v89
	v_min_u32_e32 v89, v79, v89
	v_max_u32_e32 v79, v83, v91
	v_min_u32_e32 v91, v83, v91
	v_max_u32_e32 v83, v116, v109
	v_min_u32_e32 v109, v116, v109
	v_max_u32_e32 v116, v111, v73
	v_min_u32_e32 v73, v111, v73
	v_max_u32_e32 v111, v110, v70
	v_min_u32_e32 v70, v110, v70
	v_max_u32_e32 v110, v82, v117
	v_min_u32_e32 v117, v82, v117
	v_max_u32_e32 v82, v88, v118
	v_min_u32_e32 v118, v88, v118
	v_max_u32_e32 v88, v87, v71
	v_min_u32_e32 v71, v87, v71
	v_max_u32_e32 v87, v96, v79
	v_min_u32_e32 v79, v96, v79
	v_max_u32_e32 v96, v89, v91
	v_min_u32_e32 v91, v89, v91
	v_max_u32_e32 v89, v83, v116
	v_min_u32_e32 v116, v83, v116
	v_max_u32_e32 v83, v109, v73
	v_min_u32_e32 v73, v109, v73
	v_add_f32_e32 v109, v105, v90
	v_ashrrev_i32_e32 v81, 31, v109
	v_and_b32_e32 v109, 0xffffff00, v109
	v_lshl_or_b32 v81, v81, 8, s33
	v_xor_b32_e32 v109, v109, v81
	v_xor_b32_e32 v109, 31, v109
	v_max_u32_e32 v81, v111, v109
	v_med3_u32 v74, v111, v70, v109
	v_med3_u32 v80, v70, v110, v109
	v_med3_u32 v101, v110, v117, v109
	v_med3_u32 v85, v117, v82, v109
	v_med3_u32 v86, v82, v118, v109
	v_med3_u32 v94, v118, v88, v109
	v_med3_u32 v84, v88, v71, v109
	v_med3_u32 v100, v71, v87, v109
	v_med3_u32 v76, v87, v79, v109
	v_med3_u32 v95, v79, v96, v109
	v_med3_u32 v135, v96, v91, v109
	v_med3_u32 v77, v91, v89, v109
	v_med3_u32 v99, v89, v116, v109
	v_med3_u32 v93, v116, v83, v109
	v_med3_u32 v104, v83, v73, v109
	v_add_f32_e32 v109, v112, v90
	v_ashrrev_i32_e32 v73, 31, v109
	v_and_b32_e32 v109, 0xffffff00, v109
	v_lshl_or_b32 v73, v73, 8, s33
	v_xor_b32_e32 v109, v109, v73
	v_xor_b32_e32 v109, 15, v109
	v_max_u32_e32 v73, v81, v109
	v_med3_u32 v83, v81, v74, v109
	v_med3_u32 v116, v74, v80, v109
	v_med3_u32 v89, v80, v101, v109
	v_med3_u32 v91, v101, v85, v109
	v_med3_u32 v96, v85, v86, v109
	v_med3_u32 v79, v86, v94, v109
	v_med3_u32 v87, v94, v84, v109
	v_med3_u32 v71, v84, v100, v109
	v_med3_u32 v88, v100, v76, v109
	v_med3_u32 v118, v76, v95, v109
	v_med3_u32 v82, v95, v135, v109
	v_med3_u32 v117, v135, v77, v109
	v_med3_u32 v110, v77, v99, v109
	v_med3_u32 v70, v99, v93, v109
	v_med3_u32 v111, v93, v104, v109
	v_ashrrev_i32_e32 v133, 31, v73
	v_and_b32_e32 v134, 0xffffff00, v73
	v_bitop3_b32 v134, v134, v133, s41 bitop3:0x87
	v_ashrrev_i32_e32 v131, 31, v73
	v_and_b32_e32 v132, 0xffffff00, v73
	v_bitop3_b32 v132, v132, v131, s41 bitop3:0x87
	v_sub_f32_e32 v132, v132, v134
	v_mul_f32_e32 v132, 0x3fb8aa3b, v132
	v_exp_f32_e32 v132, v132
	v_ashrrev_i32_e32 v130, 31, v83
	v_and_b32_e32 v131, 0xffffff00, v83
	v_bitop3_b32 v131, v131, v130, s41 bitop3:0x87
	v_sub_f32_e32 v131, v131, v134
	v_mul_f32_e32 v131, 0x3fb8aa3b, v131
	v_exp_f32_e32 v131, v131
	v_ashrrev_i32_e32 v129, 31, v116
	v_and_b32_e32 v130, 0xffffff00, v116
	v_bitop3_b32 v130, v130, v129, s41 bitop3:0x87
	v_sub_f32_e32 v130, v130, v134
	v_mul_f32_e32 v130, 0x3fb8aa3b, v130
	v_exp_f32_e32 v130, v130
	v_ashrrev_i32_e32 v128, 31, v89
	v_and_b32_e32 v129, 0xffffff00, v89
	v_bitop3_b32 v129, v129, v128, s41 bitop3:0x87
	v_sub_f32_e32 v129, v129, v134
	v_mul_f32_e32 v129, 0x3fb8aa3b, v129
	v_exp_f32_e32 v129, v129
	v_ashrrev_i32_e32 v127, 31, v91
	v_and_b32_e32 v128, 0xffffff00, v91
	v_bitop3_b32 v128, v128, v127, s41 bitop3:0x87
	v_sub_f32_e32 v128, v128, v134
	v_mul_f32_e32 v128, 0x3fb8aa3b, v128
	v_exp_f32_e32 v128, v128
	v_ashrrev_i32_e32 v126, 31, v96
	v_and_b32_e32 v127, 0xffffff00, v96
	v_bitop3_b32 v127, v127, v126, s41 bitop3:0x87
	v_sub_f32_e32 v127, v127, v134
	v_mul_f32_e32 v127, 0x3fb8aa3b, v127
	v_exp_f32_e32 v127, v127
	v_ashrrev_i32_e32 v125, 31, v79
	v_and_b32_e32 v126, 0xffffff00, v79
	v_bitop3_b32 v126, v126, v125, s41 bitop3:0x87
	v_sub_f32_e32 v126, v126, v134
	v_mul_f32_e32 v126, 0x3fb8aa3b, v126
	v_exp_f32_e32 v126, v126
	v_ashrrev_i32_e32 v124, 31, v87
	v_and_b32_e32 v125, 0xffffff00, v87
	v_bitop3_b32 v125, v125, v124, s41 bitop3:0x87
	v_sub_f32_e32 v125, v125, v134
	v_mul_f32_e32 v125, 0x3fb8aa3b, v125
	v_exp_f32_e32 v125, v125
	v_ashrrev_i32_e32 v123, 31, v71
	v_and_b32_e32 v124, 0xffffff00, v71
	v_bitop3_b32 v124, v124, v123, s41 bitop3:0x87
	v_sub_f32_e32 v124, v124, v134
	v_mul_f32_e32 v124, 0x3fb8aa3b, v124
	v_exp_f32_e32 v124, v124
	v_ashrrev_i32_e32 v122, 31, v88
	v_and_b32_e32 v123, 0xffffff00, v88
	v_bitop3_b32 v123, v123, v122, s41 bitop3:0x87
	v_sub_f32_e32 v123, v123, v134
	v_mul_f32_e32 v123, 0x3fb8aa3b, v123
	v_exp_f32_e32 v123, v123
	v_ashrrev_i32_e32 v121, 31, v118
	v_and_b32_e32 v122, 0xffffff00, v118
	v_bitop3_b32 v122, v122, v121, s41 bitop3:0x87
	v_sub_f32_e32 v122, v122, v134
	v_mul_f32_e32 v122, 0x3fb8aa3b, v122
	v_exp_f32_e32 v122, v122
	v_ashrrev_i32_e32 v120, 31, v82
	v_and_b32_e32 v121, 0xffffff00, v82
	v_bitop3_b32 v121, v121, v120, s41 bitop3:0x87
	v_sub_f32_e32 v121, v121, v134
	v_mul_f32_e32 v121, 0x3fb8aa3b, v121
	v_exp_f32_e32 v121, v121
	v_ashrrev_i32_e32 v90, 31, v117
	v_and_b32_e32 v120, 0xffffff00, v117
	v_bitop3_b32 v120, v120, v90, s41 bitop3:0x87
	v_sub_f32_e32 v120, v120, v134
; #define LDS_WAIT() asm volatile("s_waitcnt lgkmcnt(0)" ::: "memory")
; __device__ __forceinline__ float key2f(unsigned k) { const unsigned u = (k & 0x80000000u) ? (k & 0x7fffffffu) : ~k; return __uint_as_float(u); }
; __device__ __forceinline__ void peer_tile(const Args& A, LAS unsigned char* lds, int tile) {
;     ...
;             for (int k = 0; k < 16; ++k) { fv[k] = __expf(key2f(Lf[k] & ~255u) - f0); den += fv[k]; }
;             const float rden = 1.f / den;
;             LDS_WAIT();
; #pragma unroll
;             for (int k = 0; k < 16; ++k) { const unsigned code = 255u - (Lf[k] & 255u); const unsigned e = idx[code >> 4] * 128u + idx[16 + (code & 15u)];
;                 u32x2 sv; sv.x = e; sv.y = __float_as_uint(fv[k] * rden); SEL[(tl * 8 + h) * 16 + k] = sv; }
	v_mul_f32_e32 v120, 0x3fb8aa3b, v120
	v_exp_f32_e32 v120, v120
	v_ashrrev_i32_e32 v112, 31, v110
	v_and_b32_e32 v90, 0xffffff00, v110
	v_bitop3_b32 v90, v90, v112, s41 bitop3:0x87
	v_sub_f32_e32 v90, v90, v134
	v_mul_f32_e32 v90, 0x3fb8aa3b, v90
	v_exp_f32_e32 v90, v90
	v_ashrrev_i32_e32 v105, 31, v70
	v_and_b32_e32 v112, 0xffffff00, v70
	v_bitop3_b32 v112, v112, v105, s41 bitop3:0x87
	v_sub_f32_e32 v112, v112, v134
	v_mul_f32_e32 v112, 0x3fb8aa3b, v112
	v_exp_f32_e32 v112, v112
	v_ashrrev_i32_e32 v115, 31, v111
	v_and_b32_e32 v105, 0xffffff00, v111
	v_bitop3_b32 v105, v105, v115, s41 bitop3:0x87
	v_sub_f32_e32 v105, v105, v134
	v_mul_f32_e32 v105, 0x3fb8aa3b, v105
	v_exp_f32_e32 v105, v105
	v_add_f32_e32 v133, 0, v132
	v_add_f32_e32 v133, v133, v131
	v_add_f32_e32 v133, v133, v130
	v_add_f32_e32 v133, v133, v129
	v_add_f32_e32 v133, v133, v128
	v_add_f32_e32 v133, v133, v127
	v_add_f32_e32 v133, v133, v126
	v_add_f32_e32 v133, v133, v125
	v_add_f32_e32 v133, v133, v124
	v_add_f32_e32 v133, v133, v123
	v_add_f32_e32 v133, v133, v122
	v_add_f32_e32 v133, v133, v121
	v_add_f32_e32 v133, v133, v120
	v_add_f32_e32 v133, v133, v90
	v_add_f32_e32 v133, v133, v112
	v_add_f32_e32 v133, v133, v105
	v_div_scale_f32 v115, s[0:1], v133, v133, 1.0
	v_rcp_f32_e32 v78, v115
	s_nop 0
	v_fma_f32 v98, -v115, v78, 1.0
	v_fmac_f32_e32 v78, v98, v78
	v_div_scale_f32 v98, vcc, 1.0, v133, 1.0
	v_mul_f32_e32 v107, v98, v78
	v_fma_f32 v106, -v115, v107, v98
	v_fmac_f32_e32 v107, v106, v78
	v_fma_f32 v115, -v115, v107, v98
	s_nop 1
	v_div_fmas_f32 v115, v115, v78, v107
	v_div_fixup_f32 v115, v115, v133, 1.0
	s_waitcnt lgkmcnt(0)
	v_xor_b32_e32 v106, 0xff, v73
	v_bfe_u32 v107, v106, 4, 4
	v_and_b32_e32 v106, 15, v106
	v_lshl_add_u32 v107, v107, 2, v67
	v_lshl_add_u32 v106, v106, 2, v67
	ds_read_b32 v107, v107
	ds_read_b32 v106, v106 offset:64
	v_xor_b32_e32 v98, 0xff, v83
	v_bfe_u32 v78, v98, 4, 4
	v_and_b32_e32 v98, 15, v98
	v_lshl_add_u32 v78, v78, 2, v67
	v_lshl_add_u32 v98, v98, 2, v67
	ds_read_b32 v78, v78
	ds_read_b32 v98, v98 offset:64
	v_xor_b32_e32 v108, 0xff, v116
	v_bfe_u32 v103, v108, 4, 4
	v_and_b32_e32 v108, 15, v108
	v_lshl_add_u32 v103, v103, 2, v67
	v_lshl_add_u32 v108, v108, 2, v67
	ds_read_b32 v103, v103
	ds_read_b32 v108, v108 offset:64
	v_xor_b32_e32 v72, 0xff, v89
	v_bfe_u32 v92, v72, 4, 4
	v_and_b32_e32 v72, 15, v72
	v_lshl_add_u32 v92, v92, 2, v67
	v_lshl_add_u32 v72, v72, 2, v67
	ds_read_b32 v92, v92
	ds_read_b32 v72, v72 offset:64
	v_xor_b32_e32 v75, 0xff, v91
	v_bfe_u32 v119, v75, 4, 4
	v_and_b32_e32 v75, 15, v75
	v_lshl_add_u32 v119, v119, 2, v67
	v_lshl_add_u32 v75, v75, 2, v67
	ds_read_b32 v119, v119
	ds_read_b32 v75, v75 offset:64
	v_xor_b32_e32 v114, 0xff, v96
	v_bfe_u32 v102, v114, 4, 4
	v_and_b32_e32 v114, 15, v114
	v_lshl_add_u32 v102, v102, 2, v67
	v_lshl_add_u32 v114, v114, 2, v67
	ds_read_b32 v102, v102
	ds_read_b32 v114, v114 offset:64
	v_xor_b32_e32 v97, 0xff, v79
	v_bfe_u32 v109, v97, 4, 4
	v_and_b32_e32 v97, 15, v97
	v_lshl_add_u32 v109, v109, 2, v67
	v_lshl_add_u32 v97, v97, 2, v67
	ds_read_b32 v109, v109
	ds_read_b32 v97, v97 offset:64
	v_xor_b32_e32 v104, 0xff, v87
	v_bfe_u32 v93, v104, 4, 4
	v_and_b32_e32 v104, 15, v104
	v_lshl_add_u32 v93, v93, 2, v67
	v_lshl_add_u32 v104, v104, 2, v67
	ds_read_b32 v93, v93
	ds_read_b32 v104, v104 offset:64
	v_xor_b32_e32 v99, 0xff, v71
	v_bfe_u32 v77, v99, 4, 4
	v_and_b32_e32 v99, 15, v99
	v_lshl_add_u32 v77, v77, 2, v67
	v_lshl_add_u32 v99, v99, 2, v67
	ds_read_b32 v77, v77
	ds_read_b32 v99, v99 offset:64
	v_xor_b32_e32 v135, 0xff, v88
	v_bfe_u32 v95, v135, 4, 4
	v_and_b32_e32 v135, 15, v135
	v_lshl_add_u32 v95, v95, 2, v67
	v_lshl_add_u32 v135, v135, 2, v67
	ds_read_b32 v95, v95
	ds_read_b32 v135, v135 offset:64
	v_xor_b32_e32 v76, 0xff, v118
	v_bfe_u32 v100, v76, 4, 4
	v_and_b32_e32 v76, 15, v76
	v_lshl_add_u32 v100, v100, 2, v67
	v_lshl_add_u32 v76, v76, 2, v67
	ds_read_b32 v100, v100
	ds_read_b32 v76, v76 offset:64
	v_xor_b32_e32 v84, 0xff, v82
	v_bfe_u32 v94, v84, 4, 4
	v_and_b32_e32 v84, 15, v84
	v_lshl_add_u32 v94, v94, 2, v67
	v_lshl_add_u32 v84, v84, 2, v67
	ds_read_b32 v94, v94
	ds_read_b32 v84, v84 offset:64
	v_xor_b32_e32 v86, 0xff, v117
	v_bfe_u32 v85, v86, 4, 4
	v_and_b32_e32 v86, 15, v86
	v_lshl_add_u32 v85, v85, 2, v67
	v_lshl_add_u32 v86, v86, 2, v67
	ds_read_b32 v85, v85
	ds_read_b32 v86, v86 offset:64
	v_xor_b32_e32 v101, 0xff, v110
	v_bfe_u32 v80, v101, 4, 4
	v_and_b32_e32 v101, 15, v101
	v_lshl_add_u32 v80, v80, 2, v67
	v_lshl_add_u32 v101, v101, 2, v67
	ds_read_b32 v80, v80
	ds_read_b32 v101, v101 offset:64
	v_xor_b32_e32 v74, 0xff, v70
	v_bfe_u32 v81, v74, 4, 4
	v_and_b32_e32 v74, 15, v74
	v_lshl_add_u32 v81, v81, 2, v67
	v_lshl_add_u32 v74, v74, 2, v67
	ds_read_b32 v81, v81
	ds_read_b32 v74, v74 offset:64
	v_xor_b32_e32 v136, 0xff, v111
	v_bfe_u32 v137, v136, 4, 4
	v_and_b32_e32 v136, 15, v136
	v_lshl_add_u32 v137, v137, 2, v67
	v_lshl_add_u32 v136, v136, 2, v67
	ds_read_b32 v137, v137
	ds_read_b32 v136, v136 offset:64
	s_waitcnt lgkmcnt(0)
	v_lshl_add_u32 v138, v107, 7, v106
	v_mul_f32_e32 v139, v132, v115
	v_lshl_add_u32 v140, v78, 7, v98
	v_mul_f32_e32 v141, v131, v115
	ds_write_b128 v68, v[138:141] offset:0
	v_lshl_add_u32 v138, v103, 7, v108
	v_mul_f32_e32 v139, v130, v115
	v_lshl_add_u32 v140, v92, 7, v72
	v_mul_f32_e32 v141, v129, v115
	ds_write_b128 v68, v[138:141] offset:16
	v_lshl_add_u32 v138, v119, 7, v75
	v_mul_f32_e32 v139, v128, v115
	v_lshl_add_u32 v140, v102, 7, v114
	v_mul_f32_e32 v141, v127, v115
	ds_write_b128 v68, v[138:141] offset:32
	v_lshl_add_u32 v138, v109, 7, v97
	v_mul_f32_e32 v139, v126, v115
	v_lshl_add_u32 v140, v93, 7, v104
	v_mul_f32_e32 v141, v125, v115
	ds_write_b128 v68, v[138:141] offset:48
	v_lshl_add_u32 v138, v77, 7, v99
	v_mul_f32_e32 v139, v124, v115
	v_lshl_add_u32 v140, v95, 7, v135
	v_mul_f32_e32 v141, v123, v115
	ds_write_b128 v68, v[138:141] offset:64
	v_lshl_add_u32 v138, v100, 7, v76
	v_mul_f32_e32 v139, v122, v115
	v_lshl_add_u32 v140, v94, 7, v84
	v_mul_f32_e32 v141, v121, v115
	ds_write_b128 v68, v[138:141] offset:80
	v_lshl_add_u32 v138, v85, 7, v86
	v_mul_f32_e32 v139, v120, v115
	v_lshl_add_u32 v140, v80, 7, v101
	v_mul_f32_e32 v141, v90, v115
	ds_write_b128 v68, v[138:141] offset:96
	v_lshl_add_u32 v138, v81, 7, v74
	v_mul_f32_e32 v139, v112, v115
	v_lshl_add_u32 v140, v137, 7, v136
	v_mul_f32_e32 v141, v105, v115
	ds_write_b128 v68, v[138:141] offset:112

; __device__ __forceinline__ unsigned pk2(float lo, float hi) { const f32x2 v = {lo, hi}; const bf16x2_t b = __builtin_convertvector(v, bf16x2_t); return __builtin_bit_cast(unsigned, b); }
; __device__ __forceinline__ float bflo(unsigned u) { return __uint_as_float(u << 16); }
; __device__ __forceinline__ float bfhi(unsigned u) { return __uint_as_float(u & 0xffff0000u); }
; __device__ __forceinline__ void peer_tile(const Args& A, LAS unsigned char* lds, int tile) {
;     ...
;     const bf16_t* A3 = (const bf16_t*)(A.ws + WS_A3); const float* RSq = (const float*)(A.ws + WS_RS);
;     for (int pass = 0; pass < 2; ++pass) {
;         const int tb = 8 * w + 4 * pass;
;         u32x4 xpa[4], xpb[4]; f32x2 oacc[4][8];
; #pragma unroll
;         for (int tk = 0; tk < 4; ++tk) { const size_t m = (size_t)tile * 64 + tb + tk;
;             { const u32x4 ra = *(const u32x4*)(A3 + m * 1024 + 16 * lane), rb = *(const u32x4*)(A3 + m * 1024 + 16 * lane + 8);
;               float xr_; { const f32x4 p0 = *(const f32x4*)(RSq + m * 16), p1 = *(const f32x4*)(RSq + m * 16 + 4), p2 = *(const f32x4*)(RSq + m * 16 + 8), p3 = *(const f32x4*)(RSq + m * 16 + 12);
;                 const f32x4 ps = (p0 + p1) + (p2 + p3); xr_ = rsqrtf(((ps[0] + ps[1]) + (ps[2] + ps[3])) * (1.f / 1024.f) + 1e-6f); }
;               const unsigned rr[8] = {ra.x, ra.y, ra.z, ra.w, rb.x, rb.y, rb.z, rb.w}; unsigned hh[8];
;               const float* sp = MOD + (int)(m >> 11) * 6144 + 3072 + 16 * lane;
; #pragma unroll
;               for (int q = 0; q < 8; ++q) { const f32x2 sh = *(const f32x2*)(sp + 2 * q); hh[q] = pk2(bflo(rr[q]) * xr_ + sh[0], bfhi(rr[q]) * xr_ + sh[1]); }
;               xpa[tk] = (u32x4){hh[0], hh[1], hh[2], hh[3]}; xpb[tk] = (u32x4){hh[4], hh[5], hh[6], hh[7]}; }
	s_mov_b64 exec, -1
	v_and_b32_e32 v240, 63, v214
	v_lshrrev_b32_e32 v242, 6, v214
	v_lshlrev_b32_e32 v240, 4, v240
	v_readfirstlane_b32 s16, v242
	v_lshlrev_b32_e32 v245, 1, v240
	v_lshlrev_b32_e32 v246, 2, v240
	v_lshrrev_b32_e32 v247, 4, v240
	v_and_b32_e32 v247, 48, v247
	v_mov_b32_e32 v244, 0
	v_mov_b32_e32 v243, 0x358637bd
	v_mov_b32_e32 v242, 0xbf3a00e3
	s_add_u32 s4, s50, 0x1000000
	s_addc_u32 s5, s51, 0
	s_add_u32 s6, s50, 0x2000000
	s_addc_u32 s7, s51, 0
	s_add_u32 s8, s50, 0x3000000
	s_addc_u32 s9, s51, 0
	s_add_u32 s52, s50, 0x3010000
	s_addc_u32 s53, s51, 0
	s_add_u32 s12, s50, 0xb000000
	s_addc_u32 s13, s51, 0
	s_add_u32 s14, s50, 0xd000000
	s_addc_u32 s15, s51, 0
	s_lshr_b32 s0, s2, 5
	s_mul_i32 s0, s0, 0x6000
	s_add_u32 s10, s50, s0
	s_addc_u32 s11, s51, 0
	s_add_u32 s80, s10, 0x4000
	s_addc_u32 s81, s11, 0
	s_add_u32 s82, s10, 0x6000
	s_addc_u32 s83, s11, 0
	s_mul_i32 s22, s16, 9920
	s_cmp_eq_u32 s16, 7
	s_cselect_b32 s22, 0x21000, s22
	s_mov_b32 s85, 0xffffffff
	s_mov_b32 s72, 0x3e6d3388
	s_mov_b32 s56, s4
	s_and_b32 s57, s5, 0xffff
	s_or_b32 s57, s57, 0x04000000
	s_mov_b32 s58, 16384
	s_mov_b32 s59, 0x00027000
	s_mov_b32 s60, s6
	s_and_b32 s61, s7, 0xffff
	s_or_b32 s61, s61, 0x04000000
	s_mov_b32 s62, 16384
	s_mov_b32 s63, 0x00027000
	s_lshl_b32 s76, s16, 3
	s_lshl_b32 s0, s2, 6
	s_add_i32 s77, s0, s76
	global_load_dwordx4 v[192:195], v246, s[80:81] offset:0
	global_load_dwordx4 v[196:199], v246, s[80:81] offset:16
	global_load_dwordx4 v[200:203], v246, s[80:81] offset:32
	global_load_dwordx4 v[204:207], v246, s[80:81] offset:48
	s_add_i32 s0, s77, 0
	s_lshl_b32 s1, s0, 11
	s_add_u32 s78, s12, s1
	s_addc_u32 s79, s13, 0
	global_load_dwordx4 v[128:131], v245, s[78:79]
	global_load_dwordx4 v[132:135], v245, s[78:79] offset:16
	global_load_dwordx4 v[136:139], v245, s[78:79] offset:2048
	global_load_dwordx4 v[140:143], v245, s[78:79] offset:2064
	s_lshl_b32 s1, s0, 6
	s_add_u32 s78, s14, s1
	s_addc_u32 s79, s15, 0
	global_load_dwordx4 v[144:147], v244, s[78:79] offset:0
	global_load_dwordx4 v[148:151], v244, s[78:79] offset:16
	global_load_dwordx4 v[152:155], v244, s[78:79] offset:32
	global_load_dwordx4 v[156:159], v244, s[78:79] offset:48
	global_load_dwordx4 v[160:163], v244, s[78:79] offset:64
	global_load_dwordx4 v[164:167], v244, s[78:79] offset:80
	global_load_dwordx4 v[168:171], v244, s[78:79] offset:96
	global_load_dwordx4 v[172:175], v244, s[78:79] offset:112
	s_waitcnt lgkmcnt(0)
	s_barrier
	s_add_i32 s0, s77, 2
	s_lshl_b32 s1, s0, 11
	s_add_u32 s78, s12, s1
	s_addc_u32 s79, s13, 0
	global_load_dwordx4 v[176:179], v245, s[78:79]
	global_load_dwordx4 v[180:183], v245, s[78:79] offset:16
	global_load_dwordx4 v[184:187], v245, s[78:79] offset:2048
	global_load_dwordx4 v[188:191], v245, s[78:79] offset:2064
	s_lshl_b32 s1, s0, 6
	s_add_u32 s78, s14, s1
	s_addc_u32 s79, s15, 0
	global_load_dwordx4 v[216:219], v244, s[78:79] offset:0
	global_load_dwordx4 v[220:223], v244, s[78:79] offset:16
	global_load_dwordx4 v[224:227], v244, s[78:79] offset:32
	global_load_dwordx4 v[228:231], v244, s[78:79] offset:48
	global_load_dwordx4 v[232:235], v244, s[78:79] offset:64
	global_load_dwordx4 v[236:239], v244, s[78:79] offset:80
	global_load_dwordx4 v[248:251], v244, s[78:79] offset:96
	global_load_dwordx4 v[252:255], v244, s[78:79] offset:112
	s_waitcnt vmcnt(12)
	v_pk_add_f32 v[144:145], v[144:145], v[148:149]
	v_pk_add_f32 v[146:147], v[146:147], v[150:151]
	v_pk_add_f32 v[152:153], v[152:153], v[156:157]
	v_pk_add_f32 v[154:155], v[154:155], v[158:159]
	v_pk_add_f32 v[144:145], v[144:145], v[152:153]
	v_pk_add_f32 v[146:147], v[146:147], v[154:155]
	v_add_f32_e32 v144, v144, v145
	v_add_f32_e32 v146, v146, v147
	v_add_f32_e32 v144, v144, v146
	v_fmamk_f32 v144, v144, 0x3a800000, v243
	v_rsq_f32_e32 v144, v144
	v_pk_add_f32 v[160:161], v[160:161], v[164:165]
	v_pk_add_f32 v[162:163], v[162:163], v[166:167]
	v_pk_add_f32 v[168:169], v[168:169], v[172:173]
	v_pk_add_f32 v[170:171], v[170:171], v[174:175]
	v_pk_add_f32 v[160:161], v[160:161], v[168:169]
	v_pk_add_f32 v[162:163], v[162:163], v[170:171]
	v_add_f32_e32 v160, v160, v161
	v_add_f32_e32 v162, v162, v163
	v_add_f32_e32 v160, v160, v162
	v_fmamk_f32 v160, v160, 0x3a800000, v243
	v_rsq_f32_e32 v160, v160
	v_lshlrev_b32_e32 v208, 16, v128
	v_and_b32_e32 v209, 0xffff0000, v128
	v_fma_f32 v208, v208, v144, v192
	v_fma_f32 v209, v209, v144, v193
	v_cvt_pk_bf16_f32 v210, v208, v209
	v_lshlrev_b32_e32 v0, 16, v210
	v_and_b32_e32 v1, 0xffff0000, v210
	v_lshlrev_b32_e32 v208, 16, v129
	v_and_b32_e32 v209, 0xffff0000, v129
	v_fma_f32 v208, v208, v144, v194
	v_fma_f32 v209, v209, v144, v195
	v_cvt_pk_bf16_f32 v210, v208, v209
	v_lshlrev_b32_e32 v2, 16, v210
	v_and_b32_e32 v3, 0xffff0000, v210
	v_lshlrev_b32_e32 v208, 16, v130
	v_and_b32_e32 v209, 0xffff0000, v130
	v_fma_f32 v208, v208, v144, v196
	v_fma_f32 v209, v209, v144, v197
	v_cvt_pk_bf16_f32 v210, v208, v209
	v_lshlrev_b32_e32 v4, 16, v210
	v_and_b32_e32 v5, 0xffff0000, v210
	v_lshlrev_b32_e32 v208, 16, v131
	v_and_b32_e32 v209, 0xffff0000, v131
	v_fma_f32 v208, v208, v144, v198
	v_fma_f32 v209, v209, v144, v199
	v_cvt_pk_bf16_f32 v210, v208, v209
	v_lshlrev_b32_e32 v6, 16, v210
	v_and_b32_e32 v7, 0xffff0000, v210
	v_lshlrev_b32_e32 v208, 16, v132
	v_and_b32_e32 v209, 0xffff0000, v132
	v_fma_f32 v208, v208, v144, v200
	v_fma_f32 v209, v209, v144, v201
	v_cvt_pk_bf16_f32 v210, v208, v209
	v_lshlrev_b32_e32 v8, 16, v210
	v_and_b32_e32 v9, 0xffff0000, v210
	v_lshlrev_b32_e32 v208, 16, v133
	v_and_b32_e32 v209, 0xffff0000, v133
	v_fma_f32 v208, v208, v144, v202
	v_fma_f32 v209, v209, v144, v203
	v_cvt_pk_bf16_f32 v210, v208, v209
; __device__ __forceinline__ unsigned pk2(float lo, float hi) { const f32x2 v = {lo, hi}; const bf16x2_t b = __builtin_convertvector(v, bf16x2_t); return __builtin_bit_cast(unsigned, b); }
; __device__ __forceinline__ float bflo(unsigned u) { return __uint_as_float(u << 16); }
; __device__ __forceinline__ float bfhi(unsigned u) { return __uint_as_float(u & 0xffff0000u); }
; __device__ __forceinline__ void peer_tile(const Args& A, LAS unsigned char* lds, int tile) {
;     ...
;         for (int tk = 0; tk < 4; ++tk) { const size_t m = (size_t)tile * 64 + tb + tk;
;             { const u32x4 ra = *(const u32x4*)(A3 + m * 1024 + 16 * lane), rb = *(const u32x4*)(A3 + m * 1024 + 16 * lane + 8);
;               float xr_; { const f32x4 p0 = *(const f32x4*)(RSq + m * 16), p1 = *(const f32x4*)(RSq + m * 16 + 4), p2 = *(const f32x4*)(RSq + m * 16 + 8), p3 = *(const f32x4*)(RSq + m * 16 + 12);
;                 const f32x4 ps = (p0 + p1) + (p2 + p3); xr_ = rsqrtf(((ps[0] + ps[1]) + (ps[2] + ps[3])) * (1.f / 1024.f) + 1e-6f); }
;               const unsigned rr[8] = {ra.x, ra.y, ra.z, ra.w, rb.x, rb.y, rb.z, rb.w}; unsigned hh[8];
;               const float* sp = MOD + (int)(m >> 11) * 6144 + 3072 + 16 * lane;
; #pragma unroll
;               for (int q = 0; q < 8; ++q) { const f32x2 sh = *(const f32x2*)(sp + 2 * q); hh[q] = pk2(bflo(rr[q]) * xr_ + sh[0], bfhi(rr[q]) * xr_ + sh[1]); }
;               xpa[tk] = (u32x4){hh[0], hh[1], hh[2], hh[3]}; xpb[tk] = (u32x4){hh[4], hh[5], hh[6], hh[7]}; }
	v_lshlrev_b32_e32 v10, 16, v210
	v_and_b32_e32 v11, 0xffff0000, v210
	v_lshlrev_b32_e32 v208, 16, v134
	v_and_b32_e32 v209, 0xffff0000, v134
	v_fma_f32 v208, v208, v144, v204
	v_fma_f32 v209, v209, v144, v205
	v_cvt_pk_bf16_f32 v210, v208, v209
	v_lshlrev_b32_e32 v12, 16, v210
	v_and_b32_e32 v13, 0xffff0000, v210
	v_lshlrev_b32_e32 v208, 16, v135
	v_and_b32_e32 v209, 0xffff0000, v135
	v_fma_f32 v208, v208, v144, v206
	v_fma_f32 v209, v209, v144, v207
	v_cvt_pk_bf16_f32 v210, v208, v209
	v_lshlrev_b32_e32 v14, 16, v210
	v_and_b32_e32 v15, 0xffff0000, v210
	v_lshlrev_b32_e32 v208, 16, v136
	v_and_b32_e32 v209, 0xffff0000, v136
	v_fma_f32 v208, v208, v160, v192
	v_fma_f32 v209, v209, v160, v193
	v_cvt_pk_bf16_f32 v210, v208, v209
	v_lshlrev_b32_e32 v16, 16, v210
	v_and_b32_e32 v17, 0xffff0000, v210
	v_lshlrev_b32_e32 v208, 16, v137
	v_and_b32_e32 v209, 0xffff0000, v137
	v_fma_f32 v208, v208, v160, v194
	v_fma_f32 v209, v209, v160, v195
	v_cvt_pk_bf16_f32 v210, v208, v209
	v_lshlrev_b32_e32 v18, 16, v210
	v_and_b32_e32 v19, 0xffff0000, v210
	v_lshlrev_b32_e32 v208, 16, v138
	v_and_b32_e32 v209, 0xffff0000, v138
	v_fma_f32 v208, v208, v160, v196
	v_fma_f32 v209, v209, v160, v197
	v_cvt_pk_bf16_f32 v210, v208, v209
	v_lshlrev_b32_e32 v20, 16, v210
	v_and_b32_e32 v21, 0xffff0000, v210
	v_lshlrev_b32_e32 v208, 16, v139
	v_and_b32_e32 v209, 0xffff0000, v139
	v_fma_f32 v208, v208, v160, v198
	v_fma_f32 v209, v209, v160, v199
	v_cvt_pk_bf16_f32 v210, v208, v209
	v_lshlrev_b32_e32 v22, 16, v210
	v_and_b32_e32 v23, 0xffff0000, v210
	v_lshlrev_b32_e32 v208, 16, v140
	v_and_b32_e32 v209, 0xffff0000, v140
	v_fma_f32 v208, v208, v160, v200
	v_fma_f32 v209, v209, v160, v201
	v_cvt_pk_bf16_f32 v210, v208, v209
	v_lshlrev_b32_e32 v24, 16, v210
	v_and_b32_e32 v25, 0xffff0000, v210
	v_lshlrev_b32_e32 v208, 16, v141
	v_and_b32_e32 v209, 0xffff0000, v141
	v_fma_f32 v208, v208, v160, v202
	v_fma_f32 v209, v209, v160, v203
	v_cvt_pk_bf16_f32 v210, v208, v209
	v_lshlrev_b32_e32 v26, 16, v210
	v_and_b32_e32 v27, 0xffff0000, v210
	v_lshlrev_b32_e32 v208, 16, v142
	v_and_b32_e32 v209, 0xffff0000, v142
	v_fma_f32 v208, v208, v160, v204
	v_fma_f32 v209, v209, v160, v205
	v_cvt_pk_bf16_f32 v210, v208, v209
	v_lshlrev_b32_e32 v28, 16, v210
	v_and_b32_e32 v29, 0xffff0000, v210
	v_lshlrev_b32_e32 v208, 16, v143
	v_and_b32_e32 v209, 0xffff0000, v143
	v_fma_f32 v208, v208, v160, v206
	v_fma_f32 v209, v209, v160, v207
	v_cvt_pk_bf16_f32 v210, v208, v209
	v_lshlrev_b32_e32 v30, 16, v210
	v_and_b32_e32 v31, 0xffff0000, v210
	s_nop 0
	s_add_i32 s0, s77, 4
	s_lshl_b32 s1, s0, 11
	s_add_u32 s78, s12, s1
	s_addc_u32 s79, s13, 0
	global_load_dwordx4 v[128:131], v245, s[78:79]
	global_load_dwordx4 v[132:135], v245, s[78:79] offset:16
	global_load_dwordx4 v[136:139], v245, s[78:79] offset:2048
	global_load_dwordx4 v[140:143], v245, s[78:79] offset:2064
	s_lshl_b32 s1, s0, 6
	s_add_u32 s78, s14, s1
	s_addc_u32 s79, s15, 0
	global_load_dwordx4 v[144:147], v244, s[78:79] offset:0
	global_load_dwordx4 v[148:151], v244, s[78:79] offset:16
	global_load_dwordx4 v[152:155], v244, s[78:79] offset:32
	global_load_dwordx4 v[156:159], v244, s[78:79] offset:48
	global_load_dwordx4 v[160:163], v244, s[78:79] offset:64
	global_load_dwordx4 v[164:167], v244, s[78:79] offset:80
	global_load_dwordx4 v[168:171], v244, s[78:79] offset:96
	global_load_dwordx4 v[172:175], v244, s[78:79] offset:112
	s_waitcnt vmcnt(12)
	v_pk_add_f32 v[216:217], v[216:217], v[220:221]
	v_pk_add_f32 v[218:219], v[218:219], v[222:223]
	v_pk_add_f32 v[224:225], v[224:225], v[228:229]
	v_pk_add_f32 v[226:227], v[226:227], v[230:231]
	v_pk_add_f32 v[216:217], v[216:217], v[224:225]
	v_pk_add_f32 v[218:219], v[218:219], v[226:227]
	v_add_f32_e32 v216, v216, v217
	v_add_f32_e32 v218, v218, v219
	v_add_f32_e32 v216, v216, v218
	v_fmamk_f32 v216, v216, 0x3a800000, v243
	v_rsq_f32_e32 v216, v216
	v_pk_add_f32 v[232:233], v[232:233], v[236:237]
	v_pk_add_f32 v[234:235], v[234:235], v[238:239]
	v_pk_add_f32 v[248:249], v[248:249], v[252:253]
	v_pk_add_f32 v[250:251], v[250:251], v[254:255]
	v_pk_add_f32 v[232:233], v[232:233], v[248:249]
	v_pk_add_f32 v[234:235], v[234:235], v[250:251]
	v_add_f32_e32 v232, v232, v233
	v_add_f32_e32 v234, v234, v235
	v_add_f32_e32 v232, v232, v234
	v_fmamk_f32 v232, v232, 0x3a800000, v243
	v_rsq_f32_e32 v232, v232
	v_lshlrev_b32_e32 v208, 16, v176
	v_and_b32_e32 v209, 0xffff0000, v176
	v_fma_f32 v208, v208, v216, v192
	v_fma_f32 v209, v209, v216, v193
	v_cvt_pk_bf16_f32 v210, v208, v209
	v_lshlrev_b32_e32 v32, 16, v210
	v_and_b32_e32 v33, 0xffff0000, v210
	v_lshlrev_b32_e32 v208, 16, v177
	v_and_b32_e32 v209, 0xffff0000, v177
	v_fma_f32 v208, v208, v216, v194
	v_fma_f32 v209, v209, v216, v195
	v_cvt_pk_bf16_f32 v210, v208, v209
	v_lshlrev_b32_e32 v34, 16, v210
	v_and_b32_e32 v35, 0xffff0000, v210
	v_lshlrev_b32_e32 v208, 16, v178
	v_and_b32_e32 v209, 0xffff0000, v178
	v_fma_f32 v208, v208, v216, v196
	v_fma_f32 v209, v209, v216, v197
	v_cvt_pk_bf16_f32 v210, v208, v209
	v_lshlrev_b32_e32 v36, 16, v210
	v_and_b32_e32 v37, 0xffff0000, v210
	v_lshlrev_b32_e32 v208, 16, v179
	v_and_b32_e32 v209, 0xffff0000, v179
	v_fma_f32 v208, v208, v216, v198
	v_fma_f32 v209, v209, v216, v199
	v_cvt_pk_bf16_f32 v210, v208, v209
	v_lshlrev_b32_e32 v38, 16, v210
	v_and_b32_e32 v39, 0xffff0000, v210
	v_lshlrev_b32_e32 v208, 16, v180
	v_and_b32_e32 v209, 0xffff0000, v180
	v_fma_f32 v208, v208, v216, v200
	v_fma_f32 v209, v209, v216, v201
	v_cvt_pk_bf16_f32 v210, v208, v209
	v_lshlrev_b32_e32 v40, 16, v210
	v_and_b32_e32 v41, 0xffff0000, v210
	v_lshlrev_b32_e32 v208, 16, v181
	v_and_b32_e32 v209, 0xffff0000, v181
; __device__ __forceinline__ unsigned pk2(float lo, float hi) { const f32x2 v = {lo, hi}; const bf16x2_t b = __builtin_convertvector(v, bf16x2_t); return __builtin_bit_cast(unsigned, b); }
; __device__ __forceinline__ float bflo(unsigned u) { return __uint_as_float(u << 16); }
; __device__ __forceinline__ float bfhi(unsigned u) { return __uint_as_float(u & 0xffff0000u); }
; __device__ __forceinline__ void peer_tile(const Args& A, LAS unsigned char* lds, int tile) {
;     ...
;         for (int tk = 0; tk < 4; ++tk) { const size_t m = (size_t)tile * 64 + tb + tk;
;             { const u32x4 ra = *(const u32x4*)(A3 + m * 1024 + 16 * lane), rb = *(const u32x4*)(A3 + m * 1024 + 16 * lane + 8);
;               float xr_; { const f32x4 p0 = *(const f32x4*)(RSq + m * 16), p1 = *(const f32x4*)(RSq + m * 16 + 4), p2 = *(const f32x4*)(RSq + m * 16 + 8), p3 = *(const f32x4*)(RSq + m * 16 + 12);
;                 const f32x4 ps = (p0 + p1) + (p2 + p3); xr_ = rsqrtf(((ps[0] + ps[1]) + (ps[2] + ps[3])) * (1.f / 1024.f) + 1e-6f); }
;               const unsigned rr[8] = {ra.x, ra.y, ra.z, ra.w, rb.x, rb.y, rb.z, rb.w}; unsigned hh[8];
;               const float* sp = MOD + (int)(m >> 11) * 6144 + 3072 + 16 * lane;
; #pragma unroll
;               for (int q = 0; q < 8; ++q) { const f32x2 sh = *(const f32x2*)(sp + 2 * q); hh[q] = pk2(bflo(rr[q]) * xr_ + sh[0], bfhi(rr[q]) * xr_ + sh[1]); }
;               xpa[tk] = (u32x4){hh[0], hh[1], hh[2], hh[3]}; xpb[tk] = (u32x4){hh[4], hh[5], hh[6], hh[7]}; }
	v_fma_f32 v208, v208, v216, v202
	v_fma_f32 v209, v209, v216, v203
	v_cvt_pk_bf16_f32 v210, v208, v209
	v_lshlrev_b32_e32 v42, 16, v210
	v_and_b32_e32 v43, 0xffff0000, v210
	v_lshlrev_b32_e32 v208, 16, v182
	v_and_b32_e32 v209, 0xffff0000, v182
	v_fma_f32 v208, v208, v216, v204
	v_fma_f32 v209, v209, v216, v205
	v_cvt_pk_bf16_f32 v210, v208, v209
	v_lshlrev_b32_e32 v44, 16, v210
	v_and_b32_e32 v45, 0xffff0000, v210
	v_lshlrev_b32_e32 v208, 16, v183
	v_and_b32_e32 v209, 0xffff0000, v183
	v_fma_f32 v208, v208, v216, v206
	v_fma_f32 v209, v209, v216, v207
	v_cvt_pk_bf16_f32 v210, v208, v209
	v_lshlrev_b32_e32 v46, 16, v210
	v_and_b32_e32 v47, 0xffff0000, v210
	v_lshlrev_b32_e32 v208, 16, v184
	v_and_b32_e32 v209, 0xffff0000, v184
	v_fma_f32 v208, v208, v232, v192
	v_fma_f32 v209, v209, v232, v193
	v_cvt_pk_bf16_f32 v210, v208, v209
	v_lshlrev_b32_e32 v48, 16, v210
	v_and_b32_e32 v49, 0xffff0000, v210
	v_lshlrev_b32_e32 v208, 16, v185
	v_and_b32_e32 v209, 0xffff0000, v185
	v_fma_f32 v208, v208, v232, v194
	v_fma_f32 v209, v209, v232, v195
	v_cvt_pk_bf16_f32 v210, v208, v209
	v_lshlrev_b32_e32 v50, 16, v210
	v_and_b32_e32 v51, 0xffff0000, v210
	v_lshlrev_b32_e32 v208, 16, v186
	v_and_b32_e32 v209, 0xffff0000, v186
	v_fma_f32 v208, v208, v232, v196
	v_fma_f32 v209, v209, v232, v197
	v_cvt_pk_bf16_f32 v210, v208, v209
	v_lshlrev_b32_e32 v52, 16, v210
	v_and_b32_e32 v53, 0xffff0000, v210
	v_lshlrev_b32_e32 v208, 16, v187
	v_and_b32_e32 v209, 0xffff0000, v187
	v_fma_f32 v208, v208, v232, v198
	v_fma_f32 v209, v209, v232, v199
	v_cvt_pk_bf16_f32 v210, v208, v209
	v_lshlrev_b32_e32 v54, 16, v210
	v_and_b32_e32 v55, 0xffff0000, v210
	v_lshlrev_b32_e32 v208, 16, v188
	v_and_b32_e32 v209, 0xffff0000, v188
	v_fma_f32 v208, v208, v232, v200
	v_fma_f32 v209, v209, v232, v201
	v_cvt_pk_bf16_f32 v210, v208, v209
	v_lshlrev_b32_e32 v56, 16, v210
	v_and_b32_e32 v57, 0xffff0000, v210
	v_lshlrev_b32_e32 v208, 16, v189
	v_and_b32_e32 v209, 0xffff0000, v189
	v_fma_f32 v208, v208, v232, v202
	v_fma_f32 v209, v209, v232, v203
	v_cvt_pk_bf16_f32 v210, v208, v209
	v_lshlrev_b32_e32 v58, 16, v210
	v_and_b32_e32 v59, 0xffff0000, v210
	v_lshlrev_b32_e32 v208, 16, v190
	v_and_b32_e32 v209, 0xffff0000, v190
	v_fma_f32 v208, v208, v232, v204
	v_fma_f32 v209, v209, v232, v205
	v_cvt_pk_bf16_f32 v210, v208, v209
	v_lshlrev_b32_e32 v60, 16, v210
	v_and_b32_e32 v61, 0xffff0000, v210
	v_lshlrev_b32_e32 v208, 16, v191
	v_and_b32_e32 v209, 0xffff0000, v191
	v_fma_f32 v208, v208, v232, v206
	v_fma_f32 v209, v209, v232, v207
	v_cvt_pk_bf16_f32 v210, v208, v209
	v_lshlrev_b32_e32 v62, 16, v210
	v_and_b32_e32 v63, 0xffff0000, v210
	s_nop 0
	s_add_i32 s0, s77, 6
	s_lshl_b32 s1, s0, 11
	s_add_u32 s78, s12, s1
	s_addc_u32 s79, s13, 0
	global_load_dwordx4 v[176:179], v245, s[78:79]
	global_load_dwordx4 v[180:183], v245, s[78:79] offset:16
	global_load_dwordx4 v[184:187], v245, s[78:79] offset:2048
	global_load_dwordx4 v[188:191], v245, s[78:79] offset:2064
	s_lshl_b32 s1, s0, 6
	s_add_u32 s78, s14, s1
	s_addc_u32 s79, s15, 0
	global_load_dwordx4 v[216:219], v244, s[78:79] offset:0
	global_load_dwordx4 v[220:223], v244, s[78:79] offset:16
	global_load_dwordx4 v[224:227], v244, s[78:79] offset:32
	global_load_dwordx4 v[228:231], v244, s[78:79] offset:48
	global_load_dwordx4 v[232:235], v244, s[78:79] offset:64
	global_load_dwordx4 v[236:239], v244, s[78:79] offset:80
	global_load_dwordx4 v[248:251], v244, s[78:79] offset:96
	global_load_dwordx4 v[252:255], v244, s[78:79] offset:112
	s_waitcnt vmcnt(12)
	v_pk_add_f32 v[144:145], v[144:145], v[148:149]
	v_pk_add_f32 v[146:147], v[146:147], v[150:151]
	v_pk_add_f32 v[152:153], v[152:153], v[156:157]
	v_pk_add_f32 v[154:155], v[154:155], v[158:159]
	v_pk_add_f32 v[144:145], v[144:145], v[152:153]
	v_pk_add_f32 v[146:147], v[146:147], v[154:155]
	v_add_f32_e32 v144, v144, v145
	v_add_f32_e32 v146, v146, v147
	v_add_f32_e32 v144, v144, v146
	v_fmamk_f32 v144, v144, 0x3a800000, v243
	v_rsq_f32_e32 v144, v144
	v_pk_add_f32 v[160:161], v[160:161], v[164:165]
	v_pk_add_f32 v[162:163], v[162:163], v[166:167]
	v_pk_add_f32 v[168:169], v[168:169], v[172:173]
	v_pk_add_f32 v[170:171], v[170:171], v[174:175]
	v_pk_add_f32 v[160:161], v[160:161], v[168:169]
	v_pk_add_f32 v[162:163], v[162:163], v[170:171]
	v_add_f32_e32 v160, v160, v161
	v_add_f32_e32 v162, v162, v163
	v_add_f32_e32 v160, v160, v162
	v_fmamk_f32 v160, v160, 0x3a800000, v243
	v_rsq_f32_e32 v160, v160
	v_lshlrev_b32_e32 v208, 16, v128
	v_and_b32_e32 v209, 0xffff0000, v128
	v_fma_f32 v208, v208, v144, v192
	v_fma_f32 v209, v209, v144, v193
	v_cvt_pk_bf16_f32 v210, v208, v209
	v_lshlrev_b32_e32 v64, 16, v210
	v_and_b32_e32 v65, 0xffff0000, v210
	v_lshlrev_b32_e32 v208, 16, v129
	v_and_b32_e32 v209, 0xffff0000, v129
	v_fma_f32 v208, v208, v144, v194
	v_fma_f32 v209, v209, v144, v195
	v_cvt_pk_bf16_f32 v210, v208, v209
	v_lshlrev_b32_e32 v66, 16, v210
	v_and_b32_e32 v67, 0xffff0000, v210
	v_lshlrev_b32_e32 v208, 16, v130
	v_and_b32_e32 v209, 0xffff0000, v130
	v_fma_f32 v208, v208, v144, v196
	v_fma_f32 v209, v209, v144, v197
	v_cvt_pk_bf16_f32 v210, v208, v209
	v_lshlrev_b32_e32 v68, 16, v210
	v_and_b32_e32 v69, 0xffff0000, v210
	v_lshlrev_b32_e32 v208, 16, v131
	v_and_b32_e32 v209, 0xffff0000, v131
	v_fma_f32 v208, v208, v144, v198
	v_fma_f32 v209, v209, v144, v199
	v_cvt_pk_bf16_f32 v210, v208, v209
	v_lshlrev_b32_e32 v70, 16, v210
	v_and_b32_e32 v71, 0xffff0000, v210
	v_lshlrev_b32_e32 v208, 16, v132
	v_and_b32_e32 v209, 0xffff0000, v132
	v_fma_f32 v208, v208, v144, v200
	v_fma_f32 v209, v209, v144, v201
	v_cvt_pk_bf16_f32 v210, v208, v209
	v_lshlrev_b32_e32 v72, 16, v210
; __device__ __forceinline__ unsigned pk2(float lo, float hi) { const f32x2 v = {lo, hi}; const bf16x2_t b = __builtin_convertvector(v, bf16x2_t); return __builtin_bit_cast(unsigned, b); }
; __device__ __forceinline__ float bflo(unsigned u) { return __uint_as_float(u << 16); }
; __device__ __forceinline__ float bfhi(unsigned u) { return __uint_as_float(u & 0xffff0000u); }
; __device__ __forceinline__ void peer_tile(const Args& A, LAS unsigned char* lds, int tile) {
;     ...
;         for (int tk = 0; tk < 4; ++tk) { const size_t m = (size_t)tile * 64 + tb + tk;
;             { const u32x4 ra = *(const u32x4*)(A3 + m * 1024 + 16 * lane), rb = *(const u32x4*)(A3 + m * 1024 + 16 * lane + 8);
;               float xr_; { const f32x4 p0 = *(const f32x4*)(RSq + m * 16), p1 = *(const f32x4*)(RSq + m * 16 + 4), p2 = *(const f32x4*)(RSq + m * 16 + 8), p3 = *(const f32x4*)(RSq + m * 16 + 12);
;                 const f32x4 ps = (p0 + p1) + (p2 + p3); xr_ = rsqrtf(((ps[0] + ps[1]) + (ps[2] + ps[3])) * (1.f / 1024.f) + 1e-6f); }
;               const unsigned rr[8] = {ra.x, ra.y, ra.z, ra.w, rb.x, rb.y, rb.z, rb.w}; unsigned hh[8];
;               const float* sp = MOD + (int)(m >> 11) * 6144 + 3072 + 16 * lane;
; #pragma unroll
;               for (int q = 0; q < 8; ++q) { const f32x2 sh = *(const f32x2*)(sp + 2 * q); hh[q] = pk2(bflo(rr[q]) * xr_ + sh[0], bfhi(rr[q]) * xr_ + sh[1]); }
;               xpa[tk] = (u32x4){hh[0], hh[1], hh[2], hh[3]}; xpb[tk] = (u32x4){hh[4], hh[5], hh[6], hh[7]}; }
	v_and_b32_e32 v73, 0xffff0000, v210
	v_lshlrev_b32_e32 v208, 16, v133
	v_and_b32_e32 v209, 0xffff0000, v133
	v_fma_f32 v208, v208, v144, v202
	v_fma_f32 v209, v209, v144, v203
	v_cvt_pk_bf16_f32 v210, v208, v209
	v_lshlrev_b32_e32 v74, 16, v210
	v_and_b32_e32 v75, 0xffff0000, v210
	v_lshlrev_b32_e32 v208, 16, v134
	v_and_b32_e32 v209, 0xffff0000, v134
	v_fma_f32 v208, v208, v144, v204
	v_fma_f32 v209, v209, v144, v205
	v_cvt_pk_bf16_f32 v210, v208, v209
	v_lshlrev_b32_e32 v76, 16, v210
	v_and_b32_e32 v77, 0xffff0000, v210
	v_lshlrev_b32_e32 v208, 16, v135
	v_and_b32_e32 v209, 0xffff0000, v135
	v_fma_f32 v208, v208, v144, v206
	v_fma_f32 v209, v209, v144, v207
	v_cvt_pk_bf16_f32 v210, v208, v209
	v_lshlrev_b32_e32 v78, 16, v210
	v_and_b32_e32 v79, 0xffff0000, v210
	v_lshlrev_b32_e32 v208, 16, v136
	v_and_b32_e32 v209, 0xffff0000, v136
	v_fma_f32 v208, v208, v160, v192
	v_fma_f32 v209, v209, v160, v193
	v_cvt_pk_bf16_f32 v210, v208, v209
	v_lshlrev_b32_e32 v80, 16, v210
	v_and_b32_e32 v81, 0xffff0000, v210
	v_lshlrev_b32_e32 v208, 16, v137
	v_and_b32_e32 v209, 0xffff0000, v137
	v_fma_f32 v208, v208, v160, v194
	v_fma_f32 v209, v209, v160, v195
	v_cvt_pk_bf16_f32 v210, v208, v209
	v_lshlrev_b32_e32 v82, 16, v210
	v_and_b32_e32 v83, 0xffff0000, v210
	v_lshlrev_b32_e32 v208, 16, v138
	v_and_b32_e32 v209, 0xffff0000, v138
	v_fma_f32 v208, v208, v160, v196
	v_fma_f32 v209, v209, v160, v197
	v_cvt_pk_bf16_f32 v210, v208, v209
	v_lshlrev_b32_e32 v84, 16, v210
	v_and_b32_e32 v85, 0xffff0000, v210
	v_lshlrev_b32_e32 v208, 16, v139
	v_and_b32_e32 v209, 0xffff0000, v139
	v_fma_f32 v208, v208, v160, v198
	v_fma_f32 v209, v209, v160, v199
	v_cvt_pk_bf16_f32 v210, v208, v209
	v_lshlrev_b32_e32 v86, 16, v210
	v_and_b32_e32 v87, 0xffff0000, v210
	v_lshlrev_b32_e32 v208, 16, v140
	v_and_b32_e32 v209, 0xffff0000, v140
	v_fma_f32 v208, v208, v160, v200
	v_fma_f32 v209, v209, v160, v201
	v_cvt_pk_bf16_f32 v210, v208, v209
	v_lshlrev_b32_e32 v88, 16, v210
	v_and_b32_e32 v89, 0xffff0000, v210
	v_lshlrev_b32_e32 v208, 16, v141
	v_and_b32_e32 v209, 0xffff0000, v141
	v_fma_f32 v208, v208, v160, v202
	v_fma_f32 v209, v209, v160, v203
	v_cvt_pk_bf16_f32 v210, v208, v209
	v_lshlrev_b32_e32 v90, 16, v210
	v_and_b32_e32 v91, 0xffff0000, v210
	v_lshlrev_b32_e32 v208, 16, v142
	v_and_b32_e32 v209, 0xffff0000, v142
	v_fma_f32 v208, v208, v160, v204
	v_fma_f32 v209, v209, v160, v205
	v_cvt_pk_bf16_f32 v210, v208, v209
	v_lshlrev_b32_e32 v92, 16, v210
	v_and_b32_e32 v93, 0xffff0000, v210
	v_lshlrev_b32_e32 v208, 16, v143
	v_and_b32_e32 v209, 0xffff0000, v143
	v_fma_f32 v208, v208, v160, v206
	v_fma_f32 v209, v209, v160, v207
	v_cvt_pk_bf16_f32 v210, v208, v209
	v_lshlrev_b32_e32 v94, 16, v210
	v_and_b32_e32 v95, 0xffff0000, v210
	s_nop 0
	s_waitcnt vmcnt(0)
	v_pk_add_f32 v[216:217], v[216:217], v[220:221]
	v_pk_add_f32 v[218:219], v[218:219], v[222:223]
	v_pk_add_f32 v[224:225], v[224:225], v[228:229]
	v_pk_add_f32 v[226:227], v[226:227], v[230:231]
	v_pk_add_f32 v[216:217], v[216:217], v[224:225]
	v_pk_add_f32 v[218:219], v[218:219], v[226:227]
	v_add_f32_e32 v216, v216, v217
	v_add_f32_e32 v218, v218, v219
	v_add_f32_e32 v216, v216, v218
	v_fmamk_f32 v216, v216, 0x3a800000, v243
	v_rsq_f32_e32 v216, v216
	v_pk_add_f32 v[232:233], v[232:233], v[236:237]
	v_pk_add_f32 v[234:235], v[234:235], v[238:239]
	v_pk_add_f32 v[248:249], v[248:249], v[252:253]
	v_pk_add_f32 v[250:251], v[250:251], v[254:255]
	v_pk_add_f32 v[232:233], v[232:233], v[248:249]
	v_pk_add_f32 v[234:235], v[234:235], v[250:251]
	v_add_f32_e32 v232, v232, v233
	v_add_f32_e32 v234, v234, v235
	v_add_f32_e32 v232, v232, v234
	v_fmamk_f32 v232, v232, 0x3a800000, v243
	v_rsq_f32_e32 v232, v232
	v_lshlrev_b32_e32 v208, 16, v176
	v_and_b32_e32 v209, 0xffff0000, v176
	v_fma_f32 v208, v208, v216, v192
	v_fma_f32 v209, v209, v216, v193
	v_cvt_pk_bf16_f32 v210, v208, v209
	v_lshlrev_b32_e32 v96, 16, v210
	v_and_b32_e32 v97, 0xffff0000, v210
	v_lshlrev_b32_e32 v208, 16, v177
	v_and_b32_e32 v209, 0xffff0000, v177
	v_fma_f32 v208, v208, v216, v194
	v_fma_f32 v209, v209, v216, v195
	v_cvt_pk_bf16_f32 v210, v208, v209
	v_lshlrev_b32_e32 v98, 16, v210
	v_and_b32_e32 v99, 0xffff0000, v210
	v_lshlrev_b32_e32 v208, 16, v178
	v_and_b32_e32 v209, 0xffff0000, v178
	v_fma_f32 v208, v208, v216, v196
	v_fma_f32 v209, v209, v216, v197
	v_cvt_pk_bf16_f32 v210, v208, v209
	v_lshlrev_b32_e32 v100, 16, v210
	v_and_b32_e32 v101, 0xffff0000, v210
	v_lshlrev_b32_e32 v208, 16, v179
	v_and_b32_e32 v209, 0xffff0000, v179
	v_fma_f32 v208, v208, v216, v198
	v_fma_f32 v209, v209, v216, v199
	v_cvt_pk_bf16_f32 v210, v208, v209
	v_lshlrev_b32_e32 v102, 16, v210
	v_and_b32_e32 v103, 0xffff0000, v210
	v_lshlrev_b32_e32 v208, 16, v180
	v_and_b32_e32 v209, 0xffff0000, v180
	v_fma_f32 v208, v208, v216, v200
	v_fma_f32 v209, v209, v216, v201
	v_cvt_pk_bf16_f32 v210, v208, v209
	v_lshlrev_b32_e32 v104, 16, v210
	v_and_b32_e32 v105, 0xffff0000, v210
	v_lshlrev_b32_e32 v208, 16, v181
	v_and_b32_e32 v209, 0xffff0000, v181
	v_fma_f32 v208, v208, v216, v202
	v_fma_f32 v209, v209, v216, v203
	v_cvt_pk_bf16_f32 v210, v208, v209
	v_lshlrev_b32_e32 v106, 16, v210
	v_and_b32_e32 v107, 0xffff0000, v210
	v_lshlrev_b32_e32 v208, 16, v182
	v_and_b32_e32 v209, 0xffff0000, v182
	v_fma_f32 v208, v208, v216, v204
	v_fma_f32 v209, v209, v216, v205
	v_cvt_pk_bf16_f32 v210, v208, v209
	v_lshlrev_b32_e32 v108, 16, v210
	v_and_b32_e32 v109, 0xffff0000, v210
	v_lshlrev_b32_e32 v208, 16, v183
	v_and_b32_e32 v209, 0xffff0000, v183
	v_fma_f32 v208, v208, v216, v206
	v_fma_f32 v209, v209, v216, v207
	v_cvt_pk_bf16_f32 v210, v208, v209
	v_lshlrev_b32_e32 v110, 16, v210
; __device__ __forceinline__ unsigned pk2(float lo, float hi) { const f32x2 v = {lo, hi}; const bf16x2_t b = __builtin_convertvector(v, bf16x2_t); return __builtin_bit_cast(unsigned, b); }
; __device__ __forceinline__ float bflo(unsigned u) { return __uint_as_float(u << 16); }
; __device__ __forceinline__ void peer_tile(const Args& A, LAS unsigned char* lds, int tile) {
;     ...
;     for (int ti = 0; ti < 8; ++ti) {
;         const int tl = 8 * w + ti;
;         const u32x2 e0 = SEL[tl * 128 + lane], e1 = SEL[tl * 128 + 64 + lane];
;         const int p0 = (int)(e0.x >> 10), p1 = (int)(e1.x >> 10);
;         int off = 0;
;         for (int p = 0; p < 16; ++p) {
;             const unsigned long long m0 = __ballot(p0 == p), m1 = __ballot(p1 == p);
;             const int c0 = __popcll(m0), c1 = __popcll(m1);
;             const int r0 = __builtin_amdgcn_mbcnt_hi((unsigned)(m0 >> 32), __builtin_amdgcn_mbcnt_lo((unsigned)m0, 0u));
;             const int r1 = __builtin_amdgcn_mbcnt_hi((unsigned)(m1 >> 32), __builtin_amdgcn_mbcnt_lo((unsigned)m1, 0u));
;             if (p0 == p) SORT[tl * 128 + off + r0] = e0;
;             if (p1 == p) SORT[tl * 128 + off + c0 + r1] = e1;
;             if (lane == 0) OFFS[tl * 17 + p] = off;
;             off += c0 + c1;
;         }
;         if (lane == 0) OFFS[tl * 17 + 16] = off;
;     }
;     ...
;         for (int tk = 0; tk < 4; ++tk) { const size_t m = (size_t)tile * 64 + tb + tk;
;             { const u32x4 ra = *(const u32x4*)(A3 + m * 1024 + 16 * lane), rb = *(const u32x4*)(A3 + m * 1024 + 16 * lane + 8);
;               float xr_; { const f32x4 p0 = *(const f32x4*)(RSq + m * 16), p1 = *(const f32x4*)(RSq + m * 16 + 4), p2 = *(const f32x4*)(RSq + m * 16 + 8), p3 = *(const f32x4*)(RSq + m * 16 + 12);
;                 const f32x4 ps = (p0 + p1) + (p2 + p3); xr_ = rsqrtf(((ps[0] + ps[1]) + (ps[2] + ps[3])) * (1.f / 1024.f) + 1e-6f); }
;               const unsigned rr[8] = {ra.x, ra.y, ra.z, ra.w, rb.x, rb.y, rb.z, rb.w}; unsigned hh[8];
;               const float* sp = MOD + (int)(m >> 11) * 6144 + 3072 + 16 * lane;
; #pragma unroll
;               for (int q = 0; q < 8; ++q) { const f32x2 sh = *(const f32x2*)(sp + 2 * q); hh[q] = pk2(bflo(rr[q]) * xr_ + sh[0], bfhi(rr[q]) * xr_ + sh[1]); }
;               xpa[tk] = (u32x4){hh[0], hh[1], hh[2], hh[3]}; xpb[tk] = (u32x4){hh[4], hh[5], hh[6], hh[7]}; }
	v_and_b32_e32 v111, 0xffff0000, v210
	v_lshlrev_b32_e32 v208, 16, v184
	v_and_b32_e32 v209, 0xffff0000, v184
	v_fma_f32 v208, v208, v232, v192
	v_fma_f32 v209, v209, v232, v193
	v_cvt_pk_bf16_f32 v210, v208, v209
	v_lshlrev_b32_e32 v112, 16, v210
	v_and_b32_e32 v113, 0xffff0000, v210
	v_lshlrev_b32_e32 v208, 16, v185
	v_and_b32_e32 v209, 0xffff0000, v185
	v_fma_f32 v208, v208, v232, v194
	v_fma_f32 v209, v209, v232, v195
	v_cvt_pk_bf16_f32 v210, v208, v209
	v_lshlrev_b32_e32 v114, 16, v210
	v_and_b32_e32 v115, 0xffff0000, v210
	v_lshlrev_b32_e32 v208, 16, v186
	v_and_b32_e32 v209, 0xffff0000, v186
	v_fma_f32 v208, v208, v232, v196
	v_fma_f32 v209, v209, v232, v197
	v_cvt_pk_bf16_f32 v210, v208, v209
	v_lshlrev_b32_e32 v116, 16, v210
	v_and_b32_e32 v117, 0xffff0000, v210
	v_lshlrev_b32_e32 v208, 16, v187
	v_and_b32_e32 v209, 0xffff0000, v187
	v_fma_f32 v208, v208, v232, v198
	v_fma_f32 v209, v209, v232, v199
	v_cvt_pk_bf16_f32 v210, v208, v209
	v_lshlrev_b32_e32 v118, 16, v210
	v_and_b32_e32 v119, 0xffff0000, v210
	v_lshlrev_b32_e32 v208, 16, v188
	v_and_b32_e32 v209, 0xffff0000, v188
	v_fma_f32 v208, v208, v232, v200
	v_fma_f32 v209, v209, v232, v201
	v_cvt_pk_bf16_f32 v210, v208, v209
	v_lshlrev_b32_e32 v120, 16, v210
	v_and_b32_e32 v121, 0xffff0000, v210
	v_lshlrev_b32_e32 v208, 16, v189
	v_and_b32_e32 v209, 0xffff0000, v189
	v_fma_f32 v208, v208, v232, v202
	v_fma_f32 v209, v209, v232, v203
	v_cvt_pk_bf16_f32 v210, v208, v209
	v_lshlrev_b32_e32 v122, 16, v210
	v_and_b32_e32 v123, 0xffff0000, v210
	v_lshlrev_b32_e32 v208, 16, v190
	v_and_b32_e32 v209, 0xffff0000, v190
	v_fma_f32 v208, v208, v232, v204
	v_fma_f32 v209, v209, v232, v205
	v_cvt_pk_bf16_f32 v210, v208, v209
	v_lshlrev_b32_e32 v124, 16, v210
	v_and_b32_e32 v125, 0xffff0000, v210
	v_lshlrev_b32_e32 v208, 16, v191
	v_and_b32_e32 v209, 0xffff0000, v191
	v_fma_f32 v208, v208, v232, v206
	v_fma_f32 v209, v209, v232, v207
	v_cvt_pk_bf16_f32 v210, v208, v209
	v_lshlrev_b32_e32 v126, 16, v210
	v_and_b32_e32 v127, 0xffff0000, v210
	s_nop 0
	s_mov_b32 s24, s8
	s_and_b32 s25, s9, 0xffff
	s_mov_b32 s26, 0x20000
	s_mov_b32 s27, 0x00027000
	s_lshl_b32 s0, s76, 10
	s_add_i32 s0, s0, 0x11000
	s_sub_i32 s85, s0, s22
	v_mov_b32_e32 v224, 0x7fffffff
	v_mov_b32_e32 v225, 0x7fffffff
	v_mov_b32_e32 v226, 0x7fffffff
	v_mov_b32_e32 v227, 0x7fffffff
	v_mov_b32_e32 v228, 0
	v_mov_b32_e32 v229, 0
	v_mov_b32_e32 v230, 0
	v_mov_b32_e32 v231, 0
	v_add_u32_e32 v232, s22, v240
	ds_write_b128 v232, v[224:227] offset:0
	ds_write_b128 v232, v[228:231] offset:4992
	ds_write_b128 v232, v[224:227] offset:1024
	ds_write_b128 v232, v[228:231] offset:6016
	ds_write_b128 v232, v[224:227] offset:2048
	ds_write_b128 v232, v[228:231] offset:7040
	ds_write_b128 v232, v[224:227] offset:3072
	ds_write_b128 v232, v[228:231] offset:8064
	s_mov_b32 exec_hi, 0x00ffffff
	ds_write_b128 v232, v[224:227] offset:4096
	s_mov_b32 exec_hi, 0x000fffff
	ds_write_b128 v232, v[228:231] offset:9088
	s_mov_b64 exec, -1
	v_lshrrev_b32_e32 v221, 2, v240
	v_add_u32_e32 v221, s22, v221
	ds_write_b32 v221, v228 offset:4224
	v_lshrrev_b32_e32 v233, 1, v240
	s_lshl_b32 s0, s76, 10
	s_add_i32 s0, s0, 0x11000
	v_add_u32_e32 v233, s0, v233
	ds_read_b64 v[128:129], v233 offset:0
	ds_read_b64 v[130:131], v233 offset:512
	ds_read_b64 v[132:133], v233 offset:1024
	ds_read_b64 v[134:135], v233 offset:1536
	ds_read_b64 v[136:137], v233 offset:2048
	ds_read_b64 v[138:139], v233 offset:2560
	ds_read_b64 v[140:141], v233 offset:3072
	ds_read_b64 v[142:143], v233 offset:3584
	ds_read_b64 v[144:145], v233 offset:4096
	ds_read_b64 v[146:147], v233 offset:4608
	ds_read_b64 v[148:149], v233 offset:5120
	ds_read_b64 v[150:151], v233 offset:5632
	ds_read_b64 v[152:153], v233 offset:6144
	ds_read_b64 v[154:155], v233 offset:6656
	ds_read_b64 v[156:157], v233 offset:7168
	ds_read_b64 v[158:159], v233 offset:7680
	v_mov_b32_e32 v220, 1
	v_lshrrev_b32_e32 v200, 4, v240
	v_lshrrev_b32_e32 v201, 3, v200
	v_and_b32_e32 v200, 7, v200
	s_add_i32 s3, s22, 4224
	s_and_b32 s1, s32, 7
	s_waitcnt lgkmcnt(0)
	v_lshrrev_b32_e32 v160, 11, v128
	v_subrev_u32_e32 v160, s1, v160
	v_and_b32_e32 v160, 7, v160
	v_lshl_add_u32 v176, v160, 2, s3
	v_lshrrev_b32_e32 v161, 11, v130
	v_subrev_u32_e32 v161, s1, v161
	v_and_b32_e32 v161, 7, v161
	v_lshl_add_u32 v177, v161, 2, s3
	v_lshrrev_b32_e32 v162, 11, v132
	v_subrev_u32_e32 v162, s1, v162
	v_and_b32_e32 v162, 7, v162
	v_lshl_add_u32 v178, v162, 2, s3
	v_lshrrev_b32_e32 v163, 11, v134
	v_subrev_u32_e32 v163, s1, v163
	v_and_b32_e32 v163, 7, v163
	v_lshl_add_u32 v179, v163, 2, s3
	v_lshrrev_b32_e32 v164, 11, v136
	v_subrev_u32_e32 v164, s1, v164
	v_and_b32_e32 v164, 7, v164
	v_lshl_add_u32 v180, v164, 2, s3
	v_lshrrev_b32_e32 v165, 11, v138
	v_subrev_u32_e32 v165, s1, v165
	v_and_b32_e32 v165, 7, v165
	v_lshl_add_u32 v181, v165, 2, s3
	v_lshrrev_b32_e32 v166, 11, v140
	v_subrev_u32_e32 v166, s1, v166
	v_and_b32_e32 v166, 7, v166
	v_lshl_add_u32 v182, v166, 2, s3
	v_lshrrev_b32_e32 v167, 11, v142
	v_subrev_u32_e32 v167, s1, v167
	v_and_b32_e32 v167, 7, v167
	v_lshl_add_u32 v183, v167, 2, s3
	v_lshrrev_b32_e32 v168, 11, v144
	v_subrev_u32_e32 v168, s1, v168
	v_and_b32_e32 v168, 7, v168
	v_lshl_add_u32 v184, v168, 2, s3
	v_lshrrev_b32_e32 v169, 11, v146
	v_subrev_u32_e32 v169, s1, v169
	v_and_b32_e32 v169, 7, v169
	v_lshl_add_u32 v185, v169, 2, s3
	v_lshrrev_b32_e32 v170, 11, v148
	v_subrev_u32_e32 v170, s1, v170
	v_and_b32_e32 v170, 7, v170
	v_lshl_add_u32 v186, v170, 2, s3
	v_lshrrev_b32_e32 v171, 11, v150
	v_subrev_u32_e32 v171, s1, v171
	v_and_b32_e32 v171, 7, v171
	v_lshl_add_u32 v187, v171, 2, s3
	v_lshrrev_b32_e32 v172, 11, v152
; __device__ __forceinline__ void peer_tile(const Args& A, LAS unsigned char* lds, int tile) {
;     ...
;     for (int ti = 0; ti < 8; ++ti) {
;         const int tl = 8 * w + ti;
;         const u32x2 e0 = SEL[tl * 128 + lane], e1 = SEL[tl * 128 + 64 + lane];
;         const int p0 = (int)(e0.x >> 10), p1 = (int)(e1.x >> 10);
;         int off = 0;
;         for (int p = 0; p < 16; ++p) {
;             const unsigned long long m0 = __ballot(p0 == p), m1 = __ballot(p1 == p);
;             const int c0 = __popcll(m0), c1 = __popcll(m1);
;             const int r0 = __builtin_amdgcn_mbcnt_hi((unsigned)(m0 >> 32), __builtin_amdgcn_mbcnt_lo((unsigned)m0, 0u));
;             const int r1 = __builtin_amdgcn_mbcnt_hi((unsigned)(m1 >> 32), __builtin_amdgcn_mbcnt_lo((unsigned)m1, 0u));
;             if (p0 == p) SORT[tl * 128 + off + r0] = e0;
;             if (p1 == p) SORT[tl * 128 + off + c0 + r1] = e1;
;             if (lane == 0) OFFS[tl * 17 + p] = off;
;             off += c0 + c1;
;         }
;         if (lane == 0) OFFS[tl * 17 + 16] = off;
;     }
	v_subrev_u32_e32 v172, s1, v172
	v_and_b32_e32 v172, 7, v172
	v_lshl_add_u32 v188, v172, 2, s3
	v_lshrrev_b32_e32 v173, 11, v154
	v_subrev_u32_e32 v173, s1, v173
	v_and_b32_e32 v173, 7, v173
	v_lshl_add_u32 v189, v173, 2, s3
	v_lshrrev_b32_e32 v174, 11, v156
	v_subrev_u32_e32 v174, s1, v174
	v_and_b32_e32 v174, 7, v174
	v_lshl_add_u32 v190, v174, 2, s3
	v_lshrrev_b32_e32 v175, 11, v158
	v_subrev_u32_e32 v175, s1, v175
	v_and_b32_e32 v175, 7, v175
	v_lshl_add_u32 v191, v175, 2, s3
	v_lshlrev_b32_e32 v206, 3, v128
	buffer_load_dwordx2 v[224:225], v206, s[24:27], 0 offen
	v_lshlrev_b32_e32 v206, 3, v130
	buffer_load_dwordx2 v[226:227], v206, s[24:27], 0 offen
	v_lshlrev_b32_e32 v206, 3, v132
	buffer_load_dwordx2 v[228:229], v206, s[24:27], 0 offen
	v_lshlrev_b32_e32 v206, 3, v134
	buffer_load_dwordx2 v[230:231], v206, s[24:27], 0 offen
	v_lshlrev_b32_e32 v206, 3, v136
	buffer_load_dwordx2 v[232:233], v206, s[24:27], 0 offen
	v_lshlrev_b32_e32 v206, 3, v138
	buffer_load_dwordx2 v[234:235], v206, s[24:27], 0 offen
	v_lshlrev_b32_e32 v206, 3, v140
	buffer_load_dwordx2 v[236:237], v206, s[24:27], 0 offen
	v_lshlrev_b32_e32 v206, 3, v142
	buffer_load_dwordx2 v[238:239], v206, s[24:27], 0 offen
	v_lshlrev_b32_e32 v206, 3, v144
	buffer_load_dwordx2 v[248:249], v206, s[24:27], 0 offen
	v_lshlrev_b32_e32 v206, 3, v146
	buffer_load_dwordx2 v[250:251], v206, s[24:27], 0 offen
	v_lshlrev_b32_e32 v206, 3, v148
	buffer_load_dwordx2 v[252:253], v206, s[24:27], 0 offen
	v_lshlrev_b32_e32 v206, 3, v150
	buffer_load_dwordx2 v[254:255], v206, s[24:27], 0 offen
	ds_add_rtn_u32 v176, v176, v220 offset:0
	ds_add_rtn_u32 v177, v177, v220 offset:0
	ds_add_rtn_u32 v178, v178, v220 offset:32
	ds_add_rtn_u32 v179, v179, v220 offset:32
	ds_add_rtn_u32 v180, v180, v220 offset:64
	ds_add_rtn_u32 v181, v181, v220 offset:64
	ds_add_rtn_u32 v182, v182, v220 offset:96
	ds_add_rtn_u32 v183, v183, v220 offset:96
	ds_add_rtn_u32 v184, v184, v220 offset:128
	ds_add_rtn_u32 v185, v185, v220 offset:128
	ds_add_rtn_u32 v186, v186, v220 offset:160
	ds_add_rtn_u32 v187, v187, v220 offset:160
	ds_add_rtn_u32 v188, v188, v220 offset:192
	ds_add_rtn_u32 v189, v189, v220 offset:192
	ds_add_rtn_u32 v190, v190, v220 offset:224
	ds_add_rtn_u32 v191, v191, v220 offset:224
	v_lshl_add_u32 v207, v201, 5, s3
	ds_read_b32 v203, v221 offset:4224
	ds_read_b128 v[192:195], v207
	ds_read_b128 v[196:199], v207 offset:16
	v_mov_b32_e32 v202, 0
	s_waitcnt lgkmcnt(0)
	v_cmp_lt_u32_e64 s[38:39], 0, v200
	v_cmp_lt_u32_e64 s[40:41], 1, v200
	v_cmp_lt_u32_e64 s[42:43], 2, v200
	v_cmp_lt_u32_e64 s[44:45], 3, v200
	v_cmp_lt_u32_e64 s[64:65], 4, v200
	v_cmp_lt_u32_e64 s[66:67], 5, v200
	v_cmp_lt_u32_e64 s[94:95], 6, v200
	v_cndmask_b32_e64 v206, 0, v192, s[38:39]
	v_add_u32_e32 v202, v202, v206
	v_cndmask_b32_e64 v206, 0, v193, s[40:41]
	v_add_u32_e32 v202, v202, v206
	v_cndmask_b32_e64 v206, 0, v194, s[42:43]
	v_add_u32_e32 v202, v202, v206
	v_cndmask_b32_e64 v206, 0, v195, s[44:45]
	v_add_u32_e32 v202, v202, v206
	v_cndmask_b32_e64 v206, 0, v196, s[64:65]
	v_add_u32_e32 v202, v202, v206
	v_cndmask_b32_e64 v206, 0, v197, s[66:67]
	v_add_u32_e32 v202, v202, v206
	v_cndmask_b32_e64 v206, 0, v198, s[94:95]
	v_add_u32_e32 v202, v202, v206
	v_add_u32_e32 v204, 3, v202
	v_add3_u32 v212, v202, v203, 3
	v_lshrrev_b32_e32 v204, 2, v204
	v_lshrrev_b32_e32 v212, 2, v212
	v_sub_u32_e32 v212, v212, v204
	v_lshl_add_u32 v207, v200, 3, v201
	v_lshl_add_u32 v207, v207, 2, s3
	ds_write_b32 v207, v212 offset:256
	v_lshl_add_u32 v208, v200, 5, s3
	ds_read_b128 v[192:195], v208 offset:256
	ds_read_b128 v[196:199], v208 offset:272
	v_mov_b32_e32 v205, 0
	s_waitcnt lgkmcnt(0)
	v_cmp_lt_u32_e64 s[38:39], 0, v201
	v_cmp_lt_u32_e64 s[40:41], 1, v201
	v_cmp_lt_u32_e64 s[42:43], 2, v201
	v_cmp_lt_u32_e64 s[44:45], 3, v201
	v_cmp_lt_u32_e64 s[64:65], 4, v201
	v_cmp_lt_u32_e64 s[66:67], 5, v201
	v_cmp_lt_u32_e64 s[94:95], 6, v201
	v_cndmask_b32_e64 v206, 0, v192, s[38:39]
	v_add_u32_e32 v205, v205, v206
	v_cndmask_b32_e64 v206, 0, v193, s[40:41]
	v_add_u32_e32 v205, v205, v206
	v_cndmask_b32_e64 v206, 0, v194, s[42:43]
	v_add_u32_e32 v205, v205, v206
	v_cndmask_b32_e64 v206, 0, v195, s[44:45]
	v_add_u32_e32 v205, v205, v206
	v_cndmask_b32_e64 v206, 0, v196, s[64:65]
	v_add_u32_e32 v205, v205, v206
	v_cndmask_b32_e64 v206, 0, v197, s[66:67]
	v_add_u32_e32 v205, v205, v206
	v_cndmask_b32_e64 v206, 0, v198, s[94:95]
	v_add_u32_e32 v205, v205, v206
	v_add_u32_e32 v206, v192, v193
	v_add_u32_e32 v206, v206, v194
	v_add_u32_e32 v206, v206, v195
	v_add_u32_e32 v206, v206, v196
	v_add_u32_e32 v206, v206, v197
	v_add_u32_e32 v206, v206, v198
	v_add_u32_e32 v206, v206, v199
	v_lshl_add_u32 v207, v200, 2, s3
	ds_write_b32 v207, v206 offset:512
	v_mov_b32_e32 v207, s3
	ds_read_b128 v[192:195], v207 offset:512
	ds_read_b128 v[196:199], v207 offset:528
	ds_write_b32 v221, v202 offset:4224
	s_waitcnt lgkmcnt(0)
	v_cmp_lt_u32_e64 s[38:39], 0, v200
	v_cmp_lt_u32_e64 s[40:41], 1, v200
	v_cmp_lt_u32_e64 s[42:43], 2, v200
	v_cmp_lt_u32_e64 s[44:45], 3, v200
	v_cmp_lt_u32_e64 s[64:65], 4, v200
	v_cmp_lt_u32_e64 s[66:67], 5, v200
	v_cmp_lt_u32_e64 s[94:95], 6, v200
	v_cndmask_b32_e64 v206, 0, v192, s[38:39]
	v_add_u32_e32 v205, v205, v206
	v_cndmask_b32_e64 v206, 0, v193, s[40:41]
	v_add_u32_e32 v205, v205, v206
	v_cndmask_b32_e64 v206, 0, v194, s[42:43]
	v_add_u32_e32 v205, v205, v206
	v_cndmask_b32_e64 v206, 0, v195, s[44:45]
	v_add_u32_e32 v205, v205, v206
	v_cndmask_b32_e64 v206, 0, v196, s[64:65]
	v_add_u32_e32 v205, v205, v206
	v_cndmask_b32_e64 v206, 0, v197, s[66:67]
	v_add_u32_e32 v205, v205, v206
	v_cndmask_b32_e64 v206, 0, v198, s[94:95]
	v_add_u32_e32 v205, v205, v206
	v_sub_u32_e32 v205, v205, v204
	v_lshrrev_b32_e32 v208, 4, v240
	v_and_b32_e32 v222, 31, v208
	v_lshrrev_b32_e32 v208, 5, v208
	v_add_u32_e32 v207, 0, v208
	v_lshl_add_u32 v206, v207, 5, s3
	ds_read_b128 v[192:195], v206
	ds_read_b128 v[196:199], v206 offset:16
	v_lshlrev_b32_e32 v206, 2, v222
	v_lshlrev_b32_e32 v223, 3, v207
	s_waitcnt lgkmcnt(0)
; __device__ __forceinline__ void peer_tile(const Args& A, LAS unsigned char* lds, int tile) {
;     ...
;     for (int ti = 0; ti < 8; ++ti) {
;         const int tl = 8 * w + ti;
;         const u32x2 e0 = SEL[tl * 128 + lane], e1 = SEL[tl * 128 + 64 + lane];
;         const int p0 = (int)(e0.x >> 10), p1 = (int)(e1.x >> 10);
;         int off = 0;
;         for (int p = 0; p < 16; ++p) {
;             const unsigned long long m0 = __ballot(p0 == p), m1 = __ballot(p1 == p);
;             const int c0 = __popcll(m0), c1 = __popcll(m1);
;             const int r0 = __builtin_amdgcn_mbcnt_hi((unsigned)(m0 >> 32), __builtin_amdgcn_mbcnt_lo((unsigned)m0, 0u));
;             const int r1 = __builtin_amdgcn_mbcnt_hi((unsigned)(m1 >> 32), __builtin_amdgcn_mbcnt_lo((unsigned)m1, 0u));
;             if (p0 == p) SORT[tl * 128 + off + r0] = e0;
;             if (p1 == p) SORT[tl * 128 + off + c0 + r1] = e1;
;             if (lane == 0) OFFS[tl * 17 + p] = off;
;             off += c0 + c1;
;         }
;         if (lane == 0) OFFS[tl * 17 + 16] = off;
;     }
	v_cmp_le_u32_e64 s[38:39], v193, v206
	v_cmp_le_u32_e64 s[40:41], v194, v206
	v_cmp_le_u32_e64 s[42:43], v195, v206
	v_cmp_le_u32_e64 s[44:45], v196, v206
	v_cmp_le_u32_e64 s[64:65], v197, v206
	v_cmp_le_u32_e64 s[66:67], v198, v206
	v_cmp_le_u32_e64 s[94:95], v199, v206
	v_addc_co_u32_e64 v223, s[92:93], 0, v223, s[38:39]
	v_addc_co_u32_e64 v223, s[92:93], 0, v223, s[40:41]
	v_addc_co_u32_e64 v223, s[92:93], 0, v223, s[42:43]
	v_addc_co_u32_e64 v223, s[92:93], 0, v223, s[44:45]
	v_addc_co_u32_e64 v223, s[92:93], 0, v223, s[64:65]
	v_addc_co_u32_e64 v223, s[92:93], 0, v223, s[66:67]
	v_addc_co_u32_e64 v223, s[92:93], 0, v223, s[94:95]
	v_lshlrev_b32_e32 v223, 2, v223
	ds_bpermute_b32 v216, v223, v205
	v_add_u32_e32 v207, 2, v208
	v_lshl_add_u32 v206, v207, 5, s3
	ds_read_b128 v[192:195], v206
	ds_read_b128 v[196:199], v206 offset:16
	v_lshlrev_b32_e32 v206, 2, v222
	v_lshlrev_b32_e32 v223, 3, v207
	s_waitcnt lgkmcnt(0)
	v_cmp_le_u32_e64 s[38:39], v193, v206
	v_cmp_le_u32_e64 s[40:41], v194, v206
	v_cmp_le_u32_e64 s[42:43], v195, v206
	v_cmp_le_u32_e64 s[44:45], v196, v206
	v_cmp_le_u32_e64 s[64:65], v197, v206
	v_cmp_le_u32_e64 s[66:67], v198, v206
	v_cmp_le_u32_e64 s[94:95], v199, v206
	v_addc_co_u32_e64 v223, s[92:93], 0, v223, s[38:39]
	v_addc_co_u32_e64 v223, s[92:93], 0, v223, s[40:41]
	v_addc_co_u32_e64 v223, s[92:93], 0, v223, s[42:43]
	v_addc_co_u32_e64 v223, s[92:93], 0, v223, s[44:45]
	v_addc_co_u32_e64 v223, s[92:93], 0, v223, s[64:65]
	v_addc_co_u32_e64 v223, s[92:93], 0, v223, s[66:67]
	v_addc_co_u32_e64 v223, s[92:93], 0, v223, s[94:95]
	v_lshlrev_b32_e32 v223, 2, v223
	ds_bpermute_b32 v217, v223, v205
	v_add_u32_e32 v207, 4, v208
	v_lshl_add_u32 v206, v207, 5, s3
	ds_read_b128 v[192:195], v206
	ds_read_b128 v[196:199], v206 offset:16
	v_lshlrev_b32_e32 v206, 2, v222
	v_lshlrev_b32_e32 v223, 3, v207
	s_waitcnt lgkmcnt(0)
	v_cmp_le_u32_e64 s[38:39], v193, v206
	v_cmp_le_u32_e64 s[40:41], v194, v206
	v_cmp_le_u32_e64 s[42:43], v195, v206
	v_cmp_le_u32_e64 s[44:45], v196, v206
	v_cmp_le_u32_e64 s[64:65], v197, v206
	v_cmp_le_u32_e64 s[66:67], v198, v206
	v_cmp_le_u32_e64 s[94:95], v199, v206
	v_addc_co_u32_e64 v223, s[92:93], 0, v223, s[38:39]
	v_addc_co_u32_e64 v223, s[92:93], 0, v223, s[40:41]
	v_addc_co_u32_e64 v223, s[92:93], 0, v223, s[42:43]
	v_addc_co_u32_e64 v223, s[92:93], 0, v223, s[44:45]
	v_addc_co_u32_e64 v223, s[92:93], 0, v223, s[64:65]
	v_addc_co_u32_e64 v223, s[92:93], 0, v223, s[66:67]
	v_addc_co_u32_e64 v223, s[92:93], 0, v223, s[94:95]
	v_lshlrev_b32_e32 v223, 2, v223
	ds_bpermute_b32 v218, v223, v205
	v_add_u32_e32 v207, 6, v208
	v_lshl_add_u32 v206, v207, 5, s3
	ds_read_b128 v[192:195], v206
	ds_read_b128 v[196:199], v206 offset:16
	v_lshlrev_b32_e32 v206, 2, v222
	v_lshlrev_b32_e32 v223, 3, v207
	s_waitcnt lgkmcnt(0)
	v_cmp_le_u32_e64 s[38:39], v193, v206
	v_cmp_le_u32_e64 s[40:41], v194, v206
	v_cmp_le_u32_e64 s[42:43], v195, v206
	v_cmp_le_u32_e64 s[44:45], v196, v206
	v_cmp_le_u32_e64 s[64:65], v197, v206
	v_cmp_le_u32_e64 s[66:67], v198, v206
	v_cmp_le_u32_e64 s[94:95], v199, v206
	v_addc_co_u32_e64 v223, s[92:93], 0, v223, s[38:39]
	v_addc_co_u32_e64 v223, s[92:93], 0, v223, s[40:41]
	v_addc_co_u32_e64 v223, s[92:93], 0, v223, s[42:43]
	v_addc_co_u32_e64 v223, s[92:93], 0, v223, s[44:45]
	v_addc_co_u32_e64 v223, s[92:93], 0, v223, s[64:65]
	v_addc_co_u32_e64 v223, s[92:93], 0, v223, s[66:67]
	v_addc_co_u32_e64 v223, s[92:93], 0, v223, s[94:95]
	v_lshlrev_b32_e32 v223, 2, v223
	ds_bpermute_b32 v219, v223, v205
	s_waitcnt lgkmcnt(0)
	v_add_u32_e32 v216, v216, v222
	v_add_u32_e32 v217, v217, v222
	v_add_u32_e32 v218, v218, v222
	v_add_u32_e32 v219, v219, v222
	v_lshlrev_b32_e32 v206, 3, v152
	buffer_load_dwordx2 v[192:193], v206, s[24:27], 0 offen
	v_lshlrev_b32_e32 v206, 3, v154
	buffer_load_dwordx2 v[194:195], v206, s[24:27], 0 offen
	v_lshlrev_b32_e32 v206, 3, v156
	buffer_load_dwordx2 v[196:197], v206, s[24:27], 0 offen
	v_lshlrev_b32_e32 v206, 3, v158
	buffer_load_dwordx2 v[198:199], v206, s[24:27], 0 offen
	v_lshlrev_b32_e32 v160, 2, v160
	ds_bpermute_b32 v160, v160, v202
	v_lshlrev_b32_e32 v161, 2, v161
	ds_bpermute_b32 v161, v161, v202
	v_lshlrev_b32_e32 v162, 2, v162
	v_add_u32_e32 v162, 32, v162
	ds_bpermute_b32 v162, v162, v202
	v_lshlrev_b32_e32 v163, 2, v163
	v_add_u32_e32 v163, 32, v163
	ds_bpermute_b32 v163, v163, v202
	v_lshlrev_b32_e32 v164, 2, v164
	v_add_u32_e32 v164, 64, v164
	ds_bpermute_b32 v164, v164, v202
	v_lshlrev_b32_e32 v165, 2, v165
	v_add_u32_e32 v165, 64, v165
	ds_bpermute_b32 v165, v165, v202
	v_lshlrev_b32_e32 v166, 2, v166
	v_add_u32_e32 v166, 96, v166
	ds_bpermute_b32 v166, v166, v202
	v_lshlrev_b32_e32 v167, 2, v167
	v_add_u32_e32 v167, 96, v167
	ds_bpermute_b32 v167, v167, v202
	v_lshlrev_b32_e32 v168, 2, v168
	v_add_u32_e32 v168, 128, v168
	ds_bpermute_b32 v168, v168, v202
	v_lshlrev_b32_e32 v169, 2, v169
	v_add_u32_e32 v169, 128, v169
	ds_bpermute_b32 v169, v169, v202
	v_lshlrev_b32_e32 v170, 2, v170
	v_add_u32_e32 v170, 160, v170
	ds_bpermute_b32 v170, v170, v202
	v_lshlrev_b32_e32 v171, 2, v171
	v_add_u32_e32 v171, 160, v171
	ds_bpermute_b32 v171, v171, v202
	v_lshlrev_b32_e32 v172, 2, v172
	v_add_u32_e32 v172, 192, v172
	ds_bpermute_b32 v172, v172, v202
	v_lshlrev_b32_e32 v173, 2, v173
	v_add_u32_e32 v173, 192, v173
	ds_bpermute_b32 v173, v173, v202
	v_lshlrev_b32_e32 v174, 2, v174
	v_add_u32_e32 v174, 224, v174
	ds_bpermute_b32 v174, v174, v202
	v_lshlrev_b32_e32 v175, 2, v175
	v_add_u32_e32 v175, 224, v175
	ds_bpermute_b32 v175, v175, v202
	s_waitcnt lgkmcnt(0)
; __device__ __forceinline__ void peer_tile(const Args& A, LAS unsigned char* lds, int tile) {
;     ...
;     for (int ti = 0; ti < 8; ++ti) {
;         const int tl = 8 * w + ti;
;         const u32x2 e0 = SEL[tl * 128 + lane], e1 = SEL[tl * 128 + 64 + lane];
;         const int p0 = (int)(e0.x >> 10), p1 = (int)(e1.x >> 10);
;         int off = 0;
;         for (int p = 0; p < 16; ++p) {
;             const unsigned long long m0 = __ballot(p0 == p), m1 = __ballot(p1 == p);
;             const int c0 = __popcll(m0), c1 = __popcll(m1);
;             const int r0 = __builtin_amdgcn_mbcnt_hi((unsigned)(m0 >> 32), __builtin_amdgcn_mbcnt_lo((unsigned)m0, 0u));
;             const int r1 = __builtin_amdgcn_mbcnt_hi((unsigned)(m1 >> 32), __builtin_amdgcn_mbcnt_lo((unsigned)m1, 0u));
;             if (p0 == p) SORT[tl * 128 + off + r0] = e0;
;             if (p1 == p) SORT[tl * 128 + off + c0 + r1] = e1;
;             if (lane == 0) OFFS[tl * 17 + p] = off;
;             off += c0 + c1;
;         }
;         if (lane == 0) OFFS[tl * 17 + 16] = off;
;     }
	v_add_u32_e32 v176, v176, v160
	v_lshrrev_b32_e32 v160, 2, v176
	v_and_b32_e32 v176, 3, v176
	v_lshlrev_b32_e32 v160, 2, v160
	ds_bpermute_b32 v160, v160, v216
	v_add_u32_e32 v177, v177, v161
	v_lshrrev_b32_e32 v161, 2, v177
	v_and_b32_e32 v177, 3, v177
	v_lshlrev_b32_e32 v161, 2, v161
	ds_bpermute_b32 v161, v161, v216
	v_add_u32_e32 v178, v178, v162
	v_lshrrev_b32_e32 v162, 2, v178
	v_and_b32_e32 v178, 3, v178
	v_lshlrev_b32_e32 v162, 2, v162
	v_add_u32_e32 v162, 128, v162
	ds_bpermute_b32 v162, v162, v216
	v_add_u32_e32 v179, v179, v163
	v_lshrrev_b32_e32 v163, 2, v179
	v_and_b32_e32 v179, 3, v179
	v_lshlrev_b32_e32 v163, 2, v163
	v_add_u32_e32 v163, 128, v163
	ds_bpermute_b32 v163, v163, v216
	v_add_u32_e32 v180, v180, v164
	v_lshrrev_b32_e32 v164, 2, v180
	v_and_b32_e32 v180, 3, v180
	v_lshlrev_b32_e32 v164, 2, v164
	ds_bpermute_b32 v164, v164, v217
	v_add_u32_e32 v181, v181, v165
	v_lshrrev_b32_e32 v165, 2, v181
	v_and_b32_e32 v181, 3, v181
	v_lshlrev_b32_e32 v165, 2, v165
	ds_bpermute_b32 v165, v165, v217
	v_add_u32_e32 v182, v182, v166
	v_lshrrev_b32_e32 v166, 2, v182
	v_and_b32_e32 v182, 3, v182
	v_lshlrev_b32_e32 v166, 2, v166
	v_add_u32_e32 v166, 128, v166
	ds_bpermute_b32 v166, v166, v217
	v_add_u32_e32 v183, v183, v167
	v_lshrrev_b32_e32 v167, 2, v183
	v_and_b32_e32 v183, 3, v183
	v_lshlrev_b32_e32 v167, 2, v167
	v_add_u32_e32 v167, 128, v167
	ds_bpermute_b32 v167, v167, v217
	v_add_u32_e32 v184, v184, v168
	v_lshrrev_b32_e32 v168, 2, v184
	v_and_b32_e32 v184, 3, v184
	v_lshlrev_b32_e32 v168, 2, v168
	ds_bpermute_b32 v168, v168, v218
	v_add_u32_e32 v185, v185, v169
	v_lshrrev_b32_e32 v169, 2, v185
	v_and_b32_e32 v185, 3, v185
	v_lshlrev_b32_e32 v169, 2, v169
	ds_bpermute_b32 v169, v169, v218
	v_add_u32_e32 v186, v186, v170
	v_lshrrev_b32_e32 v170, 2, v186
	v_and_b32_e32 v186, 3, v186
	v_lshlrev_b32_e32 v170, 2, v170
	v_add_u32_e32 v170, 128, v170
	ds_bpermute_b32 v170, v170, v218
	v_add_u32_e32 v187, v187, v171
	v_lshrrev_b32_e32 v171, 2, v187
	v_and_b32_e32 v187, 3, v187
	v_lshlrev_b32_e32 v171, 2, v171
	v_add_u32_e32 v171, 128, v171
	ds_bpermute_b32 v171, v171, v218
	v_add_u32_e32 v188, v188, v172
	v_lshrrev_b32_e32 v172, 2, v188
	v_and_b32_e32 v188, 3, v188
	v_lshlrev_b32_e32 v172, 2, v172
	ds_bpermute_b32 v172, v172, v219
	v_add_u32_e32 v189, v189, v173
	v_lshrrev_b32_e32 v173, 2, v189
	v_and_b32_e32 v189, 3, v189
	v_lshlrev_b32_e32 v173, 2, v173
	ds_bpermute_b32 v173, v173, v219
	v_add_u32_e32 v190, v190, v174
	v_lshrrev_b32_e32 v174, 2, v190
	v_and_b32_e32 v190, 3, v190
	v_lshlrev_b32_e32 v174, 2, v174
	v_add_u32_e32 v174, 128, v174
	ds_bpermute_b32 v174, v174, v219
	v_add_u32_e32 v191, v191, v175
	v_lshrrev_b32_e32 v175, 2, v191
	v_and_b32_e32 v191, 3, v191
	v_lshlrev_b32_e32 v175, 2, v175
	v_add_u32_e32 v175, 128, v175
	ds_bpermute_b32 v175, v175, v219
	s_waitcnt lgkmcnt(0)
	v_lshl_add_u32 v160, v160, 4, s22
	v_lshl_add_u32 v160, v176, 2, v160
	ds_write_b32 v160, v128
	ds_write_b32 v160, v129 offset:4992
	v_lshl_add_u32 v161, v161, 4, s22
	v_lshl_add_u32 v161, v177, 2, v161
	ds_write_b32 v161, v130
	ds_write_b32 v161, v131 offset:4992
	v_lshl_add_u32 v162, v162, 4, s22
	v_lshl_add_u32 v162, v178, 2, v162
	ds_write_b32 v162, v132
	ds_write_b32 v162, v133 offset:4992
	v_lshl_add_u32 v163, v163, 4, s22
	v_lshl_add_u32 v163, v179, 2, v163
	ds_write_b32 v163, v134
	ds_write_b32 v163, v135 offset:4992
	v_lshl_add_u32 v164, v164, 4, s22
	v_lshl_add_u32 v164, v180, 2, v164
	ds_write_b32 v164, v136
	ds_write_b32 v164, v137 offset:4992
	v_lshl_add_u32 v165, v165, 4, s22
	v_lshl_add_u32 v165, v181, 2, v165
	ds_write_b32 v165, v138
	ds_write_b32 v165, v139 offset:4992
	v_lshl_add_u32 v166, v166, 4, s22
	v_lshl_add_u32 v166, v182, 2, v166
	ds_write_b32 v166, v140
	ds_write_b32 v166, v141 offset:4992
	v_lshl_add_u32 v167, v167, 4, s22
	v_lshl_add_u32 v167, v183, 2, v167
	ds_write_b32 v167, v142
	ds_write_b32 v167, v143 offset:4992
	v_lshl_add_u32 v168, v168, 4, s22
	v_lshl_add_u32 v168, v184, 2, v168
	ds_write_b32 v168, v144
	ds_write_b32 v168, v145 offset:4992
	v_lshl_add_u32 v169, v169, 4, s22
	v_lshl_add_u32 v169, v185, 2, v169
	ds_write_b32 v169, v146
	ds_write_b32 v169, v147 offset:4992
	v_lshl_add_u32 v170, v170, 4, s22
	v_lshl_add_u32 v170, v186, 2, v170
	ds_write_b32 v170, v148
	ds_write_b32 v170, v149 offset:4992
	v_lshl_add_u32 v171, v171, 4, s22
	v_lshl_add_u32 v171, v187, 2, v171
	ds_write_b32 v171, v150
	ds_write_b32 v171, v151 offset:4992
	v_lshl_add_u32 v172, v172, 4, s22
	v_lshl_add_u32 v172, v188, 2, v172
	ds_write_b32 v172, v152
	ds_write_b32 v172, v153 offset:4992
	v_lshl_add_u32 v173, v173, 4, s22
	v_lshl_add_u32 v173, v189, 2, v173
	ds_write_b32 v173, v154
	ds_write_b32 v173, v155 offset:4992
	v_lshl_add_u32 v174, v174, 4, s22
	v_lshl_add_u32 v174, v190, 2, v174
	ds_write_b32 v174, v156
	ds_write_b32 v174, v157 offset:4992
	v_lshl_add_u32 v175, v175, 4, s22
	v_lshl_add_u32 v175, v191, 2, v175
	ds_write_b32 v175, v158
	ds_write_b32 v175, v159 offset:4992
	s_waitcnt vmcnt(0)
; #define IT_ADVANCE() do { it_j += 4; while (it_j >= it_end) { if (it_done) break; ++it_tk; if (it_tk == 4) { it_tk = 0; ++it_p; if (it_p == 16) { it_done = true; it_p = 15; it_j = 0; it_end = 1; break; } } \
;             it_j = __builtin_amdgcn_readfirstlane(OFFS[(tb + it_tk) * 17 + it_p]); it_end = __builtin_amdgcn_readfirstlane(OFFS[(tb + it_tk) * 17 + it_p + 1]); } } while (0)
; __device__ __forceinline__ void peer_tile(const Args& A, LAS unsigned char* lds, int tile) {
;     ...
;         int it_p = 0, it_tk = -1, it_j = 0, it_end = 0; bool it_done = false;
;     ...
;         u32x4 uA[4], vA[4], uB[4], vB[4]; float cgA = 0.f, suA = 0.f, svA = 0.f, cgB = 0.f, suB = 0.f, svB = 0.f;
; #pragma unroll
;         for (int k = 0; k < 4; ++k) { uA[k] = (u32x4){0u, 0u, 0u, 0u}; vA[k] = uA[k]; uB[k] = uA[k]; vB[k] = uA[k]; }
;         IT_ADVANCE();
;         LOAD_SET(uA, vA, cgA, suA, svA);
	v_add_u32_e32 v160, s85, v160
	ds_write_b32 v160, v224
	ds_write_b32 v160, v225 offset:4096
	v_add_u32_e32 v161, s85, v161
	ds_write_b32 v161, v226
	ds_write_b32 v161, v227 offset:4096
	v_add_u32_e32 v162, s85, v162
	ds_write_b32 v162, v228
	ds_write_b32 v162, v229 offset:4096
	v_add_u32_e32 v163, s85, v163
	ds_write_b32 v163, v230
	ds_write_b32 v163, v231 offset:4096
	v_add_u32_e32 v164, s85, v164
	ds_write_b32 v164, v232
	ds_write_b32 v164, v233 offset:4096
	v_add_u32_e32 v165, s85, v165
	ds_write_b32 v165, v234
	ds_write_b32 v165, v235 offset:4096
	v_add_u32_e32 v166, s85, v166
	ds_write_b32 v166, v236
	ds_write_b32 v166, v237 offset:4096
	v_add_u32_e32 v167, s85, v167
	ds_write_b32 v167, v238
	ds_write_b32 v167, v239 offset:4096
	v_add_u32_e32 v168, s85, v168
	ds_write_b32 v168, v248
	ds_write_b32 v168, v249 offset:4096
	v_add_u32_e32 v169, s85, v169
	ds_write_b32 v169, v250
	ds_write_b32 v169, v251 offset:4096
	v_add_u32_e32 v170, s85, v170
	ds_write_b32 v170, v252
	ds_write_b32 v170, v253 offset:4096
	v_add_u32_e32 v171, s85, v171
	ds_write_b32 v171, v254
	ds_write_b32 v171, v255 offset:4096
	v_add_u32_e32 v172, s85, v172
	ds_write_b32 v172, v192
	ds_write_b32 v172, v193 offset:4096
	v_add_u32_e32 v173, s85, v173
	ds_write_b32 v173, v194
	ds_write_b32 v173, v195 offset:4096
	v_add_u32_e32 v174, s85, v174
	ds_write_b32 v174, v196
	ds_write_b32 v174, v197 offset:4096
	v_add_u32_e32 v175, s85, v175
	ds_write_b32 v175, v198
	ds_write_b32 v175, v199 offset:4096
	v_mov_b32_e32 v206, 0x7fffffff
	ds_write_b32 v221, v206 offset:4224
	ds_write_b32 v221, v206 offset:4480
	ds_write_b32 v221, v206 offset:4736
	s_mov_b32 s91, 256
	s_add_i32 s20, s91, 3
	s_and_b32 s20, s20, -4
	s_mov_b32 s24, s8
	s_and_b32 s25, s9, 0xffff
	s_mov_b32 s26, 0x20000
	s_mov_b32 s27, 0x00027000
	s_mov_b32 s28, s52
	s_and_b32 s29, s53, 0xffff
	s_mov_b32 s30, 0x20000
	s_mov_b32 s31, 0x00027000
	s_waitcnt vmcnt(0) lgkmcnt(0)
	v_mov_b32_e32 v213, s22
	v_mov_b32_e32 v233, v240
	v_mov_b32_e32 v235, v240
	v_mov_b32_e32 v237, v240
	v_mov_b32_e32 v239, v240
	ds_read_b32 v232, v213 offset:0
	ds_read_b32 v234, v213 offset:4
	ds_read_b32 v236, v213 offset:8
	ds_read_b32 v238, v213 offset:12
	s_waitcnt lgkmcnt(0)
	buffer_load_dwordx4 v[128:131], v[232:233], s[56:59], 0 idxen offen
	buffer_load_dwordx4 v[132:135], v[234:235], s[56:59], 0 idxen offen
	buffer_load_dwordx4 v[136:139], v[236:237], s[56:59], 0 idxen offen
	buffer_load_dwordx4 v[140:143], v[238:239], s[56:59], 0 idxen offen
	ds_read_b32 v232, v213 offset:16
	ds_read_b32 v234, v213 offset:20
	ds_read_b32 v236, v213 offset:24
	ds_read_b32 v238, v213 offset:28
	s_waitcnt lgkmcnt(0)
	buffer_load_dwordx4 v[144:147], v[232:233], s[56:59], 0 idxen offen
	buffer_load_dwordx4 v[148:151], v[234:235], s[56:59], 0 idxen offen
	buffer_load_dwordx4 v[152:155], v[236:237], s[56:59], 0 idxen offen
	buffer_load_dwordx4 v[156:159], v[238:239], s[56:59], 0 idxen offen
	ds_read_b32 v232, v213 offset:32
	ds_read_b32 v234, v213 offset:36
	ds_read_b32 v236, v213 offset:40
	ds_read_b32 v238, v213 offset:44
	s_waitcnt lgkmcnt(0)
	buffer_load_dwordx4 v[160:163], v[232:233], s[56:59], 0 idxen offen
	buffer_load_dwordx4 v[164:167], v[234:235], s[56:59], 0 idxen offen
	buffer_load_dwordx4 v[168:171], v[236:237], s[56:59], 0 idxen offen
	buffer_load_dwordx4 v[172:175], v[238:239], s[56:59], 0 idxen offen
	ds_read_b32 v232, v213 offset:48
	ds_read_b32 v234, v213 offset:52
	ds_read_b32 v236, v213 offset:56
	ds_read_b32 v238, v213 offset:60
	s_mov_b32 s21, 0
	s_mov_b32 s89, -1
	s_mov_b32 s86, 0
	v_lshrrev_b32_e32 v208, 6, v240
	v_and_b32_e32 v208, 3, v208
	v_lshrrev_b32_e32 v209, 1, v208
	v_lshlrev_b32_e32 v208, 1, v208
	v_and_b32_e32 v208, 2, v208
	v_or_b32_e32 v208, v208, v209
	v_lshlrev_b32_e32 v208, 2, v208
	v_add3_u32 v211, v208, v247, s22
	v_add_u32_e32 v250, s85, v211
	ds_read_b32 v252, v250
	ds_read_b32 v253, v250 offset:4096
	ds_read_b32 v249, v211 offset:4992
	s_branch .LU_sw0
